# LDS-DMA issue reordered so the VALU address add sits between the m0 write and the load (179 s_nop removed); on top of v45
# baseline (speedup 1.0000x reference)
; #define LDA8(dst, b, h) _Pragma("unroll") for (int m = 0; m < 4; ++m) _Pragma("unroll") for (int k = 0; k < 2; ++k) \
;     dst[m][k] = *(const bf16x8*)((const char*)SA8(b, h) + lds_byte8(wr * 64 + m * 16 + fr, k * 32 + fq * 8))
; #define LDB8(dst, b, h) _Pragma("unroll") for (int n = 0; n < 2; ++n) _Pragma("unroll") for (int k = 0; k < 2; ++k) \
;     dst[n][k] = *(const bf16x8*)((const char*)SB8(b, h) + lds_byte8(wc * 32 + n * 16 + fr, k * 32 + fq * 8))
; #define WAIT_V8(n) asm volatile("s_waitcnt vmcnt(" #n ")" ::: "memory")
; #define WAIT_L8(n) asm volatile("s_waitcnt lgkmcnt(" #n ")" ::: "memory")
; #define BAR8 __builtin_amdgcn_s_barrier()
; #define SCHED8 __builtin_amdgcn_sched_barrier(0)
;     ...
;     STAGE8(SB8(0, 0), Bt, K, bcol, 0); STAGE8(SA8(0, 0), A, lda, brow, 0);
;     STAGE8(SB8(0, 1), Bt, K, bcol + 128, 0); STAGE8(SA8(0, 1), A, lda, brow + 128, 0);
;   }
;   if (wr == 1) BAR8;
;   WAIT_V8(4); BAR8;
;   STAGE8(SB8(1, 0), Bt, K, bcol, 1); STAGE8(SA8(1, 0), A, lda, brow, 1); STAGE8(SB8(1, 1), Bt, K, bcol + 128, 1);
;   WAIT_V8(6); BAR8;
;   for (int tt = 0; tt < nt - 2; tt += 2) {
;     LDB8(B0, 0, 0); SCHED8; LDA8(At, 0, 0); STAGE8(SA8(1, 1), A, lda, brow + 128, tt + 1);
;     WAIT_L8(8); BAR8; WAIT_L8(0); MMA8(0, 0, At, B0); BAR8; SCHED8;
;     LDB8(B1, 0, 1); STAGE8(SB8(0, 0), Bt, K, bcol, tt + 2);
;     BAR8; WAIT_L8(0); MMA8(0, 1, At, B1); BAR8;
;     LDA8(At, 0, 1); STAGE8(SA8(0, 0), A, lda, brow, tt + 2);
;     BAR8; WAIT_L8(0); MMA8(1, 0, At, B0); BAR8; SCHED8;
.LBB0_191:
	s_or_b64 exec, exec, s[14:15]
	s_mov_b64 s[60:61], 0x80
	v_lshl_add_u64 v[10:11], v[10:11], 0, s[60:61]
	s_or_b32 m0, s100, 0x18000
	s_waitcnt vmcnt(4)
	s_barrier
	global_load_lds_dwordx4 v[10:11], off
	v_lshl_add_u64 v[10:11], v[12:13], 0, s[60:61]
	s_or_b32 m0, s100, 0x1a000
	global_load_lds_dwordx4 v[10:11], off
	v_lshl_add_u64 v[10:11], v[14:15], 0, s[60:61]
	s_or_b32 m0, s100, 0x8000
	global_load_lds_dwordx4 v[10:11], off
	v_lshl_add_u64 v[10:11], v[16:17], 0, s[60:61]
	s_or_b32 m0, s100, 0xa000
	global_load_lds_dwordx4 v[10:11], off
	s_or_b32 m0, s100, 0x1c000
	v_lshl_add_u64 v[10:11], v[18:19], 0, s[60:61]
	global_load_lds_dwordx4 v[10:11], off
	v_lshl_add_u64 v[10:11], v[20:21], 0, s[60:61]
	s_or_b32 m0, s100, 0x1e000
	v_and_b32_e32 v147, 15, v3
	global_load_lds_dwordx4 v[10:11], off
	v_bfe_u32 v148, v3, 4, 2
	v_lshlrev_b32_e32 v10, 4, v148
	v_lshlrev_b32_e32 v11, 6, v147
	v_lshlrev_b32_e32 v14, 2, v3
	v_or_b32_e32 v13, v10, v11
	v_and_b32_e32 v14, 32, v14
	s_mov_b32 s14, 0x10000
	v_bitop3_b32 v16, v13, s14, v14 bitop3:0xde
	s_mov_b32 s14, 0x14000
	v_bitop3_b32 v15, v10, v14, v11 bitop3:0x36
	v_bitop3_b32 v17, v13, s14, v14 bitop3:0xde
	s_mov_b32 s14, 0x18000
	v_lshlrev_b32_e32 v11, 6, v3
	v_bitop3_b32 v18, v13, s14, v14 bitop3:0xde
	s_mov_b32 s14, 0x1c000
	v_and_b32_e32 v11, 0x3c0, v11
	v_bitop3_b32 v13, v13, s14, v14 bitop3:0xde
	v_bitop3_b32 v14, v11, v14, v10 bitop3:0x36
	v_lshl_add_u64 v[10:11], s[30:31], 0, v[136:137]
	v_lshl_add_u64 v[10:11], v[10:11], 0, v[8:9]
	v_lshl_add_u64 v[138:139], s[12:13], 0, v[10:11]
	v_lshl_add_u64 v[10:11], s[30:31], 0, v[132:133]
	v_lshl_add_u64 v[10:11], v[10:11], 0, v[6:7]
	v_lshl_add_u64 v[140:141], s[12:13], 0, v[10:11]
	v_lshl_add_u64 v[10:11], s[56:57], 0, v[132:133]
	v_lshl_add_u64 v[6:7], v[10:11], 0, v[6:7]
	v_bfe_u32 v146, v3, 6, 2
	s_waitcnt vmcnt(6)
	v_lshlrev_b32_e32 v149, 6, v5
	v_lshlrev_b32_e32 v5, 13, v5
	v_lshl_add_u64 v[142:143], s[46:47], 0, v[6:7]
	v_lshl_add_u64 v[6:7], s[56:57], 0, v[136:137]
	v_lshlrev_b32_e32 v12, 12, v146
	v_or_b32_e32 v19, 0x800, v5
	v_or_b32_e32 v20, 0x1000, v5
	v_or_b32_e32 v21, 0x1800, v5
	v_lshl_add_u64 v[6:7], v[6:7], 0, v[8:9]
	v_lshl_add_u64 v[144:145], s[46:47], 0, v[6:7]
	s_mov_b32 s14, -2
	s_mov_b64 s[12:13], 0
	v_add_u32_e32 v173, v16, v12
	v_add_u32_e32 v156, v15, v5
	v_add_u32_e32 v154, v14, v19
	v_add_u32_e32 v153, v14, v20
	v_add_u32_e32 v152, v14, v21
	v_add_u32_e32 v169, v17, v12
	v_add_u32_e32 v159, v18, v12
	v_add_u32_e32 v158, v13, v12
	s_mov_b64 s[60:61], 0xc000100
	s_mov_b64 s[62:63], 0xc040100
	s_mov_b64 s[64:65], 0xc000180
	s_mov_b64 s[66:67], 0xc040180
	s_barrier
	ds_read_b128 v[174:177], v173
	ds_read_b128 v[178:181], v173 offset:1024
	ds_read_b128 v[182:185], v173 offset:2048
	ds_read_b128 v[186:189], v173 offset:3072
	v_lshl_add_u64 v[222:223], v[140:141], 0, s[12:13]
	v_lshl_add_u64 v[226:227], v[222:223], 0, s[34:35]
	s_or_b32 m0, s100, 0xc000
	ds_read_b128 v[190:193], v156
	ds_read_b128 v[194:197], v156 offset:1024
	ds_read_b128 v[198:201], v154
	ds_read_b128 v[202:205], v154 offset:1024
	ds_read_b128 v[206:209], v153
	ds_read_b128 v[210:213], v153 offset:1024
	ds_read_b128 v[214:217], v152
	ds_read_b128 v[218:221], v152 offset:1024
	global_load_lds_dwordx4 v[226:227], off
	v_lshl_add_u64 v[226:227], v[138:139], 0, s[12:13]
	s_or_b32 m0, s100, 0xe000
	v_lshl_add_u64 v[228:229], v[226:227], 0, s[34:35]
	global_load_lds_dwordx4 v[228:229], off
	s_waitcnt lgkmcnt(8)
	s_barrier
	s_waitcnt lgkmcnt(0)
	v_mfma_f32_16x16x32_f16 v[128:131], v[190:193], v[174:177], 0
	v_mfma_f32_16x16x32_f16 v[124:127], v[190:193], v[182:185], 0
	v_mfma_f32_16x16x32_f16 v[120:123], v[198:201], v[174:177], 0
	v_mfma_f32_16x16x32_f16 v[116:119], v[198:201], v[182:185], 0
	v_mfma_f32_16x16x32_f16 v[112:115], v[206:209], v[174:177], 0
	v_mfma_f32_16x16x32_f16 v[108:111], v[206:209], v[182:185], 0
	v_mfma_f32_16x16x32_f16 v[104:107], v[214:217], v[174:177], 0
	v_mfma_f32_16x16x32_f16 v[100:103], v[214:217], v[182:185], 0
	v_mfma_f32_16x16x32_f16 v[128:131], v[194:197], v[178:181], v[128:131]
	v_mfma_f32_16x16x32_f16 v[124:127], v[194:197], v[186:189], v[124:127]
	v_mfma_f32_16x16x32_f16 v[120:123], v[202:205], v[178:181], v[120:123]
	v_mfma_f32_16x16x32_f16 v[116:119], v[202:205], v[186:189], v[116:119]
	v_mfma_f32_16x16x32_f16 v[112:115], v[210:213], v[178:181], v[112:115]
	v_mfma_f32_16x16x32_f16 v[108:111], v[210:213], v[186:189], v[108:111]
	v_mfma_f32_16x16x32_f16 v[104:107], v[218:221], v[178:181], v[104:107]
	v_mfma_f32_16x16x32_f16 v[100:103], v[218:221], v[186:189], v[100:103]
	s_barrier
	v_lshl_add_u64 v[228:229], v[142:143], 0, s[12:13]
	v_lshl_add_u64 v[236:237], v[228:229], 0, s[60:61]
	s_or_b32 m0, s100, 0x10000
	ds_read_b128 v[238:241], v169
	ds_read_b128 v[242:245], v169 offset:1024
	ds_read_b128 v[246:249], v169 offset:2048
	ds_read_b128 v[230:233], v169 offset:3072
	global_load_lds_dwordx4 v[236:237], off
	v_lshl_add_u64 v[236:237], v[144:145], 0, s[12:13]
	s_or_b32 m0, s100, 0x12000
	v_lshl_add_u64 v[250:251], v[236:237], 0, s[60:61]
	global_load_lds_dwordx4 v[250:251], off
	s_barrier
; #define LDA8(dst, b, h) _Pragma("unroll") for (int m = 0; m < 4; ++m) _Pragma("unroll") for (int k = 0; k < 2; ++k) \
;     dst[m][k] = *(const bf16x8*)((const char*)SA8(b, h) + lds_byte8(wr * 64 + m * 16 + fr, k * 32 + fq * 8))
; #define LDB8(dst, b, h) _Pragma("unroll") for (int n = 0; n < 2; ++n) _Pragma("unroll") for (int k = 0; k < 2; ++k) \
;     dst[n][k] = *(const bf16x8*)((const char*)SB8(b, h) + lds_byte8(wc * 32 + n * 16 + fr, k * 32 + fq * 8))
; #define WAIT_V8(n) asm volatile("s_waitcnt vmcnt(" #n ")" ::: "memory")
; #define WAIT_L8(n) asm volatile("s_waitcnt lgkmcnt(" #n ")" ::: "memory")
; #define BAR8 __builtin_amdgcn_s_barrier()
; #define SCHED8 __builtin_amdgcn_sched_barrier(0)
;     ...
;     WAIT_L8(8); BAR8; WAIT_L8(0); MMA8(0, 0, At, B0); BAR8; SCHED8;
;     LDB8(B1, 0, 1); STAGE8(SB8(0, 0), Bt, K, bcol, tt + 2);
;     BAR8; WAIT_L8(0); MMA8(0, 1, At, B1); BAR8;
;     LDA8(At, 0, 1); STAGE8(SA8(0, 0), A, lda, brow, tt + 2);
;     BAR8; WAIT_L8(0); MMA8(1, 0, At, B0); BAR8; SCHED8;
;     STAGE8(SB8(0, 1), Bt, K, bcol + 128, tt + 2);
;     WAIT_V8(6); BAR8; MMA8(1, 1, At, B1); BAR8;
;     LDB8(B0, 1, 0); SCHED8; LDA8(At, 1, 0); STAGE8(SA8(0, 1), A, lda, brow + 128, tt + 2);
;     WAIT_L8(8); BAR8; WAIT_L8(0); MMA8(0, 0, At, B0); BAR8; SCHED8;
	s_waitcnt lgkmcnt(0)
	v_mfma_f32_16x16x32_f16 v[96:99], v[190:193], v[238:241], 0
	v_mfma_f32_16x16x32_f16 v[92:95], v[190:193], v[246:249], 0
	v_mfma_f32_16x16x32_f16 v[88:91], v[198:201], v[238:241], 0
	v_mfma_f32_16x16x32_f16 v[84:87], v[198:201], v[246:249], 0
	v_mfma_f32_16x16x32_f16 v[80:83], v[206:209], v[238:241], 0
	v_mfma_f32_16x16x32_f16 v[76:79], v[206:209], v[246:249], 0
	v_mfma_f32_16x16x32_f16 v[72:75], v[214:217], v[238:241], 0
	v_mfma_f32_16x16x32_f16 v[68:71], v[214:217], v[246:249], 0
	v_mfma_f32_16x16x32_f16 v[96:99], v[194:197], v[242:245], v[96:99]
	v_mfma_f32_16x16x32_f16 v[92:95], v[194:197], v[230:233], v[92:95]
	v_mfma_f32_16x16x32_f16 v[88:91], v[202:205], v[242:245], v[88:91]
	v_mfma_f32_16x16x32_f16 v[84:87], v[202:205], v[230:233], v[84:87]
	v_mfma_f32_16x16x32_f16 v[80:83], v[210:213], v[242:245], v[80:83]
	v_mfma_f32_16x16x32_f16 v[76:79], v[210:213], v[230:233], v[76:79]
	v_mfma_f32_16x16x32_f16 v[72:75], v[218:221], v[242:245], v[72:75]
	v_mfma_f32_16x16x32_f16 v[68:71], v[218:221], v[230:233], v[68:71]
	v_lshl_add_u64 v[250:251], v[222:223], 0, s[10:11]
	s_mov_b32 m0, s100
	s_barrier
	ds_read_b128 v[190:193], v156 offset:16384
	ds_read_b128 v[194:197], v156 offset:17408
	ds_read_b128 v[198:201], v154 offset:16384
	ds_read_b128 v[202:205], v154 offset:17408
	ds_read_b128 v[206:209], v153 offset:16384
	ds_read_b128 v[210:213], v153 offset:17408
	ds_read_b128 v[214:217], v152 offset:16384
	ds_read_b128 v[218:221], v152 offset:17408
	global_load_lds_dwordx4 v[250:251], off
	s_or_b32 m0, s100, 0x2000
	v_lshl_add_u64 v[250:251], v[226:227], 0, s[10:11]
	global_load_lds_dwordx4 v[250:251], off
	s_barrier
	s_waitcnt lgkmcnt(0)
	v_mfma_f32_16x16x32_f16 v[64:67], v[190:193], v[174:177], 0
	v_mfma_f32_16x16x32_f16 v[60:63], v[190:193], v[182:185], 0
	v_mfma_f32_16x16x32_f16 v[56:59], v[198:201], v[174:177], 0
	v_mfma_f32_16x16x32_f16 v[52:55], v[198:201], v[182:185], 0
	v_mfma_f32_16x16x32_f16 v[48:51], v[206:209], v[174:177], 0
	v_mfma_f32_16x16x32_f16 v[44:47], v[206:209], v[182:185], 0
	v_mfma_f32_16x16x32_f16 v[40:43], v[214:217], v[174:177], 0
	v_mfma_f32_16x16x32_f16 v[36:39], v[214:217], v[182:185], 0
	v_mfma_f32_16x16x32_f16 v[64:67], v[194:197], v[178:181], v[64:67]
	v_mfma_f32_16x16x32_f16 v[60:63], v[194:197], v[186:189], v[60:63]
	v_mfma_f32_16x16x32_f16 v[56:59], v[202:205], v[178:181], v[56:59]
	v_mfma_f32_16x16x32_f16 v[52:55], v[202:205], v[186:189], v[52:55]
	v_mfma_f32_16x16x32_f16 v[48:51], v[210:213], v[178:181], v[48:51]
	v_mfma_f32_16x16x32_f16 v[44:47], v[210:213], v[186:189], v[44:47]
	v_mfma_f32_16x16x32_f16 v[40:43], v[218:221], v[178:181], v[40:43]
	v_mfma_f32_16x16x32_f16 v[36:39], v[218:221], v[186:189], v[36:39]
	s_barrier
	s_or_b32 m0, s100, 0x14000
	v_lshl_add_u64 v[174:175], v[228:229], 0, s[62:63]
	global_load_lds_dwordx4 v[174:175], off
	s_or_b32 m0, s100, 0x16000
	v_lshl_add_u64 v[174:175], v[236:237], 0, s[62:63]
	global_load_lds_dwordx4 v[174:175], off
	s_waitcnt vmcnt(6)
	s_barrier
	v_mfma_f32_16x16x32_f16 v[32:35], v[190:193], v[238:241], 0
	v_mfma_f32_16x16x32_f16 v[28:31], v[190:193], v[246:249], 0
	v_mfma_f32_16x16x32_f16 v[24:27], v[198:201], v[238:241], 0
	v_mfma_f32_16x16x32_f16 v[20:23], v[198:201], v[246:249], 0
	v_mfma_f32_16x16x32_f16 v[16:19], v[206:209], v[238:241], 0
	v_mfma_f32_16x16x32_f16 v[12:15], v[206:209], v[246:249], 0
	v_mfma_f32_16x16x32_f16 v[8:11], v[214:217], v[238:241], 0
	v_mfma_f32_16x16x32_f16 v[4:7], v[214:217], v[246:249], 0
	v_mfma_f32_16x16x32_f16 v[32:35], v[194:197], v[242:245], v[32:35]
	v_mfma_f32_16x16x32_f16 v[28:31], v[194:197], v[230:233], v[28:31]
	v_mfma_f32_16x16x32_f16 v[24:27], v[202:205], v[242:245], v[24:27]
	v_mfma_f32_16x16x32_f16 v[20:23], v[202:205], v[230:233], v[20:23]
	v_mfma_f32_16x16x32_f16 v[16:19], v[210:213], v[242:245], v[16:19]
	v_mfma_f32_16x16x32_f16 v[12:15], v[210:213], v[230:233], v[12:15]
	v_mfma_f32_16x16x32_f16 v[8:11], v[218:221], v[242:245], v[8:11]
	v_mfma_f32_16x16x32_f16 v[4:7], v[218:221], v[230:233], v[4:7]
	s_barrier
	ds_read_b128 v[174:177], v159
	ds_read_b128 v[178:181], v159 offset:1024
	ds_read_b128 v[182:185], v159 offset:2048
	ds_read_b128 v[186:189], v159 offset:3072
	v_lshl_add_u64 v[230:231], v[222:223], 0, s[18:19]
	s_or_b32 m0, s100, 0x4000
	ds_read_b128 v[190:193], v156 offset:32768
	ds_read_b128 v[194:197], v156 offset:33792
	ds_read_b128 v[198:201], v154 offset:32768
	ds_read_b128 v[202:205], v154 offset:33792
	ds_read_b128 v[206:209], v153 offset:32768
	ds_read_b128 v[210:213], v153 offset:33792
	ds_read_b128 v[214:217], v152 offset:32768
	ds_read_b128 v[218:221], v152 offset:33792
	global_load_lds_dwordx4 v[230:231], off
	s_or_b32 m0, s100, 0x6000
	v_lshl_add_u64 v[230:231], v[226:227], 0, s[18:19]
	global_load_lds_dwordx4 v[230:231], off
	s_waitcnt lgkmcnt(8)
	s_barrier
	s_waitcnt lgkmcnt(0)
	v_mfma_f32_16x16x32_f16 v[128:131], v[190:193], v[174:177], v[128:131]
	v_mfma_f32_16x16x32_f16 v[124:127], v[190:193], v[182:185], v[124:127]
	v_mfma_f32_16x16x32_f16 v[120:123], v[198:201], v[174:177], v[120:123]
	v_mfma_f32_16x16x32_f16 v[116:119], v[198:201], v[182:185], v[116:119]
	v_mfma_f32_16x16x32_f16 v[112:115], v[206:209], v[174:177], v[112:115]
	v_mfma_f32_16x16x32_f16 v[108:111], v[206:209], v[182:185], v[108:111]
	v_mfma_f32_16x16x32_f16 v[104:107], v[214:217], v[174:177], v[104:107]
	v_mfma_f32_16x16x32_f16 v[100:103], v[214:217], v[182:185], v[100:103]
	v_mfma_f32_16x16x32_f16 v[128:131], v[194:197], v[178:181], v[128:131]
	v_mfma_f32_16x16x32_f16 v[124:127], v[194:197], v[186:189], v[124:127]
	v_mfma_f32_16x16x32_f16 v[120:123], v[202:205], v[178:181], v[120:123]
	v_mfma_f32_16x16x32_f16 v[116:119], v[202:205], v[186:189], v[116:119]
	v_mfma_f32_16x16x32_f16 v[112:115], v[210:213], v[178:181], v[112:115]
	v_mfma_f32_16x16x32_f16 v[108:111], v[210:213], v[186:189], v[108:111]
	v_mfma_f32_16x16x32_f16 v[104:107], v[218:221], v[178:181], v[104:107]
	v_mfma_f32_16x16x32_f16 v[100:103], v[218:221], v[186:189], v[100:103]
	s_barrier
; #define LDA8(dst, b, h) _Pragma("unroll") for (int m = 0; m < 4; ++m) _Pragma("unroll") for (int k = 0; k < 2; ++k) \
;     dst[m][k] = *(const bf16x8*)((const char*)SA8(b, h) + lds_byte8(wr * 64 + m * 16 + fr, k * 32 + fq * 8))
; #define LDB8(dst, b, h) _Pragma("unroll") for (int n = 0; n < 2; ++n) _Pragma("unroll") for (int k = 0; k < 2; ++k) \
;     dst[n][k] = *(const bf16x8*)((const char*)SB8(b, h) + lds_byte8(wc * 32 + n * 16 + fr, k * 32 + fq * 8))
; #define WAIT_V8(n) asm volatile("s_waitcnt vmcnt(" #n ")" ::: "memory")
; #define WAIT_L8(n) asm volatile("s_waitcnt lgkmcnt(" #n ")" ::: "memory")
; #define BAR8 __builtin_amdgcn_s_barrier()
; #define SCHED8 __builtin_amdgcn_sched_barrier(0)
;     ...
;     WAIT_L8(8); BAR8; WAIT_L8(0); MMA8(0, 0, At, B0); BAR8; SCHED8;
;     LDB8(B1, 1, 1); STAGE8(SB8(1, 0), Bt, K, bcol, tt + 3);
;     BAR8; WAIT_L8(0); MMA8(0, 1, At, B1); BAR8;
;     LDA8(At, 1, 1); STAGE8(SA8(1, 0), A, lda, brow, tt + 3);
;     BAR8; WAIT_L8(0); MMA8(1, 0, At, B0); BAR8; SCHED8;
;     STAGE8(SB8(1, 1), Bt, K, bcol + 128, tt + 3);
;     WAIT_V8(6); BAR8; MMA8(1, 1, At, B1); BAR8;
;   }
	v_lshl_add_u64 v[250:251], v[228:229], 0, s[64:65]
	s_or_b32 m0, s100, 0x18000
	ds_read_b128 v[230:233], v158
	ds_read_b128 v[238:241], v158 offset:1024
	ds_read_b128 v[242:245], v158 offset:2048
	ds_read_b128 v[246:249], v158 offset:3072
	global_load_lds_dwordx4 v[250:251], off
	s_or_b32 m0, s100, 0x1a000
	v_lshl_add_u64 v[250:251], v[236:237], 0, s[64:65]
	global_load_lds_dwordx4 v[250:251], off
	s_barrier
	s_waitcnt lgkmcnt(0)
	v_mfma_f32_16x16x32_f16 v[96:99], v[190:193], v[230:233], v[96:99]
	v_mfma_f32_16x16x32_f16 v[92:95], v[190:193], v[242:245], v[92:95]
	v_mfma_f32_16x16x32_f16 v[88:91], v[198:201], v[230:233], v[88:91]
	v_mfma_f32_16x16x32_f16 v[84:87], v[198:201], v[242:245], v[84:87]
	v_mfma_f32_16x16x32_f16 v[80:83], v[206:209], v[230:233], v[80:83]
	v_mfma_f32_16x16x32_f16 v[76:79], v[206:209], v[242:245], v[76:79]
	v_mfma_f32_16x16x32_f16 v[72:75], v[214:217], v[230:233], v[72:75]
	v_mfma_f32_16x16x32_f16 v[68:71], v[214:217], v[242:245], v[68:71]
	v_mfma_f32_16x16x32_f16 v[96:99], v[194:197], v[238:241], v[96:99]
	v_mfma_f32_16x16x32_f16 v[92:95], v[194:197], v[246:249], v[92:95]
	v_mfma_f32_16x16x32_f16 v[88:91], v[202:205], v[238:241], v[88:91]
	v_mfma_f32_16x16x32_f16 v[84:87], v[202:205], v[246:249], v[84:87]
	v_mfma_f32_16x16x32_f16 v[80:83], v[210:213], v[238:241], v[80:83]
	v_mfma_f32_16x16x32_f16 v[76:79], v[210:213], v[246:249], v[76:79]
	v_mfma_f32_16x16x32_f16 v[72:75], v[218:221], v[238:241], v[72:75]
	v_mfma_f32_16x16x32_f16 v[68:71], v[218:221], v[246:249], v[68:71]
	v_lshl_add_u64 v[222:223], v[222:223], 0, s[22:23]
	s_or_b32 m0, s100, 0x8000
	s_barrier
	ds_read_b128 v[190:193], v156 offset:49152
	ds_read_b128 v[194:197], v156 offset:50176
	ds_read_b128 v[198:201], v154 offset:49152
	ds_read_b128 v[202:205], v154 offset:50176
	ds_read_b128 v[206:209], v153 offset:49152
	ds_read_b128 v[210:213], v153 offset:50176
	ds_read_b128 v[214:217], v152 offset:49152
	ds_read_b128 v[218:221], v152 offset:50176
	global_load_lds_dwordx4 v[222:223], off
	s_or_b32 m0, s100, 0xa000
	v_lshl_add_u64 v[222:223], v[226:227], 0, s[22:23]
	global_load_lds_dwordx4 v[222:223], off
	s_barrier
	s_waitcnt lgkmcnt(0)
	v_mfma_f32_16x16x32_f16 v[64:67], v[190:193], v[174:177], v[64:67]
	v_mfma_f32_16x16x32_f16 v[60:63], v[190:193], v[182:185], v[60:63]
	v_mfma_f32_16x16x32_f16 v[56:59], v[198:201], v[174:177], v[56:59]
	v_mfma_f32_16x16x32_f16 v[52:55], v[198:201], v[182:185], v[52:55]
	v_mfma_f32_16x16x32_f16 v[48:51], v[206:209], v[174:177], v[48:51]
	v_mfma_f32_16x16x32_f16 v[44:47], v[206:209], v[182:185], v[44:47]
	v_mfma_f32_16x16x32_f16 v[40:43], v[214:217], v[174:177], v[40:43]
	v_mfma_f32_16x16x32_f16 v[36:39], v[214:217], v[182:185], v[36:39]
	v_mfma_f32_16x16x32_f16 v[64:67], v[194:197], v[178:181], v[64:67]
	v_mfma_f32_16x16x32_f16 v[60:63], v[194:197], v[186:189], v[60:63]
	v_mfma_f32_16x16x32_f16 v[56:59], v[202:205], v[178:181], v[56:59]
	v_mfma_f32_16x16x32_f16 v[52:55], v[202:205], v[186:189], v[52:55]
	v_mfma_f32_16x16x32_f16 v[48:51], v[210:213], v[178:181], v[48:51]
	v_mfma_f32_16x16x32_f16 v[44:47], v[210:213], v[186:189], v[44:47]
	v_mfma_f32_16x16x32_f16 v[40:43], v[218:221], v[178:181], v[40:43]
	v_mfma_f32_16x16x32_f16 v[36:39], v[218:221], v[186:189], v[36:39]
	s_barrier
	s_or_b32 m0, s100, 0x1c000
	v_lshl_add_u64 v[174:175], v[228:229], 0, s[66:67]
	global_load_lds_dwordx4 v[174:175], off
	s_or_b32 m0, s100, 0x1e000
	v_lshl_add_u64 v[174:175], v[236:237], 0, s[66:67]
	global_load_lds_dwordx4 v[174:175], off
	s_waitcnt vmcnt(6)
	s_barrier
	v_mfma_f32_16x16x32_f16 v[32:35], v[190:193], v[230:233], v[32:35]
	v_mfma_f32_16x16x32_f16 v[28:31], v[190:193], v[242:245], v[28:31]
	v_mfma_f32_16x16x32_f16 v[24:27], v[198:201], v[230:233], v[24:27]
	v_mfma_f32_16x16x32_f16 v[20:23], v[198:201], v[242:245], v[20:23]
	v_mfma_f32_16x16x32_f16 v[16:19], v[206:209], v[230:233], v[16:19]
	v_mfma_f32_16x16x32_f16 v[12:15], v[206:209], v[242:245], v[12:15]
	v_mfma_f32_16x16x32_f16 v[8:11], v[214:217], v[230:233], v[8:11]
	v_mfma_f32_16x16x32_f16 v[4:7], v[214:217], v[242:245], v[4:7]
	v_mfma_f32_16x16x32_f16 v[32:35], v[194:197], v[238:241], v[32:35]
	v_mfma_f32_16x16x32_f16 v[28:31], v[194:197], v[246:249], v[28:31]
	v_mfma_f32_16x16x32_f16 v[24:27], v[202:205], v[238:241], v[24:27]
	v_mfma_f32_16x16x32_f16 v[20:23], v[202:205], v[246:249], v[20:23]
	v_mfma_f32_16x16x32_f16 v[16:19], v[210:213], v[238:241], v[16:19]
	v_mfma_f32_16x16x32_f16 v[12:15], v[210:213], v[246:249], v[12:15]
	v_mfma_f32_16x16x32_f16 v[8:11], v[218:221], v[238:241], v[8:11]
	v_mfma_f32_16x16x32_f16 v[4:7], v[218:221], v[246:249], v[4:7]
	s_add_i32 s14, s14, 2
	s_add_u32 s12, s12, 0x100
	s_addc_u32 s13, s13, 0
	s_cmp_lt_u32 s14, 12
	s_barrier
	s_cbranch_scc0 .Lpk_exit_0
; #define LDA8(dst, b, h) _Pragma("unroll") for (int m = 0; m < 4; ++m) _Pragma("unroll") for (int k = 0; k < 2; ++k) \
;     dst[m][k] = *(const bf16x8*)((const char*)SA8(b, h) + lds_byte8(wr * 64 + m * 16 + fr, k * 32 + fq * 8))
; #define LDB8(dst, b, h) _Pragma("unroll") for (int n = 0; n < 2; ++n) _Pragma("unroll") for (int k = 0; k < 2; ++k) \
;     dst[n][k] = *(const bf16x8*)((const char*)SB8(b, h) + lds_byte8(wc * 32 + n * 16 + fr, k * 32 + fq * 8))
; #define WAIT_V8(n) asm volatile("s_waitcnt vmcnt(" #n ")" ::: "memory")
; #define WAIT_L8(n) asm volatile("s_waitcnt lgkmcnt(" #n ")" ::: "memory")
; #define BAR8 __builtin_amdgcn_s_barrier()
; #define SCHED8 __builtin_amdgcn_sched_barrier(0)
;     ...
;   for (int tt = 0; tt < nt - 2; tt += 2) {
;     LDB8(B0, 0, 0); SCHED8; LDA8(At, 0, 0); STAGE8(SA8(1, 1), A, lda, brow + 128, tt + 1);
;     WAIT_L8(8); BAR8; WAIT_L8(0); MMA8(0, 0, At, B0); BAR8; SCHED8;
;     LDB8(B1, 0, 1); STAGE8(SB8(0, 0), Bt, K, bcol, tt + 2);
;     BAR8; WAIT_L8(0); MMA8(0, 1, At, B1); BAR8;
;     LDA8(At, 0, 1); STAGE8(SA8(0, 0), A, lda, brow, tt + 2);
;     BAR8; WAIT_L8(0); MMA8(1, 0, At, B0); BAR8; SCHED8;
;     STAGE8(SB8(0, 1), Bt, K, bcol + 128, tt + 2);
;     WAIT_V8(6); BAR8; MMA8(1, 1, At, B1); BAR8;
;     LDB8(B0, 1, 0); SCHED8; LDA8(At, 1, 0); STAGE8(SA8(0, 1), A, lda, brow + 128, tt + 2);
;     WAIT_L8(8); BAR8; WAIT_L8(0); MMA8(0, 0, At, B0); BAR8; SCHED8;
.LBB0_192:
	ds_read_b128 v[174:177], v173
	ds_read_b128 v[178:181], v173 offset:1024
	ds_read_b128 v[182:185], v173 offset:2048
	ds_read_b128 v[186:189], v173 offset:3072
	v_lshl_add_u64 v[222:223], v[140:141], 0, s[12:13]
	v_lshl_add_u64 v[226:227], v[222:223], 0, s[34:35]
	s_or_b32 m0, s100, 0xc000
	ds_read_b128 v[190:193], v156
	ds_read_b128 v[194:197], v156 offset:1024
	ds_read_b128 v[198:201], v154
	ds_read_b128 v[202:205], v154 offset:1024
	ds_read_b128 v[206:209], v153
	ds_read_b128 v[210:213], v153 offset:1024
	ds_read_b128 v[214:217], v152
	ds_read_b128 v[218:221], v152 offset:1024
	global_load_lds_dwordx4 v[226:227], off
	v_lshl_add_u64 v[226:227], v[138:139], 0, s[12:13]
	s_or_b32 m0, s100, 0xe000
	v_lshl_add_u64 v[228:229], v[226:227], 0, s[34:35]
	global_load_lds_dwordx4 v[228:229], off
	s_waitcnt lgkmcnt(8)
	s_barrier
	s_waitcnt lgkmcnt(0)
	v_mfma_f32_16x16x32_f16 v[128:131], v[190:193], v[174:177], v[128:131]
	v_mfma_f32_16x16x32_f16 v[124:127], v[190:193], v[182:185], v[124:127]
	v_mfma_f32_16x16x32_f16 v[120:123], v[198:201], v[174:177], v[120:123]
	v_mfma_f32_16x16x32_f16 v[116:119], v[198:201], v[182:185], v[116:119]
	v_mfma_f32_16x16x32_f16 v[112:115], v[206:209], v[174:177], v[112:115]
	v_mfma_f32_16x16x32_f16 v[108:111], v[206:209], v[182:185], v[108:111]
	v_mfma_f32_16x16x32_f16 v[104:107], v[214:217], v[174:177], v[104:107]
	v_mfma_f32_16x16x32_f16 v[100:103], v[214:217], v[182:185], v[100:103]
	v_mfma_f32_16x16x32_f16 v[128:131], v[194:197], v[178:181], v[128:131]
	v_mfma_f32_16x16x32_f16 v[124:127], v[194:197], v[186:189], v[124:127]
	v_mfma_f32_16x16x32_f16 v[120:123], v[202:205], v[178:181], v[120:123]
	v_mfma_f32_16x16x32_f16 v[116:119], v[202:205], v[186:189], v[116:119]
	v_mfma_f32_16x16x32_f16 v[112:115], v[210:213], v[178:181], v[112:115]
	v_mfma_f32_16x16x32_f16 v[108:111], v[210:213], v[186:189], v[108:111]
	v_mfma_f32_16x16x32_f16 v[104:107], v[218:221], v[178:181], v[104:107]
	v_mfma_f32_16x16x32_f16 v[100:103], v[218:221], v[186:189], v[100:103]
	s_barrier
	v_lshl_add_u64 v[228:229], v[142:143], 0, s[12:13]
	v_lshl_add_u64 v[236:237], v[228:229], 0, s[60:61]
	s_or_b32 m0, s100, 0x10000
	ds_read_b128 v[238:241], v169
	ds_read_b128 v[242:245], v169 offset:1024
	ds_read_b128 v[246:249], v169 offset:2048
	ds_read_b128 v[230:233], v169 offset:3072
	global_load_lds_dwordx4 v[236:237], off
	v_lshl_add_u64 v[236:237], v[144:145], 0, s[12:13]
	s_or_b32 m0, s100, 0x12000
	v_lshl_add_u64 v[250:251], v[236:237], 0, s[60:61]
	global_load_lds_dwordx4 v[250:251], off
	s_barrier
	s_waitcnt lgkmcnt(0)
	v_mfma_f32_16x16x32_f16 v[96:99], v[190:193], v[238:241], v[96:99]
	v_mfma_f32_16x16x32_f16 v[92:95], v[190:193], v[246:249], v[92:95]
	v_mfma_f32_16x16x32_f16 v[88:91], v[198:201], v[238:241], v[88:91]
	v_mfma_f32_16x16x32_f16 v[84:87], v[198:201], v[246:249], v[84:87]
	v_mfma_f32_16x16x32_f16 v[80:83], v[206:209], v[238:241], v[80:83]
	v_mfma_f32_16x16x32_f16 v[76:79], v[206:209], v[246:249], v[76:79]
	v_mfma_f32_16x16x32_f16 v[72:75], v[214:217], v[238:241], v[72:75]
	v_mfma_f32_16x16x32_f16 v[68:71], v[214:217], v[246:249], v[68:71]
	v_mfma_f32_16x16x32_f16 v[96:99], v[194:197], v[242:245], v[96:99]
	v_mfma_f32_16x16x32_f16 v[92:95], v[194:197], v[230:233], v[92:95]
	v_mfma_f32_16x16x32_f16 v[88:91], v[202:205], v[242:245], v[88:91]
	v_mfma_f32_16x16x32_f16 v[84:87], v[202:205], v[230:233], v[84:87]
	v_mfma_f32_16x16x32_f16 v[80:83], v[210:213], v[242:245], v[80:83]
	v_mfma_f32_16x16x32_f16 v[76:79], v[210:213], v[230:233], v[76:79]
	v_mfma_f32_16x16x32_f16 v[72:75], v[218:221], v[242:245], v[72:75]
	v_mfma_f32_16x16x32_f16 v[68:71], v[218:221], v[230:233], v[68:71]
	v_lshl_add_u64 v[250:251], v[222:223], 0, s[10:11]
	s_mov_b32 m0, s100
	s_barrier
	ds_read_b128 v[190:193], v156 offset:16384
	ds_read_b128 v[194:197], v156 offset:17408
	ds_read_b128 v[198:201], v154 offset:16384
	ds_read_b128 v[202:205], v154 offset:17408
	ds_read_b128 v[206:209], v153 offset:16384
	ds_read_b128 v[210:213], v153 offset:17408
	ds_read_b128 v[214:217], v152 offset:16384
	ds_read_b128 v[218:221], v152 offset:17408
	global_load_lds_dwordx4 v[250:251], off
	s_or_b32 m0, s100, 0x2000
	v_lshl_add_u64 v[250:251], v[226:227], 0, s[10:11]
	global_load_lds_dwordx4 v[250:251], off
	s_barrier
	s_waitcnt lgkmcnt(0)
	v_mfma_f32_16x16x32_f16 v[64:67], v[190:193], v[174:177], v[64:67]
	v_mfma_f32_16x16x32_f16 v[60:63], v[190:193], v[182:185], v[60:63]
	v_mfma_f32_16x16x32_f16 v[56:59], v[198:201], v[174:177], v[56:59]
	v_mfma_f32_16x16x32_f16 v[52:55], v[198:201], v[182:185], v[52:55]
	v_mfma_f32_16x16x32_f16 v[48:51], v[206:209], v[174:177], v[48:51]
	v_mfma_f32_16x16x32_f16 v[44:47], v[206:209], v[182:185], v[44:47]
	v_mfma_f32_16x16x32_f16 v[40:43], v[214:217], v[174:177], v[40:43]
	v_mfma_f32_16x16x32_f16 v[36:39], v[214:217], v[182:185], v[36:39]
	v_mfma_f32_16x16x32_f16 v[64:67], v[194:197], v[178:181], v[64:67]
	v_mfma_f32_16x16x32_f16 v[60:63], v[194:197], v[186:189], v[60:63]
	v_mfma_f32_16x16x32_f16 v[56:59], v[202:205], v[178:181], v[56:59]
	v_mfma_f32_16x16x32_f16 v[52:55], v[202:205], v[186:189], v[52:55]
	v_mfma_f32_16x16x32_f16 v[48:51], v[210:213], v[178:181], v[48:51]
	v_mfma_f32_16x16x32_f16 v[44:47], v[210:213], v[186:189], v[44:47]
	v_mfma_f32_16x16x32_f16 v[40:43], v[218:221], v[178:181], v[40:43]
	v_mfma_f32_16x16x32_f16 v[36:39], v[218:221], v[186:189], v[36:39]
	s_barrier
	s_or_b32 m0, s100, 0x14000
	v_lshl_add_u64 v[174:175], v[228:229], 0, s[62:63]
	global_load_lds_dwordx4 v[174:175], off
	s_or_b32 m0, s100, 0x16000
	v_lshl_add_u64 v[174:175], v[236:237], 0, s[62:63]
	global_load_lds_dwordx4 v[174:175], off
	s_waitcnt vmcnt(6)
	s_barrier
; #define LDA8(dst, b, h) _Pragma("unroll") for (int m = 0; m < 4; ++m) _Pragma("unroll") for (int k = 0; k < 2; ++k) \
;     dst[m][k] = *(const bf16x8*)((const char*)SA8(b, h) + lds_byte8(wr * 64 + m * 16 + fr, k * 32 + fq * 8))
; #define LDB8(dst, b, h) _Pragma("unroll") for (int n = 0; n < 2; ++n) _Pragma("unroll") for (int k = 0; k < 2; ++k) \
;     dst[n][k] = *(const bf16x8*)((const char*)SB8(b, h) + lds_byte8(wc * 32 + n * 16 + fr, k * 32 + fq * 8))
; #define WAIT_V8(n) asm volatile("s_waitcnt vmcnt(" #n ")" ::: "memory")
; #define WAIT_L8(n) asm volatile("s_waitcnt lgkmcnt(" #n ")" ::: "memory")
; #define BAR8 __builtin_amdgcn_s_barrier()
; #define SCHED8 __builtin_amdgcn_sched_barrier(0)
;     ...
;     WAIT_V8(6); BAR8; MMA8(1, 1, At, B1); BAR8;
;     LDB8(B0, 1, 0); SCHED8; LDA8(At, 1, 0); STAGE8(SA8(0, 1), A, lda, brow + 128, tt + 2);
;     WAIT_L8(8); BAR8; WAIT_L8(0); MMA8(0, 0, At, B0); BAR8; SCHED8;
;     LDB8(B1, 1, 1); STAGE8(SB8(1, 0), Bt, K, bcol, tt + 3);
;     BAR8; WAIT_L8(0); MMA8(0, 1, At, B1); BAR8;
;     LDA8(At, 1, 1); STAGE8(SA8(1, 0), A, lda, brow, tt + 3);
;     BAR8; WAIT_L8(0); MMA8(1, 0, At, B0); BAR8; SCHED8;
	v_mfma_f32_16x16x32_f16 v[32:35], v[190:193], v[238:241], v[32:35]
	v_mfma_f32_16x16x32_f16 v[28:31], v[190:193], v[246:249], v[28:31]
	v_mfma_f32_16x16x32_f16 v[24:27], v[198:201], v[238:241], v[24:27]
	v_mfma_f32_16x16x32_f16 v[20:23], v[198:201], v[246:249], v[20:23]
	v_mfma_f32_16x16x32_f16 v[16:19], v[206:209], v[238:241], v[16:19]
	v_mfma_f32_16x16x32_f16 v[12:15], v[206:209], v[246:249], v[12:15]
	v_mfma_f32_16x16x32_f16 v[8:11], v[214:217], v[238:241], v[8:11]
	v_mfma_f32_16x16x32_f16 v[4:7], v[214:217], v[246:249], v[4:7]
	v_mfma_f32_16x16x32_f16 v[32:35], v[194:197], v[242:245], v[32:35]
	v_mfma_f32_16x16x32_f16 v[28:31], v[194:197], v[230:233], v[28:31]
	v_mfma_f32_16x16x32_f16 v[24:27], v[202:205], v[242:245], v[24:27]
	v_mfma_f32_16x16x32_f16 v[20:23], v[202:205], v[230:233], v[20:23]
	v_mfma_f32_16x16x32_f16 v[16:19], v[210:213], v[242:245], v[16:19]
	v_mfma_f32_16x16x32_f16 v[12:15], v[210:213], v[230:233], v[12:15]
	v_mfma_f32_16x16x32_f16 v[8:11], v[218:221], v[242:245], v[8:11]
	v_mfma_f32_16x16x32_f16 v[4:7], v[218:221], v[230:233], v[4:7]
	s_barrier
	ds_read_b128 v[174:177], v159
	ds_read_b128 v[178:181], v159 offset:1024
	ds_read_b128 v[182:185], v159 offset:2048
	ds_read_b128 v[186:189], v159 offset:3072
	v_lshl_add_u64 v[230:231], v[222:223], 0, s[18:19]
	s_or_b32 m0, s100, 0x4000
	ds_read_b128 v[190:193], v156 offset:32768
	ds_read_b128 v[194:197], v156 offset:33792
	ds_read_b128 v[198:201], v154 offset:32768
	ds_read_b128 v[202:205], v154 offset:33792
	ds_read_b128 v[206:209], v153 offset:32768
	ds_read_b128 v[210:213], v153 offset:33792
	ds_read_b128 v[214:217], v152 offset:32768
	ds_read_b128 v[218:221], v152 offset:33792
	global_load_lds_dwordx4 v[230:231], off
	s_or_b32 m0, s100, 0x6000
	v_lshl_add_u64 v[230:231], v[226:227], 0, s[18:19]
	global_load_lds_dwordx4 v[230:231], off
	s_waitcnt lgkmcnt(8)
	s_barrier
	s_waitcnt lgkmcnt(0)
	v_mfma_f32_16x16x32_f16 v[128:131], v[190:193], v[174:177], v[128:131]
	v_mfma_f32_16x16x32_f16 v[124:127], v[190:193], v[182:185], v[124:127]
	v_mfma_f32_16x16x32_f16 v[120:123], v[198:201], v[174:177], v[120:123]
	v_mfma_f32_16x16x32_f16 v[116:119], v[198:201], v[182:185], v[116:119]
	v_mfma_f32_16x16x32_f16 v[112:115], v[206:209], v[174:177], v[112:115]
	v_mfma_f32_16x16x32_f16 v[108:111], v[206:209], v[182:185], v[108:111]
	v_mfma_f32_16x16x32_f16 v[104:107], v[214:217], v[174:177], v[104:107]
	v_mfma_f32_16x16x32_f16 v[100:103], v[214:217], v[182:185], v[100:103]
	v_mfma_f32_16x16x32_f16 v[128:131], v[194:197], v[178:181], v[128:131]
	v_mfma_f32_16x16x32_f16 v[124:127], v[194:197], v[186:189], v[124:127]
	v_mfma_f32_16x16x32_f16 v[120:123], v[202:205], v[178:181], v[120:123]
	v_mfma_f32_16x16x32_f16 v[116:119], v[202:205], v[186:189], v[116:119]
	v_mfma_f32_16x16x32_f16 v[112:115], v[210:213], v[178:181], v[112:115]
	v_mfma_f32_16x16x32_f16 v[108:111], v[210:213], v[186:189], v[108:111]
	v_mfma_f32_16x16x32_f16 v[104:107], v[218:221], v[178:181], v[104:107]
	v_mfma_f32_16x16x32_f16 v[100:103], v[218:221], v[186:189], v[100:103]
	s_barrier
	v_lshl_add_u64 v[250:251], v[228:229], 0, s[64:65]
	s_or_b32 m0, s100, 0x18000
	ds_read_b128 v[230:233], v158
	ds_read_b128 v[238:241], v158 offset:1024
	ds_read_b128 v[242:245], v158 offset:2048
	ds_read_b128 v[246:249], v158 offset:3072
	global_load_lds_dwordx4 v[250:251], off
	s_or_b32 m0, s100, 0x1a000
	v_lshl_add_u64 v[250:251], v[236:237], 0, s[64:65]
	global_load_lds_dwordx4 v[250:251], off
	s_barrier
	s_waitcnt lgkmcnt(0)
	v_mfma_f32_16x16x32_f16 v[96:99], v[190:193], v[230:233], v[96:99]
	v_mfma_f32_16x16x32_f16 v[92:95], v[190:193], v[242:245], v[92:95]
	v_mfma_f32_16x16x32_f16 v[88:91], v[198:201], v[230:233], v[88:91]
	v_mfma_f32_16x16x32_f16 v[84:87], v[198:201], v[242:245], v[84:87]
	v_mfma_f32_16x16x32_f16 v[80:83], v[206:209], v[230:233], v[80:83]
	v_mfma_f32_16x16x32_f16 v[76:79], v[206:209], v[242:245], v[76:79]
	v_mfma_f32_16x16x32_f16 v[72:75], v[214:217], v[230:233], v[72:75]
	v_mfma_f32_16x16x32_f16 v[68:71], v[214:217], v[242:245], v[68:71]
	v_mfma_f32_16x16x32_f16 v[96:99], v[194:197], v[238:241], v[96:99]
	v_mfma_f32_16x16x32_f16 v[92:95], v[194:197], v[246:249], v[92:95]
	v_mfma_f32_16x16x32_f16 v[88:91], v[202:205], v[238:241], v[88:91]
	v_mfma_f32_16x16x32_f16 v[84:87], v[202:205], v[246:249], v[84:87]
	v_mfma_f32_16x16x32_f16 v[80:83], v[210:213], v[238:241], v[80:83]
	v_mfma_f32_16x16x32_f16 v[76:79], v[210:213], v[246:249], v[76:79]
	v_mfma_f32_16x16x32_f16 v[72:75], v[218:221], v[238:241], v[72:75]
	v_mfma_f32_16x16x32_f16 v[68:71], v[218:221], v[246:249], v[68:71]
	v_lshl_add_u64 v[222:223], v[222:223], 0, s[22:23]
	s_or_b32 m0, s100, 0x8000
	s_barrier
	ds_read_b128 v[190:193], v156 offset:49152
	ds_read_b128 v[194:197], v156 offset:50176
	ds_read_b128 v[198:201], v154 offset:49152
	ds_read_b128 v[202:205], v154 offset:50176
	ds_read_b128 v[206:209], v153 offset:49152
	ds_read_b128 v[210:213], v153 offset:50176
	ds_read_b128 v[214:217], v152 offset:49152
	ds_read_b128 v[218:221], v152 offset:50176
	global_load_lds_dwordx4 v[222:223], off
	s_or_b32 m0, s100, 0xa000
	v_lshl_add_u64 v[222:223], v[226:227], 0, s[22:23]
	global_load_lds_dwordx4 v[222:223], off
	s_barrier
; #define LDA8(dst, b, h) _Pragma("unroll") for (int m = 0; m < 4; ++m) _Pragma("unroll") for (int k = 0; k < 2; ++k) \
;     dst[m][k] = *(const bf16x8*)((const char*)SA8(b, h) + lds_byte8(wr * 64 + m * 16 + fr, k * 32 + fq * 8))
; #define LDB8(dst, b, h) _Pragma("unroll") for (int n = 0; n < 2; ++n) _Pragma("unroll") for (int k = 0; k < 2; ++k) \
;     dst[n][k] = *(const bf16x8*)((const char*)SB8(b, h) + lds_byte8(wc * 32 + n * 16 + fr, k * 32 + fq * 8))
; #define WAIT_V8(n) asm volatile("s_waitcnt vmcnt(" #n ")" ::: "memory")
; #define WAIT_L8(n) asm volatile("s_waitcnt lgkmcnt(" #n ")" ::: "memory")
; #define BAR8 __builtin_amdgcn_s_barrier()
; #define SCHED8 __builtin_amdgcn_sched_barrier(0)
;     ...
;     BAR8; WAIT_L8(0); MMA8(1, 0, At, B0); BAR8; SCHED8;
;     STAGE8(SB8(1, 1), Bt, K, bcol + 128, tt + 3);
;     WAIT_V8(6); BAR8; MMA8(1, 1, At, B1); BAR8;
;   }
;   { LDB8(B0, 0, 0); LDA8(At, 0, 0); STAGE8(SA8(1, 1), A, lda, brow + 128, nt - 1);
;     BAR8; WAIT_L8(0); MMA8(0, 0, At, B0); BAR8;
;     LDB8(B1, 0, 1); BAR8; WAIT_L8(0); MMA8(0, 1, At, B1); BAR8;
;     LDA8(At, 0, 1); WAIT_V8(4); BAR8; WAIT_L8(0); MMA8(1, 0, At, B0); MMA8(1, 1, At, B1); BAR8; }
;   { LDB8(B0, 1, 0); LDA8(At, 1, 0); WAIT_V8(2); BAR8; WAIT_L8(0); MMA8(0, 0, At, B0); BAR8;
	s_waitcnt lgkmcnt(0)
	v_mfma_f32_16x16x32_f16 v[64:67], v[190:193], v[174:177], v[64:67]
	v_mfma_f32_16x16x32_f16 v[60:63], v[190:193], v[182:185], v[60:63]
	v_mfma_f32_16x16x32_f16 v[56:59], v[198:201], v[174:177], v[56:59]
	v_mfma_f32_16x16x32_f16 v[52:55], v[198:201], v[182:185], v[52:55]
	v_mfma_f32_16x16x32_f16 v[48:51], v[206:209], v[174:177], v[48:51]
	v_mfma_f32_16x16x32_f16 v[44:47], v[206:209], v[182:185], v[44:47]
	v_mfma_f32_16x16x32_f16 v[40:43], v[214:217], v[174:177], v[40:43]
	v_mfma_f32_16x16x32_f16 v[36:39], v[214:217], v[182:185], v[36:39]
	v_mfma_f32_16x16x32_f16 v[64:67], v[194:197], v[178:181], v[64:67]
	v_mfma_f32_16x16x32_f16 v[60:63], v[194:197], v[186:189], v[60:63]
	v_mfma_f32_16x16x32_f16 v[56:59], v[202:205], v[178:181], v[56:59]
	v_mfma_f32_16x16x32_f16 v[52:55], v[202:205], v[186:189], v[52:55]
	v_mfma_f32_16x16x32_f16 v[48:51], v[210:213], v[178:181], v[48:51]
	v_mfma_f32_16x16x32_f16 v[44:47], v[210:213], v[186:189], v[44:47]
	v_mfma_f32_16x16x32_f16 v[40:43], v[218:221], v[178:181], v[40:43]
	v_mfma_f32_16x16x32_f16 v[36:39], v[218:221], v[186:189], v[36:39]
	s_barrier
	s_or_b32 m0, s100, 0x1c000
	v_lshl_add_u64 v[174:175], v[228:229], 0, s[66:67]
	global_load_lds_dwordx4 v[174:175], off
	s_or_b32 m0, s100, 0x1e000
	v_lshl_add_u64 v[174:175], v[236:237], 0, s[66:67]
	global_load_lds_dwordx4 v[174:175], off
	s_waitcnt vmcnt(6)
	s_barrier
	v_mfma_f32_16x16x32_f16 v[32:35], v[190:193], v[230:233], v[32:35]
	v_mfma_f32_16x16x32_f16 v[28:31], v[190:193], v[242:245], v[28:31]
	v_mfma_f32_16x16x32_f16 v[24:27], v[198:201], v[230:233], v[24:27]
	v_mfma_f32_16x16x32_f16 v[20:23], v[198:201], v[242:245], v[20:23]
	v_mfma_f32_16x16x32_f16 v[16:19], v[206:209], v[230:233], v[16:19]
	v_mfma_f32_16x16x32_f16 v[12:15], v[206:209], v[242:245], v[12:15]
	v_mfma_f32_16x16x32_f16 v[8:11], v[214:217], v[230:233], v[8:11]
	v_mfma_f32_16x16x32_f16 v[4:7], v[214:217], v[242:245], v[4:7]
	v_mfma_f32_16x16x32_f16 v[32:35], v[194:197], v[238:241], v[32:35]
	v_mfma_f32_16x16x32_f16 v[28:31], v[194:197], v[246:249], v[28:31]
	v_mfma_f32_16x16x32_f16 v[24:27], v[202:205], v[238:241], v[24:27]
	v_mfma_f32_16x16x32_f16 v[20:23], v[202:205], v[246:249], v[20:23]
	v_mfma_f32_16x16x32_f16 v[16:19], v[210:213], v[238:241], v[16:19]
	v_mfma_f32_16x16x32_f16 v[12:15], v[210:213], v[246:249], v[12:15]
	v_mfma_f32_16x16x32_f16 v[8:11], v[218:221], v[238:241], v[8:11]
	v_mfma_f32_16x16x32_f16 v[4:7], v[218:221], v[246:249], v[4:7]
	s_add_i32 s14, s14, 2
	s_add_u32 s12, s12, 0x100
	s_addc_u32 s13, s13, 0
	s_cmp_lt_u32 s14, 12
	s_barrier
	s_cbranch_scc1 .LBB0_192
.Lpk_exit_0:
	s_add_u32 s4, s4, 0x40780
	s_addc_u32 s5, s5, 0
	v_lshl_add_u64 v[132:133], s[4:5], 0, v[132:133]
	v_lshl_add_u64 v[0:1], v[0:1], 1, v[132:133]
	s_or_b32 m0, s100, 0xc000
	ds_read_b128 v[138:141], v173
	ds_read_b128 v[142:145], v173 offset:1024
	ds_read_b128 v[160:163], v173 offset:2048
	ds_read_b128 v[164:167], v173 offset:3072
	ds_read_b128 v[174:177], v156
	ds_read_b128 v[178:181], v156 offset:1024
	ds_read_b128 v[182:185], v154
	ds_read_b128 v[186:189], v154 offset:1024
	ds_read_b128 v[190:193], v153
	ds_read_b128 v[194:197], v153 offset:1024
	ds_read_b128 v[198:201], v152
	ds_read_b128 v[202:205], v152 offset:1024
	global_load_lds_dwordx4 v[0:1], off
	v_lshl_add_u64 v[0:1], s[4:5], 0, v[136:137]
	s_or_b32 m0, s100, 0xe000
	v_lshl_add_u64 v[0:1], v[134:135], 1, v[0:1]
	global_load_lds_dwordx4 v[0:1], off
	s_barrier
	s_waitcnt lgkmcnt(0)
	v_mfma_f32_16x16x32_f16 v[128:131], v[174:177], v[138:141], v[128:131]
	v_mfma_f32_16x16x32_f16 v[124:127], v[174:177], v[160:163], v[124:127]
	v_mfma_f32_16x16x32_f16 v[120:123], v[182:185], v[138:141], v[120:123]
	v_mfma_f32_16x16x32_f16 v[112:115], v[190:193], v[138:141], v[112:115]
	v_mfma_f32_16x16x32_f16 v[128:131], v[178:181], v[142:145], v[128:131]
	v_mfma_f32_16x16x32_f16 v[124:127], v[178:181], v[164:167], v[124:127]
	v_mfma_f32_16x16x32_f16 v[120:123], v[186:189], v[142:145], v[120:123]
	v_mfma_f32_16x16x32_f16 v[116:119], v[182:185], v[160:163], v[116:119]
	v_mfma_f32_16x16x32_f16 v[112:115], v[194:197], v[142:145], v[112:115]
	v_mfma_f32_16x16x32_f16 v[108:111], v[190:193], v[160:163], v[108:111]
	v_mfma_f32_16x16x32_f16 v[104:107], v[198:201], v[138:141], v[104:107]
	v_mfma_f32_16x16x32_f16 v[100:103], v[198:201], v[160:163], v[100:103]
	v_mfma_f32_16x16x32_f16 v[132:135], v[186:189], v[164:167], v[116:119]
	v_mfma_f32_16x16x32_f16 v[170:173], v[194:197], v[164:167], v[108:111]
	v_mfma_f32_16x16x32_f16 v[206:209], v[202:205], v[142:145], v[104:107]
	v_mfma_f32_16x16x32_f16 v[210:213], v[202:205], v[164:167], v[100:103]
	s_barrier
	s_nop 1
	ds_read_b128 v[100:103], v169
	ds_read_b128 v[104:107], v169 offset:1024
	ds_read_b128 v[108:111], v169 offset:2048
	ds_read_b128 v[116:119], v169 offset:3072
	s_barrier
	s_waitcnt lgkmcnt(0)
	v_mfma_f32_16x16x32_f16 v[80:83], v[190:193], v[100:103], v[80:83]
	v_mfma_f32_16x16x32_f16 v[76:79], v[190:193], v[108:111], v[76:79]
	v_mfma_f32_16x16x32_f16 v[72:75], v[198:201], v[100:103], v[72:75]
	v_mfma_f32_16x16x32_f16 v[68:71], v[198:201], v[108:111], v[68:71]
	v_mfma_f32_16x16x32_f16 v[96:99], v[174:177], v[100:103], v[96:99]
	v_mfma_f32_16x16x32_f16 v[92:95], v[174:177], v[108:111], v[92:95]
	v_mfma_f32_16x16x32_f16 v[88:91], v[182:185], v[100:103], v[88:91]
	v_mfma_f32_16x16x32_f16 v[84:87], v[182:185], v[108:111], v[84:87]
	v_mfma_f32_16x16x32_f16 v[80:83], v[194:197], v[104:107], v[80:83]
	v_mfma_f32_16x16x32_f16 v[76:79], v[194:197], v[116:119], v[76:79]
	v_mfma_f32_16x16x32_f16 v[72:75], v[202:205], v[104:107], v[72:75]
	v_mfma_f32_16x16x32_f16 v[68:71], v[202:205], v[116:119], v[68:71]
	v_mfma_f32_16x16x32_f16 v[214:217], v[178:181], v[104:107], v[96:99]
	v_mfma_f32_16x16x32_f16 v[174:177], v[178:181], v[116:119], v[92:95]
	v_mfma_f32_16x16x32_f16 v[178:181], v[186:189], v[104:107], v[88:91]
	v_mfma_f32_16x16x32_f16 v[182:185], v[186:189], v[116:119], v[84:87]
	s_barrier
; #define LDA8(dst, b, h) _Pragma("unroll") for (int m = 0; m < 4; ++m) _Pragma("unroll") for (int k = 0; k < 2; ++k) \
;     dst[m][k] = *(const bf16x8*)((const char*)SA8(b, h) + lds_byte8(wr * 64 + m * 16 + fr, k * 32 + fq * 8))
; #define LDB8(dst, b, h) _Pragma("unroll") for (int n = 0; n < 2; ++n) _Pragma("unroll") for (int k = 0; k < 2; ++k) \
;     dst[n][k] = *(const bf16x8*)((const char*)SB8(b, h) + lds_byte8(wc * 32 + n * 16 + fr, k * 32 + fq * 8))
; #define WAIT_V8(n) asm volatile("s_waitcnt vmcnt(" #n ")" ::: "memory")
; #define WAIT_L8(n) asm volatile("s_waitcnt lgkmcnt(" #n ")" ::: "memory")
; #define BAR8 __builtin_amdgcn_s_barrier()
;     ...
;   { LDB8(B0, 0, 0); LDA8(At, 0, 0); STAGE8(SA8(1, 1), A, lda, brow + 128, nt - 1);
;     BAR8; WAIT_L8(0); MMA8(0, 0, At, B0); BAR8;
;     LDB8(B1, 0, 1); BAR8; WAIT_L8(0); MMA8(0, 1, At, B1); BAR8;
;     LDA8(At, 0, 1); WAIT_V8(4); BAR8; WAIT_L8(0); MMA8(1, 0, At, B0); MMA8(1, 1, At, B1); BAR8; }
;   { LDB8(B0, 1, 0); LDA8(At, 1, 0); WAIT_V8(2); BAR8; WAIT_L8(0); MMA8(0, 0, At, B0); BAR8;
;     LDB8(B1, 1, 1); WAIT_V8(0); BAR8; WAIT_L8(0); MMA8(0, 1, At, B1); BAR8;
;     LDA8(At, 1, 1); BAR8; WAIT_L8(0); MMA8(1, 0, At, B0); MMA8(1, 1, At, B1); BAR8; }
	s_nop 0
	ds_read_b128 v[84:87], v156 offset:16384
	ds_read_b128 v[88:91], v156 offset:17408
	ds_read_b128 v[92:95], v154 offset:16384
	ds_read_b128 v[96:99], v154 offset:17408
	ds_read_b128 v[186:189], v153 offset:16384
	ds_read_b128 v[190:193], v153 offset:17408
	ds_read_b128 v[194:197], v152 offset:16384
	ds_read_b128 v[198:201], v152 offset:17408
	s_waitcnt vmcnt(4)
	s_barrier
	s_waitcnt lgkmcnt(0)
	v_mfma_f32_16x16x32_f16 v[64:67], v[84:87], v[138:141], v[64:67]
	v_mfma_f32_16x16x32_f16 v[60:63], v[84:87], v[160:163], v[60:63]
	v_mfma_f32_16x16x32_f16 v[56:59], v[92:95], v[138:141], v[56:59]
	v_mfma_f32_16x16x32_f16 v[52:55], v[92:95], v[160:163], v[52:55]
	v_mfma_f32_16x16x32_f16 v[48:51], v[186:189], v[138:141], v[48:51]
	v_mfma_f32_16x16x32_f16 v[44:47], v[186:189], v[160:163], v[44:47]
	v_mfma_f32_16x16x32_f16 v[64:67], v[88:91], v[142:145], v[64:67]
	v_mfma_f32_16x16x32_f16 v[60:63], v[88:91], v[164:167], v[60:63]
	v_mfma_f32_16x16x32_f16 v[56:59], v[96:99], v[142:145], v[56:59]
	v_mfma_f32_16x16x32_f16 v[52:55], v[96:99], v[164:167], v[52:55]
	v_mfma_f32_16x16x32_f16 v[48:51], v[190:193], v[142:145], v[48:51]
	v_mfma_f32_16x16x32_f16 v[44:47], v[190:193], v[164:167], v[44:47]
	v_mfma_f32_16x16x32_f16 v[40:43], v[194:197], v[138:141], v[40:43]
	v_mfma_f32_16x16x32_f16 v[36:39], v[194:197], v[160:163], v[36:39]
	v_mfma_f32_16x16x32_f16 v[136:139], v[198:201], v[142:145], v[40:43]
	v_mfma_f32_16x16x32_f16 v[140:143], v[198:201], v[164:167], v[36:39]
	v_mfma_f32_16x16x32_f16 v[32:35], v[84:87], v[100:103], v[32:35]
	v_mfma_f32_16x16x32_f16 v[28:31], v[84:87], v[108:111], v[28:31]
	v_mfma_f32_16x16x32_f16 v[24:27], v[92:95], v[100:103], v[24:27]
	v_mfma_f32_16x16x32_f16 v[20:23], v[92:95], v[108:111], v[20:23]
	v_mfma_f32_16x16x32_f16 v[16:19], v[186:189], v[100:103], v[16:19]
	v_mfma_f32_16x16x32_f16 v[12:15], v[186:189], v[108:111], v[12:15]
	v_mfma_f32_16x16x32_f16 v[8:11], v[194:197], v[100:103], v[8:11]
	v_mfma_f32_16x16x32_f16 v[4:7], v[194:197], v[108:111], v[4:7]
	v_mfma_f32_16x16x32_f16 v[160:163], v[88:91], v[104:107], v[32:35]
	v_mfma_f32_16x16x32_f16 v[164:167], v[88:91], v[116:119], v[28:31]
	v_mfma_f32_16x16x32_f16 v[202:205], v[96:99], v[104:107], v[24:27]
	v_mfma_f32_16x16x32_f16 v[218:221], v[96:99], v[116:119], v[20:23]
	v_mfma_f32_16x16x32_f16 v[230:233], v[190:193], v[104:107], v[16:19]
	v_mfma_f32_16x16x32_f16 v[186:189], v[190:193], v[116:119], v[12:15]
	v_mfma_f32_16x16x32_f16 v[190:193], v[198:201], v[104:107], v[8:11]
	v_mfma_f32_16x16x32_f16 v[194:197], v[198:201], v[116:119], v[4:7]
	s_barrier
	s_nop 0
	ds_read_b128 v[4:7], v159
	ds_read_b128 v[8:11], v159 offset:1024
	ds_read_b128 v[198:201], v159 offset:2048
	ds_read_b128 v[238:241], v159 offset:3072
	ds_read_b128 v[16:19], v156 offset:32768
	ds_read_b128 v[20:23], v156 offset:33792
	ds_read_b128 v[24:27], v154 offset:32768
	ds_read_b128 v[32:35], v154 offset:33792
	ds_read_b128 v[36:39], v153 offset:32768
	ds_read_b128 v[40:43], v153 offset:33792
	ds_read_b128 v[242:245], v152 offset:32768
	ds_read_b128 v[246:249], v152 offset:33792
	s_waitcnt vmcnt(2)
	s_barrier
	s_waitcnt lgkmcnt(0)
	v_mfma_f32_16x16x32_f16 v[12:15], v[16:19], v[4:7], v[128:131]
	v_mfma_f32_16x16x32_f16 v[104:107], v[20:23], v[8:11], v[12:15]
	v_mfma_f32_16x16x32_f16 v[12:15], v[16:19], v[198:201], v[124:127]
	v_mfma_f32_16x16x32_f16 v[116:119], v[20:23], v[238:241], v[12:15]
	v_mfma_f32_16x16x32_f16 v[12:15], v[24:27], v[4:7], v[120:123]
	v_mfma_f32_16x16x32_f16 v[100:103], v[32:35], v[8:11], v[12:15]
	v_mfma_f32_16x16x32_f16 v[12:15], v[24:27], v[198:201], v[132:135]
	v_mfma_f32_16x16x32_f16 v[108:111], v[32:35], v[238:241], v[12:15]
	v_mfma_f32_16x16x32_f16 v[12:15], v[36:39], v[4:7], v[112:115]
	v_mfma_f32_16x16x32_f16 v[92:95], v[40:43], v[8:11], v[12:15]
	v_mfma_f32_16x16x32_f16 v[12:15], v[36:39], v[198:201], v[170:173]
	v_mfma_f32_16x16x32_f16 v[96:99], v[40:43], v[238:241], v[12:15]
	v_mfma_f32_16x16x32_f16 v[12:15], v[242:245], v[4:7], v[206:209]
	v_mfma_f32_16x16x32_f16 v[84:87], v[246:249], v[8:11], v[12:15]
	v_mfma_f32_16x16x32_f16 v[12:15], v[242:245], v[198:201], v[210:213]
	v_mfma_f32_16x16x32_f16 v[88:91], v[246:249], v[238:241], v[12:15]
	s_barrier
; #define LDA8(dst, b, h) _Pragma("unroll") for (int m = 0; m < 4; ++m) _Pragma("unroll") for (int k = 0; k < 2; ++k) \
;     dst[m][k] = *(const bf16x8*)((const char*)SA8(b, h) + lds_byte8(wr * 64 + m * 16 + fr, k * 32 + fq * 8))
; #define LDB8(dst, b, h) _Pragma("unroll") for (int n = 0; n < 2; ++n) _Pragma("unroll") for (int k = 0; k < 2; ++k) \
;     dst[n][k] = *(const bf16x8*)((const char*)SB8(b, h) + lds_byte8(wc * 32 + n * 16 + fr, k * 32 + fq * 8))
; #define WAIT_V8(n) asm volatile("s_waitcnt vmcnt(" #n ")" ::: "memory")
; #define WAIT_L8(n) asm volatile("s_waitcnt lgkmcnt(" #n ")" ::: "memory")
; #define BAR8 __builtin_amdgcn_s_barrier()
;     ...
;   { LDB8(B0, 1, 0); LDA8(At, 1, 0); WAIT_V8(2); BAR8; WAIT_L8(0); MMA8(0, 0, At, B0); BAR8;
;     LDB8(B1, 1, 1); WAIT_V8(0); BAR8; WAIT_L8(0); MMA8(0, 1, At, B1); BAR8;
;     LDA8(At, 1, 1); BAR8; WAIT_L8(0); MMA8(1, 0, At, B0); MMA8(1, 1, At, B1); BAR8; }
;   if (wr == 0) BAR8;
	ds_read_b128 v[132:135], v158
	ds_read_b128 v[168:171], v158 offset:1024
	ds_read_b128 v[206:209], v158 offset:2048
	ds_read_b128 v[210:213], v158 offset:3072
	s_waitcnt vmcnt(0)
	s_barrier
	s_waitcnt lgkmcnt(0)
	v_mfma_f32_16x16x32_f16 v[12:15], v[16:19], v[132:135], v[214:217]
	v_mfma_f32_16x16x32_f16 v[16:19], v[16:19], v[206:209], v[174:177]
	v_mfma_f32_16x16x32_f16 v[12:15], v[20:23], v[168:171], v[12:15]
	v_mfma_f32_16x16x32_f16 v[28:31], v[20:23], v[210:213], v[16:19]
	v_mfma_f32_16x16x32_f16 v[16:19], v[24:27], v[132:135], v[178:181]
	v_mfma_f32_16x16x32_f16 v[20:23], v[24:27], v[206:209], v[182:185]
	v_mfma_f32_16x16x32_f16 v[16:19], v[32:35], v[168:171], v[16:19]
	v_mfma_f32_16x16x32_f16 v[32:35], v[32:35], v[210:213], v[20:23]
	v_mfma_f32_16x16x32_f16 v[20:23], v[36:39], v[132:135], v[80:83]
	v_mfma_f32_16x16x32_f16 v[24:27], v[36:39], v[206:209], v[76:79]
	v_mfma_f32_16x16x32_f16 v[20:23], v[40:43], v[168:171], v[20:23]
	v_mfma_f32_16x16x32_f16 v[36:39], v[40:43], v[210:213], v[24:27]
	v_mfma_f32_16x16x32_f16 v[24:27], v[242:245], v[132:135], v[72:75]
	v_mfma_f32_16x16x32_f16 v[40:43], v[242:245], v[206:209], v[68:71]
	v_mfma_f32_16x16x32_f16 v[24:27], v[246:249], v[168:171], v[24:27]
	v_mfma_f32_16x16x32_f16 v[40:43], v[246:249], v[210:213], v[40:43]
	s_barrier
	ds_read_b128 v[68:71], v156 offset:49152
	ds_read_b128 v[72:75], v156 offset:50176
	ds_read_b128 v[156:159], v154 offset:49152
	ds_read_b128 v[172:175], v154 offset:50176
	ds_read_b128 v[176:179], v153 offset:49152
	ds_read_b128 v[180:183], v153 offset:50176
	ds_read_b128 v[214:217], v152 offset:49152
	ds_read_b128 v[150:153], v152 offset:50176
	s_barrier
	s_waitcnt lgkmcnt(0)
	v_mfma_f32_16x16x32_f16 v[64:67], v[68:71], v[4:7], v[64:67]
	v_mfma_f32_16x16x32_f16 v[56:59], v[156:159], v[4:7], v[56:59]
	v_mfma_f32_16x16x32_f16 v[48:51], v[176:179], v[4:7], v[48:51]
	v_mfma_f32_16x16x32_f16 v[4:7], v[214:217], v[4:7], v[136:139]
	v_mfma_f32_16x16x32_f16 v[128:131], v[72:75], v[8:11], v[64:67]
	v_mfma_f32_16x16x32_f16 v[60:63], v[68:71], v[198:201], v[60:63]
	v_mfma_f32_16x16x32_f16 v[120:123], v[172:175], v[8:11], v[56:59]
	v_mfma_f32_16x16x32_f16 v[52:55], v[156:159], v[198:201], v[52:55]
	v_mfma_f32_16x16x32_f16 v[80:83], v[180:183], v[8:11], v[48:51]
	v_mfma_f32_16x16x32_f16 v[44:47], v[176:179], v[198:201], v[44:47]
	v_mfma_f32_16x16x32_f16 v[8:11], v[150:153], v[8:11], v[4:7]
	v_mfma_f32_16x16x32_f16 v[4:7], v[214:217], v[198:201], v[140:143]
	v_mfma_f32_16x16x32_f16 v[124:127], v[72:75], v[238:241], v[60:63]
	v_mfma_f32_16x16x32_f16 v[112:115], v[172:175], v[238:241], v[52:55]
	v_mfma_f32_16x16x32_f16 v[76:79], v[180:183], v[238:241], v[44:47]
	v_mfma_f32_16x16x32_f16 v[4:7], v[150:153], v[238:241], v[4:7]
	v_mfma_f32_16x16x32_f16 v[44:47], v[68:71], v[132:135], v[160:163]
	v_mfma_f32_16x16x32_f16 v[48:51], v[68:71], v[206:209], v[164:167]
	v_mfma_f32_16x16x32_f16 v[52:55], v[156:159], v[206:209], v[218:221]
	v_mfma_f32_16x16x32_f16 v[56:59], v[176:179], v[206:209], v[186:189]
	v_mfma_f32_16x16x32_f16 v[44:47], v[72:75], v[168:171], v[44:47]
	v_mfma_f32_16x16x32_f16 v[60:63], v[72:75], v[210:213], v[48:51]
	v_mfma_f32_16x16x32_f16 v[48:51], v[156:159], v[132:135], v[202:205]
	v_mfma_f32_16x16x32_f16 v[64:67], v[172:175], v[210:213], v[52:55]
	v_mfma_f32_16x16x32_f16 v[52:55], v[176:179], v[132:135], v[230:233]
	v_mfma_f32_16x16x32_f16 v[68:71], v[180:183], v[210:213], v[56:59]
	v_mfma_f32_16x16x32_f16 v[56:59], v[214:217], v[132:135], v[190:193]
	v_mfma_f32_16x16x32_f16 v[72:75], v[214:217], v[206:209], v[194:197]
	v_mfma_f32_16x16x32_f16 v[48:51], v[172:175], v[168:171], v[48:51]
	v_mfma_f32_16x16x32_f16 v[52:55], v[180:183], v[168:171], v[52:55]
	v_mfma_f32_16x16x32_f16 v[56:59], v[150:153], v[168:171], v[56:59]
	v_mfma_f32_16x16x32_f16 v[72:75], v[150:153], v[210:213], v[72:75]
	s_movk_i32 s4, 0x100
	v_cmp_gt_u32_e32 vcc, s4, v3
	s_barrier
	s_and_saveexec_b64 s[4:5], vcc
	s_cbranch_execz .LBB0_195
	s_barrier

; #define WAIT_V8(n) asm volatile("s_waitcnt vmcnt(" #n ")" ::: "memory")
; #define BAR8 __builtin_amdgcn_s_barrier()
;     ...
;   const int brow = m0, bcol = n0;
;   const int wid = t >> 6, lane = t & 63, wr = wid >> 2, wc = wid & 3, fr = lane & 15, fq = lane >> 4;
;   f32x4 acc[2][2][4][2];
;   {
;     float zinit = 0.f;
;     asm volatile("" : "+v"(zinit));
; #pragma unroll
;     for (int a = 0; a < 2; ++a)
; #pragma unroll
;       for (int b = 0; b < 2; ++b)
; #pragma unroll
;         for (int m = 0; m < 4; ++m)
; #pragma unroll
;           for (int n = 0; n < 2; ++n)
; #pragma unroll
;             for (int j = 0; j < 4; ++j) acc[a][b][m][n][j] = zinit;
;   }
;   bf16x8 At[4][2], B0[2][2], B1[2][2];
;   const int nt = K / 64;
;   if (!pre) {
;     STAGE8(SB8(0, 0), Bt, K, bcol, 0); STAGE8(SA8(0, 0), A, lda, brow, 0);
;     STAGE8(SB8(0, 1), Bt, K, bcol + 128, 0); STAGE8(SA8(0, 1), A, lda, brow + 128, 0);
;   }
;   if (wr == 1) BAR8;
;   WAIT_V8(4); BAR8;
;   STAGE8(SB8(1, 0), Bt, K, bcol, 1); STAGE8(SA8(1, 0), A, lda, brow, 1); STAGE8(SB8(1, 1), Bt, K, bcol + 128, 1);
.LBB0_238:
	s_and_b64 vcc, exec, s[0:1]
	s_cbranch_vccz .LBB0_187
	s_mov_b32 s0, 25
	s_ashr_i32 s1, s0, 31
	s_lshl_b64 s[0:1], s[0:1], 3
	s_add_u32 s0, s70, s0
	s_addc_u32 s1, s71, s1
	v_readlane_b32 s2, v255, 60
	v_readlane_b32 s3, v255, 61
	s_nop 4
	s_mov_b32 s0, 25
	s_ashr_i32 s1, s0, 31
	s_lshl_b64 s[0:1], s[0:1], 3
	s_add_u32 s0, s70, s0
	s_addc_u32 s1, s71, s1
	v_readlane_b32 s4, v255, 60
	v_readlane_b32 s5, v255, 61
	s_nop 4
	s_mov_b32 s0, 25
	s_ashr_i32 s1, s0, 31
	s_lshl_b64 s[0:1], s[0:1], 3
	s_add_u32 s0, s70, s0
	s_addc_u32 s1, s71, s1
	v_mov_b32_e32 v3, v224
	v_readlane_b32 s14, v255, 60
	v_readlane_b32 s15, v255, 61
	s_nop 4
	s_ashr_i32 s53, s52, 31
	v_bfe_i32 v1, v3, 27, 1
	s_waitcnt vmcnt(10)
	v_lshlrev_b32_e32 v150, 4, v3
	s_nop 0
	v_readfirstlane_b32 s100, v150
	v_lshrrev_b32_e32 v1, 22, v1
	v_add_u32_e32 v1, v150, v1
	v_and_b32_e32 v1, 0xfffffc00, v1
	v_ashrrev_i32_e32 v0, 31, v3
	v_sub_u32_e32 v1, v150, v1
	v_lshrrev_b32_e32 v0, 26, v0
	v_lshrrev_b32_e32 v5, 4, v1
	v_add_u32_e32 v0, v3, v0
	v_bitop3_b32 v5, v5, v1, 32 bitop3:0x6c
	v_ashrrev_i32_e32 v1, 31, v1
	v_ashrrev_i32_e32 v0, 6, v0
	v_lshrrev_b32_e32 v1, 26, v1
	v_lshlrev_b32_e32 v6, 3, v0
	v_add_u32_e32 v1, v5, v1
	v_and_b32_e32 v6, -16, v6
	v_ashrrev_i32_e32 v1, 6, v1
	v_add_u32_e32 v6, v1, v6
	v_mul_i32_i24_e32 v1, 64, v1
	v_lshlrev_b32_e32 v0, 5, v0
	v_sub_u32_e32 v1, v5, v1
	v_mov_b32_e32 v14, 1
	s_waitcnt vmcnt(9)
	v_add_u32_e32 v155, 0x2000, v150
	s_lshl_b64 s[0:1], s[52:53], 11
	v_readlane_b32 s27, v254, 44
	v_and_b32_e32 v0, 32, v0
	v_ashrrev_i16_sdwa v1, v14, sext(v1) dst_sel:DWORD dst_unused:UNUSED_PAD src0_sel:DWORD src1_sel:BYTE_0
	v_ashrrev_i32_e32 v5, 31, v155
	s_add_u32 s0, s27, s0
	v_readlane_b32 s29, v254, 45
	v_add_u32_sdwa v0, v0, sext(v1) dst_sel:DWORD dst_unused:UNUSED_PAD src0_sel:DWORD src1_sel:WORD_0
	v_ashrrev_i32_e32 v7, 31, v6
	v_lshrrev_b32_e32 v5, 22, v5
	s_addc_u32 s1, s29, s1
	v_lshlrev_b64 v[132:133], 11, v[6:7]
	v_ashrrev_i32_e32 v1, 31, v0
	v_add_u32_e32 v5, v155, v5
	v_lshl_add_u64 v[8:9], s[0:1], 0, v[132:133]
	v_lshlrev_b64 v[6:7], 1, v[0:1]
	v_ashrrev_i32_e32 v5, 10, v5
	v_lshl_add_u64 v[10:11], v[8:9], 0, v[6:7]
	v_mul_i32_i24_e32 v8, 0x400, v5
	v_sub_u32_e32 v8, v155, v8
	v_lshrrev_b32_e32 v9, 4, v8
	v_bitop3_b32 v9, v9, v8, 32 bitop3:0x6c
	v_ashrrev_i32_e32 v12, 31, v9
	v_lshrrev_b32_e32 v12, 26, v12
	v_add_u32_e32 v12, v9, v12
	v_lshlrev_b32_e32 v8, 3, v5
	v_ashrrev_i32_e32 v13, 6, v12
	v_and_b32_e32 v12, 0xc0, v12
	v_and_b32_e32 v8, -16, v8
	v_lshlrev_b32_e32 v5, 5, v5
	v_sub_u32_e32 v9, v9, v12
	v_add_u32_e32 v8, v13, v8
	v_and_b32_e32 v5, 32, v5
	v_ashrrev_i16_sdwa v9, v14, sext(v9) dst_sel:DWORD dst_unused:UNUSED_PAD src0_sel:DWORD src1_sel:BYTE_0
	v_add_u32_sdwa v134, v5, sext(v9) dst_sel:DWORD dst_unused:UNUSED_PAD src0_sel:DWORD src1_sel:WORD_0
	v_ashrrev_i32_e32 v9, 31, v8
	v_lshlrev_b64 v[136:137], 11, v[8:9]
	s_waitcnt vmcnt(8)
	v_mov_b32_e32 v4, v2
	s_or_b32 m0, s100, 0x10000
	v_lshl_add_u64 v[12:13], s[0:1], 0, v[136:137]
	global_load_lds_dwordx4 v[10:11], off
	s_or_b32 m0, s100, 0x12000
	s_lshl_b32 s0, s20, 19
	v_ashrrev_i32_e32 v135, 31, v134
	s_waitcnt lgkmcnt(0)
	s_add_u32 s12, s14, s0
	v_lshlrev_b64 v[8:9], 1, v[134:135]
	s_addc_u32 s13, s15, 0
	v_lshl_add_u64 v[12:13], v[12:13], 0, v[8:9]
	v_lshl_add_u64 v[14:15], s[12:13], 0, v[132:133]
	global_load_lds_dwordx4 v[12:13], off
	s_mov_b32 m0, s100
	v_lshl_add_u64 v[14:15], v[14:15], 0, v[6:7]
	global_load_lds_dwordx4 v[14:15], off
	s_or_b32 m0, s100, 0x2000
	s_or_b32 s0, s52, 0x80
	s_ashr_i32 s1, s0, 31
	s_lshl_b64 s[20:21], s[0:1], 11
	s_add_u32 s20, s27, s20
	v_lshl_add_u64 v[16:17], s[12:13], 0, v[136:137]
	s_addc_u32 s21, s29, s21
	v_lshl_add_u64 v[16:17], v[16:17], 0, v[8:9]
	v_lshl_add_u64 v[18:19], s[20:21], 0, v[132:133]
	v_lshl_add_u64 v[20:21], s[20:21], 0, v[136:137]
	s_add_u32 s20, s12, 0x40000
	global_load_lds_dwordx4 v[16:17], off
	v_lshl_add_u64 v[18:19], v[18:19], 0, v[6:7]
	s_addc_u32 s21, s13, 0
	s_or_b32 m0, s100, 0x14000
	global_load_lds_dwordx4 v[18:19], off
	v_lshl_add_u64 v[20:21], v[20:21], 0, v[8:9]
	s_or_b32 m0, s100, 0x16000
	v_lshl_add_u64 v[22:23], s[20:21], 0, v[132:133]
	global_load_lds_dwordx4 v[20:21], off
	v_lshl_add_u64 v[22:23], v[22:23], 0, v[6:7]
	s_or_b32 m0, s100, 0x4000
	global_load_lds_dwordx4 v[22:23], off
	v_lshl_add_u64 v[22:23], s[20:21], 0, v[136:137]
	v_lshl_add_u64 v[22:23], v[22:23], 0, v[8:9]
	s_or_b32 m0, s100, 0x6000
	v_ashrrev_i32_e32 v5, 8, v3
	global_load_lds_dwordx4 v[22:23], off
	v_cmp_eq_u32_e32 vcc, 1, v5
	s_and_saveexec_b64 s[20:21], vcc
	s_cbranch_execz .LBB0_241
	s_barrier
; #define LDA8(dst, b, h) _Pragma("unroll") for (int m = 0; m < 4; ++m) _Pragma("unroll") for (int k = 0; k < 2; ++k) \
;     dst[m][k] = *(const bf16x8*)((const char*)SA8(b, h) + lds_byte8(wr * 64 + m * 16 + fr, k * 32 + fq * 8))
; #define LDB8(dst, b, h) _Pragma("unroll") for (int n = 0; n < 2; ++n) _Pragma("unroll") for (int k = 0; k < 2; ++k) \
;     dst[n][k] = *(const bf16x8*)((const char*)SB8(b, h) + lds_byte8(wc * 32 + n * 16 + fr, k * 32 + fq * 8))
; #define WAIT_V8(n) asm volatile("s_waitcnt vmcnt(" #n ")" ::: "memory")
; #define WAIT_L8(n) asm volatile("s_waitcnt lgkmcnt(" #n ")" ::: "memory")
; #define BAR8 __builtin_amdgcn_s_barrier()
; #define SCHED8 __builtin_amdgcn_sched_barrier(0)
;     ...
;     STAGE8(SB8(0, 0), Bt, K, bcol, 0); STAGE8(SA8(0, 0), A, lda, brow, 0);
;     STAGE8(SB8(0, 1), Bt, K, bcol + 128, 0); STAGE8(SA8(0, 1), A, lda, brow + 128, 0);
;   }
;   if (wr == 1) BAR8;
;   WAIT_V8(4); BAR8;
;   STAGE8(SB8(1, 0), Bt, K, bcol, 1); STAGE8(SA8(1, 0), A, lda, brow, 1); STAGE8(SB8(1, 1), Bt, K, bcol + 128, 1);
;   WAIT_V8(6); BAR8;
;   for (int tt = 0; tt < nt - 2; tt += 2) {
;     LDB8(B0, 0, 0); SCHED8; LDA8(At, 0, 0); STAGE8(SA8(1, 1), A, lda, brow + 128, tt + 1);
;     WAIT_L8(8); BAR8; WAIT_L8(0); MMA8(0, 0, At, B0); BAR8; SCHED8;
;     LDB8(B1, 0, 1); STAGE8(SB8(0, 0), Bt, K, bcol, tt + 2);
;     BAR8; WAIT_L8(0); MMA8(0, 1, At, B1); BAR8;
;     LDA8(At, 0, 1); STAGE8(SA8(0, 0), A, lda, brow, tt + 2);
;     BAR8; WAIT_L8(0); MMA8(1, 0, At, B0); BAR8; SCHED8;
.LBB0_241:
	s_or_b64 exec, exec, s[20:21]
	s_mov_b64 s[20:21], 0x80
	v_lshl_add_u64 v[10:11], v[10:11], 0, s[20:21]
	s_or_b32 m0, s100, 0x18000
	s_waitcnt vmcnt(4)
	s_barrier
	global_load_lds_dwordx4 v[10:11], off
	v_lshl_add_u64 v[10:11], v[12:13], 0, s[20:21]
	s_or_b32 m0, s100, 0x1a000
	global_load_lds_dwordx4 v[10:11], off
	v_lshl_add_u64 v[10:11], v[14:15], 0, s[20:21]
	s_or_b32 m0, s100, 0x8000
	global_load_lds_dwordx4 v[10:11], off
	v_lshl_add_u64 v[10:11], v[16:17], 0, s[20:21]
	s_or_b32 m0, s100, 0xa000
	global_load_lds_dwordx4 v[10:11], off
	s_or_b32 m0, s100, 0x1c000
	v_lshl_add_u64 v[10:11], v[18:19], 0, s[20:21]
	global_load_lds_dwordx4 v[10:11], off
	v_lshl_add_u64 v[10:11], v[20:21], 0, s[20:21]
	s_or_b32 m0, s100, 0x1e000
	v_and_b32_e32 v147, 15, v3
	global_load_lds_dwordx4 v[10:11], off
	v_bfe_u32 v148, v3, 4, 2
	v_lshlrev_b32_e32 v10, 4, v148
	v_lshlrev_b32_e32 v11, 6, v147
	v_lshlrev_b32_e32 v14, 2, v3
	v_or_b32_e32 v13, v10, v11
	v_and_b32_e32 v14, 32, v14
	s_mov_b32 s1, 0x10000
	v_bitop3_b32 v16, v13, s1, v14 bitop3:0xde
	s_mov_b32 s1, 0x14000
	v_bitop3_b32 v15, v10, v14, v11 bitop3:0x36
	v_bitop3_b32 v17, v13, s1, v14 bitop3:0xde
	s_mov_b32 s1, 0x18000
	v_lshlrev_b32_e32 v11, 6, v3
	v_bitop3_b32 v18, v13, s1, v14 bitop3:0xde
	s_mov_b32 s1, 0x1c000
	v_and_b32_e32 v11, 0x3c0, v11
	v_bitop3_b32 v13, v13, s1, v14 bitop3:0xde
	v_bitop3_b32 v14, v11, v14, v10 bitop3:0x36
	v_lshl_add_u64 v[10:11], s[30:31], 0, v[136:137]
	v_lshl_add_u64 v[10:11], v[10:11], 0, v[8:9]
	v_lshl_add_u64 v[138:139], s[14:15], 0, v[10:11]
	v_lshl_add_u64 v[10:11], s[30:31], 0, v[132:133]
	v_lshl_add_u64 v[10:11], v[10:11], 0, v[6:7]
	v_lshl_add_u64 v[140:141], s[14:15], 0, v[10:11]
	v_lshl_add_u64 v[10:11], s[56:57], 0, v[132:133]
	v_lshl_add_u64 v[6:7], v[10:11], 0, v[6:7]
	v_bfe_u32 v146, v3, 6, 2
	s_waitcnt vmcnt(6)
	v_lshlrev_b32_e32 v149, 6, v5
	v_lshlrev_b32_e32 v5, 13, v5
	v_lshl_add_u64 v[142:143], s[46:47], 0, v[6:7]
	v_lshl_add_u64 v[6:7], s[56:57], 0, v[136:137]
	v_lshlrev_b32_e32 v12, 12, v146
	v_or_b32_e32 v19, 0x800, v5
	v_or_b32_e32 v20, 0x1000, v5
	v_or_b32_e32 v21, 0x1800, v5
	v_lshl_add_u64 v[6:7], v[6:7], 0, v[8:9]
	v_lshl_add_u64 v[144:145], s[46:47], 0, v[6:7]
	s_mov_b32 s1, -2
	s_mov_b64 s[14:15], 0
	v_add_u32_e32 v171, v16, v12
	v_add_u32_e32 v156, v15, v5
	v_add_u32_e32 v154, v14, v19
	v_add_u32_e32 v153, v14, v20
	v_add_u32_e32 v152, v14, v21
	v_add_u32_e32 v168, v17, v12
	v_add_u32_e32 v159, v18, v12
	v_add_u32_e32 v157, v13, v12
	s_mov_b64 s[30:31], 0xc000100
	s_mov_b64 s[56:57], 0xc040100
	s_mov_b64 s[58:59], 0xc000180
	s_mov_b64 s[60:61], 0xc040180
	s_barrier
	ds_read_b128 v[174:177], v171
	ds_read_b128 v[178:181], v171 offset:1024
	ds_read_b128 v[182:185], v171 offset:2048
	ds_read_b128 v[186:189], v171 offset:3072
	v_lshl_add_u64 v[222:223], v[140:141], 0, s[14:15]
	v_lshl_add_u64 v[226:227], v[222:223], 0, s[34:35]
	s_or_b32 m0, s100, 0xc000
	ds_read_b128 v[190:193], v156
	ds_read_b128 v[194:197], v156 offset:1024
	ds_read_b128 v[198:201], v154
	ds_read_b128 v[202:205], v154 offset:1024
	ds_read_b128 v[206:209], v153
	ds_read_b128 v[210:213], v153 offset:1024
	ds_read_b128 v[214:217], v152
	ds_read_b128 v[218:221], v152 offset:1024
	global_load_lds_dwordx4 v[226:227], off
	v_lshl_add_u64 v[226:227], v[138:139], 0, s[14:15]
	s_or_b32 m0, s100, 0xe000
	v_lshl_add_u64 v[228:229], v[226:227], 0, s[34:35]
	global_load_lds_dwordx4 v[228:229], off
	s_waitcnt lgkmcnt(8)
	s_barrier
	s_waitcnt lgkmcnt(0)
	v_mfma_f32_16x16x32_f16 v[128:131], v[190:193], v[174:177], 0
	v_mfma_f32_16x16x32_f16 v[124:127], v[190:193], v[182:185], 0
	v_mfma_f32_16x16x32_f16 v[120:123], v[198:201], v[174:177], 0
	v_mfma_f32_16x16x32_f16 v[116:119], v[198:201], v[182:185], 0
	v_mfma_f32_16x16x32_f16 v[112:115], v[206:209], v[174:177], 0
	v_mfma_f32_16x16x32_f16 v[108:111], v[206:209], v[182:185], 0
	v_mfma_f32_16x16x32_f16 v[104:107], v[214:217], v[174:177], 0
	v_mfma_f32_16x16x32_f16 v[100:103], v[214:217], v[182:185], 0
	v_mfma_f32_16x16x32_f16 v[128:131], v[194:197], v[178:181], v[128:131]
	v_mfma_f32_16x16x32_f16 v[124:127], v[194:197], v[186:189], v[124:127]
	v_mfma_f32_16x16x32_f16 v[120:123], v[202:205], v[178:181], v[120:123]
	v_mfma_f32_16x16x32_f16 v[116:119], v[202:205], v[186:189], v[116:119]
	v_mfma_f32_16x16x32_f16 v[112:115], v[210:213], v[178:181], v[112:115]
	v_mfma_f32_16x16x32_f16 v[108:111], v[210:213], v[186:189], v[108:111]
	v_mfma_f32_16x16x32_f16 v[104:107], v[218:221], v[178:181], v[104:107]
	v_mfma_f32_16x16x32_f16 v[100:103], v[218:221], v[186:189], v[100:103]
	s_barrier
	v_lshl_add_u64 v[228:229], v[142:143], 0, s[14:15]
	v_lshl_add_u64 v[236:237], v[228:229], 0, s[30:31]
	s_or_b32 m0, s100, 0x10000
	ds_read_b128 v[230:233], v168
	ds_read_b128 v[238:241], v168 offset:1024
	ds_read_b128 v[242:245], v168 offset:2048
	ds_read_b128 v[246:249], v168 offset:3072
	global_load_lds_dwordx4 v[236:237], off
	v_lshl_add_u64 v[236:237], v[144:145], 0, s[14:15]
	s_or_b32 m0, s100, 0x12000
	v_lshl_add_u64 v[250:251], v[236:237], 0, s[30:31]
	global_load_lds_dwordx4 v[250:251], off
	s_barrier
; #define LDA8(dst, b, h) _Pragma("unroll") for (int m = 0; m < 4; ++m) _Pragma("unroll") for (int k = 0; k < 2; ++k) \
;     dst[m][k] = *(const bf16x8*)((const char*)SA8(b, h) + lds_byte8(wr * 64 + m * 16 + fr, k * 32 + fq * 8))
; #define LDB8(dst, b, h) _Pragma("unroll") for (int n = 0; n < 2; ++n) _Pragma("unroll") for (int k = 0; k < 2; ++k) \
;     dst[n][k] = *(const bf16x8*)((const char*)SB8(b, h) + lds_byte8(wc * 32 + n * 16 + fr, k * 32 + fq * 8))
; #define WAIT_V8(n) asm volatile("s_waitcnt vmcnt(" #n ")" ::: "memory")
; #define WAIT_L8(n) asm volatile("s_waitcnt lgkmcnt(" #n ")" ::: "memory")
; #define BAR8 __builtin_amdgcn_s_barrier()
; #define SCHED8 __builtin_amdgcn_sched_barrier(0)
;     ...
;     WAIT_L8(8); BAR8; WAIT_L8(0); MMA8(0, 0, At, B0); BAR8; SCHED8;
;     LDB8(B1, 0, 1); STAGE8(SB8(0, 0), Bt, K, bcol, tt + 2);
;     BAR8; WAIT_L8(0); MMA8(0, 1, At, B1); BAR8;
;     LDA8(At, 0, 1); STAGE8(SA8(0, 0), A, lda, brow, tt + 2);
;     BAR8; WAIT_L8(0); MMA8(1, 0, At, B0); BAR8; SCHED8;
;     STAGE8(SB8(0, 1), Bt, K, bcol + 128, tt + 2);
;     WAIT_V8(6); BAR8; MMA8(1, 1, At, B1); BAR8;
;     LDB8(B0, 1, 0); SCHED8; LDA8(At, 1, 0); STAGE8(SA8(0, 1), A, lda, brow + 128, tt + 2);
;     WAIT_L8(8); BAR8; WAIT_L8(0); MMA8(0, 0, At, B0); BAR8; SCHED8;
	s_waitcnt lgkmcnt(0)
	v_mfma_f32_16x16x32_f16 v[96:99], v[190:193], v[230:233], 0
	v_mfma_f32_16x16x32_f16 v[92:95], v[190:193], v[242:245], 0
	v_mfma_f32_16x16x32_f16 v[88:91], v[198:201], v[230:233], 0
	v_mfma_f32_16x16x32_f16 v[84:87], v[198:201], v[242:245], 0
	v_mfma_f32_16x16x32_f16 v[80:83], v[206:209], v[230:233], 0
	v_mfma_f32_16x16x32_f16 v[76:79], v[206:209], v[242:245], 0
	v_mfma_f32_16x16x32_f16 v[72:75], v[214:217], v[230:233], 0
	v_mfma_f32_16x16x32_f16 v[68:71], v[214:217], v[242:245], 0
	v_mfma_f32_16x16x32_f16 v[96:99], v[194:197], v[238:241], v[96:99]
	v_mfma_f32_16x16x32_f16 v[92:95], v[194:197], v[246:249], v[92:95]
	v_mfma_f32_16x16x32_f16 v[88:91], v[202:205], v[238:241], v[88:91]
	v_mfma_f32_16x16x32_f16 v[84:87], v[202:205], v[246:249], v[84:87]
	v_mfma_f32_16x16x32_f16 v[80:83], v[210:213], v[238:241], v[80:83]
	v_mfma_f32_16x16x32_f16 v[76:79], v[210:213], v[246:249], v[76:79]
	v_mfma_f32_16x16x32_f16 v[72:75], v[218:221], v[238:241], v[72:75]
	v_mfma_f32_16x16x32_f16 v[68:71], v[218:221], v[246:249], v[68:71]
	v_lshl_add_u64 v[250:251], v[222:223], 0, s[10:11]
	s_mov_b32 m0, s100
	s_barrier
	ds_read_b128 v[190:193], v156 offset:16384
	ds_read_b128 v[194:197], v156 offset:17408
	ds_read_b128 v[198:201], v154 offset:16384
	ds_read_b128 v[202:205], v154 offset:17408
	ds_read_b128 v[206:209], v153 offset:16384
	ds_read_b128 v[210:213], v153 offset:17408
	ds_read_b128 v[214:217], v152 offset:16384
	ds_read_b128 v[218:221], v152 offset:17408
	global_load_lds_dwordx4 v[250:251], off
	s_or_b32 m0, s100, 0x2000
	v_lshl_add_u64 v[250:251], v[226:227], 0, s[10:11]
	global_load_lds_dwordx4 v[250:251], off
	s_barrier
	s_waitcnt lgkmcnt(0)
	v_mfma_f32_16x16x32_f16 v[64:67], v[190:193], v[174:177], 0
	v_mfma_f32_16x16x32_f16 v[60:63], v[190:193], v[182:185], 0
	v_mfma_f32_16x16x32_f16 v[56:59], v[198:201], v[174:177], 0
	v_mfma_f32_16x16x32_f16 v[52:55], v[198:201], v[182:185], 0
	v_mfma_f32_16x16x32_f16 v[48:51], v[206:209], v[174:177], 0
	v_mfma_f32_16x16x32_f16 v[44:47], v[206:209], v[182:185], 0
	v_mfma_f32_16x16x32_f16 v[40:43], v[214:217], v[174:177], 0
	v_mfma_f32_16x16x32_f16 v[36:39], v[214:217], v[182:185], 0
	v_mfma_f32_16x16x32_f16 v[64:67], v[194:197], v[178:181], v[64:67]
	v_mfma_f32_16x16x32_f16 v[60:63], v[194:197], v[186:189], v[60:63]
	v_mfma_f32_16x16x32_f16 v[56:59], v[202:205], v[178:181], v[56:59]
	v_mfma_f32_16x16x32_f16 v[52:55], v[202:205], v[186:189], v[52:55]
	v_mfma_f32_16x16x32_f16 v[48:51], v[210:213], v[178:181], v[48:51]
	v_mfma_f32_16x16x32_f16 v[44:47], v[210:213], v[186:189], v[44:47]
	v_mfma_f32_16x16x32_f16 v[40:43], v[218:221], v[178:181], v[40:43]
	v_mfma_f32_16x16x32_f16 v[36:39], v[218:221], v[186:189], v[36:39]
	s_barrier
	s_or_b32 m0, s100, 0x14000
	v_lshl_add_u64 v[174:175], v[228:229], 0, s[56:57]
	global_load_lds_dwordx4 v[174:175], off
	s_or_b32 m0, s100, 0x16000
	v_lshl_add_u64 v[174:175], v[236:237], 0, s[56:57]
	global_load_lds_dwordx4 v[174:175], off
	s_waitcnt vmcnt(6)
	s_barrier
	v_mfma_f32_16x16x32_f16 v[32:35], v[190:193], v[230:233], 0
	v_mfma_f32_16x16x32_f16 v[28:31], v[190:193], v[242:245], 0
	v_mfma_f32_16x16x32_f16 v[24:27], v[198:201], v[230:233], 0
	v_mfma_f32_16x16x32_f16 v[20:23], v[198:201], v[242:245], 0
	v_mfma_f32_16x16x32_f16 v[16:19], v[206:209], v[230:233], 0
	v_mfma_f32_16x16x32_f16 v[12:15], v[206:209], v[242:245], 0
	v_mfma_f32_16x16x32_f16 v[8:11], v[214:217], v[230:233], 0
	v_mfma_f32_16x16x32_f16 v[4:7], v[214:217], v[242:245], 0
	v_mfma_f32_16x16x32_f16 v[32:35], v[194:197], v[238:241], v[32:35]
	v_mfma_f32_16x16x32_f16 v[28:31], v[194:197], v[246:249], v[28:31]
	v_mfma_f32_16x16x32_f16 v[24:27], v[202:205], v[238:241], v[24:27]
	v_mfma_f32_16x16x32_f16 v[20:23], v[202:205], v[246:249], v[20:23]
	v_mfma_f32_16x16x32_f16 v[16:19], v[210:213], v[238:241], v[16:19]
	v_mfma_f32_16x16x32_f16 v[12:15], v[210:213], v[246:249], v[12:15]
	v_mfma_f32_16x16x32_f16 v[8:11], v[218:221], v[238:241], v[8:11]
	v_mfma_f32_16x16x32_f16 v[4:7], v[218:221], v[246:249], v[4:7]
	s_barrier
	ds_read_b128 v[174:177], v159
	ds_read_b128 v[178:181], v159 offset:1024
	ds_read_b128 v[182:185], v159 offset:2048
	ds_read_b128 v[186:189], v159 offset:3072
	v_lshl_add_u64 v[230:231], v[222:223], 0, s[18:19]
	s_or_b32 m0, s100, 0x4000
	ds_read_b128 v[190:193], v156 offset:32768
	ds_read_b128 v[194:197], v156 offset:33792
	ds_read_b128 v[198:201], v154 offset:32768
	ds_read_b128 v[202:205], v154 offset:33792
	ds_read_b128 v[206:209], v153 offset:32768
	ds_read_b128 v[210:213], v153 offset:33792
	ds_read_b128 v[214:217], v152 offset:32768
	ds_read_b128 v[218:221], v152 offset:33792
	global_load_lds_dwordx4 v[230:231], off
	s_or_b32 m0, s100, 0x6000
	v_lshl_add_u64 v[230:231], v[226:227], 0, s[18:19]
	global_load_lds_dwordx4 v[230:231], off
	s_waitcnt lgkmcnt(8)
	s_barrier
	s_waitcnt lgkmcnt(0)
	v_mfma_f32_16x16x32_f16 v[128:131], v[190:193], v[174:177], v[128:131]
	v_mfma_f32_16x16x32_f16 v[124:127], v[190:193], v[182:185], v[124:127]
	v_mfma_f32_16x16x32_f16 v[120:123], v[198:201], v[174:177], v[120:123]
	v_mfma_f32_16x16x32_f16 v[116:119], v[198:201], v[182:185], v[116:119]
	v_mfma_f32_16x16x32_f16 v[112:115], v[206:209], v[174:177], v[112:115]
	v_mfma_f32_16x16x32_f16 v[108:111], v[206:209], v[182:185], v[108:111]
	v_mfma_f32_16x16x32_f16 v[104:107], v[214:217], v[174:177], v[104:107]
	v_mfma_f32_16x16x32_f16 v[100:103], v[214:217], v[182:185], v[100:103]
	v_mfma_f32_16x16x32_f16 v[128:131], v[194:197], v[178:181], v[128:131]
	v_mfma_f32_16x16x32_f16 v[124:127], v[194:197], v[186:189], v[124:127]
	v_mfma_f32_16x16x32_f16 v[120:123], v[202:205], v[178:181], v[120:123]
	v_mfma_f32_16x16x32_f16 v[116:119], v[202:205], v[186:189], v[116:119]
	v_mfma_f32_16x16x32_f16 v[112:115], v[210:213], v[178:181], v[112:115]
	v_mfma_f32_16x16x32_f16 v[108:111], v[210:213], v[186:189], v[108:111]
	v_mfma_f32_16x16x32_f16 v[104:107], v[218:221], v[178:181], v[104:107]
	v_mfma_f32_16x16x32_f16 v[100:103], v[218:221], v[186:189], v[100:103]
	s_barrier
; #define LDA8(dst, b, h) _Pragma("unroll") for (int m = 0; m < 4; ++m) _Pragma("unroll") for (int k = 0; k < 2; ++k) \
;     dst[m][k] = *(const bf16x8*)((const char*)SA8(b, h) + lds_byte8(wr * 64 + m * 16 + fr, k * 32 + fq * 8))
; #define LDB8(dst, b, h) _Pragma("unroll") for (int n = 0; n < 2; ++n) _Pragma("unroll") for (int k = 0; k < 2; ++k) \
;     dst[n][k] = *(const bf16x8*)((const char*)SB8(b, h) + lds_byte8(wc * 32 + n * 16 + fr, k * 32 + fq * 8))
; #define WAIT_V8(n) asm volatile("s_waitcnt vmcnt(" #n ")" ::: "memory")
; #define WAIT_L8(n) asm volatile("s_waitcnt lgkmcnt(" #n ")" ::: "memory")
; #define BAR8 __builtin_amdgcn_s_barrier()
; #define SCHED8 __builtin_amdgcn_sched_barrier(0)
;     ...
;     WAIT_L8(8); BAR8; WAIT_L8(0); MMA8(0, 0, At, B0); BAR8; SCHED8;
;     LDB8(B1, 1, 1); STAGE8(SB8(1, 0), Bt, K, bcol, tt + 3);
;     BAR8; WAIT_L8(0); MMA8(0, 1, At, B1); BAR8;
;     LDA8(At, 1, 1); STAGE8(SA8(1, 0), A, lda, brow, tt + 3);
;     BAR8; WAIT_L8(0); MMA8(1, 0, At, B0); BAR8; SCHED8;
;     STAGE8(SB8(1, 1), Bt, K, bcol + 128, tt + 3);
;     WAIT_V8(6); BAR8; MMA8(1, 1, At, B1); BAR8;
;   }
	v_lshl_add_u64 v[250:251], v[228:229], 0, s[58:59]
	s_or_b32 m0, s100, 0x18000
	ds_read_b128 v[230:233], v157
	ds_read_b128 v[238:241], v157 offset:1024
	ds_read_b128 v[242:245], v157 offset:2048
	ds_read_b128 v[246:249], v157 offset:3072
	global_load_lds_dwordx4 v[250:251], off
	s_or_b32 m0, s100, 0x1a000
	v_lshl_add_u64 v[250:251], v[236:237], 0, s[58:59]
	global_load_lds_dwordx4 v[250:251], off
	s_barrier
	s_waitcnt lgkmcnt(0)
	v_mfma_f32_16x16x32_f16 v[96:99], v[190:193], v[230:233], v[96:99]
	v_mfma_f32_16x16x32_f16 v[92:95], v[190:193], v[242:245], v[92:95]
	v_mfma_f32_16x16x32_f16 v[88:91], v[198:201], v[230:233], v[88:91]
	v_mfma_f32_16x16x32_f16 v[84:87], v[198:201], v[242:245], v[84:87]
	v_mfma_f32_16x16x32_f16 v[80:83], v[206:209], v[230:233], v[80:83]
	v_mfma_f32_16x16x32_f16 v[76:79], v[206:209], v[242:245], v[76:79]
	v_mfma_f32_16x16x32_f16 v[72:75], v[214:217], v[230:233], v[72:75]
	v_mfma_f32_16x16x32_f16 v[68:71], v[214:217], v[242:245], v[68:71]
	v_mfma_f32_16x16x32_f16 v[96:99], v[194:197], v[238:241], v[96:99]
	v_mfma_f32_16x16x32_f16 v[92:95], v[194:197], v[246:249], v[92:95]
	v_mfma_f32_16x16x32_f16 v[88:91], v[202:205], v[238:241], v[88:91]
	v_mfma_f32_16x16x32_f16 v[84:87], v[202:205], v[246:249], v[84:87]
	v_mfma_f32_16x16x32_f16 v[80:83], v[210:213], v[238:241], v[80:83]
	v_mfma_f32_16x16x32_f16 v[76:79], v[210:213], v[246:249], v[76:79]
	v_mfma_f32_16x16x32_f16 v[72:75], v[218:221], v[238:241], v[72:75]
	v_mfma_f32_16x16x32_f16 v[68:71], v[218:221], v[246:249], v[68:71]
	v_lshl_add_u64 v[222:223], v[222:223], 0, s[22:23]
	s_or_b32 m0, s100, 0x8000
	s_barrier
	ds_read_b128 v[190:193], v156 offset:49152
	ds_read_b128 v[194:197], v156 offset:50176
	ds_read_b128 v[198:201], v154 offset:49152
	ds_read_b128 v[202:205], v154 offset:50176
	ds_read_b128 v[206:209], v153 offset:49152
	ds_read_b128 v[210:213], v153 offset:50176
	ds_read_b128 v[214:217], v152 offset:49152
	ds_read_b128 v[218:221], v152 offset:50176
	global_load_lds_dwordx4 v[222:223], off
	s_or_b32 m0, s100, 0xa000
	v_lshl_add_u64 v[222:223], v[226:227], 0, s[22:23]
	global_load_lds_dwordx4 v[222:223], off
	s_barrier
	s_waitcnt lgkmcnt(0)
	v_mfma_f32_16x16x32_f16 v[64:67], v[190:193], v[174:177], v[64:67]
	v_mfma_f32_16x16x32_f16 v[60:63], v[190:193], v[182:185], v[60:63]
	v_mfma_f32_16x16x32_f16 v[56:59], v[198:201], v[174:177], v[56:59]
	v_mfma_f32_16x16x32_f16 v[52:55], v[198:201], v[182:185], v[52:55]
	v_mfma_f32_16x16x32_f16 v[48:51], v[206:209], v[174:177], v[48:51]
	v_mfma_f32_16x16x32_f16 v[44:47], v[206:209], v[182:185], v[44:47]
	v_mfma_f32_16x16x32_f16 v[40:43], v[214:217], v[174:177], v[40:43]
	v_mfma_f32_16x16x32_f16 v[36:39], v[214:217], v[182:185], v[36:39]
	v_mfma_f32_16x16x32_f16 v[64:67], v[194:197], v[178:181], v[64:67]
	v_mfma_f32_16x16x32_f16 v[60:63], v[194:197], v[186:189], v[60:63]
	v_mfma_f32_16x16x32_f16 v[56:59], v[202:205], v[178:181], v[56:59]
	v_mfma_f32_16x16x32_f16 v[52:55], v[202:205], v[186:189], v[52:55]
	v_mfma_f32_16x16x32_f16 v[48:51], v[210:213], v[178:181], v[48:51]
	v_mfma_f32_16x16x32_f16 v[44:47], v[210:213], v[186:189], v[44:47]
	v_mfma_f32_16x16x32_f16 v[40:43], v[218:221], v[178:181], v[40:43]
	v_mfma_f32_16x16x32_f16 v[36:39], v[218:221], v[186:189], v[36:39]
	s_barrier
	s_or_b32 m0, s100, 0x1c000
	v_lshl_add_u64 v[174:175], v[228:229], 0, s[60:61]
	global_load_lds_dwordx4 v[174:175], off
	s_or_b32 m0, s100, 0x1e000
	v_lshl_add_u64 v[174:175], v[236:237], 0, s[60:61]
	global_load_lds_dwordx4 v[174:175], off
	s_waitcnt vmcnt(6)
	s_barrier
	v_mfma_f32_16x16x32_f16 v[32:35], v[190:193], v[230:233], v[32:35]
	v_mfma_f32_16x16x32_f16 v[28:31], v[190:193], v[242:245], v[28:31]
	v_mfma_f32_16x16x32_f16 v[24:27], v[198:201], v[230:233], v[24:27]
	v_mfma_f32_16x16x32_f16 v[20:23], v[198:201], v[242:245], v[20:23]
	v_mfma_f32_16x16x32_f16 v[16:19], v[206:209], v[230:233], v[16:19]
	v_mfma_f32_16x16x32_f16 v[12:15], v[206:209], v[242:245], v[12:15]
	v_mfma_f32_16x16x32_f16 v[8:11], v[214:217], v[230:233], v[8:11]
	v_mfma_f32_16x16x32_f16 v[4:7], v[214:217], v[242:245], v[4:7]
	v_mfma_f32_16x16x32_f16 v[32:35], v[194:197], v[238:241], v[32:35]
	v_mfma_f32_16x16x32_f16 v[28:31], v[194:197], v[246:249], v[28:31]
	v_mfma_f32_16x16x32_f16 v[24:27], v[202:205], v[238:241], v[24:27]
	v_mfma_f32_16x16x32_f16 v[20:23], v[202:205], v[246:249], v[20:23]
	v_mfma_f32_16x16x32_f16 v[16:19], v[210:213], v[238:241], v[16:19]
	v_mfma_f32_16x16x32_f16 v[12:15], v[210:213], v[246:249], v[12:15]
	v_mfma_f32_16x16x32_f16 v[8:11], v[218:221], v[238:241], v[8:11]
	v_mfma_f32_16x16x32_f16 v[4:7], v[218:221], v[246:249], v[4:7]
	s_add_i32 s1, s1, 2
	s_add_u32 s14, s14, 0x100
	s_addc_u32 s15, s15, 0
	s_cmp_lt_u32 s1, 12
	s_barrier
	s_cbranch_scc0 .Lpk_exit_1
; #define LDA8(dst, b, h) _Pragma("unroll") for (int m = 0; m < 4; ++m) _Pragma("unroll") for (int k = 0; k < 2; ++k) \
;     dst[m][k] = *(const bf16x8*)((const char*)SA8(b, h) + lds_byte8(wr * 64 + m * 16 + fr, k * 32 + fq * 8))
; #define LDB8(dst, b, h) _Pragma("unroll") for (int n = 0; n < 2; ++n) _Pragma("unroll") for (int k = 0; k < 2; ++k) \
;     dst[n][k] = *(const bf16x8*)((const char*)SB8(b, h) + lds_byte8(wc * 32 + n * 16 + fr, k * 32 + fq * 8))
; #define WAIT_V8(n) asm volatile("s_waitcnt vmcnt(" #n ")" ::: "memory")
; #define WAIT_L8(n) asm volatile("s_waitcnt lgkmcnt(" #n ")" ::: "memory")
; #define BAR8 __builtin_amdgcn_s_barrier()
; #define SCHED8 __builtin_amdgcn_sched_barrier(0)
;     ...
;   for (int tt = 0; tt < nt - 2; tt += 2) {
;     LDB8(B0, 0, 0); SCHED8; LDA8(At, 0, 0); STAGE8(SA8(1, 1), A, lda, brow + 128, tt + 1);
;     WAIT_L8(8); BAR8; WAIT_L8(0); MMA8(0, 0, At, B0); BAR8; SCHED8;
;     LDB8(B1, 0, 1); STAGE8(SB8(0, 0), Bt, K, bcol, tt + 2);
;     BAR8; WAIT_L8(0); MMA8(0, 1, At, B1); BAR8;
;     LDA8(At, 0, 1); STAGE8(SA8(0, 0), A, lda, brow, tt + 2);
;     BAR8; WAIT_L8(0); MMA8(1, 0, At, B0); BAR8; SCHED8;
;     STAGE8(SB8(0, 1), Bt, K, bcol + 128, tt + 2);
;     WAIT_V8(6); BAR8; MMA8(1, 1, At, B1); BAR8;
;     LDB8(B0, 1, 0); SCHED8; LDA8(At, 1, 0); STAGE8(SA8(0, 1), A, lda, brow + 128, tt + 2);
;     WAIT_L8(8); BAR8; WAIT_L8(0); MMA8(0, 0, At, B0); BAR8; SCHED8;
.LBB0_242:
	ds_read_b128 v[174:177], v171
	ds_read_b128 v[178:181], v171 offset:1024
	ds_read_b128 v[182:185], v171 offset:2048
	ds_read_b128 v[186:189], v171 offset:3072
	v_lshl_add_u64 v[222:223], v[140:141], 0, s[14:15]
	v_lshl_add_u64 v[226:227], v[222:223], 0, s[34:35]
	s_or_b32 m0, s100, 0xc000
	ds_read_b128 v[190:193], v156
	ds_read_b128 v[194:197], v156 offset:1024
	ds_read_b128 v[198:201], v154
	ds_read_b128 v[202:205], v154 offset:1024
	ds_read_b128 v[206:209], v153
	ds_read_b128 v[210:213], v153 offset:1024
	ds_read_b128 v[214:217], v152
	ds_read_b128 v[218:221], v152 offset:1024
	global_load_lds_dwordx4 v[226:227], off
	v_lshl_add_u64 v[226:227], v[138:139], 0, s[14:15]
	s_or_b32 m0, s100, 0xe000
	v_lshl_add_u64 v[228:229], v[226:227], 0, s[34:35]
	global_load_lds_dwordx4 v[228:229], off
	s_waitcnt lgkmcnt(8)
	s_barrier
	s_waitcnt lgkmcnt(0)
	v_mfma_f32_16x16x32_f16 v[128:131], v[190:193], v[174:177], v[128:131]
	v_mfma_f32_16x16x32_f16 v[124:127], v[190:193], v[182:185], v[124:127]
	v_mfma_f32_16x16x32_f16 v[120:123], v[198:201], v[174:177], v[120:123]
	v_mfma_f32_16x16x32_f16 v[116:119], v[198:201], v[182:185], v[116:119]
	v_mfma_f32_16x16x32_f16 v[112:115], v[206:209], v[174:177], v[112:115]
	v_mfma_f32_16x16x32_f16 v[108:111], v[206:209], v[182:185], v[108:111]
	v_mfma_f32_16x16x32_f16 v[104:107], v[214:217], v[174:177], v[104:107]
	v_mfma_f32_16x16x32_f16 v[100:103], v[214:217], v[182:185], v[100:103]
	v_mfma_f32_16x16x32_f16 v[128:131], v[194:197], v[178:181], v[128:131]
	v_mfma_f32_16x16x32_f16 v[124:127], v[194:197], v[186:189], v[124:127]
	v_mfma_f32_16x16x32_f16 v[120:123], v[202:205], v[178:181], v[120:123]
	v_mfma_f32_16x16x32_f16 v[116:119], v[202:205], v[186:189], v[116:119]
	v_mfma_f32_16x16x32_f16 v[112:115], v[210:213], v[178:181], v[112:115]
	v_mfma_f32_16x16x32_f16 v[108:111], v[210:213], v[186:189], v[108:111]
	v_mfma_f32_16x16x32_f16 v[104:107], v[218:221], v[178:181], v[104:107]
	v_mfma_f32_16x16x32_f16 v[100:103], v[218:221], v[186:189], v[100:103]
	s_barrier
	v_lshl_add_u64 v[228:229], v[142:143], 0, s[14:15]
	v_lshl_add_u64 v[236:237], v[228:229], 0, s[30:31]
	s_or_b32 m0, s100, 0x10000
	ds_read_b128 v[230:233], v168
	ds_read_b128 v[238:241], v168 offset:1024
	ds_read_b128 v[242:245], v168 offset:2048
	ds_read_b128 v[246:249], v168 offset:3072
	global_load_lds_dwordx4 v[236:237], off
	v_lshl_add_u64 v[236:237], v[144:145], 0, s[14:15]
	s_or_b32 m0, s100, 0x12000
	v_lshl_add_u64 v[250:251], v[236:237], 0, s[30:31]
	global_load_lds_dwordx4 v[250:251], off
	s_barrier
	s_waitcnt lgkmcnt(0)
	v_mfma_f32_16x16x32_f16 v[96:99], v[190:193], v[230:233], v[96:99]
	v_mfma_f32_16x16x32_f16 v[92:95], v[190:193], v[242:245], v[92:95]
	v_mfma_f32_16x16x32_f16 v[88:91], v[198:201], v[230:233], v[88:91]
	v_mfma_f32_16x16x32_f16 v[84:87], v[198:201], v[242:245], v[84:87]
	v_mfma_f32_16x16x32_f16 v[80:83], v[206:209], v[230:233], v[80:83]
	v_mfma_f32_16x16x32_f16 v[76:79], v[206:209], v[242:245], v[76:79]
	v_mfma_f32_16x16x32_f16 v[72:75], v[214:217], v[230:233], v[72:75]
	v_mfma_f32_16x16x32_f16 v[68:71], v[214:217], v[242:245], v[68:71]
	v_mfma_f32_16x16x32_f16 v[96:99], v[194:197], v[238:241], v[96:99]
	v_mfma_f32_16x16x32_f16 v[92:95], v[194:197], v[246:249], v[92:95]
	v_mfma_f32_16x16x32_f16 v[88:91], v[202:205], v[238:241], v[88:91]
	v_mfma_f32_16x16x32_f16 v[84:87], v[202:205], v[246:249], v[84:87]
	v_mfma_f32_16x16x32_f16 v[80:83], v[210:213], v[238:241], v[80:83]
	v_mfma_f32_16x16x32_f16 v[76:79], v[210:213], v[246:249], v[76:79]
	v_mfma_f32_16x16x32_f16 v[72:75], v[218:221], v[238:241], v[72:75]
	v_mfma_f32_16x16x32_f16 v[68:71], v[218:221], v[246:249], v[68:71]
	v_lshl_add_u64 v[250:251], v[222:223], 0, s[10:11]
	s_mov_b32 m0, s100
	s_barrier
	ds_read_b128 v[190:193], v156 offset:16384
	ds_read_b128 v[194:197], v156 offset:17408
	ds_read_b128 v[198:201], v154 offset:16384
	ds_read_b128 v[202:205], v154 offset:17408
	ds_read_b128 v[206:209], v153 offset:16384
	ds_read_b128 v[210:213], v153 offset:17408
	ds_read_b128 v[214:217], v152 offset:16384
	ds_read_b128 v[218:221], v152 offset:17408
	global_load_lds_dwordx4 v[250:251], off
	s_or_b32 m0, s100, 0x2000
	v_lshl_add_u64 v[250:251], v[226:227], 0, s[10:11]
	global_load_lds_dwordx4 v[250:251], off
	s_barrier
	s_waitcnt lgkmcnt(0)
	v_mfma_f32_16x16x32_f16 v[64:67], v[190:193], v[174:177], v[64:67]
	v_mfma_f32_16x16x32_f16 v[60:63], v[190:193], v[182:185], v[60:63]
	v_mfma_f32_16x16x32_f16 v[56:59], v[198:201], v[174:177], v[56:59]
	v_mfma_f32_16x16x32_f16 v[52:55], v[198:201], v[182:185], v[52:55]
	v_mfma_f32_16x16x32_f16 v[48:51], v[206:209], v[174:177], v[48:51]
	v_mfma_f32_16x16x32_f16 v[44:47], v[206:209], v[182:185], v[44:47]
	v_mfma_f32_16x16x32_f16 v[40:43], v[214:217], v[174:177], v[40:43]
	v_mfma_f32_16x16x32_f16 v[36:39], v[214:217], v[182:185], v[36:39]
	v_mfma_f32_16x16x32_f16 v[64:67], v[194:197], v[178:181], v[64:67]
	v_mfma_f32_16x16x32_f16 v[60:63], v[194:197], v[186:189], v[60:63]
	v_mfma_f32_16x16x32_f16 v[56:59], v[202:205], v[178:181], v[56:59]
	v_mfma_f32_16x16x32_f16 v[52:55], v[202:205], v[186:189], v[52:55]
	v_mfma_f32_16x16x32_f16 v[48:51], v[210:213], v[178:181], v[48:51]
	v_mfma_f32_16x16x32_f16 v[44:47], v[210:213], v[186:189], v[44:47]
	v_mfma_f32_16x16x32_f16 v[40:43], v[218:221], v[178:181], v[40:43]
	v_mfma_f32_16x16x32_f16 v[36:39], v[218:221], v[186:189], v[36:39]
	s_barrier
	s_or_b32 m0, s100, 0x14000
	v_lshl_add_u64 v[174:175], v[228:229], 0, s[56:57]
	global_load_lds_dwordx4 v[174:175], off
	s_or_b32 m0, s100, 0x16000
	v_lshl_add_u64 v[174:175], v[236:237], 0, s[56:57]
	global_load_lds_dwordx4 v[174:175], off
	s_waitcnt vmcnt(6)
	s_barrier
; #define LDA8(dst, b, h) _Pragma("unroll") for (int m = 0; m < 4; ++m) _Pragma("unroll") for (int k = 0; k < 2; ++k) \
;     dst[m][k] = *(const bf16x8*)((const char*)SA8(b, h) + lds_byte8(wr * 64 + m * 16 + fr, k * 32 + fq * 8))
; #define LDB8(dst, b, h) _Pragma("unroll") for (int n = 0; n < 2; ++n) _Pragma("unroll") for (int k = 0; k < 2; ++k) \
;     dst[n][k] = *(const bf16x8*)((const char*)SB8(b, h) + lds_byte8(wc * 32 + n * 16 + fr, k * 32 + fq * 8))
; #define WAIT_V8(n) asm volatile("s_waitcnt vmcnt(" #n ")" ::: "memory")
; #define WAIT_L8(n) asm volatile("s_waitcnt lgkmcnt(" #n ")" ::: "memory")
; #define BAR8 __builtin_amdgcn_s_barrier()
; #define SCHED8 __builtin_amdgcn_sched_barrier(0)
;     ...
;     WAIT_V8(6); BAR8; MMA8(1, 1, At, B1); BAR8;
;     LDB8(B0, 1, 0); SCHED8; LDA8(At, 1, 0); STAGE8(SA8(0, 1), A, lda, brow + 128, tt + 2);
;     WAIT_L8(8); BAR8; WAIT_L8(0); MMA8(0, 0, At, B0); BAR8; SCHED8;
;     LDB8(B1, 1, 1); STAGE8(SB8(1, 0), Bt, K, bcol, tt + 3);
;     BAR8; WAIT_L8(0); MMA8(0, 1, At, B1); BAR8;
;     LDA8(At, 1, 1); STAGE8(SA8(1, 0), A, lda, brow, tt + 3);
;     BAR8; WAIT_L8(0); MMA8(1, 0, At, B0); BAR8; SCHED8;
	v_mfma_f32_16x16x32_f16 v[32:35], v[190:193], v[230:233], v[32:35]
	v_mfma_f32_16x16x32_f16 v[28:31], v[190:193], v[242:245], v[28:31]
	v_mfma_f32_16x16x32_f16 v[24:27], v[198:201], v[230:233], v[24:27]
	v_mfma_f32_16x16x32_f16 v[20:23], v[198:201], v[242:245], v[20:23]
	v_mfma_f32_16x16x32_f16 v[16:19], v[206:209], v[230:233], v[16:19]
	v_mfma_f32_16x16x32_f16 v[12:15], v[206:209], v[242:245], v[12:15]
	v_mfma_f32_16x16x32_f16 v[8:11], v[214:217], v[230:233], v[8:11]
	v_mfma_f32_16x16x32_f16 v[4:7], v[214:217], v[242:245], v[4:7]
	v_mfma_f32_16x16x32_f16 v[32:35], v[194:197], v[238:241], v[32:35]
	v_mfma_f32_16x16x32_f16 v[28:31], v[194:197], v[246:249], v[28:31]
	v_mfma_f32_16x16x32_f16 v[24:27], v[202:205], v[238:241], v[24:27]
	v_mfma_f32_16x16x32_f16 v[20:23], v[202:205], v[246:249], v[20:23]
	v_mfma_f32_16x16x32_f16 v[16:19], v[210:213], v[238:241], v[16:19]
	v_mfma_f32_16x16x32_f16 v[12:15], v[210:213], v[246:249], v[12:15]
	v_mfma_f32_16x16x32_f16 v[8:11], v[218:221], v[238:241], v[8:11]
	v_mfma_f32_16x16x32_f16 v[4:7], v[218:221], v[246:249], v[4:7]
	s_barrier
	ds_read_b128 v[174:177], v159
	ds_read_b128 v[178:181], v159 offset:1024
	ds_read_b128 v[182:185], v159 offset:2048
	ds_read_b128 v[186:189], v159 offset:3072
	v_lshl_add_u64 v[230:231], v[222:223], 0, s[18:19]
	s_or_b32 m0, s100, 0x4000
	ds_read_b128 v[190:193], v156 offset:32768
	ds_read_b128 v[194:197], v156 offset:33792
	ds_read_b128 v[198:201], v154 offset:32768
	ds_read_b128 v[202:205], v154 offset:33792
	ds_read_b128 v[206:209], v153 offset:32768
	ds_read_b128 v[210:213], v153 offset:33792
	ds_read_b128 v[214:217], v152 offset:32768
	ds_read_b128 v[218:221], v152 offset:33792
	global_load_lds_dwordx4 v[230:231], off
	s_or_b32 m0, s100, 0x6000
	v_lshl_add_u64 v[230:231], v[226:227], 0, s[18:19]
	global_load_lds_dwordx4 v[230:231], off
	s_waitcnt lgkmcnt(8)
	s_barrier
	s_waitcnt lgkmcnt(0)
	v_mfma_f32_16x16x32_f16 v[128:131], v[190:193], v[174:177], v[128:131]
	v_mfma_f32_16x16x32_f16 v[124:127], v[190:193], v[182:185], v[124:127]
	v_mfma_f32_16x16x32_f16 v[120:123], v[198:201], v[174:177], v[120:123]
	v_mfma_f32_16x16x32_f16 v[116:119], v[198:201], v[182:185], v[116:119]
	v_mfma_f32_16x16x32_f16 v[112:115], v[206:209], v[174:177], v[112:115]
	v_mfma_f32_16x16x32_f16 v[108:111], v[206:209], v[182:185], v[108:111]
	v_mfma_f32_16x16x32_f16 v[104:107], v[214:217], v[174:177], v[104:107]
	v_mfma_f32_16x16x32_f16 v[100:103], v[214:217], v[182:185], v[100:103]
	v_mfma_f32_16x16x32_f16 v[128:131], v[194:197], v[178:181], v[128:131]
	v_mfma_f32_16x16x32_f16 v[124:127], v[194:197], v[186:189], v[124:127]
	v_mfma_f32_16x16x32_f16 v[120:123], v[202:205], v[178:181], v[120:123]
	v_mfma_f32_16x16x32_f16 v[116:119], v[202:205], v[186:189], v[116:119]
	v_mfma_f32_16x16x32_f16 v[112:115], v[210:213], v[178:181], v[112:115]
	v_mfma_f32_16x16x32_f16 v[108:111], v[210:213], v[186:189], v[108:111]
	v_mfma_f32_16x16x32_f16 v[104:107], v[218:221], v[178:181], v[104:107]
	v_mfma_f32_16x16x32_f16 v[100:103], v[218:221], v[186:189], v[100:103]
	s_barrier
	v_lshl_add_u64 v[250:251], v[228:229], 0, s[58:59]
	s_or_b32 m0, s100, 0x18000
	ds_read_b128 v[230:233], v157
	ds_read_b128 v[238:241], v157 offset:1024
	ds_read_b128 v[242:245], v157 offset:2048
	ds_read_b128 v[246:249], v157 offset:3072
	global_load_lds_dwordx4 v[250:251], off
	s_or_b32 m0, s100, 0x1a000
	v_lshl_add_u64 v[250:251], v[236:237], 0, s[58:59]
	global_load_lds_dwordx4 v[250:251], off
	s_barrier
	s_waitcnt lgkmcnt(0)
	v_mfma_f32_16x16x32_f16 v[96:99], v[190:193], v[230:233], v[96:99]
	v_mfma_f32_16x16x32_f16 v[92:95], v[190:193], v[242:245], v[92:95]
	v_mfma_f32_16x16x32_f16 v[88:91], v[198:201], v[230:233], v[88:91]
	v_mfma_f32_16x16x32_f16 v[84:87], v[198:201], v[242:245], v[84:87]
	v_mfma_f32_16x16x32_f16 v[80:83], v[206:209], v[230:233], v[80:83]
	v_mfma_f32_16x16x32_f16 v[76:79], v[206:209], v[242:245], v[76:79]
	v_mfma_f32_16x16x32_f16 v[72:75], v[214:217], v[230:233], v[72:75]
	v_mfma_f32_16x16x32_f16 v[68:71], v[214:217], v[242:245], v[68:71]
	v_mfma_f32_16x16x32_f16 v[96:99], v[194:197], v[238:241], v[96:99]
	v_mfma_f32_16x16x32_f16 v[92:95], v[194:197], v[246:249], v[92:95]
	v_mfma_f32_16x16x32_f16 v[88:91], v[202:205], v[238:241], v[88:91]
	v_mfma_f32_16x16x32_f16 v[84:87], v[202:205], v[246:249], v[84:87]
	v_mfma_f32_16x16x32_f16 v[80:83], v[210:213], v[238:241], v[80:83]
	v_mfma_f32_16x16x32_f16 v[76:79], v[210:213], v[246:249], v[76:79]
	v_mfma_f32_16x16x32_f16 v[72:75], v[218:221], v[238:241], v[72:75]
	v_mfma_f32_16x16x32_f16 v[68:71], v[218:221], v[246:249], v[68:71]
	v_lshl_add_u64 v[222:223], v[222:223], 0, s[22:23]
	s_or_b32 m0, s100, 0x8000
	s_barrier
	ds_read_b128 v[190:193], v156 offset:49152
	ds_read_b128 v[194:197], v156 offset:50176
	ds_read_b128 v[198:201], v154 offset:49152
	ds_read_b128 v[202:205], v154 offset:50176
	ds_read_b128 v[206:209], v153 offset:49152
	ds_read_b128 v[210:213], v153 offset:50176
	ds_read_b128 v[214:217], v152 offset:49152
	ds_read_b128 v[218:221], v152 offset:50176
	global_load_lds_dwordx4 v[222:223], off
	s_or_b32 m0, s100, 0xa000
	v_lshl_add_u64 v[222:223], v[226:227], 0, s[22:23]
	global_load_lds_dwordx4 v[222:223], off
	s_barrier
; #define LDA8(dst, b, h) _Pragma("unroll") for (int m = 0; m < 4; ++m) _Pragma("unroll") for (int k = 0; k < 2; ++k) \
;     dst[m][k] = *(const bf16x8*)((const char*)SA8(b, h) + lds_byte8(wr * 64 + m * 16 + fr, k * 32 + fq * 8))
; #define LDB8(dst, b, h) _Pragma("unroll") for (int n = 0; n < 2; ++n) _Pragma("unroll") for (int k = 0; k < 2; ++k) \
;     dst[n][k] = *(const bf16x8*)((const char*)SB8(b, h) + lds_byte8(wc * 32 + n * 16 + fr, k * 32 + fq * 8))
; #define WAIT_V8(n) asm volatile("s_waitcnt vmcnt(" #n ")" ::: "memory")
; #define WAIT_L8(n) asm volatile("s_waitcnt lgkmcnt(" #n ")" ::: "memory")
; #define BAR8 __builtin_amdgcn_s_barrier()
; #define SCHED8 __builtin_amdgcn_sched_barrier(0)
;     ...
;     BAR8; WAIT_L8(0); MMA8(1, 0, At, B0); BAR8; SCHED8;
;     STAGE8(SB8(1, 1), Bt, K, bcol + 128, tt + 3);
;     WAIT_V8(6); BAR8; MMA8(1, 1, At, B1); BAR8;
;   }
;   { LDB8(B0, 0, 0); LDA8(At, 0, 0); STAGE8(SA8(1, 1), A, lda, brow + 128, nt - 1);
;     BAR8; WAIT_L8(0); MMA8(0, 0, At, B0); BAR8;
;     LDB8(B1, 0, 1); BAR8; WAIT_L8(0); MMA8(0, 1, At, B1); BAR8;
;     LDA8(At, 0, 1); WAIT_V8(4); BAR8; WAIT_L8(0); MMA8(1, 0, At, B0); MMA8(1, 1, At, B1); BAR8; }
;   { LDB8(B0, 1, 0); LDA8(At, 1, 0); WAIT_V8(2); BAR8; WAIT_L8(0); MMA8(0, 0, At, B0); BAR8;
	s_waitcnt lgkmcnt(0)
	v_mfma_f32_16x16x32_f16 v[64:67], v[190:193], v[174:177], v[64:67]
	v_mfma_f32_16x16x32_f16 v[60:63], v[190:193], v[182:185], v[60:63]
	v_mfma_f32_16x16x32_f16 v[56:59], v[198:201], v[174:177], v[56:59]
	v_mfma_f32_16x16x32_f16 v[52:55], v[198:201], v[182:185], v[52:55]
	v_mfma_f32_16x16x32_f16 v[48:51], v[206:209], v[174:177], v[48:51]
	v_mfma_f32_16x16x32_f16 v[44:47], v[206:209], v[182:185], v[44:47]
	v_mfma_f32_16x16x32_f16 v[40:43], v[214:217], v[174:177], v[40:43]
	v_mfma_f32_16x16x32_f16 v[36:39], v[214:217], v[182:185], v[36:39]
	v_mfma_f32_16x16x32_f16 v[64:67], v[194:197], v[178:181], v[64:67]
	v_mfma_f32_16x16x32_f16 v[60:63], v[194:197], v[186:189], v[60:63]
	v_mfma_f32_16x16x32_f16 v[56:59], v[202:205], v[178:181], v[56:59]
	v_mfma_f32_16x16x32_f16 v[52:55], v[202:205], v[186:189], v[52:55]
	v_mfma_f32_16x16x32_f16 v[48:51], v[210:213], v[178:181], v[48:51]
	v_mfma_f32_16x16x32_f16 v[44:47], v[210:213], v[186:189], v[44:47]
	v_mfma_f32_16x16x32_f16 v[40:43], v[218:221], v[178:181], v[40:43]
	v_mfma_f32_16x16x32_f16 v[36:39], v[218:221], v[186:189], v[36:39]
	s_barrier
	s_or_b32 m0, s100, 0x1c000
	v_lshl_add_u64 v[174:175], v[228:229], 0, s[60:61]
	global_load_lds_dwordx4 v[174:175], off
	s_or_b32 m0, s100, 0x1e000
	v_lshl_add_u64 v[174:175], v[236:237], 0, s[60:61]
	global_load_lds_dwordx4 v[174:175], off
	s_waitcnt vmcnt(6)
	s_barrier
	v_mfma_f32_16x16x32_f16 v[32:35], v[190:193], v[230:233], v[32:35]
	v_mfma_f32_16x16x32_f16 v[28:31], v[190:193], v[242:245], v[28:31]
	v_mfma_f32_16x16x32_f16 v[24:27], v[198:201], v[230:233], v[24:27]
	v_mfma_f32_16x16x32_f16 v[20:23], v[198:201], v[242:245], v[20:23]
	v_mfma_f32_16x16x32_f16 v[16:19], v[206:209], v[230:233], v[16:19]
	v_mfma_f32_16x16x32_f16 v[12:15], v[206:209], v[242:245], v[12:15]
	v_mfma_f32_16x16x32_f16 v[8:11], v[214:217], v[230:233], v[8:11]
	v_mfma_f32_16x16x32_f16 v[4:7], v[214:217], v[242:245], v[4:7]
	v_mfma_f32_16x16x32_f16 v[32:35], v[194:197], v[238:241], v[32:35]
	v_mfma_f32_16x16x32_f16 v[28:31], v[194:197], v[246:249], v[28:31]
	v_mfma_f32_16x16x32_f16 v[24:27], v[202:205], v[238:241], v[24:27]
	v_mfma_f32_16x16x32_f16 v[20:23], v[202:205], v[246:249], v[20:23]
	v_mfma_f32_16x16x32_f16 v[16:19], v[210:213], v[238:241], v[16:19]
	v_mfma_f32_16x16x32_f16 v[12:15], v[210:213], v[246:249], v[12:15]
	v_mfma_f32_16x16x32_f16 v[8:11], v[218:221], v[238:241], v[8:11]
	v_mfma_f32_16x16x32_f16 v[4:7], v[218:221], v[246:249], v[4:7]
	s_add_i32 s1, s1, 2
	s_add_u32 s14, s14, 0x100
	s_addc_u32 s15, s15, 0
	s_cmp_lt_u32 s1, 12
	s_barrier
	s_cbranch_scc1 .LBB0_242
.Lpk_exit_1:
	s_add_u32 s12, s12, 0x40780
	s_addc_u32 s13, s13, 0
	v_lshl_add_u64 v[132:133], s[12:13], 0, v[132:133]
	v_lshl_add_u64 v[0:1], v[0:1], 1, v[132:133]
	s_or_b32 m0, s100, 0xc000
	ds_read_b128 v[138:141], v171
	ds_read_b128 v[142:145], v171 offset:1024
	ds_read_b128 v[160:163], v171 offset:2048
	ds_read_b128 v[164:167], v171 offset:3072
	ds_read_b128 v[174:177], v156
	ds_read_b128 v[178:181], v156 offset:1024
	ds_read_b128 v[182:185], v154
	ds_read_b128 v[186:189], v154 offset:1024
	ds_read_b128 v[190:193], v153
	ds_read_b128 v[194:197], v153 offset:1024
	ds_read_b128 v[198:201], v152
	ds_read_b128 v[202:205], v152 offset:1024
	global_load_lds_dwordx4 v[0:1], off
	v_lshl_add_u64 v[0:1], s[12:13], 0, v[136:137]
	s_or_b32 m0, s100, 0xe000
	v_lshl_add_u64 v[0:1], v[134:135], 1, v[0:1]
	global_load_lds_dwordx4 v[0:1], off
	s_barrier
	s_waitcnt lgkmcnt(0)
	v_mfma_f32_16x16x32_f16 v[128:131], v[174:177], v[138:141], v[128:131]
	v_mfma_f32_16x16x32_f16 v[124:127], v[174:177], v[160:163], v[124:127]
	v_mfma_f32_16x16x32_f16 v[120:123], v[182:185], v[138:141], v[120:123]
	v_mfma_f32_16x16x32_f16 v[112:115], v[190:193], v[138:141], v[112:115]
	v_mfma_f32_16x16x32_f16 v[128:131], v[178:181], v[142:145], v[128:131]
	v_mfma_f32_16x16x32_f16 v[124:127], v[178:181], v[164:167], v[124:127]
	v_mfma_f32_16x16x32_f16 v[120:123], v[186:189], v[142:145], v[120:123]
	v_mfma_f32_16x16x32_f16 v[116:119], v[182:185], v[160:163], v[116:119]
	v_mfma_f32_16x16x32_f16 v[112:115], v[194:197], v[142:145], v[112:115]
	v_mfma_f32_16x16x32_f16 v[108:111], v[190:193], v[160:163], v[108:111]
	v_mfma_f32_16x16x32_f16 v[104:107], v[198:201], v[138:141], v[104:107]
	v_mfma_f32_16x16x32_f16 v[100:103], v[198:201], v[160:163], v[100:103]
	v_mfma_f32_16x16x32_f16 v[132:135], v[186:189], v[164:167], v[116:119]
	v_mfma_f32_16x16x32_f16 v[170:173], v[194:197], v[164:167], v[108:111]
	v_mfma_f32_16x16x32_f16 v[206:209], v[202:205], v[142:145], v[104:107]
	v_mfma_f32_16x16x32_f16 v[210:213], v[202:205], v[164:167], v[100:103]
	s_barrier
	s_nop 1
	ds_read_b128 v[100:103], v168
	ds_read_b128 v[104:107], v168 offset:1024
	ds_read_b128 v[108:111], v168 offset:2048
	ds_read_b128 v[116:119], v168 offset:3072
	s_barrier
	s_waitcnt lgkmcnt(0)
	v_mfma_f32_16x16x32_f16 v[80:83], v[190:193], v[100:103], v[80:83]
	v_mfma_f32_16x16x32_f16 v[76:79], v[190:193], v[108:111], v[76:79]
	v_mfma_f32_16x16x32_f16 v[72:75], v[198:201], v[100:103], v[72:75]
	v_mfma_f32_16x16x32_f16 v[68:71], v[198:201], v[108:111], v[68:71]
	v_mfma_f32_16x16x32_f16 v[96:99], v[174:177], v[100:103], v[96:99]
	v_mfma_f32_16x16x32_f16 v[92:95], v[174:177], v[108:111], v[92:95]
	v_mfma_f32_16x16x32_f16 v[88:91], v[182:185], v[100:103], v[88:91]
	v_mfma_f32_16x16x32_f16 v[84:87], v[182:185], v[108:111], v[84:87]
	v_mfma_f32_16x16x32_f16 v[80:83], v[194:197], v[104:107], v[80:83]
	v_mfma_f32_16x16x32_f16 v[76:79], v[194:197], v[116:119], v[76:79]
	v_mfma_f32_16x16x32_f16 v[72:75], v[202:205], v[104:107], v[72:75]
	v_mfma_f32_16x16x32_f16 v[68:71], v[202:205], v[116:119], v[68:71]
	v_mfma_f32_16x16x32_f16 v[214:217], v[178:181], v[104:107], v[96:99]
	v_mfma_f32_16x16x32_f16 v[174:177], v[178:181], v[116:119], v[92:95]
	v_mfma_f32_16x16x32_f16 v[178:181], v[186:189], v[104:107], v[88:91]
	v_mfma_f32_16x16x32_f16 v[182:185], v[186:189], v[116:119], v[84:87]
	s_barrier
; #define LDA8(dst, b, h) _Pragma("unroll") for (int m = 0; m < 4; ++m) _Pragma("unroll") for (int k = 0; k < 2; ++k) \
;     dst[m][k] = *(const bf16x8*)((const char*)SA8(b, h) + lds_byte8(wr * 64 + m * 16 + fr, k * 32 + fq * 8))
; #define LDB8(dst, b, h) _Pragma("unroll") for (int n = 0; n < 2; ++n) _Pragma("unroll") for (int k = 0; k < 2; ++k) \
;     dst[n][k] = *(const bf16x8*)((const char*)SB8(b, h) + lds_byte8(wc * 32 + n * 16 + fr, k * 32 + fq * 8))
; #define WAIT_V8(n) asm volatile("s_waitcnt vmcnt(" #n ")" ::: "memory")
; #define WAIT_L8(n) asm volatile("s_waitcnt lgkmcnt(" #n ")" ::: "memory")
; #define BAR8 __builtin_amdgcn_s_barrier()
;     ...
;     LDA8(At, 0, 1); WAIT_V8(4); BAR8; WAIT_L8(0); MMA8(1, 0, At, B0); MMA8(1, 1, At, B1); BAR8; }
;   { LDB8(B0, 1, 0); LDA8(At, 1, 0); WAIT_V8(2); BAR8; WAIT_L8(0); MMA8(0, 0, At, B0); BAR8;
	s_nop 0
	ds_read_b128 v[84:87], v156 offset:16384
	ds_read_b128 v[88:91], v156 offset:17408
	ds_read_b128 v[92:95], v154 offset:16384
	ds_read_b128 v[96:99], v154 offset:17408
	ds_read_b128 v[186:189], v153 offset:16384
	ds_read_b128 v[190:193], v153 offset:17408
	ds_read_b128 v[194:197], v152 offset:16384
	ds_read_b128 v[198:201], v152 offset:17408
	s_waitcnt vmcnt(4)
	s_barrier
	s_waitcnt lgkmcnt(0)
	v_mfma_f32_16x16x32_f16 v[64:67], v[84:87], v[138:141], v[64:67]
	v_mfma_f32_16x16x32_f16 v[60:63], v[84:87], v[160:163], v[60:63]
	v_mfma_f32_16x16x32_f16 v[56:59], v[92:95], v[138:141], v[56:59]
	v_mfma_f32_16x16x32_f16 v[52:55], v[92:95], v[160:163], v[52:55]
	v_mfma_f32_16x16x32_f16 v[48:51], v[186:189], v[138:141], v[48:51]
	v_mfma_f32_16x16x32_f16 v[44:47], v[186:189], v[160:163], v[44:47]
	v_mfma_f32_16x16x32_f16 v[40:43], v[194:197], v[138:141], v[40:43]
	v_mfma_f32_16x16x32_f16 v[36:39], v[194:197], v[160:163], v[36:39]
	v_mfma_f32_16x16x32_f16 v[64:67], v[88:91], v[142:145], v[64:67]
	v_mfma_f32_16x16x32_f16 v[60:63], v[88:91], v[164:167], v[60:63]
	v_mfma_f32_16x16x32_f16 v[56:59], v[96:99], v[142:145], v[56:59]
	v_mfma_f32_16x16x32_f16 v[52:55], v[96:99], v[164:167], v[52:55]
	v_mfma_f32_16x16x32_f16 v[48:51], v[190:193], v[142:145], v[48:51]
	v_mfma_f32_16x16x32_f16 v[44:47], v[190:193], v[164:167], v[44:47]
	v_mfma_f32_16x16x32_f16 v[40:43], v[198:201], v[142:145], v[40:43]
	v_mfma_f32_16x16x32_f16 v[36:39], v[198:201], v[164:167], v[36:39]
	v_mfma_f32_16x16x32_f16 v[32:35], v[84:87], v[100:103], v[32:35]
	v_mfma_f32_16x16x32_f16 v[28:31], v[84:87], v[108:111], v[28:31]
	v_mfma_f32_16x16x32_f16 v[24:27], v[92:95], v[100:103], v[24:27]
	v_mfma_f32_16x16x32_f16 v[20:23], v[92:95], v[108:111], v[20:23]
	v_mfma_f32_16x16x32_f16 v[16:19], v[186:189], v[100:103], v[16:19]
	v_mfma_f32_16x16x32_f16 v[12:15], v[186:189], v[108:111], v[12:15]
	v_mfma_f32_16x16x32_f16 v[8:11], v[194:197], v[100:103], v[8:11]
	v_mfma_f32_16x16x32_f16 v[4:7], v[194:197], v[108:111], v[4:7]
	v_mfma_f32_16x16x32_f16 v[136:139], v[88:91], v[104:107], v[32:35]
	v_mfma_f32_16x16x32_f16 v[140:143], v[88:91], v[116:119], v[28:31]
	v_mfma_f32_16x16x32_f16 v[160:163], v[96:99], v[104:107], v[24:27]
	v_mfma_f32_16x16x32_f16 v[164:167], v[96:99], v[116:119], v[20:23]
	v_mfma_f32_16x16x32_f16 v[202:205], v[190:193], v[104:107], v[16:19]
	v_mfma_f32_16x16x32_f16 v[186:189], v[190:193], v[116:119], v[12:15]
	v_mfma_f32_16x16x32_f16 v[190:193], v[198:201], v[104:107], v[8:11]
	v_mfma_f32_16x16x32_f16 v[194:197], v[198:201], v[116:119], v[4:7]
	s_barrier
	ds_read_b128 v[198:201], v159
	ds_read_b128 v[218:221], v159 offset:1024
	ds_read_b128 v[230:233], v159 offset:2048
	ds_read_b128 v[238:241], v159 offset:3072
	ds_read_b128 v[8:11], v156 offset:32768
	ds_read_b128 v[12:15], v156 offset:33792
	ds_read_b128 v[16:19], v154 offset:32768
	ds_read_b128 v[24:27], v154 offset:33792
	ds_read_b128 v[28:31], v153 offset:32768
	ds_read_b128 v[32:35], v153 offset:33792
	ds_read_b128 v[242:245], v152 offset:32768
	ds_read_b128 v[246:249], v152 offset:33792
	s_waitcnt vmcnt(2)
	s_barrier
	s_waitcnt lgkmcnt(0)
	v_mfma_f32_16x16x32_f16 v[4:7], v[8:11], v[198:201], v[128:131]
	v_mfma_f32_16x16x32_f16 v[104:107], v[12:15], v[218:221], v[4:7]
	v_mfma_f32_16x16x32_f16 v[4:7], v[8:11], v[230:233], v[124:127]
	v_mfma_f32_16x16x32_f16 v[116:119], v[12:15], v[238:241], v[4:7]
	v_mfma_f32_16x16x32_f16 v[4:7], v[16:19], v[198:201], v[120:123]
	v_mfma_f32_16x16x32_f16 v[100:103], v[24:27], v[218:221], v[4:7]
	v_mfma_f32_16x16x32_f16 v[4:7], v[16:19], v[230:233], v[132:135]
	v_mfma_f32_16x16x32_f16 v[108:111], v[24:27], v[238:241], v[4:7]
	v_mfma_f32_16x16x32_f16 v[4:7], v[28:31], v[198:201], v[112:115]
	v_mfma_f32_16x16x32_f16 v[92:95], v[32:35], v[218:221], v[4:7]
	v_mfma_f32_16x16x32_f16 v[4:7], v[28:31], v[230:233], v[170:173]
	v_mfma_f32_16x16x32_f16 v[96:99], v[32:35], v[238:241], v[4:7]
	v_mfma_f32_16x16x32_f16 v[4:7], v[242:245], v[198:201], v[206:209]
	v_mfma_f32_16x16x32_f16 v[84:87], v[246:249], v[218:221], v[4:7]
	v_mfma_f32_16x16x32_f16 v[4:7], v[242:245], v[230:233], v[210:213]
	v_mfma_f32_16x16x32_f16 v[88:91], v[246:249], v[238:241], v[4:7]
	s_barrier
; #define LDA8(dst, b, h) _Pragma("unroll") for (int m = 0; m < 4; ++m) _Pragma("unroll") for (int k = 0; k < 2; ++k) \
;     dst[m][k] = *(const bf16x8*)((const char*)SA8(b, h) + lds_byte8(wr * 64 + m * 16 + fr, k * 32 + fq * 8))
; #define LDB8(dst, b, h) _Pragma("unroll") for (int n = 0; n < 2; ++n) _Pragma("unroll") for (int k = 0; k < 2; ++k) \
;     dst[n][k] = *(const bf16x8*)((const char*)SB8(b, h) + lds_byte8(wc * 32 + n * 16 + fr, k * 32 + fq * 8))
; #define WAIT_V8(n) asm volatile("s_waitcnt vmcnt(" #n ")" ::: "memory")
; #define WAIT_L8(n) asm volatile("s_waitcnt lgkmcnt(" #n ")" ::: "memory")
; #define BAR8 __builtin_amdgcn_s_barrier()
;     ...
;     LDB8(B1, 1, 1); WAIT_V8(0); BAR8; WAIT_L8(0); MMA8(0, 1, At, B1); BAR8;
;     LDA8(At, 1, 1); BAR8; WAIT_L8(0); MMA8(1, 0, At, B0); MMA8(1, 1, At, B1); BAR8; }
;   if (wr == 0) BAR8;
;     ...
;   if (t < 256) {
	ds_read_b128 v[132:135], v157
	ds_read_b128 v[168:171], v157 offset:1024
	ds_read_b128 v[206:209], v157 offset:2048
	ds_read_b128 v[210:213], v157 offset:3072
	s_waitcnt vmcnt(0)
	s_barrier
	s_waitcnt lgkmcnt(0)
	v_mfma_f32_16x16x32_f16 v[4:7], v[8:11], v[132:135], v[214:217]
	v_mfma_f32_16x16x32_f16 v[8:11], v[8:11], v[206:209], v[174:177]
	v_mfma_f32_16x16x32_f16 v[4:7], v[12:15], v[168:171], v[4:7]
	v_mfma_f32_16x16x32_f16 v[20:23], v[12:15], v[210:213], v[8:11]
	v_mfma_f32_16x16x32_f16 v[8:11], v[16:19], v[132:135], v[178:181]
	v_mfma_f32_16x16x32_f16 v[12:15], v[16:19], v[206:209], v[182:185]
	v_mfma_f32_16x16x32_f16 v[8:11], v[24:27], v[168:171], v[8:11]
	v_mfma_f32_16x16x32_f16 v[24:27], v[24:27], v[210:213], v[12:15]
	v_mfma_f32_16x16x32_f16 v[12:15], v[28:31], v[132:135], v[80:83]
	v_mfma_f32_16x16x32_f16 v[16:19], v[28:31], v[206:209], v[76:79]
	v_mfma_f32_16x16x32_f16 v[12:15], v[32:35], v[168:171], v[12:15]
	v_mfma_f32_16x16x32_f16 v[28:31], v[32:35], v[210:213], v[16:19]
	v_mfma_f32_16x16x32_f16 v[16:19], v[242:245], v[132:135], v[72:75]
	v_mfma_f32_16x16x32_f16 v[32:35], v[242:245], v[206:209], v[68:71]
	v_mfma_f32_16x16x32_f16 v[16:19], v[246:249], v[168:171], v[16:19]
	v_mfma_f32_16x16x32_f16 v[32:35], v[246:249], v[210:213], v[32:35]
	s_barrier
	ds_read_b128 v[172:175], v156 offset:49152
	ds_read_b128 v[156:159], v156 offset:50176
	ds_read_b128 v[176:179], v154 offset:49152
	ds_read_b128 v[180:183], v154 offset:50176
	ds_read_b128 v[214:217], v153 offset:49152
	ds_read_b128 v[242:245], v153 offset:50176
	ds_read_b128 v[246:249], v152 offset:49152
	ds_read_b128 v[150:153], v152 offset:50176
	s_barrier
	s_waitcnt lgkmcnt(0)
	v_mfma_f32_16x16x32_f16 v[64:67], v[172:175], v[198:201], v[64:67]
	v_mfma_f32_16x16x32_f16 v[60:63], v[172:175], v[230:233], v[60:63]
	v_mfma_f32_16x16x32_f16 v[56:59], v[176:179], v[198:201], v[56:59]
	v_mfma_f32_16x16x32_f16 v[52:55], v[176:179], v[230:233], v[52:55]
	v_mfma_f32_16x16x32_f16 v[48:51], v[214:217], v[198:201], v[48:51]
	v_mfma_f32_16x16x32_f16 v[44:47], v[214:217], v[230:233], v[44:47]
	v_mfma_f32_16x16x32_f16 v[40:43], v[246:249], v[198:201], v[40:43]
	v_mfma_f32_16x16x32_f16 v[36:39], v[246:249], v[230:233], v[36:39]
	v_mfma_f32_16x16x32_f16 v[128:131], v[156:159], v[218:221], v[64:67]
	v_mfma_f32_16x16x32_f16 v[124:127], v[156:159], v[238:241], v[60:63]
	v_mfma_f32_16x16x32_f16 v[120:123], v[180:183], v[218:221], v[56:59]
	v_mfma_f32_16x16x32_f16 v[112:115], v[180:183], v[238:241], v[52:55]
	v_mfma_f32_16x16x32_f16 v[80:83], v[242:245], v[218:221], v[48:51]
	v_mfma_f32_16x16x32_f16 v[76:79], v[242:245], v[238:241], v[44:47]
	v_mfma_f32_16x16x32_f16 v[72:75], v[150:153], v[218:221], v[40:43]
	v_mfma_f32_16x16x32_f16 v[68:71], v[150:153], v[238:241], v[36:39]
	v_mfma_f32_16x16x32_f16 v[40:43], v[172:175], v[206:209], v[140:143]
	v_mfma_f32_16x16x32_f16 v[44:47], v[176:179], v[206:209], v[164:167]
	v_mfma_f32_16x16x32_f16 v[48:51], v[214:217], v[206:209], v[186:189]
	v_mfma_f32_16x16x32_f16 v[36:39], v[172:175], v[132:135], v[136:139]
	v_mfma_f32_16x16x32_f16 v[52:55], v[156:159], v[210:213], v[40:43]
	v_mfma_f32_16x16x32_f16 v[40:43], v[176:179], v[132:135], v[160:163]
	v_mfma_f32_16x16x32_f16 v[56:59], v[180:183], v[210:213], v[44:47]
	v_mfma_f32_16x16x32_f16 v[44:47], v[214:217], v[132:135], v[202:205]
	v_mfma_f32_16x16x32_f16 v[60:63], v[242:245], v[210:213], v[48:51]
	v_mfma_f32_16x16x32_f16 v[48:51], v[246:249], v[132:135], v[190:193]
	v_mfma_f32_16x16x32_f16 v[64:67], v[246:249], v[206:209], v[194:197]
	v_mfma_f32_16x16x32_f16 v[36:39], v[156:159], v[168:171], v[36:39]
	v_mfma_f32_16x16x32_f16 v[40:43], v[180:183], v[168:171], v[40:43]
	v_mfma_f32_16x16x32_f16 v[44:47], v[242:245], v[168:171], v[44:47]
	v_mfma_f32_16x16x32_f16 v[48:51], v[150:153], v[168:171], v[48:51]
	v_mfma_f32_16x16x32_f16 v[64:67], v[150:153], v[210:213], v[64:67]
	s_movk_i32 s1, 0x100
	v_cmp_gt_u32_e32 vcc, s1, v3
	s_barrier
	s_and_saveexec_b64 s[12:13], vcc
	s_cbranch_execz .LBB0_245
	s_barrier

; #define LDA8(dst, b, h) _Pragma("unroll") for (int m = 0; m < 4; ++m) _Pragma("unroll") for (int k = 0; k < 2; ++k) \
;     dst[m][k] = *(const bf16x8*)((const char*)SA8(b, h) + lds_byte8(wr * 64 + m * 16 + fr, k * 32 + fq * 8))
; #define LDB8(dst, b, h) _Pragma("unroll") for (int n = 0; n < 2; ++n) _Pragma("unroll") for (int k = 0; k < 2; ++k) \
;     dst[n][k] = *(const bf16x8*)((const char*)SB8(b, h) + lds_byte8(wc * 32 + n * 16 + fr, k * 32 + fq * 8))
; #define WAIT_V8(n) asm volatile("s_waitcnt vmcnt(" #n ")" ::: "memory")
; #define WAIT_L8(n) asm volatile("s_waitcnt lgkmcnt(" #n ")" ::: "memory")
; #define BAR8 __builtin_amdgcn_s_barrier()
; #define SCHED8 __builtin_amdgcn_sched_barrier(0)
;     ...
;   if (wr == 1) BAR8;
;   WAIT_V8(4); BAR8;
;   STAGE8(SB8(1, 0), Bt, K, bcol, 1); STAGE8(SA8(1, 0), A, lda, brow, 1); STAGE8(SB8(1, 1), Bt, K, bcol + 128, 1);
;   WAIT_V8(6); BAR8;
;   for (int tt = 0; tt < nt - 2; tt += 2) {
;     LDB8(B0, 0, 0); SCHED8; LDA8(At, 0, 0); STAGE8(SA8(1, 1), A, lda, brow + 128, tt + 1);
;     WAIT_L8(8); BAR8; WAIT_L8(0); MMA8(0, 0, At, B0); BAR8; SCHED8;
;     LDB8(B1, 0, 1); STAGE8(SB8(0, 0), Bt, K, bcol, tt + 2);
;     BAR8; WAIT_L8(0); MMA8(0, 1, At, B1); BAR8;
.LBB0_907:
	s_or_b64 exec, exec, s[12:13]
	s_lshl_b32 s29, s20, 11
	s_waitcnt vmcnt(0)
	s_and_b32 s36, s29, 0x1f80000
	s_mov_b64 s[38:39], 0x80
	v_lshl_add_u64 v[14:15], v[14:15], 0, s[38:39]
	s_or_b32 m0, s100, 0x18000
	s_waitcnt vmcnt(4)
	s_barrier
	global_load_lds_dwordx4 v[14:15], off
	v_lshl_add_u64 v[14:15], v[18:19], 0, s[38:39]
	s_or_b32 m0, s100, 0x1a000
	global_load_lds_dwordx4 v[14:15], off
	v_lshl_add_u64 v[14:15], v[20:21], 0, s[38:39]
	s_or_b32 m0, s100, 0x8000
	global_load_lds_dwordx4 v[14:15], off
	v_lshl_add_u64 v[14:15], v[22:23], 0, s[38:39]
	s_or_b32 m0, s100, 0xa000
	global_load_lds_dwordx4 v[14:15], off
	s_or_b32 m0, s100, 0x1c000
	v_lshl_add_u64 v[14:15], v[26:27], 0, s[38:39]
	global_load_lds_dwordx4 v[14:15], off
	v_lshl_add_u64 v[14:15], v[28:29], 0, s[38:39]
	s_or_b32 m0, s100, 0x1e000
	v_and_b32_e32 v147, 15, v3
	global_load_lds_dwordx4 v[14:15], off
	v_bfe_u32 v148, v3, 4, 2
	v_lshlrev_b32_e32 v14, 4, v148
	v_lshlrev_b32_e32 v15, 6, v147
	v_lshlrev_b32_e32 v18, 2, v3
	v_lshlrev_b64 v[136:137], 10, v[16:17]
	v_or_b32_e32 v17, v14, v15
	v_and_b32_e32 v18, 32, v18
	s_mov_b32 s29, 0x10000
	s_and_b32 s12, s21, 0xffffff00
	v_bitop3_b32 v20, v17, s29, v18 bitop3:0xde
	s_mov_b32 s29, 0x14000
	s_ashr_i32 s13, s12, 31
	v_readlane_b32 s40, v254, 35
	v_bitop3_b32 v19, v14, v18, v15 bitop3:0x36
	v_bitop3_b32 v21, v17, s29, v18 bitop3:0xde
	s_mov_b32 s29, 0x18000
	v_lshlrev_b32_e32 v15, 6, v3
	s_lshl_b64 s[12:13], s[12:13], 11
	s_mov_b32 s37, s40
	v_bitop3_b32 v22, v17, s29, v18 bitop3:0xde
	s_mov_b32 s29, 0x1c000
	v_and_b32_e32 v15, 0x3c0, v15
	v_bitop3_b32 v17, v17, s29, v18 bitop3:0xde
	v_bitop3_b32 v18, v15, v18, v14 bitop3:0x36
	v_lshl_add_u64 v[14:15], s[12:13], 0, v[6:7]
	v_lshl_add_u64 v[6:7], s[36:37], 0, v[6:7]
	v_lshl_add_u64 v[14:15], v[14:15], 0, v[8:9]
	v_lshl_add_u64 v[6:7], v[6:7], 0, v[8:9]
	v_bfe_u32 v146, v3, 6, 2
	s_waitcnt vmcnt(6)
	v_lshlrev_b32_e32 v149, 6, v5
	v_lshlrev_b32_e32 v5, 13, v5
	v_lshl_add_u64 v[138:139], s[4:5], 0, v[14:15]
	v_lshl_add_u64 v[14:15], s[12:13], 0, v[10:11]
	v_lshl_add_u64 v[142:143], s[2:3], 0, v[6:7]
	v_lshl_add_u64 v[6:7], s[36:37], 0, v[10:11]
	v_lshlrev_b64 v[134:135], 10, v[24:25]
	v_readlane_b32 s41, v254, 36
	v_readlane_b32 s42, v254, 37
	v_readlane_b32 s43, v254, 38
	v_lshlrev_b32_e32 v16, 12, v146
	v_or_b32_e32 v23, 0x800, v5
	v_or_b32_e32 v24, 0x1000, v5
	v_or_b32_e32 v25, 0x1800, v5
	v_lshl_add_u64 v[14:15], v[14:15], 0, v[12:13]
	v_lshl_add_u64 v[6:7], v[6:7], 0, v[12:13]
	v_lshl_add_u64 v[140:141], s[4:5], 0, v[14:15]
	v_lshl_add_u64 v[144:145], s[2:3], 0, v[6:7]
	s_mov_b32 s29, -2
	s_mov_b64 s[12:13], 0
	v_add_u32_e32 v171, v20, v16
	v_add_u32_e32 v156, v19, v5
	v_add_u32_e32 v155, v18, v23
	v_add_u32_e32 v154, v18, v24
	v_add_u32_e32 v153, v18, v25
	v_add_u32_e32 v167, v21, v16
	v_add_u32_e32 v160, v22, v16
	v_add_u32_e32 v158, v17, v16
	s_mov_b64 s[36:37], 0x6040080
	s_mov_b64 s[38:39], 0xc4a0100
	s_mov_b64 s[40:41], 0x6000100
	s_mov_b64 s[42:43], 0xc4e0100
	s_mov_b64 s[44:45], 0x6040100
	s_mov_b64 s[46:47], 0xc4a0180
	s_mov_b64 s[48:49], 0x6000180
	s_mov_b64 s[50:51], 0xc4e0180
	s_barrier
	ds_read_b128 v[174:177], v171
	ds_read_b128 v[178:181], v171 offset:1024
	ds_read_b128 v[182:185], v171 offset:2048
	ds_read_b128 v[186:189], v171 offset:3072
	v_lshl_add_u64 v[222:223], v[142:143], 0, s[12:13]
	v_lshl_add_u64 v[226:227], v[222:223], 0, s[36:37]
	s_or_b32 m0, s100, 0xc000
	ds_read_b128 v[190:193], v156
	ds_read_b128 v[194:197], v156 offset:1024
	ds_read_b128 v[198:201], v155
	ds_read_b128 v[202:205], v155 offset:1024
	ds_read_b128 v[206:209], v154
	ds_read_b128 v[210:213], v154 offset:1024
	ds_read_b128 v[214:217], v153
	ds_read_b128 v[218:221], v153 offset:1024
	global_load_lds_dwordx4 v[226:227], off
	v_lshl_add_u64 v[226:227], v[144:145], 0, s[12:13]
	s_or_b32 m0, s100, 0xe000
	v_lshl_add_u64 v[228:229], v[226:227], 0, s[36:37]
	global_load_lds_dwordx4 v[228:229], off
	s_waitcnt lgkmcnt(8)
	s_barrier
	s_waitcnt lgkmcnt(0)
	v_mfma_f32_16x16x32_bf16 v[128:131], v[190:193], v[174:177], 0
	v_mfma_f32_16x16x32_bf16 v[124:127], v[190:193], v[182:185], 0
	v_mfma_f32_16x16x32_bf16 v[120:123], v[198:201], v[174:177], 0
	v_mfma_f32_16x16x32_bf16 v[116:119], v[198:201], v[182:185], 0
	v_mfma_f32_16x16x32_bf16 v[112:115], v[206:209], v[174:177], 0
	v_mfma_f32_16x16x32_bf16 v[108:111], v[206:209], v[182:185], 0
	v_mfma_f32_16x16x32_bf16 v[104:107], v[214:217], v[174:177], 0
	v_mfma_f32_16x16x32_bf16 v[100:103], v[214:217], v[182:185], 0
	v_mfma_f32_16x16x32_bf16 v[128:131], v[194:197], v[178:181], v[128:131]
	v_mfma_f32_16x16x32_bf16 v[124:127], v[194:197], v[186:189], v[124:127]
	v_mfma_f32_16x16x32_bf16 v[120:123], v[202:205], v[178:181], v[120:123]
	v_mfma_f32_16x16x32_bf16 v[116:119], v[202:205], v[186:189], v[116:119]
	v_mfma_f32_16x16x32_bf16 v[112:115], v[210:213], v[178:181], v[112:115]
	v_mfma_f32_16x16x32_bf16 v[108:111], v[210:213], v[186:189], v[108:111]
	v_mfma_f32_16x16x32_bf16 v[104:107], v[218:221], v[178:181], v[104:107]
	v_mfma_f32_16x16x32_bf16 v[100:103], v[218:221], v[186:189], v[100:103]
	s_barrier
	v_lshl_add_u64 v[228:229], v[138:139], 0, s[12:13]
	v_lshl_add_u64 v[236:237], v[228:229], 0, s[38:39]
	s_or_b32 m0, s100, 0x10000
	ds_read_b128 v[230:233], v167
	ds_read_b128 v[238:241], v167 offset:1024
	ds_read_b128 v[242:245], v167 offset:2048
	ds_read_b128 v[246:249], v167 offset:3072
	global_load_lds_dwordx4 v[236:237], off
	v_lshl_add_u64 v[236:237], v[140:141], 0, s[12:13]
	s_or_b32 m0, s100, 0x12000
	v_lshl_add_u64 v[250:251], v[236:237], 0, s[38:39]
	global_load_lds_dwordx4 v[250:251], off
	s_barrier
; #define LDA8(dst, b, h) _Pragma("unroll") for (int m = 0; m < 4; ++m) _Pragma("unroll") for (int k = 0; k < 2; ++k) \
;     dst[m][k] = *(const bf16x8*)((const char*)SA8(b, h) + lds_byte8(wr * 64 + m * 16 + fr, k * 32 + fq * 8))
; #define LDB8(dst, b, h) _Pragma("unroll") for (int n = 0; n < 2; ++n) _Pragma("unroll") for (int k = 0; k < 2; ++k) \
;     dst[n][k] = *(const bf16x8*)((const char*)SB8(b, h) + lds_byte8(wc * 32 + n * 16 + fr, k * 32 + fq * 8))
; #define WAIT_V8(n) asm volatile("s_waitcnt vmcnt(" #n ")" ::: "memory")
; #define WAIT_L8(n) asm volatile("s_waitcnt lgkmcnt(" #n ")" ::: "memory")
; #define BAR8 __builtin_amdgcn_s_barrier()
; #define SCHED8 __builtin_amdgcn_sched_barrier(0)
;     ...
;     BAR8; WAIT_L8(0); MMA8(0, 1, At, B1); BAR8;
;     LDA8(At, 0, 1); STAGE8(SA8(0, 0), A, lda, brow, tt + 2);
;     BAR8; WAIT_L8(0); MMA8(1, 0, At, B0); BAR8; SCHED8;
;     STAGE8(SB8(0, 1), Bt, K, bcol + 128, tt + 2);
;     WAIT_V8(6); BAR8; MMA8(1, 1, At, B1); BAR8;
;     LDB8(B0, 1, 0); SCHED8; LDA8(At, 1, 0); STAGE8(SA8(0, 1), A, lda, brow + 128, tt + 2);
;     WAIT_L8(8); BAR8; WAIT_L8(0); MMA8(0, 0, At, B0); BAR8; SCHED8;
	s_waitcnt lgkmcnt(0)
	v_mfma_f32_16x16x32_bf16 v[96:99], v[190:193], v[230:233], 0
	v_mfma_f32_16x16x32_bf16 v[92:95], v[190:193], v[242:245], 0
	v_mfma_f32_16x16x32_bf16 v[88:91], v[198:201], v[230:233], 0
	v_mfma_f32_16x16x32_bf16 v[84:87], v[198:201], v[242:245], 0
	v_mfma_f32_16x16x32_bf16 v[80:83], v[206:209], v[230:233], 0
	v_mfma_f32_16x16x32_bf16 v[76:79], v[206:209], v[242:245], 0
	v_mfma_f32_16x16x32_bf16 v[72:75], v[214:217], v[230:233], 0
	v_mfma_f32_16x16x32_bf16 v[68:71], v[214:217], v[242:245], 0
	v_mfma_f32_16x16x32_bf16 v[96:99], v[194:197], v[238:241], v[96:99]
	v_mfma_f32_16x16x32_bf16 v[92:95], v[194:197], v[246:249], v[92:95]
	v_mfma_f32_16x16x32_bf16 v[88:91], v[202:205], v[238:241], v[88:91]
	v_mfma_f32_16x16x32_bf16 v[84:87], v[202:205], v[246:249], v[84:87]
	v_mfma_f32_16x16x32_bf16 v[80:83], v[210:213], v[238:241], v[80:83]
	v_mfma_f32_16x16x32_bf16 v[76:79], v[210:213], v[246:249], v[76:79]
	v_mfma_f32_16x16x32_bf16 v[72:75], v[218:221], v[238:241], v[72:75]
	v_mfma_f32_16x16x32_bf16 v[68:71], v[218:221], v[246:249], v[68:71]
	v_lshl_add_u64 v[250:251], v[222:223], 0, s[40:41]
	s_mov_b32 m0, s100
	s_barrier
	ds_read_b128 v[190:193], v156 offset:16384
	ds_read_b128 v[194:197], v156 offset:17408
	ds_read_b128 v[198:201], v155 offset:16384
	ds_read_b128 v[202:205], v155 offset:17408
	ds_read_b128 v[206:209], v154 offset:16384
	ds_read_b128 v[210:213], v154 offset:17408
	ds_read_b128 v[214:217], v153 offset:16384
	ds_read_b128 v[218:221], v153 offset:17408
	global_load_lds_dwordx4 v[250:251], off
	s_or_b32 m0, s100, 0x2000
	v_lshl_add_u64 v[250:251], v[226:227], 0, s[40:41]
	global_load_lds_dwordx4 v[250:251], off
	s_barrier
	s_waitcnt lgkmcnt(0)
	v_mfma_f32_16x16x32_bf16 v[64:67], v[190:193], v[174:177], 0
	v_mfma_f32_16x16x32_bf16 v[60:63], v[190:193], v[182:185], 0
	v_mfma_f32_16x16x32_bf16 v[56:59], v[198:201], v[174:177], 0
	v_mfma_f32_16x16x32_bf16 v[52:55], v[198:201], v[182:185], 0
	v_mfma_f32_16x16x32_bf16 v[48:51], v[206:209], v[174:177], 0
	v_mfma_f32_16x16x32_bf16 v[44:47], v[206:209], v[182:185], 0
	v_mfma_f32_16x16x32_bf16 v[40:43], v[214:217], v[174:177], 0
	v_mfma_f32_16x16x32_bf16 v[36:39], v[214:217], v[182:185], 0
	v_mfma_f32_16x16x32_bf16 v[64:67], v[194:197], v[178:181], v[64:67]
	v_mfma_f32_16x16x32_bf16 v[60:63], v[194:197], v[186:189], v[60:63]
	v_mfma_f32_16x16x32_bf16 v[56:59], v[202:205], v[178:181], v[56:59]
	v_mfma_f32_16x16x32_bf16 v[52:55], v[202:205], v[186:189], v[52:55]
	v_mfma_f32_16x16x32_bf16 v[48:51], v[210:213], v[178:181], v[48:51]
	v_mfma_f32_16x16x32_bf16 v[44:47], v[210:213], v[186:189], v[44:47]
	v_mfma_f32_16x16x32_bf16 v[40:43], v[218:221], v[178:181], v[40:43]
	v_mfma_f32_16x16x32_bf16 v[36:39], v[218:221], v[186:189], v[36:39]
	s_barrier
	s_or_b32 m0, s100, 0x14000
	v_lshl_add_u64 v[174:175], v[228:229], 0, s[42:43]
	global_load_lds_dwordx4 v[174:175], off
	s_or_b32 m0, s100, 0x16000
	v_lshl_add_u64 v[174:175], v[236:237], 0, s[42:43]
	global_load_lds_dwordx4 v[174:175], off
	s_waitcnt vmcnt(6)
	s_barrier
	v_mfma_f32_16x16x32_bf16 v[32:35], v[190:193], v[230:233], 0
	v_mfma_f32_16x16x32_bf16 v[28:31], v[190:193], v[242:245], 0
	v_mfma_f32_16x16x32_bf16 v[24:27], v[198:201], v[230:233], 0
	v_mfma_f32_16x16x32_bf16 v[20:23], v[198:201], v[242:245], 0
	v_mfma_f32_16x16x32_bf16 v[16:19], v[206:209], v[230:233], 0
	v_mfma_f32_16x16x32_bf16 v[12:15], v[206:209], v[242:245], 0
	v_mfma_f32_16x16x32_bf16 v[8:11], v[214:217], v[230:233], 0
	v_mfma_f32_16x16x32_bf16 v[4:7], v[214:217], v[242:245], 0
	v_mfma_f32_16x16x32_bf16 v[32:35], v[194:197], v[238:241], v[32:35]
	v_mfma_f32_16x16x32_bf16 v[28:31], v[194:197], v[246:249], v[28:31]
	v_mfma_f32_16x16x32_bf16 v[24:27], v[202:205], v[238:241], v[24:27]
	v_mfma_f32_16x16x32_bf16 v[20:23], v[202:205], v[246:249], v[20:23]
	v_mfma_f32_16x16x32_bf16 v[16:19], v[210:213], v[238:241], v[16:19]
	v_mfma_f32_16x16x32_bf16 v[12:15], v[210:213], v[246:249], v[12:15]
	v_mfma_f32_16x16x32_bf16 v[8:11], v[218:221], v[238:241], v[8:11]
	v_mfma_f32_16x16x32_bf16 v[4:7], v[218:221], v[246:249], v[4:7]
	s_barrier
	ds_read_b128 v[174:177], v160
	ds_read_b128 v[178:181], v160 offset:1024
	ds_read_b128 v[182:185], v160 offset:2048
	ds_read_b128 v[186:189], v160 offset:3072
	v_lshl_add_u64 v[230:231], v[222:223], 0, s[44:45]
	s_or_b32 m0, s100, 0x4000
	ds_read_b128 v[190:193], v156 offset:32768
	ds_read_b128 v[194:197], v156 offset:33792
	ds_read_b128 v[198:201], v155 offset:32768
	ds_read_b128 v[202:205], v155 offset:33792
	ds_read_b128 v[206:209], v154 offset:32768
	ds_read_b128 v[210:213], v154 offset:33792
	ds_read_b128 v[214:217], v153 offset:32768
	ds_read_b128 v[218:221], v153 offset:33792
	global_load_lds_dwordx4 v[230:231], off
	s_or_b32 m0, s100, 0x6000
	v_lshl_add_u64 v[230:231], v[226:227], 0, s[44:45]
	global_load_lds_dwordx4 v[230:231], off
	s_waitcnt lgkmcnt(8)
	s_barrier
	s_waitcnt lgkmcnt(0)
	v_mfma_f32_16x16x32_bf16 v[128:131], v[190:193], v[174:177], v[128:131]
	v_mfma_f32_16x16x32_bf16 v[124:127], v[190:193], v[182:185], v[124:127]
	v_mfma_f32_16x16x32_bf16 v[120:123], v[198:201], v[174:177], v[120:123]
	v_mfma_f32_16x16x32_bf16 v[116:119], v[198:201], v[182:185], v[116:119]
	v_mfma_f32_16x16x32_bf16 v[112:115], v[206:209], v[174:177], v[112:115]
	v_mfma_f32_16x16x32_bf16 v[108:111], v[206:209], v[182:185], v[108:111]
	v_mfma_f32_16x16x32_bf16 v[104:107], v[214:217], v[174:177], v[104:107]
	v_mfma_f32_16x16x32_bf16 v[100:103], v[214:217], v[182:185], v[100:103]
	v_mfma_f32_16x16x32_bf16 v[128:131], v[194:197], v[178:181], v[128:131]
	v_mfma_f32_16x16x32_bf16 v[124:127], v[194:197], v[186:189], v[124:127]
	v_mfma_f32_16x16x32_bf16 v[120:123], v[202:205], v[178:181], v[120:123]
	v_mfma_f32_16x16x32_bf16 v[116:119], v[202:205], v[186:189], v[116:119]
	v_mfma_f32_16x16x32_bf16 v[112:115], v[210:213], v[178:181], v[112:115]
	v_mfma_f32_16x16x32_bf16 v[108:111], v[210:213], v[186:189], v[108:111]
	v_mfma_f32_16x16x32_bf16 v[104:107], v[218:221], v[178:181], v[104:107]
	v_mfma_f32_16x16x32_bf16 v[100:103], v[218:221], v[186:189], v[100:103]
	s_barrier
; #define LDA8(dst, b, h) _Pragma("unroll") for (int m = 0; m < 4; ++m) _Pragma("unroll") for (int k = 0; k < 2; ++k) \
;     dst[m][k] = *(const bf16x8*)((const char*)SA8(b, h) + lds_byte8(wr * 64 + m * 16 + fr, k * 32 + fq * 8))
; #define LDB8(dst, b, h) _Pragma("unroll") for (int n = 0; n < 2; ++n) _Pragma("unroll") for (int k = 0; k < 2; ++k) \
;     dst[n][k] = *(const bf16x8*)((const char*)SB8(b, h) + lds_byte8(wc * 32 + n * 16 + fr, k * 32 + fq * 8))
; #define WAIT_V8(n) asm volatile("s_waitcnt vmcnt(" #n ")" ::: "memory")
; #define WAIT_L8(n) asm volatile("s_waitcnt lgkmcnt(" #n ")" ::: "memory")
; #define BAR8 __builtin_amdgcn_s_barrier()
; #define SCHED8 __builtin_amdgcn_sched_barrier(0)
;     ...
;     LDB8(B1, 1, 1); STAGE8(SB8(1, 0), Bt, K, bcol, tt + 3);
;     BAR8; WAIT_L8(0); MMA8(0, 1, At, B1); BAR8;
;     LDA8(At, 1, 1); STAGE8(SA8(1, 0), A, lda, brow, tt + 3);
;     BAR8; WAIT_L8(0); MMA8(1, 0, At, B0); BAR8; SCHED8;
;     STAGE8(SB8(1, 1), Bt, K, bcol + 128, tt + 3);
;     WAIT_V8(6); BAR8; MMA8(1, 1, At, B1); BAR8;
	v_lshl_add_u64 v[250:251], v[228:229], 0, s[46:47]
	s_or_b32 m0, s100, 0x18000
	ds_read_b128 v[230:233], v158
	ds_read_b128 v[238:241], v158 offset:1024
	ds_read_b128 v[242:245], v158 offset:2048
	ds_read_b128 v[246:249], v158 offset:3072
	global_load_lds_dwordx4 v[250:251], off
	s_or_b32 m0, s100, 0x1a000
	v_lshl_add_u64 v[250:251], v[236:237], 0, s[46:47]
	global_load_lds_dwordx4 v[250:251], off
	s_barrier
	s_waitcnt lgkmcnt(0)
	v_mfma_f32_16x16x32_bf16 v[96:99], v[190:193], v[230:233], v[96:99]
	v_mfma_f32_16x16x32_bf16 v[92:95], v[190:193], v[242:245], v[92:95]
	v_mfma_f32_16x16x32_bf16 v[88:91], v[198:201], v[230:233], v[88:91]
	v_mfma_f32_16x16x32_bf16 v[84:87], v[198:201], v[242:245], v[84:87]
	v_mfma_f32_16x16x32_bf16 v[80:83], v[206:209], v[230:233], v[80:83]
	v_mfma_f32_16x16x32_bf16 v[76:79], v[206:209], v[242:245], v[76:79]
	v_mfma_f32_16x16x32_bf16 v[72:75], v[214:217], v[230:233], v[72:75]
	v_mfma_f32_16x16x32_bf16 v[68:71], v[214:217], v[242:245], v[68:71]
	v_mfma_f32_16x16x32_bf16 v[96:99], v[194:197], v[238:241], v[96:99]
	v_mfma_f32_16x16x32_bf16 v[92:95], v[194:197], v[246:249], v[92:95]
	v_mfma_f32_16x16x32_bf16 v[88:91], v[202:205], v[238:241], v[88:91]
	v_mfma_f32_16x16x32_bf16 v[84:87], v[202:205], v[246:249], v[84:87]
	v_mfma_f32_16x16x32_bf16 v[80:83], v[210:213], v[238:241], v[80:83]
	v_mfma_f32_16x16x32_bf16 v[76:79], v[210:213], v[246:249], v[76:79]
	v_mfma_f32_16x16x32_bf16 v[72:75], v[218:221], v[238:241], v[72:75]
	v_mfma_f32_16x16x32_bf16 v[68:71], v[218:221], v[246:249], v[68:71]
	v_lshl_add_u64 v[222:223], v[222:223], 0, s[48:49]
	s_or_b32 m0, s100, 0x8000
	s_barrier
	ds_read_b128 v[190:193], v156 offset:49152
	ds_read_b128 v[194:197], v156 offset:50176
	ds_read_b128 v[198:201], v155 offset:49152
	ds_read_b128 v[202:205], v155 offset:50176
	ds_read_b128 v[206:209], v154 offset:49152
	ds_read_b128 v[210:213], v154 offset:50176
	ds_read_b128 v[214:217], v153 offset:49152
	ds_read_b128 v[218:221], v153 offset:50176
	global_load_lds_dwordx4 v[222:223], off
	s_or_b32 m0, s100, 0xa000
	v_lshl_add_u64 v[222:223], v[226:227], 0, s[48:49]
	global_load_lds_dwordx4 v[222:223], off
	s_barrier
	s_waitcnt lgkmcnt(0)
	v_mfma_f32_16x16x32_bf16 v[64:67], v[190:193], v[174:177], v[64:67]
	v_mfma_f32_16x16x32_bf16 v[60:63], v[190:193], v[182:185], v[60:63]
	v_mfma_f32_16x16x32_bf16 v[56:59], v[198:201], v[174:177], v[56:59]
	v_mfma_f32_16x16x32_bf16 v[52:55], v[198:201], v[182:185], v[52:55]
	v_mfma_f32_16x16x32_bf16 v[48:51], v[206:209], v[174:177], v[48:51]
	v_mfma_f32_16x16x32_bf16 v[44:47], v[206:209], v[182:185], v[44:47]
	v_mfma_f32_16x16x32_bf16 v[40:43], v[214:217], v[174:177], v[40:43]
	v_mfma_f32_16x16x32_bf16 v[36:39], v[214:217], v[182:185], v[36:39]
	v_mfma_f32_16x16x32_bf16 v[64:67], v[194:197], v[178:181], v[64:67]
	v_mfma_f32_16x16x32_bf16 v[60:63], v[194:197], v[186:189], v[60:63]
	v_mfma_f32_16x16x32_bf16 v[56:59], v[202:205], v[178:181], v[56:59]
	v_mfma_f32_16x16x32_bf16 v[52:55], v[202:205], v[186:189], v[52:55]
	v_mfma_f32_16x16x32_bf16 v[48:51], v[210:213], v[178:181], v[48:51]
	v_mfma_f32_16x16x32_bf16 v[44:47], v[210:213], v[186:189], v[44:47]
	v_mfma_f32_16x16x32_bf16 v[40:43], v[218:221], v[178:181], v[40:43]
	v_mfma_f32_16x16x32_bf16 v[36:39], v[218:221], v[186:189], v[36:39]
	s_barrier
	s_or_b32 m0, s100, 0x1c000
	v_lshl_add_u64 v[174:175], v[228:229], 0, s[50:51]
	global_load_lds_dwordx4 v[174:175], off
	s_or_b32 m0, s100, 0x1e000
	v_lshl_add_u64 v[174:175], v[236:237], 0, s[50:51]
	global_load_lds_dwordx4 v[174:175], off
	s_waitcnt vmcnt(6)
	s_barrier
	v_mfma_f32_16x16x32_bf16 v[32:35], v[190:193], v[230:233], v[32:35]
	v_mfma_f32_16x16x32_bf16 v[28:31], v[190:193], v[242:245], v[28:31]
	v_mfma_f32_16x16x32_bf16 v[24:27], v[198:201], v[230:233], v[24:27]
	v_mfma_f32_16x16x32_bf16 v[20:23], v[198:201], v[242:245], v[20:23]
	v_mfma_f32_16x16x32_bf16 v[16:19], v[206:209], v[230:233], v[16:19]
	v_mfma_f32_16x16x32_bf16 v[12:15], v[206:209], v[242:245], v[12:15]
	v_mfma_f32_16x16x32_bf16 v[8:11], v[214:217], v[230:233], v[8:11]
	v_mfma_f32_16x16x32_bf16 v[4:7], v[214:217], v[242:245], v[4:7]
	v_mfma_f32_16x16x32_bf16 v[32:35], v[194:197], v[238:241], v[32:35]
	v_mfma_f32_16x16x32_bf16 v[28:31], v[194:197], v[246:249], v[28:31]
	v_mfma_f32_16x16x32_bf16 v[24:27], v[202:205], v[238:241], v[24:27]
	v_mfma_f32_16x16x32_bf16 v[20:23], v[202:205], v[246:249], v[20:23]
	v_mfma_f32_16x16x32_bf16 v[16:19], v[210:213], v[238:241], v[16:19]
	v_mfma_f32_16x16x32_bf16 v[12:15], v[210:213], v[246:249], v[12:15]
	v_mfma_f32_16x16x32_bf16 v[8:11], v[218:221], v[238:241], v[8:11]
	v_mfma_f32_16x16x32_bf16 v[4:7], v[218:221], v[246:249], v[4:7]
	s_add_i32 s29, s29, 2
	s_add_u32 s12, s12, 0x100
	s_addc_u32 s13, s13, 0
	s_cmp_lt_u32 s29, 12
	s_barrier
	s_cbranch_scc0 .Lpk_exit_2
; #define LDA8(dst, b, h) _Pragma("unroll") for (int m = 0; m < 4; ++m) _Pragma("unroll") for (int k = 0; k < 2; ++k) \
;     dst[m][k] = *(const bf16x8*)((const char*)SA8(b, h) + lds_byte8(wr * 64 + m * 16 + fr, k * 32 + fq * 8))
; #define LDB8(dst, b, h) _Pragma("unroll") for (int n = 0; n < 2; ++n) _Pragma("unroll") for (int k = 0; k < 2; ++k) \
;     dst[n][k] = *(const bf16x8*)((const char*)SB8(b, h) + lds_byte8(wc * 32 + n * 16 + fr, k * 32 + fq * 8))
; #define WAIT_V8(n) asm volatile("s_waitcnt vmcnt(" #n ")" ::: "memory")
; #define WAIT_L8(n) asm volatile("s_waitcnt lgkmcnt(" #n ")" ::: "memory")
; #define BAR8 __builtin_amdgcn_s_barrier()
; #define SCHED8 __builtin_amdgcn_sched_barrier(0)
;     ...
;   for (int tt = 0; tt < nt - 2; tt += 2) {
;     LDB8(B0, 0, 0); SCHED8; LDA8(At, 0, 0); STAGE8(SA8(1, 1), A, lda, brow + 128, tt + 1);
;     WAIT_L8(8); BAR8; WAIT_L8(0); MMA8(0, 0, At, B0); BAR8; SCHED8;
;     LDB8(B1, 0, 1); STAGE8(SB8(0, 0), Bt, K, bcol, tt + 2);
;     BAR8; WAIT_L8(0); MMA8(0, 1, At, B1); BAR8;
;     LDA8(At, 0, 1); STAGE8(SA8(0, 0), A, lda, brow, tt + 2);
;     BAR8; WAIT_L8(0); MMA8(1, 0, At, B0); BAR8; SCHED8;
;     STAGE8(SB8(0, 1), Bt, K, bcol + 128, tt + 2);
;     WAIT_V8(6); BAR8; MMA8(1, 1, At, B1); BAR8;
.LBB0_908:
	ds_read_b128 v[174:177], v171
	ds_read_b128 v[178:181], v171 offset:1024
	ds_read_b128 v[182:185], v171 offset:2048
	ds_read_b128 v[186:189], v171 offset:3072
	v_lshl_add_u64 v[222:223], v[142:143], 0, s[12:13]
	v_lshl_add_u64 v[226:227], v[222:223], 0, s[36:37]
	s_or_b32 m0, s100, 0xc000
	ds_read_b128 v[190:193], v156
	ds_read_b128 v[194:197], v156 offset:1024
	ds_read_b128 v[198:201], v155
	ds_read_b128 v[202:205], v155 offset:1024
	ds_read_b128 v[206:209], v154
	ds_read_b128 v[210:213], v154 offset:1024
	ds_read_b128 v[214:217], v153
	ds_read_b128 v[218:221], v153 offset:1024
	global_load_lds_dwordx4 v[226:227], off
	v_lshl_add_u64 v[226:227], v[144:145], 0, s[12:13]
	s_or_b32 m0, s100, 0xe000
	v_lshl_add_u64 v[228:229], v[226:227], 0, s[36:37]
	global_load_lds_dwordx4 v[228:229], off
	s_waitcnt lgkmcnt(8)
	s_barrier
	s_waitcnt lgkmcnt(0)
	v_mfma_f32_16x16x32_bf16 v[128:131], v[190:193], v[174:177], v[128:131]
	v_mfma_f32_16x16x32_bf16 v[124:127], v[190:193], v[182:185], v[124:127]
	v_mfma_f32_16x16x32_bf16 v[120:123], v[198:201], v[174:177], v[120:123]
	v_mfma_f32_16x16x32_bf16 v[116:119], v[198:201], v[182:185], v[116:119]
	v_mfma_f32_16x16x32_bf16 v[112:115], v[206:209], v[174:177], v[112:115]
	v_mfma_f32_16x16x32_bf16 v[108:111], v[206:209], v[182:185], v[108:111]
	v_mfma_f32_16x16x32_bf16 v[104:107], v[214:217], v[174:177], v[104:107]
	v_mfma_f32_16x16x32_bf16 v[100:103], v[214:217], v[182:185], v[100:103]
	v_mfma_f32_16x16x32_bf16 v[128:131], v[194:197], v[178:181], v[128:131]
	v_mfma_f32_16x16x32_bf16 v[124:127], v[194:197], v[186:189], v[124:127]
	v_mfma_f32_16x16x32_bf16 v[120:123], v[202:205], v[178:181], v[120:123]
	v_mfma_f32_16x16x32_bf16 v[116:119], v[202:205], v[186:189], v[116:119]
	v_mfma_f32_16x16x32_bf16 v[112:115], v[210:213], v[178:181], v[112:115]
	v_mfma_f32_16x16x32_bf16 v[108:111], v[210:213], v[186:189], v[108:111]
	v_mfma_f32_16x16x32_bf16 v[104:107], v[218:221], v[178:181], v[104:107]
	v_mfma_f32_16x16x32_bf16 v[100:103], v[218:221], v[186:189], v[100:103]
	s_barrier
	v_lshl_add_u64 v[228:229], v[138:139], 0, s[12:13]
	v_lshl_add_u64 v[236:237], v[228:229], 0, s[38:39]
	s_or_b32 m0, s100, 0x10000
	ds_read_b128 v[230:233], v167
	ds_read_b128 v[238:241], v167 offset:1024
	ds_read_b128 v[242:245], v167 offset:2048
	ds_read_b128 v[246:249], v167 offset:3072
	global_load_lds_dwordx4 v[236:237], off
	v_lshl_add_u64 v[236:237], v[140:141], 0, s[12:13]
	s_or_b32 m0, s100, 0x12000
	v_lshl_add_u64 v[250:251], v[236:237], 0, s[38:39]
	global_load_lds_dwordx4 v[250:251], off
	s_barrier
	s_waitcnt lgkmcnt(0)
	v_mfma_f32_16x16x32_bf16 v[96:99], v[190:193], v[230:233], v[96:99]
	v_mfma_f32_16x16x32_bf16 v[92:95], v[190:193], v[242:245], v[92:95]
	v_mfma_f32_16x16x32_bf16 v[88:91], v[198:201], v[230:233], v[88:91]
	v_mfma_f32_16x16x32_bf16 v[84:87], v[198:201], v[242:245], v[84:87]
	v_mfma_f32_16x16x32_bf16 v[80:83], v[206:209], v[230:233], v[80:83]
	v_mfma_f32_16x16x32_bf16 v[76:79], v[206:209], v[242:245], v[76:79]
	v_mfma_f32_16x16x32_bf16 v[72:75], v[214:217], v[230:233], v[72:75]
	v_mfma_f32_16x16x32_bf16 v[68:71], v[214:217], v[242:245], v[68:71]
	v_mfma_f32_16x16x32_bf16 v[96:99], v[194:197], v[238:241], v[96:99]
	v_mfma_f32_16x16x32_bf16 v[92:95], v[194:197], v[246:249], v[92:95]
	v_mfma_f32_16x16x32_bf16 v[88:91], v[202:205], v[238:241], v[88:91]
	v_mfma_f32_16x16x32_bf16 v[84:87], v[202:205], v[246:249], v[84:87]
	v_mfma_f32_16x16x32_bf16 v[80:83], v[210:213], v[238:241], v[80:83]
	v_mfma_f32_16x16x32_bf16 v[76:79], v[210:213], v[246:249], v[76:79]
	v_mfma_f32_16x16x32_bf16 v[72:75], v[218:221], v[238:241], v[72:75]
	v_mfma_f32_16x16x32_bf16 v[68:71], v[218:221], v[246:249], v[68:71]
	v_lshl_add_u64 v[250:251], v[222:223], 0, s[40:41]
	s_mov_b32 m0, s100
	s_barrier
	ds_read_b128 v[190:193], v156 offset:16384
	ds_read_b128 v[194:197], v156 offset:17408
	ds_read_b128 v[198:201], v155 offset:16384
	ds_read_b128 v[202:205], v155 offset:17408
	ds_read_b128 v[206:209], v154 offset:16384
	ds_read_b128 v[210:213], v154 offset:17408
	ds_read_b128 v[214:217], v153 offset:16384
	ds_read_b128 v[218:221], v153 offset:17408
	global_load_lds_dwordx4 v[250:251], off
	s_or_b32 m0, s100, 0x2000
	v_lshl_add_u64 v[250:251], v[226:227], 0, s[40:41]
	global_load_lds_dwordx4 v[250:251], off
	s_barrier
	s_waitcnt lgkmcnt(0)
	v_mfma_f32_16x16x32_bf16 v[64:67], v[190:193], v[174:177], v[64:67]
	v_mfma_f32_16x16x32_bf16 v[60:63], v[190:193], v[182:185], v[60:63]
	v_mfma_f32_16x16x32_bf16 v[56:59], v[198:201], v[174:177], v[56:59]
	v_mfma_f32_16x16x32_bf16 v[52:55], v[198:201], v[182:185], v[52:55]
	v_mfma_f32_16x16x32_bf16 v[48:51], v[206:209], v[174:177], v[48:51]
	v_mfma_f32_16x16x32_bf16 v[44:47], v[206:209], v[182:185], v[44:47]
	v_mfma_f32_16x16x32_bf16 v[40:43], v[214:217], v[174:177], v[40:43]
	v_mfma_f32_16x16x32_bf16 v[36:39], v[214:217], v[182:185], v[36:39]
	v_mfma_f32_16x16x32_bf16 v[64:67], v[194:197], v[178:181], v[64:67]
	v_mfma_f32_16x16x32_bf16 v[60:63], v[194:197], v[186:189], v[60:63]
	v_mfma_f32_16x16x32_bf16 v[56:59], v[202:205], v[178:181], v[56:59]
	v_mfma_f32_16x16x32_bf16 v[52:55], v[202:205], v[186:189], v[52:55]
	v_mfma_f32_16x16x32_bf16 v[48:51], v[210:213], v[178:181], v[48:51]
	v_mfma_f32_16x16x32_bf16 v[44:47], v[210:213], v[186:189], v[44:47]
	v_mfma_f32_16x16x32_bf16 v[40:43], v[218:221], v[178:181], v[40:43]
	v_mfma_f32_16x16x32_bf16 v[36:39], v[218:221], v[186:189], v[36:39]
	s_barrier
	s_or_b32 m0, s100, 0x14000
	v_lshl_add_u64 v[174:175], v[228:229], 0, s[42:43]
	global_load_lds_dwordx4 v[174:175], off
	s_or_b32 m0, s100, 0x16000
	v_lshl_add_u64 v[174:175], v[236:237], 0, s[42:43]
	global_load_lds_dwordx4 v[174:175], off
	s_waitcnt vmcnt(6)
	s_barrier
; #define LDA8(dst, b, h) _Pragma("unroll") for (int m = 0; m < 4; ++m) _Pragma("unroll") for (int k = 0; k < 2; ++k) \
;     dst[m][k] = *(const bf16x8*)((const char*)SA8(b, h) + lds_byte8(wr * 64 + m * 16 + fr, k * 32 + fq * 8))
; #define LDB8(dst, b, h) _Pragma("unroll") for (int n = 0; n < 2; ++n) _Pragma("unroll") for (int k = 0; k < 2; ++k) \
;     dst[n][k] = *(const bf16x8*)((const char*)SB8(b, h) + lds_byte8(wc * 32 + n * 16 + fr, k * 32 + fq * 8))
; #define WAIT_V8(n) asm volatile("s_waitcnt vmcnt(" #n ")" ::: "memory")
; #define WAIT_L8(n) asm volatile("s_waitcnt lgkmcnt(" #n ")" ::: "memory")
; #define BAR8 __builtin_amdgcn_s_barrier()
; #define SCHED8 __builtin_amdgcn_sched_barrier(0)
;     ...
;     WAIT_V8(6); BAR8; MMA8(1, 1, At, B1); BAR8;
;     LDB8(B0, 1, 0); SCHED8; LDA8(At, 1, 0); STAGE8(SA8(0, 1), A, lda, brow + 128, tt + 2);
;     WAIT_L8(8); BAR8; WAIT_L8(0); MMA8(0, 0, At, B0); BAR8; SCHED8;
;     LDB8(B1, 1, 1); STAGE8(SB8(1, 0), Bt, K, bcol, tt + 3);
;     BAR8; WAIT_L8(0); MMA8(0, 1, At, B1); BAR8;
;     LDA8(At, 1, 1); STAGE8(SA8(1, 0), A, lda, brow, tt + 3);
;     BAR8; WAIT_L8(0); MMA8(1, 0, At, B0); BAR8; SCHED8;
	v_mfma_f32_16x16x32_bf16 v[32:35], v[190:193], v[230:233], v[32:35]
	v_mfma_f32_16x16x32_bf16 v[28:31], v[190:193], v[242:245], v[28:31]
	v_mfma_f32_16x16x32_bf16 v[24:27], v[198:201], v[230:233], v[24:27]
	v_mfma_f32_16x16x32_bf16 v[20:23], v[198:201], v[242:245], v[20:23]
	v_mfma_f32_16x16x32_bf16 v[16:19], v[206:209], v[230:233], v[16:19]
	v_mfma_f32_16x16x32_bf16 v[12:15], v[206:209], v[242:245], v[12:15]
	v_mfma_f32_16x16x32_bf16 v[8:11], v[214:217], v[230:233], v[8:11]
	v_mfma_f32_16x16x32_bf16 v[4:7], v[214:217], v[242:245], v[4:7]
	v_mfma_f32_16x16x32_bf16 v[32:35], v[194:197], v[238:241], v[32:35]
	v_mfma_f32_16x16x32_bf16 v[28:31], v[194:197], v[246:249], v[28:31]
	v_mfma_f32_16x16x32_bf16 v[24:27], v[202:205], v[238:241], v[24:27]
	v_mfma_f32_16x16x32_bf16 v[20:23], v[202:205], v[246:249], v[20:23]
	v_mfma_f32_16x16x32_bf16 v[16:19], v[210:213], v[238:241], v[16:19]
	v_mfma_f32_16x16x32_bf16 v[12:15], v[210:213], v[246:249], v[12:15]
	v_mfma_f32_16x16x32_bf16 v[8:11], v[218:221], v[238:241], v[8:11]
	v_mfma_f32_16x16x32_bf16 v[4:7], v[218:221], v[246:249], v[4:7]
	s_barrier
	ds_read_b128 v[174:177], v160
	ds_read_b128 v[178:181], v160 offset:1024
	ds_read_b128 v[182:185], v160 offset:2048
	ds_read_b128 v[186:189], v160 offset:3072
	v_lshl_add_u64 v[230:231], v[222:223], 0, s[44:45]
	s_or_b32 m0, s100, 0x4000
	ds_read_b128 v[190:193], v156 offset:32768
	ds_read_b128 v[194:197], v156 offset:33792
	ds_read_b128 v[198:201], v155 offset:32768
	ds_read_b128 v[202:205], v155 offset:33792
	ds_read_b128 v[206:209], v154 offset:32768
	ds_read_b128 v[210:213], v154 offset:33792
	ds_read_b128 v[214:217], v153 offset:32768
	ds_read_b128 v[218:221], v153 offset:33792
	global_load_lds_dwordx4 v[230:231], off
	s_or_b32 m0, s100, 0x6000
	v_lshl_add_u64 v[230:231], v[226:227], 0, s[44:45]
	global_load_lds_dwordx4 v[230:231], off
	s_waitcnt lgkmcnt(8)
	s_barrier
	s_waitcnt lgkmcnt(0)
	v_mfma_f32_16x16x32_bf16 v[128:131], v[190:193], v[174:177], v[128:131]
	v_mfma_f32_16x16x32_bf16 v[124:127], v[190:193], v[182:185], v[124:127]
	v_mfma_f32_16x16x32_bf16 v[120:123], v[198:201], v[174:177], v[120:123]
	v_mfma_f32_16x16x32_bf16 v[116:119], v[198:201], v[182:185], v[116:119]
	v_mfma_f32_16x16x32_bf16 v[112:115], v[206:209], v[174:177], v[112:115]
	v_mfma_f32_16x16x32_bf16 v[108:111], v[206:209], v[182:185], v[108:111]
	v_mfma_f32_16x16x32_bf16 v[104:107], v[214:217], v[174:177], v[104:107]
	v_mfma_f32_16x16x32_bf16 v[100:103], v[214:217], v[182:185], v[100:103]
	v_mfma_f32_16x16x32_bf16 v[128:131], v[194:197], v[178:181], v[128:131]
	v_mfma_f32_16x16x32_bf16 v[124:127], v[194:197], v[186:189], v[124:127]
	v_mfma_f32_16x16x32_bf16 v[120:123], v[202:205], v[178:181], v[120:123]
	v_mfma_f32_16x16x32_bf16 v[116:119], v[202:205], v[186:189], v[116:119]
	v_mfma_f32_16x16x32_bf16 v[112:115], v[210:213], v[178:181], v[112:115]
	v_mfma_f32_16x16x32_bf16 v[108:111], v[210:213], v[186:189], v[108:111]
	v_mfma_f32_16x16x32_bf16 v[104:107], v[218:221], v[178:181], v[104:107]
	v_mfma_f32_16x16x32_bf16 v[100:103], v[218:221], v[186:189], v[100:103]
	s_barrier
	v_lshl_add_u64 v[250:251], v[228:229], 0, s[46:47]
	s_or_b32 m0, s100, 0x18000
	ds_read_b128 v[230:233], v158
	ds_read_b128 v[238:241], v158 offset:1024
	ds_read_b128 v[242:245], v158 offset:2048
	ds_read_b128 v[246:249], v158 offset:3072
	global_load_lds_dwordx4 v[250:251], off
	s_or_b32 m0, s100, 0x1a000
	v_lshl_add_u64 v[250:251], v[236:237], 0, s[46:47]
	global_load_lds_dwordx4 v[250:251], off
	s_barrier
	s_waitcnt lgkmcnt(0)
	v_mfma_f32_16x16x32_bf16 v[96:99], v[190:193], v[230:233], v[96:99]
	v_mfma_f32_16x16x32_bf16 v[92:95], v[190:193], v[242:245], v[92:95]
	v_mfma_f32_16x16x32_bf16 v[88:91], v[198:201], v[230:233], v[88:91]
	v_mfma_f32_16x16x32_bf16 v[84:87], v[198:201], v[242:245], v[84:87]
	v_mfma_f32_16x16x32_bf16 v[80:83], v[206:209], v[230:233], v[80:83]
	v_mfma_f32_16x16x32_bf16 v[76:79], v[206:209], v[242:245], v[76:79]
	v_mfma_f32_16x16x32_bf16 v[72:75], v[214:217], v[230:233], v[72:75]
	v_mfma_f32_16x16x32_bf16 v[68:71], v[214:217], v[242:245], v[68:71]
	v_mfma_f32_16x16x32_bf16 v[96:99], v[194:197], v[238:241], v[96:99]
	v_mfma_f32_16x16x32_bf16 v[92:95], v[194:197], v[246:249], v[92:95]
	v_mfma_f32_16x16x32_bf16 v[88:91], v[202:205], v[238:241], v[88:91]
	v_mfma_f32_16x16x32_bf16 v[84:87], v[202:205], v[246:249], v[84:87]
	v_mfma_f32_16x16x32_bf16 v[80:83], v[210:213], v[238:241], v[80:83]
	v_mfma_f32_16x16x32_bf16 v[76:79], v[210:213], v[246:249], v[76:79]
	v_mfma_f32_16x16x32_bf16 v[72:75], v[218:221], v[238:241], v[72:75]
	v_mfma_f32_16x16x32_bf16 v[68:71], v[218:221], v[246:249], v[68:71]
	v_lshl_add_u64 v[222:223], v[222:223], 0, s[48:49]
	s_or_b32 m0, s100, 0x8000
	s_barrier
	ds_read_b128 v[190:193], v156 offset:49152
	ds_read_b128 v[194:197], v156 offset:50176
	ds_read_b128 v[198:201], v155 offset:49152
	ds_read_b128 v[202:205], v155 offset:50176
	ds_read_b128 v[206:209], v154 offset:49152
	ds_read_b128 v[210:213], v154 offset:50176
	ds_read_b128 v[214:217], v153 offset:49152
	ds_read_b128 v[218:221], v153 offset:50176
	global_load_lds_dwordx4 v[222:223], off
	s_or_b32 m0, s100, 0xa000
	v_lshl_add_u64 v[222:223], v[226:227], 0, s[48:49]
	global_load_lds_dwordx4 v[222:223], off
	s_barrier
; #define LDA8(dst, b, h) _Pragma("unroll") for (int m = 0; m < 4; ++m) _Pragma("unroll") for (int k = 0; k < 2; ++k) \
;     dst[m][k] = *(const bf16x8*)((const char*)SA8(b, h) + lds_byte8(wr * 64 + m * 16 + fr, k * 32 + fq * 8))
; #define LDB8(dst, b, h) _Pragma("unroll") for (int n = 0; n < 2; ++n) _Pragma("unroll") for (int k = 0; k < 2; ++k) \
;     dst[n][k] = *(const bf16x8*)((const char*)SB8(b, h) + lds_byte8(wc * 32 + n * 16 + fr, k * 32 + fq * 8))
; #define WAIT_V8(n) asm volatile("s_waitcnt vmcnt(" #n ")" ::: "memory")
; #define WAIT_L8(n) asm volatile("s_waitcnt lgkmcnt(" #n ")" ::: "memory")
; #define BAR8 __builtin_amdgcn_s_barrier()
; #define SCHED8 __builtin_amdgcn_sched_barrier(0)
;     ...
;     BAR8; WAIT_L8(0); MMA8(1, 0, At, B0); BAR8; SCHED8;
;     STAGE8(SB8(1, 1), Bt, K, bcol + 128, tt + 3);
;     WAIT_V8(6); BAR8; MMA8(1, 1, At, B1); BAR8;
;   }
;   { LDB8(B0, 0, 0); LDA8(At, 0, 0); STAGE8(SA8(1, 1), A, lda, brow + 128, nt - 1);
;     BAR8; WAIT_L8(0); MMA8(0, 0, At, B0); BAR8;
;     LDB8(B1, 0, 1); BAR8; WAIT_L8(0); MMA8(0, 1, At, B1); BAR8;
	s_waitcnt lgkmcnt(0)
	v_mfma_f32_16x16x32_bf16 v[64:67], v[190:193], v[174:177], v[64:67]
	v_mfma_f32_16x16x32_bf16 v[60:63], v[190:193], v[182:185], v[60:63]
	v_mfma_f32_16x16x32_bf16 v[56:59], v[198:201], v[174:177], v[56:59]
	v_mfma_f32_16x16x32_bf16 v[52:55], v[198:201], v[182:185], v[52:55]
	v_mfma_f32_16x16x32_bf16 v[48:51], v[206:209], v[174:177], v[48:51]
	v_mfma_f32_16x16x32_bf16 v[44:47], v[206:209], v[182:185], v[44:47]
	v_mfma_f32_16x16x32_bf16 v[40:43], v[214:217], v[174:177], v[40:43]
	v_mfma_f32_16x16x32_bf16 v[36:39], v[214:217], v[182:185], v[36:39]
	v_mfma_f32_16x16x32_bf16 v[64:67], v[194:197], v[178:181], v[64:67]
	v_mfma_f32_16x16x32_bf16 v[60:63], v[194:197], v[186:189], v[60:63]
	v_mfma_f32_16x16x32_bf16 v[56:59], v[202:205], v[178:181], v[56:59]
	v_mfma_f32_16x16x32_bf16 v[52:55], v[202:205], v[186:189], v[52:55]
	v_mfma_f32_16x16x32_bf16 v[48:51], v[210:213], v[178:181], v[48:51]
	v_mfma_f32_16x16x32_bf16 v[44:47], v[210:213], v[186:189], v[44:47]
	v_mfma_f32_16x16x32_bf16 v[40:43], v[218:221], v[178:181], v[40:43]
	v_mfma_f32_16x16x32_bf16 v[36:39], v[218:221], v[186:189], v[36:39]
	s_barrier
	s_or_b32 m0, s100, 0x1c000
	v_lshl_add_u64 v[174:175], v[228:229], 0, s[50:51]
	global_load_lds_dwordx4 v[174:175], off
	s_or_b32 m0, s100, 0x1e000
	v_lshl_add_u64 v[174:175], v[236:237], 0, s[50:51]
	global_load_lds_dwordx4 v[174:175], off
	s_waitcnt vmcnt(6)
	s_barrier
	v_mfma_f32_16x16x32_bf16 v[32:35], v[190:193], v[230:233], v[32:35]
	v_mfma_f32_16x16x32_bf16 v[28:31], v[190:193], v[242:245], v[28:31]
	v_mfma_f32_16x16x32_bf16 v[24:27], v[198:201], v[230:233], v[24:27]
	v_mfma_f32_16x16x32_bf16 v[20:23], v[198:201], v[242:245], v[20:23]
	v_mfma_f32_16x16x32_bf16 v[16:19], v[206:209], v[230:233], v[16:19]
	v_mfma_f32_16x16x32_bf16 v[12:15], v[206:209], v[242:245], v[12:15]
	v_mfma_f32_16x16x32_bf16 v[8:11], v[214:217], v[230:233], v[8:11]
	v_mfma_f32_16x16x32_bf16 v[4:7], v[214:217], v[242:245], v[4:7]
	v_mfma_f32_16x16x32_bf16 v[32:35], v[194:197], v[238:241], v[32:35]
	v_mfma_f32_16x16x32_bf16 v[28:31], v[194:197], v[246:249], v[28:31]
	v_mfma_f32_16x16x32_bf16 v[24:27], v[202:205], v[238:241], v[24:27]
	v_mfma_f32_16x16x32_bf16 v[20:23], v[202:205], v[246:249], v[20:23]
	v_mfma_f32_16x16x32_bf16 v[16:19], v[210:213], v[238:241], v[16:19]
	v_mfma_f32_16x16x32_bf16 v[12:15], v[210:213], v[246:249], v[12:15]
	v_mfma_f32_16x16x32_bf16 v[8:11], v[218:221], v[238:241], v[8:11]
	v_mfma_f32_16x16x32_bf16 v[4:7], v[218:221], v[246:249], v[4:7]
	s_add_i32 s29, s29, 2
	s_add_u32 s12, s12, 0x100
	s_addc_u32 s13, s13, 0
	s_cmp_lt_u32 s29, 12
	s_barrier
	s_cbranch_scc1 .LBB0_908
.Lpk_exit_2:
	s_add_u32 s2, s2, s27
	s_addc_u32 s3, s3, 0
	s_add_u32 s2, s2, 0x6000780
	s_addc_u32 s3, s3, 0
	v_lshl_add_u64 v[136:137], v[136:137], 1, s[2:3]
	v_lshl_add_u64 v[0:1], v[0:1], 1, v[136:137]
	s_or_b32 m0, s100, 0xc000
	ds_read_b128 v[138:141], v171
	ds_read_b128 v[142:145], v171 offset:1024
	ds_read_b128 v[162:165], v171 offset:2048
	ds_read_b128 v[168:171], v171 offset:3072
	ds_read_b128 v[174:177], v156
	ds_read_b128 v[178:181], v156 offset:1024
	ds_read_b128 v[182:185], v155
	ds_read_b128 v[186:189], v155 offset:1024
	ds_read_b128 v[190:193], v154
	ds_read_b128 v[194:197], v154 offset:1024
	ds_read_b128 v[198:201], v153
	ds_read_b128 v[202:205], v153 offset:1024
	global_load_lds_dwordx4 v[0:1], off
	v_lshl_add_u64 v[0:1], v[134:135], 1, s[2:3]
	s_or_b32 m0, s100, 0xe000
	v_lshl_add_u64 v[0:1], v[132:133], 1, v[0:1]
	global_load_lds_dwordx4 v[0:1], off
	s_barrier
	s_waitcnt lgkmcnt(0)
	v_mfma_f32_16x16x32_bf16 v[128:131], v[174:177], v[138:141], v[128:131]
	v_mfma_f32_16x16x32_bf16 v[124:127], v[174:177], v[162:165], v[124:127]
	v_mfma_f32_16x16x32_bf16 v[120:123], v[182:185], v[138:141], v[120:123]
	v_mfma_f32_16x16x32_bf16 v[112:115], v[190:193], v[138:141], v[112:115]
	v_mfma_f32_16x16x32_bf16 v[128:131], v[178:181], v[142:145], v[128:131]
	v_mfma_f32_16x16x32_bf16 v[124:127], v[178:181], v[168:171], v[124:127]
	v_mfma_f32_16x16x32_bf16 v[120:123], v[186:189], v[142:145], v[120:123]
	v_mfma_f32_16x16x32_bf16 v[116:119], v[182:185], v[162:165], v[116:119]
	v_mfma_f32_16x16x32_bf16 v[112:115], v[194:197], v[142:145], v[112:115]
	v_mfma_f32_16x16x32_bf16 v[108:111], v[190:193], v[162:165], v[108:111]
	v_mfma_f32_16x16x32_bf16 v[104:107], v[198:201], v[138:141], v[104:107]
	v_mfma_f32_16x16x32_bf16 v[100:103], v[198:201], v[162:165], v[100:103]
	v_mfma_f32_16x16x32_bf16 v[132:135], v[186:189], v[168:171], v[116:119]
	v_mfma_f32_16x16x32_bf16 v[206:209], v[194:197], v[168:171], v[108:111]
	v_mfma_f32_16x16x32_bf16 v[210:213], v[202:205], v[142:145], v[104:107]
	v_mfma_f32_16x16x32_bf16 v[214:217], v[202:205], v[168:171], v[100:103]
	s_barrier
	s_nop 1
	ds_read_b128 v[100:103], v167
	ds_read_b128 v[104:107], v167 offset:1024
	ds_read_b128 v[108:111], v167 offset:2048
	ds_read_b128 v[116:119], v167 offset:3072
	s_barrier
	s_waitcnt lgkmcnt(0)
	v_mfma_f32_16x16x32_bf16 v[80:83], v[190:193], v[100:103], v[80:83]
	v_mfma_f32_16x16x32_bf16 v[76:79], v[190:193], v[108:111], v[76:79]
	v_mfma_f32_16x16x32_bf16 v[72:75], v[198:201], v[100:103], v[72:75]
	v_mfma_f32_16x16x32_bf16 v[68:71], v[198:201], v[108:111], v[68:71]
	v_mfma_f32_16x16x32_bf16 v[96:99], v[174:177], v[100:103], v[96:99]
	v_mfma_f32_16x16x32_bf16 v[92:95], v[174:177], v[108:111], v[92:95]
	v_mfma_f32_16x16x32_bf16 v[88:91], v[182:185], v[100:103], v[88:91]
	v_mfma_f32_16x16x32_bf16 v[84:87], v[182:185], v[108:111], v[84:87]
	v_mfma_f32_16x16x32_bf16 v[80:83], v[194:197], v[104:107], v[80:83]
	v_mfma_f32_16x16x32_bf16 v[76:79], v[194:197], v[116:119], v[76:79]
	v_mfma_f32_16x16x32_bf16 v[72:75], v[202:205], v[104:107], v[72:75]
	v_mfma_f32_16x16x32_bf16 v[68:71], v[202:205], v[116:119], v[68:71]
	v_mfma_f32_16x16x32_bf16 v[218:221], v[178:181], v[104:107], v[96:99]
	v_mfma_f32_16x16x32_bf16 v[172:175], v[178:181], v[116:119], v[92:95]
	v_mfma_f32_16x16x32_bf16 v[176:179], v[186:189], v[104:107], v[88:91]
	v_mfma_f32_16x16x32_bf16 v[180:183], v[186:189], v[116:119], v[84:87]
	s_barrier
; #define LDA8(dst, b, h) _Pragma("unroll") for (int m = 0; m < 4; ++m) _Pragma("unroll") for (int k = 0; k < 2; ++k) \
;     dst[m][k] = *(const bf16x8*)((const char*)SA8(b, h) + lds_byte8(wr * 64 + m * 16 + fr, k * 32 + fq * 8))
; #define LDB8(dst, b, h) _Pragma("unroll") for (int n = 0; n < 2; ++n) _Pragma("unroll") for (int k = 0; k < 2; ++k) \
;     dst[n][k] = *(const bf16x8*)((const char*)SB8(b, h) + lds_byte8(wc * 32 + n * 16 + fr, k * 32 + fq * 8))
; #define WAIT_V8(n) asm volatile("s_waitcnt vmcnt(" #n ")" ::: "memory")
; #define WAIT_L8(n) asm volatile("s_waitcnt lgkmcnt(" #n ")" ::: "memory")
; #define BAR8 __builtin_amdgcn_s_barrier()
;     ...
;     LDA8(At, 0, 1); WAIT_V8(4); BAR8; WAIT_L8(0); MMA8(1, 0, At, B0); MMA8(1, 1, At, B1); BAR8; }
;   { LDB8(B0, 1, 0); LDA8(At, 1, 0); WAIT_V8(2); BAR8; WAIT_L8(0); MMA8(0, 0, At, B0); BAR8;
	s_nop 0
	ds_read_b128 v[84:87], v156 offset:16384
	ds_read_b128 v[88:91], v156 offset:17408
	ds_read_b128 v[92:95], v155 offset:16384
	ds_read_b128 v[96:99], v155 offset:17408
	ds_read_b128 v[184:187], v154 offset:16384
	ds_read_b128 v[188:191], v154 offset:17408
	ds_read_b128 v[192:195], v153 offset:16384
	ds_read_b128 v[196:199], v153 offset:17408
	s_waitcnt vmcnt(4)
	s_barrier
	s_waitcnt lgkmcnt(0)
	v_mfma_f32_16x16x32_bf16 v[64:67], v[84:87], v[138:141], v[64:67]
	v_mfma_f32_16x16x32_bf16 v[60:63], v[84:87], v[162:165], v[60:63]
	v_mfma_f32_16x16x32_bf16 v[56:59], v[92:95], v[138:141], v[56:59]
	v_mfma_f32_16x16x32_bf16 v[52:55], v[92:95], v[162:165], v[52:55]
	v_mfma_f32_16x16x32_bf16 v[48:51], v[184:187], v[138:141], v[48:51]
	v_mfma_f32_16x16x32_bf16 v[44:47], v[184:187], v[162:165], v[44:47]
	v_mfma_f32_16x16x32_bf16 v[40:43], v[192:195], v[138:141], v[40:43]
	v_mfma_f32_16x16x32_bf16 v[36:39], v[192:195], v[162:165], v[36:39]
	v_mfma_f32_16x16x32_bf16 v[64:67], v[88:91], v[142:145], v[64:67]
	v_mfma_f32_16x16x32_bf16 v[60:63], v[88:91], v[168:171], v[60:63]
	v_mfma_f32_16x16x32_bf16 v[56:59], v[96:99], v[142:145], v[56:59]
	v_mfma_f32_16x16x32_bf16 v[52:55], v[96:99], v[168:171], v[52:55]
	v_mfma_f32_16x16x32_bf16 v[48:51], v[188:191], v[142:145], v[48:51]
	v_mfma_f32_16x16x32_bf16 v[44:47], v[188:191], v[168:171], v[44:47]
	v_mfma_f32_16x16x32_bf16 v[40:43], v[196:199], v[142:145], v[40:43]
	v_mfma_f32_16x16x32_bf16 v[36:39], v[196:199], v[168:171], v[36:39]
	v_mfma_f32_16x16x32_bf16 v[32:35], v[84:87], v[100:103], v[32:35]
	v_mfma_f32_16x16x32_bf16 v[28:31], v[84:87], v[108:111], v[28:31]
	v_mfma_f32_16x16x32_bf16 v[24:27], v[92:95], v[100:103], v[24:27]
	v_mfma_f32_16x16x32_bf16 v[20:23], v[92:95], v[108:111], v[20:23]
	v_mfma_f32_16x16x32_bf16 v[16:19], v[184:187], v[100:103], v[16:19]
	v_mfma_f32_16x16x32_bf16 v[12:15], v[184:187], v[108:111], v[12:15]
	v_mfma_f32_16x16x32_bf16 v[8:11], v[192:195], v[100:103], v[8:11]
	v_mfma_f32_16x16x32_bf16 v[4:7], v[192:195], v[108:111], v[4:7]
	v_mfma_f32_16x16x32_bf16 v[136:139], v[88:91], v[104:107], v[32:35]
	v_mfma_f32_16x16x32_bf16 v[140:143], v[88:91], v[116:119], v[28:31]
	v_mfma_f32_16x16x32_bf16 v[162:165], v[96:99], v[104:107], v[24:27]
	v_mfma_f32_16x16x32_bf16 v[166:169], v[96:99], v[116:119], v[20:23]
	v_mfma_f32_16x16x32_bf16 v[200:203], v[188:191], v[104:107], v[16:19]
	v_mfma_f32_16x16x32_bf16 v[184:187], v[188:191], v[116:119], v[12:15]
	v_mfma_f32_16x16x32_bf16 v[188:191], v[196:199], v[104:107], v[8:11]
	v_mfma_f32_16x16x32_bf16 v[192:195], v[196:199], v[116:119], v[4:7]
	s_barrier
	ds_read_b128 v[196:199], v160
	ds_read_b128 v[230:233], v160 offset:1024
	ds_read_b128 v[238:241], v160 offset:2048
	ds_read_b128 v[242:245], v160 offset:3072
	ds_read_b128 v[8:11], v156 offset:32768
	ds_read_b128 v[12:15], v156 offset:33792
	ds_read_b128 v[16:19], v155 offset:32768
	ds_read_b128 v[24:27], v155 offset:33792
	ds_read_b128 v[28:31], v154 offset:32768
	ds_read_b128 v[32:35], v154 offset:33792
	ds_read_b128 v[246:249], v153 offset:32768
	ds_read_b128 v[226:229], v153 offset:33792
	s_waitcnt vmcnt(2)
	s_barrier
	s_waitcnt lgkmcnt(0)
	v_mfma_f32_16x16x32_bf16 v[4:7], v[8:11], v[196:199], v[128:131]
	v_mfma_f32_16x16x32_bf16 v[104:107], v[12:15], v[230:233], v[4:7]
	v_mfma_f32_16x16x32_bf16 v[4:7], v[8:11], v[238:241], v[124:127]
	v_mfma_f32_16x16x32_bf16 v[116:119], v[12:15], v[242:245], v[4:7]
	v_mfma_f32_16x16x32_bf16 v[4:7], v[16:19], v[196:199], v[120:123]
	v_mfma_f32_16x16x32_bf16 v[100:103], v[24:27], v[230:233], v[4:7]
	v_mfma_f32_16x16x32_bf16 v[4:7], v[16:19], v[238:241], v[132:135]
	v_mfma_f32_16x16x32_bf16 v[108:111], v[24:27], v[242:245], v[4:7]
	v_mfma_f32_16x16x32_bf16 v[4:7], v[28:31], v[196:199], v[112:115]
	v_mfma_f32_16x16x32_bf16 v[92:95], v[32:35], v[230:233], v[4:7]
	v_mfma_f32_16x16x32_bf16 v[4:7], v[28:31], v[238:241], v[206:209]
	v_mfma_f32_16x16x32_bf16 v[96:99], v[32:35], v[242:245], v[4:7]
	v_mfma_f32_16x16x32_bf16 v[4:7], v[246:249], v[196:199], v[210:213]
	v_mfma_f32_16x16x32_bf16 v[84:87], v[226:229], v[230:233], v[4:7]
	v_mfma_f32_16x16x32_bf16 v[4:7], v[246:249], v[238:241], v[214:217]
	v_mfma_f32_16x16x32_bf16 v[88:91], v[226:229], v[242:245], v[4:7]
	s_barrier
; #define LDA8(dst, b, h) _Pragma("unroll") for (int m = 0; m < 4; ++m) _Pragma("unroll") for (int k = 0; k < 2; ++k) \
;     dst[m][k] = *(const bf16x8*)((const char*)SA8(b, h) + lds_byte8(wr * 64 + m * 16 + fr, k * 32 + fq * 8))
; #define LDB8(dst, b, h) _Pragma("unroll") for (int n = 0; n < 2; ++n) _Pragma("unroll") for (int k = 0; k < 2; ++k) \
;     dst[n][k] = *(const bf16x8*)((const char*)SB8(b, h) + lds_byte8(wc * 32 + n * 16 + fr, k * 32 + fq * 8))
; #define WAIT_V8(n) asm volatile("s_waitcnt vmcnt(" #n ")" ::: "memory")
; #define WAIT_L8(n) asm volatile("s_waitcnt lgkmcnt(" #n ")" ::: "memory")
; #define BAR8 __builtin_amdgcn_s_barrier()
;     ...
;     LDB8(B1, 1, 1); WAIT_V8(0); BAR8; WAIT_L8(0); MMA8(0, 1, At, B1); BAR8;
;     LDA8(At, 1, 1); BAR8; WAIT_L8(0); MMA8(1, 0, At, B0); MMA8(1, 1, At, B1); BAR8; }
;   if (wr == 0) BAR8;
;     ...
;   if (t < 256) {
	ds_read_b128 v[132:135], v158
	ds_read_b128 v[204:207], v158 offset:1024
	ds_read_b128 v[208:211], v158 offset:2048
	ds_read_b128 v[158:161], v158 offset:3072
	s_waitcnt vmcnt(0)
	s_barrier
	s_waitcnt lgkmcnt(0)
	v_mfma_f32_16x16x32_bf16 v[4:7], v[8:11], v[132:135], v[218:221]
	v_mfma_f32_16x16x32_bf16 v[8:11], v[8:11], v[208:211], v[172:175]
	v_mfma_f32_16x16x32_bf16 v[4:7], v[12:15], v[204:207], v[4:7]
	v_mfma_f32_16x16x32_bf16 v[20:23], v[12:15], v[158:161], v[8:11]
	v_mfma_f32_16x16x32_bf16 v[8:11], v[16:19], v[132:135], v[176:179]
	v_mfma_f32_16x16x32_bf16 v[12:15], v[16:19], v[208:211], v[180:183]
	v_mfma_f32_16x16x32_bf16 v[8:11], v[24:27], v[204:207], v[8:11]
	v_mfma_f32_16x16x32_bf16 v[24:27], v[24:27], v[158:161], v[12:15]
	v_mfma_f32_16x16x32_bf16 v[12:15], v[28:31], v[132:135], v[80:83]
	v_mfma_f32_16x16x32_bf16 v[16:19], v[28:31], v[208:211], v[76:79]
	v_mfma_f32_16x16x32_bf16 v[12:15], v[32:35], v[204:207], v[12:15]
	v_mfma_f32_16x16x32_bf16 v[28:31], v[32:35], v[158:161], v[16:19]
	v_mfma_f32_16x16x32_bf16 v[16:19], v[246:249], v[132:135], v[72:75]
	v_mfma_f32_16x16x32_bf16 v[32:35], v[246:249], v[208:211], v[68:71]
	v_mfma_f32_16x16x32_bf16 v[16:19], v[226:229], v[204:207], v[16:19]
	v_mfma_f32_16x16x32_bf16 v[32:35], v[226:229], v[158:161], v[32:35]
	s_barrier
	ds_read_b128 v[170:173], v156 offset:49152
	ds_read_b128 v[174:177], v156 offset:50176
	ds_read_b128 v[178:181], v155 offset:49152
	ds_read_b128 v[212:215], v155 offset:50176
	ds_read_b128 v[216:219], v154 offset:49152
	ds_read_b128 v[154:157], v154 offset:50176
	ds_read_b128 v[220:223], v153 offset:49152
	ds_read_b128 v[150:153], v153 offset:50176
	s_barrier
	s_waitcnt lgkmcnt(0)
	v_mfma_f32_16x16x32_bf16 v[64:67], v[170:173], v[196:199], v[64:67]
	v_mfma_f32_16x16x32_bf16 v[60:63], v[170:173], v[238:241], v[60:63]
	v_mfma_f32_16x16x32_bf16 v[56:59], v[178:181], v[196:199], v[56:59]
	v_mfma_f32_16x16x32_bf16 v[52:55], v[178:181], v[238:241], v[52:55]
	v_mfma_f32_16x16x32_bf16 v[48:51], v[216:219], v[196:199], v[48:51]
	v_mfma_f32_16x16x32_bf16 v[44:47], v[216:219], v[238:241], v[44:47]
	v_mfma_f32_16x16x32_bf16 v[40:43], v[220:223], v[196:199], v[40:43]
	v_mfma_f32_16x16x32_bf16 v[36:39], v[220:223], v[238:241], v[36:39]
	v_mfma_f32_16x16x32_bf16 v[128:131], v[174:177], v[230:233], v[64:67]
	v_mfma_f32_16x16x32_bf16 v[124:127], v[174:177], v[242:245], v[60:63]
	v_mfma_f32_16x16x32_bf16 v[120:123], v[212:215], v[230:233], v[56:59]
	v_mfma_f32_16x16x32_bf16 v[112:115], v[212:215], v[242:245], v[52:55]
	v_mfma_f32_16x16x32_bf16 v[80:83], v[154:157], v[230:233], v[48:51]
	v_mfma_f32_16x16x32_bf16 v[76:79], v[154:157], v[242:245], v[44:47]
	v_mfma_f32_16x16x32_bf16 v[72:75], v[150:153], v[230:233], v[40:43]
	v_mfma_f32_16x16x32_bf16 v[68:71], v[150:153], v[242:245], v[36:39]
	v_mfma_f32_16x16x32_bf16 v[40:43], v[170:173], v[208:211], v[140:143]
	v_mfma_f32_16x16x32_bf16 v[44:47], v[178:181], v[208:211], v[166:169]
	v_mfma_f32_16x16x32_bf16 v[48:51], v[216:219], v[208:211], v[184:187]
	v_mfma_f32_16x16x32_bf16 v[36:39], v[170:173], v[132:135], v[136:139]
	v_mfma_f32_16x16x32_bf16 v[52:55], v[174:177], v[158:161], v[40:43]
	v_mfma_f32_16x16x32_bf16 v[40:43], v[178:181], v[132:135], v[162:165]
	v_mfma_f32_16x16x32_bf16 v[56:59], v[212:215], v[158:161], v[44:47]
	v_mfma_f32_16x16x32_bf16 v[44:47], v[216:219], v[132:135], v[200:203]
	v_mfma_f32_16x16x32_bf16 v[60:63], v[154:157], v[158:161], v[48:51]
	v_mfma_f32_16x16x32_bf16 v[48:51], v[220:223], v[132:135], v[188:191]
	v_mfma_f32_16x16x32_bf16 v[64:67], v[220:223], v[208:211], v[192:195]
	v_mfma_f32_16x16x32_bf16 v[36:39], v[174:177], v[204:207], v[36:39]
	v_mfma_f32_16x16x32_bf16 v[40:43], v[212:215], v[204:207], v[40:43]
	v_mfma_f32_16x16x32_bf16 v[44:47], v[154:157], v[204:207], v[44:47]
	v_mfma_f32_16x16x32_bf16 v[48:51], v[150:153], v[204:207], v[48:51]
	v_mfma_f32_16x16x32_bf16 v[64:67], v[150:153], v[158:161], v[64:67]
	s_movk_i32 s2, 0x100
	v_cmp_gt_u32_e32 vcc, s2, v3
	s_barrier
	s_and_saveexec_b64 s[2:3], vcc
	s_cbranch_execz .LBB0_911
	s_barrier

; #define BAR8 __builtin_amdgcn_s_barrier()
; #define G_SS ((float*)(wsp() + OFF_SS))
; #define G_SSMEM ((float*)(wsp() + OFF_SSMEM))
;     ...
;     STAGE8(SB8(0, 0), Bt, K, bcol, 0); STAGE8(SA8(0, 0), A, lda, brow, 0);
;     STAGE8(SB8(0, 1), Bt, K, bcol + 128, 0); STAGE8(SA8(0, 1), A, lda, brow + 128, 0);
;   }
;   if (wr == 1) BAR8;
; __global__ void __launch_bounds__(512, 2) mega(Params p) {
;     ...
;     for (int item = bid; item < 2 * 64 + 4 * 8; item += nb) {
;       if (item < 128) {
;         const int nt = item >> 6, mt = item & 63;
;         e.ss = G_SS; e.nss = 16; e.inv_n = 1.f / 1024.f; e.out = G_XQ; e.ldo = 512;
;         gemm_tile<EPI_PLAIN, 256, true>(G_XB, DM, wb + W_XQ, DM, mt * 256, nt * 256, e);
;       } else {
;         const int it = item - 128;
;         const int nt = it >> 3, mt = it & 7;
;         e.ss = G_SSMEM; e.nss = 1; e.inv_n = 1.f / 1024.f; e.out = G_MEMKV; e.ldo = 1024;
;         gemm_tile<EPI_PLAIN, 256, false>(G_MEMB, DM, wb + W_XKV, DM, mt * 256, nt * 256, e);
.LBB0_1001:
	s_lshr_b32 s27, s37, 8
	s_cmpk_gt_i32 s38, 0x7f
	s_mov_b64 s[0:1], -1
	s_cbranch_scc0 .LBB0_1011
	s_mov_b32 s0, 25
	s_ashr_i32 s1, s0, 31
	s_lshl_b64 s[0:1], s[0:1], 3
	s_add_u32 s0, s70, s0
	s_addc_u32 s1, s71, s1
	v_readlane_b32 s6, v255, 60
	v_readlane_b32 s7, v255, 61
	s_nop 4
	s_mov_b32 s0, 25
	s_ashr_i32 s1, s0, 31
	s_lshl_b64 s[0:1], s[0:1], 3
	s_add_u32 s0, s70, s0
	s_addc_u32 s1, s71, s1
	v_readlane_b32 s2, v255, 60
	v_readlane_b32 s3, v255, 61
	s_nop 4
	s_mov_b32 s0, 25
	s_ashr_i32 s1, s0, 31
	s_lshl_b64 s[0:1], s[0:1], 3
	s_add_u32 s0, s70, s0
	s_addc_u32 s1, s71, s1
	v_mov_b32_e32 v3, v224
	v_readlane_b32 s12, v255, 60
	v_readlane_b32 s13, v255, 61
	s_nop 4
	s_lshl_b32 s0, s38, 8
	v_bfe_i32 v1, v3, 27, 1
	s_waitcnt vmcnt(10)
	v_lshlrev_b32_e32 v150, 4, v3
	s_nop 0
	v_readfirstlane_b32 s100, v150
	v_lshrrev_b32_e32 v1, 22, v1
	v_add_u32_e32 v1, v150, v1
	v_and_b32_e32 v1, 0xfffffc00, v1
	v_ashrrev_i32_e32 v0, 31, v3
	v_sub_u32_e32 v1, v150, v1
	v_lshrrev_b32_e32 v0, 26, v0
	v_lshrrev_b32_e32 v5, 4, v1
	v_add_u32_e32 v0, v3, v0
	v_bitop3_b32 v5, v5, v1, 32 bitop3:0x6c
	v_ashrrev_i32_e32 v1, 31, v1
	v_ashrrev_i32_e32 v0, 6, v0
	v_lshrrev_b32_e32 v1, 26, v1
	v_lshlrev_b32_e32 v6, 3, v0
	v_add_u32_e32 v1, v5, v1
	s_and_b32 s29, s0, 0x700
	s_lshl_b32 s0, s38, 5
	v_and_b32_e32 v6, -16, v6
	v_ashrrev_i32_e32 v1, 6, v1
	s_and_b32 s39, s0, 0x7fffff00
	v_add_u32_e32 v6, v1, v6
	v_mul_i32_i24_e32 v1, 64, v1
	s_add_i32 s0, s39, 0xfffff000
	v_lshlrev_b32_e32 v0, 5, v0
	v_sub_u32_e32 v1, v5, v1
	v_mov_b32_e32 v14, 1
	s_waitcnt vmcnt(9)
	v_add_u32_e32 v152, 0x2000, v150
	s_lshl_b32 s1, s0, 11
	v_and_b32_e32 v0, 32, v0
	v_ashrrev_i16_sdwa v1, v14, sext(v1) dst_sel:DWORD dst_unused:UNUSED_PAD src0_sel:DWORD src1_sel:BYTE_0
	v_ashrrev_i32_e32 v5, 31, v152
	s_add_u32 s14, s24, s1
	v_add_u32_sdwa v0, v0, sext(v1) dst_sel:DWORD dst_unused:UNUSED_PAD src0_sel:DWORD src1_sel:WORD_0
	v_ashrrev_i32_e32 v7, 31, v6
	v_lshrrev_b32_e32 v5, 22, v5
	s_addc_u32 s15, s25, 0
	v_lshlrev_b64 v[132:133], 11, v[6:7]
	v_ashrrev_i32_e32 v1, 31, v0
	v_add_u32_e32 v5, v152, v5
	v_lshl_add_u64 v[8:9], s[14:15], 0, v[132:133]
	v_lshlrev_b64 v[6:7], 1, v[0:1]
	v_ashrrev_i32_e32 v5, 10, v5
	v_lshl_add_u64 v[10:11], v[8:9], 0, v[6:7]
	v_mul_i32_i24_e32 v8, 0x400, v5
	v_sub_u32_e32 v8, v152, v8
	v_lshrrev_b32_e32 v9, 4, v8
	v_bitop3_b32 v9, v9, v8, 32 bitop3:0x6c
	v_ashrrev_i32_e32 v12, 31, v9
	v_lshrrev_b32_e32 v12, 26, v12
	v_add_u32_e32 v12, v9, v12
	s_waitcnt vmcnt(8)
	v_mov_b32_e32 v4, v2
	s_or_b32 m0, s100, 0x10000
	v_lshlrev_b32_e32 v8, 3, v5
	v_ashrrev_i32_e32 v13, 6, v12
	v_and_b32_e32 v12, 0xc0, v12
	global_load_lds_dwordx4 v[10:11], off
	v_and_b32_e32 v8, -16, v8
	v_lshlrev_b32_e32 v5, 5, v5
	v_sub_u32_e32 v9, v9, v12
	s_or_b32 m0, s100, 0x12000
	s_lshl_b32 s1, s29, 11
	v_add_u32_e32 v8, v13, v8
	v_and_b32_e32 v5, 32, v5
	v_ashrrev_i16_sdwa v9, v14, sext(v9) dst_sel:DWORD dst_unused:UNUSED_PAD src0_sel:DWORD src1_sel:BYTE_0
	s_waitcnt lgkmcnt(0)
	s_add_u32 s1, s12, s1
	v_add_u32_sdwa v134, v5, sext(v9) dst_sel:DWORD dst_unused:UNUSED_PAD src0_sel:DWORD src1_sel:WORD_0
	v_ashrrev_i32_e32 v9, 31, v8
	s_addc_u32 s40, s13, 0
	v_lshlrev_b64 v[136:137], 11, v[8:9]
	v_ashrrev_i32_e32 v135, 31, v134
	s_add_u32 s8, s1, 0xb800000
	v_lshl_add_u64 v[12:13], s[14:15], 0, v[136:137]
	v_lshlrev_b64 v[8:9], 1, v[134:135]
	s_addc_u32 s9, s40, 0
	v_lshl_add_u64 v[12:13], v[12:13], 0, v[8:9]
	v_lshl_add_u64 v[14:15], s[8:9], 0, v[132:133]
	global_load_lds_dwordx4 v[12:13], off
	s_mov_b32 m0, s100
	v_lshl_add_u64 v[16:17], v[14:15], 0, v[6:7]
	global_load_lds_dwordx4 v[16:17], off
	s_or_b32 m0, s100, 0x2000
	s_add_u32 s20, s14, 0x40000
	v_lshl_add_u64 v[14:15], s[8:9], 0, v[136:137]
	s_addc_u32 s21, s15, 0
	v_lshl_add_u64 v[14:15], v[14:15], 0, v[8:9]
	v_lshl_add_u64 v[18:19], s[20:21], 0, v[132:133]
	global_load_lds_dwordx4 v[14:15], off
	v_lshl_add_u64 v[18:19], v[18:19], 0, v[6:7]
	s_or_b32 m0, s100, 0x14000
	global_load_lds_dwordx4 v[18:19], off
	v_lshl_add_u64 v[18:19], s[20:21], 0, v[136:137]
	s_or_b32 m0, s100, 0x16000
	s_add_u32 s20, s1, 0xb840000
	v_lshl_add_u64 v[18:19], v[18:19], 0, v[8:9]
	s_addc_u32 s21, s40, 0
	global_load_lds_dwordx4 v[18:19], off
	v_lshl_add_u64 v[18:19], s[20:21], 0, v[132:133]
	v_lshl_add_u64 v[18:19], v[18:19], 0, v[6:7]
	s_or_b32 m0, s100, 0x4000
	global_load_lds_dwordx4 v[18:19], off
	v_lshl_add_u64 v[18:19], s[20:21], 0, v[136:137]
	v_lshl_add_u64 v[18:19], v[18:19], 0, v[8:9]
	s_or_b32 m0, s100, 0x6000
	v_ashrrev_i32_e32 v5, 8, v3
	global_load_lds_dwordx4 v[18:19], off
	v_cmp_eq_u32_e32 vcc, 1, v5
	s_and_saveexec_b64 s[20:21], vcc
	s_cbranch_execz .LBB0_1004
	s_barrier
; #define LDA8(dst, b, h) _Pragma("unroll") for (int m = 0; m < 4; ++m) _Pragma("unroll") for (int k = 0; k < 2; ++k) \
;     dst[m][k] = *(const bf16x8*)((const char*)SA8(b, h) + lds_byte8(wr * 64 + m * 16 + fr, k * 32 + fq * 8))
; #define LDB8(dst, b, h) _Pragma("unroll") for (int n = 0; n < 2; ++n) _Pragma("unroll") for (int k = 0; k < 2; ++k) \
;     dst[n][k] = *(const bf16x8*)((const char*)SB8(b, h) + lds_byte8(wc * 32 + n * 16 + fr, k * 32 + fq * 8))
; #define WAIT_V8(n) asm volatile("s_waitcnt vmcnt(" #n ")" ::: "memory")
; #define WAIT_L8(n) asm volatile("s_waitcnt lgkmcnt(" #n ")" ::: "memory")
; #define BAR8 __builtin_amdgcn_s_barrier()
; #define SCHED8 __builtin_amdgcn_sched_barrier(0)
;     ...
;   if (wr == 1) BAR8;
;   WAIT_V8(4); BAR8;
;   STAGE8(SB8(1, 0), Bt, K, bcol, 1); STAGE8(SA8(1, 0), A, lda, brow, 1); STAGE8(SB8(1, 1), Bt, K, bcol + 128, 1);
;   WAIT_V8(6); BAR8;
;   for (int tt = 0; tt < nt - 2; tt += 2) {
;     LDB8(B0, 0, 0); SCHED8; LDA8(At, 0, 0); STAGE8(SA8(1, 1), A, lda, brow + 128, tt + 1);
;     WAIT_L8(8); BAR8; WAIT_L8(0); MMA8(0, 0, At, B0); BAR8; SCHED8;
;     LDB8(B1, 0, 1); STAGE8(SB8(0, 0), Bt, K, bcol, tt + 2);
;     BAR8; WAIT_L8(0); MMA8(0, 1, At, B1); BAR8;
.LBB0_1004:
	s_or_b64 exec, exec, s[20:21]
	v_readlane_b32 s40, v254, 35
	s_lshl_b32 s20, s36, 10
	v_readlane_b32 s42, v254, 37
	v_readlane_b32 s43, v254, 38
	s_waitcnt vmcnt(0)
	s_and_b32 s20, s20, 0xfffc0000
	s_mov_b32 s21, s40
	s_mov_b64 s[42:43], 0x80
	s_and_b32 s1, s27, 7
	s_add_i32 s20, s20, 0xffc00000
	v_lshl_add_u64 v[10:11], v[10:11], 0, s[42:43]
	s_or_b32 m0, s100, 0x18000
	s_lshl_b32 s1, s1, 19
	s_lshl_b64 s[20:21], s[20:21], 1
	s_waitcnt vmcnt(4)
	s_barrier
	global_load_lds_dwordx4 v[10:11], off
	v_lshl_add_u64 v[10:11], v[12:13], 0, s[42:43]
	s_or_b32 m0, s100, 0x1a000
	global_load_lds_dwordx4 v[10:11], off
	v_lshl_add_u64 v[10:11], v[16:17], 0, s[42:43]
	s_or_b32 m0, s100, 0x8000
	s_add_u32 s14, s14, 0x40080
	global_load_lds_dwordx4 v[10:11], off
	v_lshl_add_u64 v[10:11], v[14:15], 0, s[42:43]
	s_addc_u32 s15, s15, 0
	s_or_b32 m0, s100, 0xa000
	global_load_lds_dwordx4 v[10:11], off
	v_lshl_add_u64 v[10:11], s[14:15], 0, v[132:133]
	v_lshl_add_u64 v[10:11], v[10:11], 0, v[6:7]
	s_or_b32 m0, s100, 0x1c000
	global_load_lds_dwordx4 v[10:11], off
	v_lshl_add_u64 v[10:11], s[14:15], 0, v[136:137]
	v_lshl_add_u64 v[10:11], v[10:11], 0, v[8:9]
	s_or_b32 m0, s100, 0x1e000
	v_and_b32_e32 v147, 15, v3
	global_load_lds_dwordx4 v[10:11], off
	v_bfe_u32 v148, v3, 4, 2
	v_lshlrev_b32_e32 v11, 4, v148
	v_lshlrev_b32_e32 v12, 6, v147
	v_lshlrev_b32_e32 v14, 2, v3
	v_or_b32_e32 v13, v11, v12
	v_and_b32_e32 v14, 32, v14
	s_mov_b32 s14, 0x10000
	v_bitop3_b32 v15, v13, s14, v14 bitop3:0xde
	s_mov_b32 s14, 0x14000
	s_add_u32 s12, s12, s1
	v_bitop3_b32 v16, v13, s14, v14 bitop3:0xde
	s_mov_b32 s14, 0x18000
	v_lshlrev_b32_e32 v18, 6, v3
	s_addc_u32 s13, s13, 0
	v_lshl_add_u64 v[8:9], v[136:137], 0, v[8:9]
	v_lshl_add_u64 v[6:7], v[132:133], 0, v[6:7]
	v_bfe_u32 v146, v3, 6, 2
	s_waitcnt vmcnt(6)
	v_lshlrev_b32_e32 v149, 6, v5
	v_bitop3_b32 v17, v13, s14, v14 bitop3:0xde
	s_mov_b32 s14, 0x1c000
	v_lshlrev_b32_e32 v5, 13, v5
	v_and_b32_e32 v18, 0x3c0, v18
	v_lshl_add_u64 v[138:139], s[12:13], 0, v[8:9]
	v_lshl_add_u64 v[140:141], s[12:13], 0, v[6:7]
	s_add_u32 s12, s4, s20
	v_readlane_b32 s41, v254, 36
	v_lshlrev_b32_e32 v10, 12, v146
	v_bitop3_b32 v12, v11, v14, v12 bitop3:0x36
	v_bitop3_b32 v13, v13, s14, v14 bitop3:0xde
	v_bitop3_b32 v11, v18, v14, v11 bitop3:0x36
	v_or_b32_e32 v14, 0x800, v5
	v_or_b32_e32 v18, 0x1000, v5
	v_or_b32_e32 v19, 0x1800, v5
	s_addc_u32 s13, s5, s21
	v_lshl_add_u64 v[142:143], s[12:13], 0, v[6:7]
	v_lshl_add_u64 v[144:145], s[12:13], 0, v[8:9]
	s_mov_b32 s1, -2
	s_mov_b64 s[12:13], 0
	v_add_u32_e32 v171, v15, v10
	v_add_u32_e32 v156, v12, v5
	v_add_u32_e32 v155, v11, v14
	v_add_u32_e32 v154, v11, v18
	v_add_u32_e32 v153, v11, v19
	v_add_u32_e32 v168, v16, v10
	v_add_u32_e32 v161, v17, v10
	v_add_u32_e32 v158, v13, v10
	s_mov_b64 s[20:21], 0xb840080
	s_mov_b64 s[40:41], 0xc7a0100
	s_mov_b64 s[42:43], 0xb800100
	s_mov_b64 s[44:45], 0xc7e0100
	s_mov_b64 s[46:47], 0xb840100
	s_mov_b64 s[48:49], 0xc7a0180
	s_mov_b64 s[50:51], 0xb800180
	s_mov_b64 s[52:53], 0xc7e0180
	s_barrier
	ds_read_b128 v[174:177], v171
	ds_read_b128 v[178:181], v171 offset:1024
	ds_read_b128 v[182:185], v171 offset:2048
	ds_read_b128 v[186:189], v171 offset:3072
	v_lshl_add_u64 v[222:223], v[140:141], 0, s[12:13]
	v_lshl_add_u64 v[226:227], v[222:223], 0, s[20:21]
	s_or_b32 m0, s100, 0xc000
	v_lshl_add_u64 v[236:237], v[138:139], 0, s[12:13]
	ds_read_b128 v[190:193], v156
	ds_read_b128 v[194:197], v156 offset:1024
	ds_read_b128 v[198:201], v155
	ds_read_b128 v[202:205], v155 offset:1024
	ds_read_b128 v[206:209], v154
	ds_read_b128 v[210:213], v154 offset:1024
	ds_read_b128 v[214:217], v153
	ds_read_b128 v[218:221], v153 offset:1024
	global_load_lds_dwordx4 v[226:227], off
	s_or_b32 m0, s100, 0xe000
	v_lshl_add_u64 v[226:227], v[236:237], 0, s[20:21]
	global_load_lds_dwordx4 v[226:227], off
	s_waitcnt lgkmcnt(8)
	s_barrier
	s_waitcnt lgkmcnt(0)
	v_mfma_f32_16x16x32_bf16 v[128:131], v[190:193], v[174:177], 0
	v_mfma_f32_16x16x32_bf16 v[124:127], v[190:193], v[182:185], 0
	v_mfma_f32_16x16x32_bf16 v[120:123], v[198:201], v[174:177], 0
	v_mfma_f32_16x16x32_bf16 v[116:119], v[198:201], v[182:185], 0
	v_mfma_f32_16x16x32_bf16 v[112:115], v[206:209], v[174:177], 0
	v_mfma_f32_16x16x32_bf16 v[108:111], v[206:209], v[182:185], 0
	v_mfma_f32_16x16x32_bf16 v[104:107], v[214:217], v[174:177], 0
	v_mfma_f32_16x16x32_bf16 v[100:103], v[214:217], v[182:185], 0
	v_mfma_f32_16x16x32_bf16 v[128:131], v[194:197], v[178:181], v[128:131]
	v_mfma_f32_16x16x32_bf16 v[124:127], v[194:197], v[186:189], v[124:127]
	v_mfma_f32_16x16x32_bf16 v[120:123], v[202:205], v[178:181], v[120:123]
	v_mfma_f32_16x16x32_bf16 v[116:119], v[202:205], v[186:189], v[116:119]
	v_mfma_f32_16x16x32_bf16 v[112:115], v[210:213], v[178:181], v[112:115]
	v_mfma_f32_16x16x32_bf16 v[108:111], v[210:213], v[186:189], v[108:111]
	v_mfma_f32_16x16x32_bf16 v[104:107], v[218:221], v[178:181], v[104:107]
	v_mfma_f32_16x16x32_bf16 v[100:103], v[218:221], v[186:189], v[100:103]
	s_barrier
	v_lshl_add_u64 v[246:247], v[142:143], 0, s[12:13]
	v_lshl_add_u64 v[248:249], v[246:247], 0, s[40:41]
	s_or_b32 m0, s100, 0x10000
	ds_read_b128 v[226:229], v168
	ds_read_b128 v[230:233], v168 offset:1024
	ds_read_b128 v[238:241], v168 offset:2048
	ds_read_b128 v[242:245], v168 offset:3072
	global_load_lds_dwordx4 v[248:249], off
	v_lshl_add_u64 v[248:249], v[144:145], 0, s[12:13]
	s_or_b32 m0, s100, 0x12000
	v_lshl_add_u64 v[250:251], v[248:249], 0, s[40:41]
	global_load_lds_dwordx4 v[250:251], off
	s_barrier
; #define LDA8(dst, b, h) _Pragma("unroll") for (int m = 0; m < 4; ++m) _Pragma("unroll") for (int k = 0; k < 2; ++k) \
;     dst[m][k] = *(const bf16x8*)((const char*)SA8(b, h) + lds_byte8(wr * 64 + m * 16 + fr, k * 32 + fq * 8))
; #define LDB8(dst, b, h) _Pragma("unroll") for (int n = 0; n < 2; ++n) _Pragma("unroll") for (int k = 0; k < 2; ++k) \
;     dst[n][k] = *(const bf16x8*)((const char*)SB8(b, h) + lds_byte8(wc * 32 + n * 16 + fr, k * 32 + fq * 8))
; #define WAIT_V8(n) asm volatile("s_waitcnt vmcnt(" #n ")" ::: "memory")
; #define WAIT_L8(n) asm volatile("s_waitcnt lgkmcnt(" #n ")" ::: "memory")
; #define BAR8 __builtin_amdgcn_s_barrier()
; #define SCHED8 __builtin_amdgcn_sched_barrier(0)
;     ...
;     BAR8; WAIT_L8(0); MMA8(0, 1, At, B1); BAR8;
;     LDA8(At, 0, 1); STAGE8(SA8(0, 0), A, lda, brow, tt + 2);
;     BAR8; WAIT_L8(0); MMA8(1, 0, At, B0); BAR8; SCHED8;
;     STAGE8(SB8(0, 1), Bt, K, bcol + 128, tt + 2);
;     WAIT_V8(6); BAR8; MMA8(1, 1, At, B1); BAR8;
;     LDB8(B0, 1, 0); SCHED8; LDA8(At, 1, 0); STAGE8(SA8(0, 1), A, lda, brow + 128, tt + 2);
;     WAIT_L8(8); BAR8; WAIT_L8(0); MMA8(0, 0, At, B0); BAR8; SCHED8;
	s_waitcnt lgkmcnt(0)
	v_mfma_f32_16x16x32_bf16 v[96:99], v[190:193], v[226:229], 0
	v_mfma_f32_16x16x32_bf16 v[92:95], v[190:193], v[238:241], 0
	v_mfma_f32_16x16x32_bf16 v[88:91], v[198:201], v[226:229], 0
	v_mfma_f32_16x16x32_bf16 v[84:87], v[198:201], v[238:241], 0
	v_mfma_f32_16x16x32_bf16 v[80:83], v[206:209], v[226:229], 0
	v_mfma_f32_16x16x32_bf16 v[76:79], v[206:209], v[238:241], 0
	v_mfma_f32_16x16x32_bf16 v[72:75], v[214:217], v[226:229], 0
	v_mfma_f32_16x16x32_bf16 v[68:71], v[214:217], v[238:241], 0
	v_mfma_f32_16x16x32_bf16 v[96:99], v[194:197], v[230:233], v[96:99]
	v_mfma_f32_16x16x32_bf16 v[92:95], v[194:197], v[242:245], v[92:95]
	v_mfma_f32_16x16x32_bf16 v[88:91], v[202:205], v[230:233], v[88:91]
	v_mfma_f32_16x16x32_bf16 v[84:87], v[202:205], v[242:245], v[84:87]
	v_mfma_f32_16x16x32_bf16 v[80:83], v[210:213], v[230:233], v[80:83]
	v_mfma_f32_16x16x32_bf16 v[76:79], v[210:213], v[242:245], v[76:79]
	v_mfma_f32_16x16x32_bf16 v[72:75], v[218:221], v[230:233], v[72:75]
	v_mfma_f32_16x16x32_bf16 v[68:71], v[218:221], v[242:245], v[68:71]
	v_lshl_add_u64 v[250:251], v[222:223], 0, s[42:43]
	s_mov_b32 m0, s100
	s_barrier
	ds_read_b128 v[190:193], v156 offset:16384
	ds_read_b128 v[194:197], v156 offset:17408
	ds_read_b128 v[198:201], v155 offset:16384
	ds_read_b128 v[202:205], v155 offset:17408
	ds_read_b128 v[206:209], v154 offset:16384
	ds_read_b128 v[210:213], v154 offset:17408
	ds_read_b128 v[214:217], v153 offset:16384
	ds_read_b128 v[218:221], v153 offset:17408
	global_load_lds_dwordx4 v[250:251], off
	s_or_b32 m0, s100, 0x2000
	v_lshl_add_u64 v[250:251], v[236:237], 0, s[42:43]
	global_load_lds_dwordx4 v[250:251], off
	s_barrier
	s_waitcnt lgkmcnt(0)
	v_mfma_f32_16x16x32_bf16 v[64:67], v[190:193], v[174:177], 0
	v_mfma_f32_16x16x32_bf16 v[60:63], v[190:193], v[182:185], 0
	v_mfma_f32_16x16x32_bf16 v[56:59], v[198:201], v[174:177], 0
	v_mfma_f32_16x16x32_bf16 v[52:55], v[198:201], v[182:185], 0
	v_mfma_f32_16x16x32_bf16 v[48:51], v[206:209], v[174:177], 0
	v_mfma_f32_16x16x32_bf16 v[44:47], v[206:209], v[182:185], 0
	v_mfma_f32_16x16x32_bf16 v[40:43], v[214:217], v[174:177], 0
	v_mfma_f32_16x16x32_bf16 v[36:39], v[214:217], v[182:185], 0
	v_mfma_f32_16x16x32_bf16 v[64:67], v[194:197], v[178:181], v[64:67]
	v_mfma_f32_16x16x32_bf16 v[60:63], v[194:197], v[186:189], v[60:63]
	v_mfma_f32_16x16x32_bf16 v[56:59], v[202:205], v[178:181], v[56:59]
	v_mfma_f32_16x16x32_bf16 v[52:55], v[202:205], v[186:189], v[52:55]
	v_mfma_f32_16x16x32_bf16 v[48:51], v[210:213], v[178:181], v[48:51]
	v_mfma_f32_16x16x32_bf16 v[44:47], v[210:213], v[186:189], v[44:47]
	v_mfma_f32_16x16x32_bf16 v[40:43], v[218:221], v[178:181], v[40:43]
	v_mfma_f32_16x16x32_bf16 v[36:39], v[218:221], v[186:189], v[36:39]
	s_barrier
	s_or_b32 m0, s100, 0x14000
	v_lshl_add_u64 v[174:175], v[246:247], 0, s[44:45]
	global_load_lds_dwordx4 v[174:175], off
	s_or_b32 m0, s100, 0x16000
	v_lshl_add_u64 v[174:175], v[248:249], 0, s[44:45]
	global_load_lds_dwordx4 v[174:175], off
	s_waitcnt vmcnt(6)
	s_barrier
	v_mfma_f32_16x16x32_bf16 v[32:35], v[190:193], v[226:229], 0
	v_mfma_f32_16x16x32_bf16 v[28:31], v[190:193], v[238:241], 0
	v_mfma_f32_16x16x32_bf16 v[24:27], v[198:201], v[226:229], 0
	v_mfma_f32_16x16x32_bf16 v[20:23], v[198:201], v[238:241], 0
	v_mfma_f32_16x16x32_bf16 v[16:19], v[206:209], v[226:229], 0
	v_mfma_f32_16x16x32_bf16 v[12:15], v[206:209], v[238:241], 0
	v_mfma_f32_16x16x32_bf16 v[8:11], v[214:217], v[226:229], 0
	v_mfma_f32_16x16x32_bf16 v[4:7], v[214:217], v[238:241], 0
	v_mfma_f32_16x16x32_bf16 v[32:35], v[194:197], v[230:233], v[32:35]
	v_mfma_f32_16x16x32_bf16 v[28:31], v[194:197], v[242:245], v[28:31]
	v_mfma_f32_16x16x32_bf16 v[24:27], v[202:205], v[230:233], v[24:27]
	v_mfma_f32_16x16x32_bf16 v[20:23], v[202:205], v[242:245], v[20:23]
	v_mfma_f32_16x16x32_bf16 v[16:19], v[210:213], v[230:233], v[16:19]
	v_mfma_f32_16x16x32_bf16 v[12:15], v[210:213], v[242:245], v[12:15]
	v_mfma_f32_16x16x32_bf16 v[8:11], v[218:221], v[230:233], v[8:11]
	v_mfma_f32_16x16x32_bf16 v[4:7], v[218:221], v[242:245], v[4:7]
	s_barrier
	ds_read_b128 v[174:177], v161
	ds_read_b128 v[178:181], v161 offset:1024
	ds_read_b128 v[182:185], v161 offset:2048
	ds_read_b128 v[186:189], v161 offset:3072
	v_lshl_add_u64 v[226:227], v[222:223], 0, s[46:47]
	s_or_b32 m0, s100, 0x4000
	ds_read_b128 v[190:193], v156 offset:32768
	ds_read_b128 v[194:197], v156 offset:33792
	ds_read_b128 v[198:201], v155 offset:32768
	ds_read_b128 v[202:205], v155 offset:33792
	ds_read_b128 v[206:209], v154 offset:32768
	ds_read_b128 v[210:213], v154 offset:33792
	ds_read_b128 v[214:217], v153 offset:32768
	ds_read_b128 v[218:221], v153 offset:33792
	global_load_lds_dwordx4 v[226:227], off
	s_or_b32 m0, s100, 0x6000
	v_lshl_add_u64 v[226:227], v[236:237], 0, s[46:47]
	global_load_lds_dwordx4 v[226:227], off
	s_waitcnt lgkmcnt(8)
	s_barrier
	s_waitcnt lgkmcnt(0)
	v_mfma_f32_16x16x32_bf16 v[128:131], v[190:193], v[174:177], v[128:131]
	v_mfma_f32_16x16x32_bf16 v[124:127], v[190:193], v[182:185], v[124:127]
	v_mfma_f32_16x16x32_bf16 v[120:123], v[198:201], v[174:177], v[120:123]
	v_mfma_f32_16x16x32_bf16 v[116:119], v[198:201], v[182:185], v[116:119]
	v_mfma_f32_16x16x32_bf16 v[112:115], v[206:209], v[174:177], v[112:115]
	v_mfma_f32_16x16x32_bf16 v[108:111], v[206:209], v[182:185], v[108:111]
	v_mfma_f32_16x16x32_bf16 v[104:107], v[214:217], v[174:177], v[104:107]
	v_mfma_f32_16x16x32_bf16 v[100:103], v[214:217], v[182:185], v[100:103]
	v_mfma_f32_16x16x32_bf16 v[128:131], v[194:197], v[178:181], v[128:131]
	v_mfma_f32_16x16x32_bf16 v[124:127], v[194:197], v[186:189], v[124:127]
	v_mfma_f32_16x16x32_bf16 v[120:123], v[202:205], v[178:181], v[120:123]
	v_mfma_f32_16x16x32_bf16 v[116:119], v[202:205], v[186:189], v[116:119]
	v_mfma_f32_16x16x32_bf16 v[112:115], v[210:213], v[178:181], v[112:115]
	v_mfma_f32_16x16x32_bf16 v[108:111], v[210:213], v[186:189], v[108:111]
	v_mfma_f32_16x16x32_bf16 v[104:107], v[218:221], v[178:181], v[104:107]
	v_mfma_f32_16x16x32_bf16 v[100:103], v[218:221], v[186:189], v[100:103]
	s_barrier
; #define LDA8(dst, b, h) _Pragma("unroll") for (int m = 0; m < 4; ++m) _Pragma("unroll") for (int k = 0; k < 2; ++k) \
;     dst[m][k] = *(const bf16x8*)((const char*)SA8(b, h) + lds_byte8(wr * 64 + m * 16 + fr, k * 32 + fq * 8))
; #define LDB8(dst, b, h) _Pragma("unroll") for (int n = 0; n < 2; ++n) _Pragma("unroll") for (int k = 0; k < 2; ++k) \
;     dst[n][k] = *(const bf16x8*)((const char*)SB8(b, h) + lds_byte8(wc * 32 + n * 16 + fr, k * 32 + fq * 8))
; #define WAIT_V8(n) asm volatile("s_waitcnt vmcnt(" #n ")" ::: "memory")
; #define WAIT_L8(n) asm volatile("s_waitcnt lgkmcnt(" #n ")" ::: "memory")
; #define BAR8 __builtin_amdgcn_s_barrier()
; #define SCHED8 __builtin_amdgcn_sched_barrier(0)
;     ...
;     LDB8(B1, 1, 1); STAGE8(SB8(1, 0), Bt, K, bcol, tt + 3);
;     BAR8; WAIT_L8(0); MMA8(0, 1, At, B1); BAR8;
;     LDA8(At, 1, 1); STAGE8(SA8(1, 0), A, lda, brow, tt + 3);
;     BAR8; WAIT_L8(0); MMA8(1, 0, At, B0); BAR8; SCHED8;
;     STAGE8(SB8(1, 1), Bt, K, bcol + 128, tt + 3);
;     WAIT_V8(6); BAR8; MMA8(1, 1, At, B1); BAR8;
	v_lshl_add_u64 v[250:251], v[246:247], 0, s[48:49]
	s_or_b32 m0, s100, 0x18000
	ds_read_b128 v[226:229], v158
	ds_read_b128 v[230:233], v158 offset:1024
	ds_read_b128 v[238:241], v158 offset:2048
	ds_read_b128 v[242:245], v158 offset:3072
	global_load_lds_dwordx4 v[250:251], off
	s_or_b32 m0, s100, 0x1a000
	v_lshl_add_u64 v[250:251], v[248:249], 0, s[48:49]
	global_load_lds_dwordx4 v[250:251], off
	s_barrier
	s_waitcnt lgkmcnt(0)
	v_mfma_f32_16x16x32_bf16 v[96:99], v[190:193], v[226:229], v[96:99]
	v_mfma_f32_16x16x32_bf16 v[92:95], v[190:193], v[238:241], v[92:95]
	v_mfma_f32_16x16x32_bf16 v[88:91], v[198:201], v[226:229], v[88:91]
	v_mfma_f32_16x16x32_bf16 v[84:87], v[198:201], v[238:241], v[84:87]
	v_mfma_f32_16x16x32_bf16 v[80:83], v[206:209], v[226:229], v[80:83]
	v_mfma_f32_16x16x32_bf16 v[76:79], v[206:209], v[238:241], v[76:79]
	v_mfma_f32_16x16x32_bf16 v[72:75], v[214:217], v[226:229], v[72:75]
	v_mfma_f32_16x16x32_bf16 v[68:71], v[214:217], v[238:241], v[68:71]
	v_mfma_f32_16x16x32_bf16 v[96:99], v[194:197], v[230:233], v[96:99]
	v_mfma_f32_16x16x32_bf16 v[92:95], v[194:197], v[242:245], v[92:95]
	v_mfma_f32_16x16x32_bf16 v[88:91], v[202:205], v[230:233], v[88:91]
	v_mfma_f32_16x16x32_bf16 v[84:87], v[202:205], v[242:245], v[84:87]
	v_mfma_f32_16x16x32_bf16 v[80:83], v[210:213], v[230:233], v[80:83]
	v_mfma_f32_16x16x32_bf16 v[76:79], v[210:213], v[242:245], v[76:79]
	v_mfma_f32_16x16x32_bf16 v[72:75], v[218:221], v[230:233], v[72:75]
	v_mfma_f32_16x16x32_bf16 v[68:71], v[218:221], v[242:245], v[68:71]
	v_lshl_add_u64 v[222:223], v[222:223], 0, s[50:51]
	s_or_b32 m0, s100, 0x8000
	s_barrier
	ds_read_b128 v[190:193], v156 offset:49152
	ds_read_b128 v[194:197], v156 offset:50176
	ds_read_b128 v[198:201], v155 offset:49152
	ds_read_b128 v[202:205], v155 offset:50176
	ds_read_b128 v[206:209], v154 offset:49152
	ds_read_b128 v[210:213], v154 offset:50176
	ds_read_b128 v[214:217], v153 offset:49152
	ds_read_b128 v[218:221], v153 offset:50176
	global_load_lds_dwordx4 v[222:223], off
	s_or_b32 m0, s100, 0xa000
	v_lshl_add_u64 v[222:223], v[236:237], 0, s[50:51]
	global_load_lds_dwordx4 v[222:223], off
	s_barrier
	s_waitcnt lgkmcnt(0)
	v_mfma_f32_16x16x32_bf16 v[64:67], v[190:193], v[174:177], v[64:67]
	v_mfma_f32_16x16x32_bf16 v[60:63], v[190:193], v[182:185], v[60:63]
	v_mfma_f32_16x16x32_bf16 v[56:59], v[198:201], v[174:177], v[56:59]
	v_mfma_f32_16x16x32_bf16 v[52:55], v[198:201], v[182:185], v[52:55]
	v_mfma_f32_16x16x32_bf16 v[48:51], v[206:209], v[174:177], v[48:51]
	v_mfma_f32_16x16x32_bf16 v[44:47], v[206:209], v[182:185], v[44:47]
	v_mfma_f32_16x16x32_bf16 v[40:43], v[214:217], v[174:177], v[40:43]
	v_mfma_f32_16x16x32_bf16 v[36:39], v[214:217], v[182:185], v[36:39]
	v_mfma_f32_16x16x32_bf16 v[64:67], v[194:197], v[178:181], v[64:67]
	v_mfma_f32_16x16x32_bf16 v[60:63], v[194:197], v[186:189], v[60:63]
	v_mfma_f32_16x16x32_bf16 v[56:59], v[202:205], v[178:181], v[56:59]
	v_mfma_f32_16x16x32_bf16 v[52:55], v[202:205], v[186:189], v[52:55]
	v_mfma_f32_16x16x32_bf16 v[48:51], v[210:213], v[178:181], v[48:51]
	v_mfma_f32_16x16x32_bf16 v[44:47], v[210:213], v[186:189], v[44:47]
	v_mfma_f32_16x16x32_bf16 v[40:43], v[218:221], v[178:181], v[40:43]
	v_mfma_f32_16x16x32_bf16 v[36:39], v[218:221], v[186:189], v[36:39]
	s_barrier
	s_or_b32 m0, s100, 0x1c000
	v_lshl_add_u64 v[174:175], v[246:247], 0, s[52:53]
	global_load_lds_dwordx4 v[174:175], off
	s_or_b32 m0, s100, 0x1e000
	v_lshl_add_u64 v[174:175], v[248:249], 0, s[52:53]
	global_load_lds_dwordx4 v[174:175], off
	s_waitcnt vmcnt(6)
	s_barrier
	v_mfma_f32_16x16x32_bf16 v[32:35], v[190:193], v[226:229], v[32:35]
	v_mfma_f32_16x16x32_bf16 v[28:31], v[190:193], v[238:241], v[28:31]
	v_mfma_f32_16x16x32_bf16 v[24:27], v[198:201], v[226:229], v[24:27]
	v_mfma_f32_16x16x32_bf16 v[20:23], v[198:201], v[238:241], v[20:23]
	v_mfma_f32_16x16x32_bf16 v[16:19], v[206:209], v[226:229], v[16:19]
	v_mfma_f32_16x16x32_bf16 v[12:15], v[206:209], v[238:241], v[12:15]
	v_mfma_f32_16x16x32_bf16 v[8:11], v[214:217], v[226:229], v[8:11]
	v_mfma_f32_16x16x32_bf16 v[4:7], v[214:217], v[238:241], v[4:7]
	v_mfma_f32_16x16x32_bf16 v[32:35], v[194:197], v[230:233], v[32:35]
	v_mfma_f32_16x16x32_bf16 v[28:31], v[194:197], v[242:245], v[28:31]
	v_mfma_f32_16x16x32_bf16 v[24:27], v[202:205], v[230:233], v[24:27]
	v_mfma_f32_16x16x32_bf16 v[20:23], v[202:205], v[242:245], v[20:23]
	v_mfma_f32_16x16x32_bf16 v[16:19], v[210:213], v[230:233], v[16:19]
	v_mfma_f32_16x16x32_bf16 v[12:15], v[210:213], v[242:245], v[12:15]
	v_mfma_f32_16x16x32_bf16 v[8:11], v[218:221], v[230:233], v[8:11]
	v_mfma_f32_16x16x32_bf16 v[4:7], v[218:221], v[242:245], v[4:7]
	s_add_i32 s1, s1, 2
	s_add_u32 s12, s12, 0x100
	s_addc_u32 s13, s13, 0
	s_cmp_lt_u32 s1, 12
	s_barrier
	s_cbranch_scc0 .Lpk_exit_3
; #define LDA8(dst, b, h) _Pragma("unroll") for (int m = 0; m < 4; ++m) _Pragma("unroll") for (int k = 0; k < 2; ++k) \
;     dst[m][k] = *(const bf16x8*)((const char*)SA8(b, h) + lds_byte8(wr * 64 + m * 16 + fr, k * 32 + fq * 8))
; #define LDB8(dst, b, h) _Pragma("unroll") for (int n = 0; n < 2; ++n) _Pragma("unroll") for (int k = 0; k < 2; ++k) \
;     dst[n][k] = *(const bf16x8*)((const char*)SB8(b, h) + lds_byte8(wc * 32 + n * 16 + fr, k * 32 + fq * 8))
; #define WAIT_V8(n) asm volatile("s_waitcnt vmcnt(" #n ")" ::: "memory")
; #define WAIT_L8(n) asm volatile("s_waitcnt lgkmcnt(" #n ")" ::: "memory")
; #define BAR8 __builtin_amdgcn_s_barrier()
; #define SCHED8 __builtin_amdgcn_sched_barrier(0)
;     ...
;   for (int tt = 0; tt < nt - 2; tt += 2) {
;     LDB8(B0, 0, 0); SCHED8; LDA8(At, 0, 0); STAGE8(SA8(1, 1), A, lda, brow + 128, tt + 1);
;     WAIT_L8(8); BAR8; WAIT_L8(0); MMA8(0, 0, At, B0); BAR8; SCHED8;
;     LDB8(B1, 0, 1); STAGE8(SB8(0, 0), Bt, K, bcol, tt + 2);
;     BAR8; WAIT_L8(0); MMA8(0, 1, At, B1); BAR8;
;     LDA8(At, 0, 1); STAGE8(SA8(0, 0), A, lda, brow, tt + 2);
;     BAR8; WAIT_L8(0); MMA8(1, 0, At, B0); BAR8; SCHED8;
;     STAGE8(SB8(0, 1), Bt, K, bcol + 128, tt + 2);
;     WAIT_V8(6); BAR8; MMA8(1, 1, At, B1); BAR8;
.LBB0_1005:
	ds_read_b128 v[174:177], v171
	ds_read_b128 v[178:181], v171 offset:1024
	ds_read_b128 v[182:185], v171 offset:2048
	ds_read_b128 v[186:189], v171 offset:3072
	v_lshl_add_u64 v[222:223], v[140:141], 0, s[12:13]
	v_lshl_add_u64 v[226:227], v[222:223], 0, s[20:21]
	s_or_b32 m0, s100, 0xc000
	v_lshl_add_u64 v[236:237], v[138:139], 0, s[12:13]
	ds_read_b128 v[190:193], v156
	ds_read_b128 v[194:197], v156 offset:1024
	ds_read_b128 v[198:201], v155
	ds_read_b128 v[202:205], v155 offset:1024
	ds_read_b128 v[206:209], v154
	ds_read_b128 v[210:213], v154 offset:1024
	ds_read_b128 v[214:217], v153
	ds_read_b128 v[218:221], v153 offset:1024
	global_load_lds_dwordx4 v[226:227], off
	s_or_b32 m0, s100, 0xe000
	v_lshl_add_u64 v[226:227], v[236:237], 0, s[20:21]
	global_load_lds_dwordx4 v[226:227], off
	s_waitcnt lgkmcnt(8)
	s_barrier
	s_waitcnt lgkmcnt(0)
	v_mfma_f32_16x16x32_bf16 v[128:131], v[190:193], v[174:177], v[128:131]
	v_mfma_f32_16x16x32_bf16 v[124:127], v[190:193], v[182:185], v[124:127]
	v_mfma_f32_16x16x32_bf16 v[120:123], v[198:201], v[174:177], v[120:123]
	v_mfma_f32_16x16x32_bf16 v[116:119], v[198:201], v[182:185], v[116:119]
	v_mfma_f32_16x16x32_bf16 v[112:115], v[206:209], v[174:177], v[112:115]
	v_mfma_f32_16x16x32_bf16 v[108:111], v[206:209], v[182:185], v[108:111]
	v_mfma_f32_16x16x32_bf16 v[104:107], v[214:217], v[174:177], v[104:107]
	v_mfma_f32_16x16x32_bf16 v[100:103], v[214:217], v[182:185], v[100:103]
	v_mfma_f32_16x16x32_bf16 v[128:131], v[194:197], v[178:181], v[128:131]
	v_mfma_f32_16x16x32_bf16 v[124:127], v[194:197], v[186:189], v[124:127]
	v_mfma_f32_16x16x32_bf16 v[120:123], v[202:205], v[178:181], v[120:123]
	v_mfma_f32_16x16x32_bf16 v[116:119], v[202:205], v[186:189], v[116:119]
	v_mfma_f32_16x16x32_bf16 v[112:115], v[210:213], v[178:181], v[112:115]
	v_mfma_f32_16x16x32_bf16 v[108:111], v[210:213], v[186:189], v[108:111]
	v_mfma_f32_16x16x32_bf16 v[104:107], v[218:221], v[178:181], v[104:107]
	v_mfma_f32_16x16x32_bf16 v[100:103], v[218:221], v[186:189], v[100:103]
	s_barrier
	v_lshl_add_u64 v[246:247], v[142:143], 0, s[12:13]
	v_lshl_add_u64 v[248:249], v[246:247], 0, s[40:41]
	s_or_b32 m0, s100, 0x10000
	ds_read_b128 v[226:229], v168
	ds_read_b128 v[230:233], v168 offset:1024
	ds_read_b128 v[238:241], v168 offset:2048
	ds_read_b128 v[242:245], v168 offset:3072
	global_load_lds_dwordx4 v[248:249], off
	v_lshl_add_u64 v[248:249], v[144:145], 0, s[12:13]
	s_or_b32 m0, s100, 0x12000
	v_lshl_add_u64 v[250:251], v[248:249], 0, s[40:41]
	global_load_lds_dwordx4 v[250:251], off
	s_barrier
	s_waitcnt lgkmcnt(0)
	v_mfma_f32_16x16x32_bf16 v[96:99], v[190:193], v[226:229], v[96:99]
	v_mfma_f32_16x16x32_bf16 v[92:95], v[190:193], v[238:241], v[92:95]
	v_mfma_f32_16x16x32_bf16 v[88:91], v[198:201], v[226:229], v[88:91]
	v_mfma_f32_16x16x32_bf16 v[84:87], v[198:201], v[238:241], v[84:87]
	v_mfma_f32_16x16x32_bf16 v[80:83], v[206:209], v[226:229], v[80:83]
	v_mfma_f32_16x16x32_bf16 v[76:79], v[206:209], v[238:241], v[76:79]
	v_mfma_f32_16x16x32_bf16 v[72:75], v[214:217], v[226:229], v[72:75]
	v_mfma_f32_16x16x32_bf16 v[68:71], v[214:217], v[238:241], v[68:71]
	v_mfma_f32_16x16x32_bf16 v[96:99], v[194:197], v[230:233], v[96:99]
	v_mfma_f32_16x16x32_bf16 v[92:95], v[194:197], v[242:245], v[92:95]
	v_mfma_f32_16x16x32_bf16 v[88:91], v[202:205], v[230:233], v[88:91]
	v_mfma_f32_16x16x32_bf16 v[84:87], v[202:205], v[242:245], v[84:87]
	v_mfma_f32_16x16x32_bf16 v[80:83], v[210:213], v[230:233], v[80:83]
	v_mfma_f32_16x16x32_bf16 v[76:79], v[210:213], v[242:245], v[76:79]
	v_mfma_f32_16x16x32_bf16 v[72:75], v[218:221], v[230:233], v[72:75]
	v_mfma_f32_16x16x32_bf16 v[68:71], v[218:221], v[242:245], v[68:71]
	v_lshl_add_u64 v[250:251], v[222:223], 0, s[42:43]
	s_mov_b32 m0, s100
	s_barrier
	ds_read_b128 v[190:193], v156 offset:16384
	ds_read_b128 v[194:197], v156 offset:17408
	ds_read_b128 v[198:201], v155 offset:16384
	ds_read_b128 v[202:205], v155 offset:17408
	ds_read_b128 v[206:209], v154 offset:16384
	ds_read_b128 v[210:213], v154 offset:17408
	ds_read_b128 v[214:217], v153 offset:16384
	ds_read_b128 v[218:221], v153 offset:17408
	global_load_lds_dwordx4 v[250:251], off
	s_or_b32 m0, s100, 0x2000
	v_lshl_add_u64 v[250:251], v[236:237], 0, s[42:43]
	global_load_lds_dwordx4 v[250:251], off
	s_barrier
	s_waitcnt lgkmcnt(0)
	v_mfma_f32_16x16x32_bf16 v[64:67], v[190:193], v[174:177], v[64:67]
	v_mfma_f32_16x16x32_bf16 v[60:63], v[190:193], v[182:185], v[60:63]
	v_mfma_f32_16x16x32_bf16 v[56:59], v[198:201], v[174:177], v[56:59]
	v_mfma_f32_16x16x32_bf16 v[52:55], v[198:201], v[182:185], v[52:55]
	v_mfma_f32_16x16x32_bf16 v[48:51], v[206:209], v[174:177], v[48:51]
	v_mfma_f32_16x16x32_bf16 v[44:47], v[206:209], v[182:185], v[44:47]
	v_mfma_f32_16x16x32_bf16 v[40:43], v[214:217], v[174:177], v[40:43]
	v_mfma_f32_16x16x32_bf16 v[36:39], v[214:217], v[182:185], v[36:39]
	v_mfma_f32_16x16x32_bf16 v[64:67], v[194:197], v[178:181], v[64:67]
	v_mfma_f32_16x16x32_bf16 v[60:63], v[194:197], v[186:189], v[60:63]
	v_mfma_f32_16x16x32_bf16 v[56:59], v[202:205], v[178:181], v[56:59]
	v_mfma_f32_16x16x32_bf16 v[52:55], v[202:205], v[186:189], v[52:55]
	v_mfma_f32_16x16x32_bf16 v[48:51], v[210:213], v[178:181], v[48:51]
	v_mfma_f32_16x16x32_bf16 v[44:47], v[210:213], v[186:189], v[44:47]
	v_mfma_f32_16x16x32_bf16 v[40:43], v[218:221], v[178:181], v[40:43]
	v_mfma_f32_16x16x32_bf16 v[36:39], v[218:221], v[186:189], v[36:39]
	s_barrier
	s_or_b32 m0, s100, 0x14000
	v_lshl_add_u64 v[174:175], v[246:247], 0, s[44:45]
	global_load_lds_dwordx4 v[174:175], off
	s_or_b32 m0, s100, 0x16000
	v_lshl_add_u64 v[174:175], v[248:249], 0, s[44:45]
	global_load_lds_dwordx4 v[174:175], off
	s_waitcnt vmcnt(6)
	s_barrier
; #define LDA8(dst, b, h) _Pragma("unroll") for (int m = 0; m < 4; ++m) _Pragma("unroll") for (int k = 0; k < 2; ++k) \
;     dst[m][k] = *(const bf16x8*)((const char*)SA8(b, h) + lds_byte8(wr * 64 + m * 16 + fr, k * 32 + fq * 8))
; #define LDB8(dst, b, h) _Pragma("unroll") for (int n = 0; n < 2; ++n) _Pragma("unroll") for (int k = 0; k < 2; ++k) \
;     dst[n][k] = *(const bf16x8*)((const char*)SB8(b, h) + lds_byte8(wc * 32 + n * 16 + fr, k * 32 + fq * 8))
; #define WAIT_V8(n) asm volatile("s_waitcnt vmcnt(" #n ")" ::: "memory")
; #define WAIT_L8(n) asm volatile("s_waitcnt lgkmcnt(" #n ")" ::: "memory")
; #define BAR8 __builtin_amdgcn_s_barrier()
; #define SCHED8 __builtin_amdgcn_sched_barrier(0)
;     ...
;     WAIT_V8(6); BAR8; MMA8(1, 1, At, B1); BAR8;
;     LDB8(B0, 1, 0); SCHED8; LDA8(At, 1, 0); STAGE8(SA8(0, 1), A, lda, brow + 128, tt + 2);
;     WAIT_L8(8); BAR8; WAIT_L8(0); MMA8(0, 0, At, B0); BAR8; SCHED8;
;     LDB8(B1, 1, 1); STAGE8(SB8(1, 0), Bt, K, bcol, tt + 3);
;     BAR8; WAIT_L8(0); MMA8(0, 1, At, B1); BAR8;
;     LDA8(At, 1, 1); STAGE8(SA8(1, 0), A, lda, brow, tt + 3);
;     BAR8; WAIT_L8(0); MMA8(1, 0, At, B0); BAR8; SCHED8;
	v_mfma_f32_16x16x32_bf16 v[32:35], v[190:193], v[226:229], v[32:35]
	v_mfma_f32_16x16x32_bf16 v[28:31], v[190:193], v[238:241], v[28:31]
	v_mfma_f32_16x16x32_bf16 v[24:27], v[198:201], v[226:229], v[24:27]
	v_mfma_f32_16x16x32_bf16 v[20:23], v[198:201], v[238:241], v[20:23]
	v_mfma_f32_16x16x32_bf16 v[16:19], v[206:209], v[226:229], v[16:19]
	v_mfma_f32_16x16x32_bf16 v[12:15], v[206:209], v[238:241], v[12:15]
	v_mfma_f32_16x16x32_bf16 v[8:11], v[214:217], v[226:229], v[8:11]
	v_mfma_f32_16x16x32_bf16 v[4:7], v[214:217], v[238:241], v[4:7]
	v_mfma_f32_16x16x32_bf16 v[32:35], v[194:197], v[230:233], v[32:35]
	v_mfma_f32_16x16x32_bf16 v[28:31], v[194:197], v[242:245], v[28:31]
	v_mfma_f32_16x16x32_bf16 v[24:27], v[202:205], v[230:233], v[24:27]
	v_mfma_f32_16x16x32_bf16 v[20:23], v[202:205], v[242:245], v[20:23]
	v_mfma_f32_16x16x32_bf16 v[16:19], v[210:213], v[230:233], v[16:19]
	v_mfma_f32_16x16x32_bf16 v[12:15], v[210:213], v[242:245], v[12:15]
	v_mfma_f32_16x16x32_bf16 v[8:11], v[218:221], v[230:233], v[8:11]
	v_mfma_f32_16x16x32_bf16 v[4:7], v[218:221], v[242:245], v[4:7]
	s_barrier
	ds_read_b128 v[174:177], v161
	ds_read_b128 v[178:181], v161 offset:1024
	ds_read_b128 v[182:185], v161 offset:2048
	ds_read_b128 v[186:189], v161 offset:3072
	v_lshl_add_u64 v[226:227], v[222:223], 0, s[46:47]
	s_or_b32 m0, s100, 0x4000
	ds_read_b128 v[190:193], v156 offset:32768
	ds_read_b128 v[194:197], v156 offset:33792
	ds_read_b128 v[198:201], v155 offset:32768
	ds_read_b128 v[202:205], v155 offset:33792
	ds_read_b128 v[206:209], v154 offset:32768
	ds_read_b128 v[210:213], v154 offset:33792
	ds_read_b128 v[214:217], v153 offset:32768
	ds_read_b128 v[218:221], v153 offset:33792
	global_load_lds_dwordx4 v[226:227], off
	s_or_b32 m0, s100, 0x6000
	v_lshl_add_u64 v[226:227], v[236:237], 0, s[46:47]
	global_load_lds_dwordx4 v[226:227], off
	s_waitcnt lgkmcnt(8)
	s_barrier
	s_waitcnt lgkmcnt(0)
	v_mfma_f32_16x16x32_bf16 v[128:131], v[190:193], v[174:177], v[128:131]
	v_mfma_f32_16x16x32_bf16 v[124:127], v[190:193], v[182:185], v[124:127]
	v_mfma_f32_16x16x32_bf16 v[120:123], v[198:201], v[174:177], v[120:123]
	v_mfma_f32_16x16x32_bf16 v[116:119], v[198:201], v[182:185], v[116:119]
	v_mfma_f32_16x16x32_bf16 v[112:115], v[206:209], v[174:177], v[112:115]
	v_mfma_f32_16x16x32_bf16 v[108:111], v[206:209], v[182:185], v[108:111]
	v_mfma_f32_16x16x32_bf16 v[104:107], v[214:217], v[174:177], v[104:107]
	v_mfma_f32_16x16x32_bf16 v[100:103], v[214:217], v[182:185], v[100:103]
	v_mfma_f32_16x16x32_bf16 v[128:131], v[194:197], v[178:181], v[128:131]
	v_mfma_f32_16x16x32_bf16 v[124:127], v[194:197], v[186:189], v[124:127]
	v_mfma_f32_16x16x32_bf16 v[120:123], v[202:205], v[178:181], v[120:123]
	v_mfma_f32_16x16x32_bf16 v[116:119], v[202:205], v[186:189], v[116:119]
	v_mfma_f32_16x16x32_bf16 v[112:115], v[210:213], v[178:181], v[112:115]
	v_mfma_f32_16x16x32_bf16 v[108:111], v[210:213], v[186:189], v[108:111]
	v_mfma_f32_16x16x32_bf16 v[104:107], v[218:221], v[178:181], v[104:107]
	v_mfma_f32_16x16x32_bf16 v[100:103], v[218:221], v[186:189], v[100:103]
	s_barrier
	v_lshl_add_u64 v[250:251], v[246:247], 0, s[48:49]
	s_or_b32 m0, s100, 0x18000
	ds_read_b128 v[226:229], v158
	ds_read_b128 v[230:233], v158 offset:1024
	ds_read_b128 v[238:241], v158 offset:2048
	ds_read_b128 v[242:245], v158 offset:3072
	global_load_lds_dwordx4 v[250:251], off
	s_or_b32 m0, s100, 0x1a000
	v_lshl_add_u64 v[250:251], v[248:249], 0, s[48:49]
	global_load_lds_dwordx4 v[250:251], off
	s_barrier
	s_waitcnt lgkmcnt(0)
	v_mfma_f32_16x16x32_bf16 v[96:99], v[190:193], v[226:229], v[96:99]
	v_mfma_f32_16x16x32_bf16 v[92:95], v[190:193], v[238:241], v[92:95]
	v_mfma_f32_16x16x32_bf16 v[88:91], v[198:201], v[226:229], v[88:91]
	v_mfma_f32_16x16x32_bf16 v[84:87], v[198:201], v[238:241], v[84:87]
	v_mfma_f32_16x16x32_bf16 v[80:83], v[206:209], v[226:229], v[80:83]
	v_mfma_f32_16x16x32_bf16 v[76:79], v[206:209], v[238:241], v[76:79]
	v_mfma_f32_16x16x32_bf16 v[72:75], v[214:217], v[226:229], v[72:75]
	v_mfma_f32_16x16x32_bf16 v[68:71], v[214:217], v[238:241], v[68:71]
	v_mfma_f32_16x16x32_bf16 v[96:99], v[194:197], v[230:233], v[96:99]
	v_mfma_f32_16x16x32_bf16 v[92:95], v[194:197], v[242:245], v[92:95]
	v_mfma_f32_16x16x32_bf16 v[88:91], v[202:205], v[230:233], v[88:91]
	v_mfma_f32_16x16x32_bf16 v[84:87], v[202:205], v[242:245], v[84:87]
	v_mfma_f32_16x16x32_bf16 v[80:83], v[210:213], v[230:233], v[80:83]
	v_mfma_f32_16x16x32_bf16 v[76:79], v[210:213], v[242:245], v[76:79]
	v_mfma_f32_16x16x32_bf16 v[72:75], v[218:221], v[230:233], v[72:75]
	v_mfma_f32_16x16x32_bf16 v[68:71], v[218:221], v[242:245], v[68:71]
	v_lshl_add_u64 v[222:223], v[222:223], 0, s[50:51]
	s_or_b32 m0, s100, 0x8000
	s_barrier
	ds_read_b128 v[190:193], v156 offset:49152
	ds_read_b128 v[194:197], v156 offset:50176
	ds_read_b128 v[198:201], v155 offset:49152
	ds_read_b128 v[202:205], v155 offset:50176
	ds_read_b128 v[206:209], v154 offset:49152
	ds_read_b128 v[210:213], v154 offset:50176
	ds_read_b128 v[214:217], v153 offset:49152
	ds_read_b128 v[218:221], v153 offset:50176
	global_load_lds_dwordx4 v[222:223], off
	s_or_b32 m0, s100, 0xa000
	v_lshl_add_u64 v[222:223], v[236:237], 0, s[50:51]
	global_load_lds_dwordx4 v[222:223], off
	s_barrier
; #define LDA8(dst, b, h) _Pragma("unroll") for (int m = 0; m < 4; ++m) _Pragma("unroll") for (int k = 0; k < 2; ++k) \
;     dst[m][k] = *(const bf16x8*)((const char*)SA8(b, h) + lds_byte8(wr * 64 + m * 16 + fr, k * 32 + fq * 8))
; #define LDB8(dst, b, h) _Pragma("unroll") for (int n = 0; n < 2; ++n) _Pragma("unroll") for (int k = 0; k < 2; ++k) \
;     dst[n][k] = *(const bf16x8*)((const char*)SB8(b, h) + lds_byte8(wc * 32 + n * 16 + fr, k * 32 + fq * 8))
; #define WAIT_V8(n) asm volatile("s_waitcnt vmcnt(" #n ")" ::: "memory")
; #define WAIT_L8(n) asm volatile("s_waitcnt lgkmcnt(" #n ")" ::: "memory")
; #define BAR8 __builtin_amdgcn_s_barrier()
; #define SCHED8 __builtin_amdgcn_sched_barrier(0)
;     ...
;     BAR8; WAIT_L8(0); MMA8(1, 0, At, B0); BAR8; SCHED8;
;     STAGE8(SB8(1, 1), Bt, K, bcol + 128, tt + 3);
;     WAIT_V8(6); BAR8; MMA8(1, 1, At, B1); BAR8;
;   }
;   { LDB8(B0, 0, 0); LDA8(At, 0, 0); STAGE8(SA8(1, 1), A, lda, brow + 128, nt - 1);
;     BAR8; WAIT_L8(0); MMA8(0, 0, At, B0); BAR8;
;     LDB8(B1, 0, 1); BAR8; WAIT_L8(0); MMA8(0, 1, At, B1); BAR8;
	s_waitcnt lgkmcnt(0)
	v_mfma_f32_16x16x32_bf16 v[64:67], v[190:193], v[174:177], v[64:67]
	v_mfma_f32_16x16x32_bf16 v[60:63], v[190:193], v[182:185], v[60:63]
	v_mfma_f32_16x16x32_bf16 v[56:59], v[198:201], v[174:177], v[56:59]
	v_mfma_f32_16x16x32_bf16 v[52:55], v[198:201], v[182:185], v[52:55]
	v_mfma_f32_16x16x32_bf16 v[48:51], v[206:209], v[174:177], v[48:51]
	v_mfma_f32_16x16x32_bf16 v[44:47], v[206:209], v[182:185], v[44:47]
	v_mfma_f32_16x16x32_bf16 v[40:43], v[214:217], v[174:177], v[40:43]
	v_mfma_f32_16x16x32_bf16 v[36:39], v[214:217], v[182:185], v[36:39]
	v_mfma_f32_16x16x32_bf16 v[64:67], v[194:197], v[178:181], v[64:67]
	v_mfma_f32_16x16x32_bf16 v[60:63], v[194:197], v[186:189], v[60:63]
	v_mfma_f32_16x16x32_bf16 v[56:59], v[202:205], v[178:181], v[56:59]
	v_mfma_f32_16x16x32_bf16 v[52:55], v[202:205], v[186:189], v[52:55]
	v_mfma_f32_16x16x32_bf16 v[48:51], v[210:213], v[178:181], v[48:51]
	v_mfma_f32_16x16x32_bf16 v[44:47], v[210:213], v[186:189], v[44:47]
	v_mfma_f32_16x16x32_bf16 v[40:43], v[218:221], v[178:181], v[40:43]
	v_mfma_f32_16x16x32_bf16 v[36:39], v[218:221], v[186:189], v[36:39]
	s_barrier
	s_or_b32 m0, s100, 0x1c000
	v_lshl_add_u64 v[174:175], v[246:247], 0, s[52:53]
	global_load_lds_dwordx4 v[174:175], off
	s_or_b32 m0, s100, 0x1e000
	v_lshl_add_u64 v[174:175], v[248:249], 0, s[52:53]
	global_load_lds_dwordx4 v[174:175], off
	s_waitcnt vmcnt(6)
	s_barrier
	v_mfma_f32_16x16x32_bf16 v[32:35], v[190:193], v[226:229], v[32:35]
	v_mfma_f32_16x16x32_bf16 v[28:31], v[190:193], v[238:241], v[28:31]
	v_mfma_f32_16x16x32_bf16 v[24:27], v[198:201], v[226:229], v[24:27]
	v_mfma_f32_16x16x32_bf16 v[20:23], v[198:201], v[238:241], v[20:23]
	v_mfma_f32_16x16x32_bf16 v[16:19], v[206:209], v[226:229], v[16:19]
	v_mfma_f32_16x16x32_bf16 v[12:15], v[206:209], v[238:241], v[12:15]
	v_mfma_f32_16x16x32_bf16 v[8:11], v[214:217], v[226:229], v[8:11]
	v_mfma_f32_16x16x32_bf16 v[4:7], v[214:217], v[238:241], v[4:7]
	v_mfma_f32_16x16x32_bf16 v[32:35], v[194:197], v[230:233], v[32:35]
	v_mfma_f32_16x16x32_bf16 v[28:31], v[194:197], v[242:245], v[28:31]
	v_mfma_f32_16x16x32_bf16 v[24:27], v[202:205], v[230:233], v[24:27]
	v_mfma_f32_16x16x32_bf16 v[20:23], v[202:205], v[242:245], v[20:23]
	v_mfma_f32_16x16x32_bf16 v[16:19], v[210:213], v[230:233], v[16:19]
	v_mfma_f32_16x16x32_bf16 v[12:15], v[210:213], v[242:245], v[12:15]
	v_mfma_f32_16x16x32_bf16 v[8:11], v[218:221], v[230:233], v[8:11]
	v_mfma_f32_16x16x32_bf16 v[4:7], v[218:221], v[242:245], v[4:7]
	s_add_i32 s1, s1, 2
	s_add_u32 s12, s12, 0x100
	s_addc_u32 s13, s13, 0
	s_cmp_lt_u32 s1, 12
	s_barrier
	s_cbranch_scc1 .LBB0_1005
.Lpk_exit_3:
	s_add_u32 s8, s8, 0x40780
	s_addc_u32 s9, s9, 0
	v_lshl_add_u64 v[132:133], s[8:9], 0, v[132:133]
	v_lshl_add_u64 v[0:1], v[0:1], 1, v[132:133]
	s_or_b32 m0, s100, 0xc000
	ds_read_b128 v[138:141], v171
	ds_read_b128 v[142:145], v171 offset:1024
	ds_read_b128 v[162:165], v171 offset:2048
	ds_read_b128 v[174:177], v171 offset:3072
	ds_read_b128 v[178:181], v156
	ds_read_b128 v[182:185], v156 offset:1024
	ds_read_b128 v[186:189], v155
	ds_read_b128 v[190:193], v155 offset:1024
	ds_read_b128 v[194:197], v154
	ds_read_b128 v[198:201], v154 offset:1024
	ds_read_b128 v[202:205], v153
	ds_read_b128 v[206:209], v153 offset:1024
	global_load_lds_dwordx4 v[0:1], off
	v_lshl_add_u64 v[0:1], s[8:9], 0, v[136:137]
	s_or_b32 m0, s100, 0xe000
	v_lshl_add_u64 v[0:1], v[134:135], 1, v[0:1]
	global_load_lds_dwordx4 v[0:1], off
	s_barrier
	s_waitcnt lgkmcnt(0)
	v_mfma_f32_16x16x32_bf16 v[128:131], v[178:181], v[138:141], v[128:131]
	v_mfma_f32_16x16x32_bf16 v[124:127], v[178:181], v[162:165], v[124:127]
	v_mfma_f32_16x16x32_bf16 v[120:123], v[186:189], v[138:141], v[120:123]
	v_mfma_f32_16x16x32_bf16 v[112:115], v[194:197], v[138:141], v[112:115]
	v_mfma_f32_16x16x32_bf16 v[128:131], v[182:185], v[142:145], v[128:131]
	v_mfma_f32_16x16x32_bf16 v[124:127], v[182:185], v[174:177], v[124:127]
	v_mfma_f32_16x16x32_bf16 v[120:123], v[190:193], v[142:145], v[120:123]
	v_mfma_f32_16x16x32_bf16 v[116:119], v[186:189], v[162:165], v[116:119]
	v_mfma_f32_16x16x32_bf16 v[112:115], v[198:201], v[142:145], v[112:115]
	v_mfma_f32_16x16x32_bf16 v[108:111], v[194:197], v[162:165], v[108:111]
	v_mfma_f32_16x16x32_bf16 v[104:107], v[202:205], v[138:141], v[104:107]
	v_mfma_f32_16x16x32_bf16 v[100:103], v[202:205], v[162:165], v[100:103]
	v_mfma_f32_16x16x32_bf16 v[132:135], v[190:193], v[174:177], v[116:119]
	v_mfma_f32_16x16x32_bf16 v[170:173], v[198:201], v[174:177], v[108:111]
	v_mfma_f32_16x16x32_bf16 v[210:213], v[206:209], v[142:145], v[104:107]
	v_mfma_f32_16x16x32_bf16 v[214:217], v[206:209], v[174:177], v[100:103]
	s_barrier
	s_nop 1
	ds_read_b128 v[100:103], v168
	ds_read_b128 v[104:107], v168 offset:1024
	ds_read_b128 v[108:111], v168 offset:2048
	ds_read_b128 v[116:119], v168 offset:3072
	s_barrier
	s_waitcnt lgkmcnt(0)
	v_mfma_f32_16x16x32_bf16 v[80:83], v[194:197], v[100:103], v[80:83]
	v_mfma_f32_16x16x32_bf16 v[76:79], v[194:197], v[108:111], v[76:79]
	v_mfma_f32_16x16x32_bf16 v[72:75], v[202:205], v[100:103], v[72:75]
	v_mfma_f32_16x16x32_bf16 v[68:71], v[202:205], v[108:111], v[68:71]
	v_mfma_f32_16x16x32_bf16 v[96:99], v[178:181], v[100:103], v[96:99]
	v_mfma_f32_16x16x32_bf16 v[92:95], v[178:181], v[108:111], v[92:95]
	v_mfma_f32_16x16x32_bf16 v[88:91], v[186:189], v[100:103], v[88:91]
	v_mfma_f32_16x16x32_bf16 v[84:87], v[186:189], v[108:111], v[84:87]
	v_mfma_f32_16x16x32_bf16 v[80:83], v[198:201], v[104:107], v[80:83]
	v_mfma_f32_16x16x32_bf16 v[76:79], v[198:201], v[116:119], v[76:79]
	v_mfma_f32_16x16x32_bf16 v[72:75], v[206:209], v[104:107], v[72:75]
	v_mfma_f32_16x16x32_bf16 v[68:71], v[206:209], v[116:119], v[68:71]
	v_mfma_f32_16x16x32_bf16 v[166:169], v[182:185], v[104:107], v[96:99]
	v_mfma_f32_16x16x32_bf16 v[178:181], v[182:185], v[116:119], v[92:95]
	v_mfma_f32_16x16x32_bf16 v[182:185], v[190:193], v[104:107], v[88:91]
	v_mfma_f32_16x16x32_bf16 v[186:189], v[190:193], v[116:119], v[84:87]
	s_barrier
; #define LDA8(dst, b, h) _Pragma("unroll") for (int m = 0; m < 4; ++m) _Pragma("unroll") for (int k = 0; k < 2; ++k) \
;     dst[m][k] = *(const bf16x8*)((const char*)SA8(b, h) + lds_byte8(wr * 64 + m * 16 + fr, k * 32 + fq * 8))
; #define LDB8(dst, b, h) _Pragma("unroll") for (int n = 0; n < 2; ++n) _Pragma("unroll") for (int k = 0; k < 2; ++k) \
;     dst[n][k] = *(const bf16x8*)((const char*)SB8(b, h) + lds_byte8(wc * 32 + n * 16 + fr, k * 32 + fq * 8))
; #define WAIT_V8(n) asm volatile("s_waitcnt vmcnt(" #n ")" ::: "memory")
; #define WAIT_L8(n) asm volatile("s_waitcnt lgkmcnt(" #n ")" ::: "memory")
; #define BAR8 __builtin_amdgcn_s_barrier()
;     ...
;     LDA8(At, 0, 1); WAIT_V8(4); BAR8; WAIT_L8(0); MMA8(1, 0, At, B0); MMA8(1, 1, At, B1); BAR8; }
;   { LDB8(B0, 1, 0); LDA8(At, 1, 0); WAIT_V8(2); BAR8; WAIT_L8(0); MMA8(0, 0, At, B0); BAR8;
	s_nop 0
	ds_read_b128 v[84:87], v156 offset:16384
	ds_read_b128 v[88:91], v156 offset:17408
	ds_read_b128 v[92:95], v155 offset:16384
	ds_read_b128 v[96:99], v155 offset:17408
	ds_read_b128 v[190:193], v154 offset:16384
	ds_read_b128 v[194:197], v154 offset:17408
	ds_read_b128 v[198:201], v153 offset:16384
	ds_read_b128 v[202:205], v153 offset:17408
	s_waitcnt vmcnt(4)
	s_barrier
	s_waitcnt lgkmcnt(0)
	v_mfma_f32_16x16x32_bf16 v[64:67], v[84:87], v[138:141], v[64:67]
	v_mfma_f32_16x16x32_bf16 v[60:63], v[84:87], v[162:165], v[60:63]
	v_mfma_f32_16x16x32_bf16 v[56:59], v[92:95], v[138:141], v[56:59]
	v_mfma_f32_16x16x32_bf16 v[52:55], v[92:95], v[162:165], v[52:55]
	v_mfma_f32_16x16x32_bf16 v[48:51], v[190:193], v[138:141], v[48:51]
	v_mfma_f32_16x16x32_bf16 v[44:47], v[190:193], v[162:165], v[44:47]
	v_mfma_f32_16x16x32_bf16 v[40:43], v[198:201], v[138:141], v[40:43]
	v_mfma_f32_16x16x32_bf16 v[36:39], v[198:201], v[162:165], v[36:39]
	v_mfma_f32_16x16x32_bf16 v[64:67], v[88:91], v[142:145], v[64:67]
	v_mfma_f32_16x16x32_bf16 v[60:63], v[88:91], v[174:177], v[60:63]
	v_mfma_f32_16x16x32_bf16 v[56:59], v[96:99], v[142:145], v[56:59]
	v_mfma_f32_16x16x32_bf16 v[52:55], v[96:99], v[174:177], v[52:55]
	v_mfma_f32_16x16x32_bf16 v[48:51], v[194:197], v[142:145], v[48:51]
	v_mfma_f32_16x16x32_bf16 v[44:47], v[194:197], v[174:177], v[44:47]
	v_mfma_f32_16x16x32_bf16 v[40:43], v[202:205], v[142:145], v[40:43]
	v_mfma_f32_16x16x32_bf16 v[36:39], v[202:205], v[174:177], v[36:39]
	v_mfma_f32_16x16x32_bf16 v[32:35], v[84:87], v[100:103], v[32:35]
	v_mfma_f32_16x16x32_bf16 v[28:31], v[84:87], v[108:111], v[28:31]
	v_mfma_f32_16x16x32_bf16 v[24:27], v[92:95], v[100:103], v[24:27]
	v_mfma_f32_16x16x32_bf16 v[20:23], v[92:95], v[108:111], v[20:23]
	v_mfma_f32_16x16x32_bf16 v[16:19], v[190:193], v[100:103], v[16:19]
	v_mfma_f32_16x16x32_bf16 v[12:15], v[190:193], v[108:111], v[12:15]
	v_mfma_f32_16x16x32_bf16 v[8:11], v[198:201], v[100:103], v[8:11]
	v_mfma_f32_16x16x32_bf16 v[4:7], v[198:201], v[108:111], v[4:7]
	v_mfma_f32_16x16x32_bf16 v[136:139], v[88:91], v[104:107], v[32:35]
	v_mfma_f32_16x16x32_bf16 v[140:143], v[88:91], v[116:119], v[28:31]
	v_mfma_f32_16x16x32_bf16 v[162:165], v[96:99], v[104:107], v[24:27]
	v_mfma_f32_16x16x32_bf16 v[174:177], v[96:99], v[116:119], v[20:23]
	v_mfma_f32_16x16x32_bf16 v[206:209], v[194:197], v[104:107], v[16:19]
	v_mfma_f32_16x16x32_bf16 v[190:193], v[194:197], v[116:119], v[12:15]
	v_mfma_f32_16x16x32_bf16 v[194:197], v[202:205], v[104:107], v[8:11]
	v_mfma_f32_16x16x32_bf16 v[198:201], v[202:205], v[116:119], v[4:7]
	s_barrier
	ds_read_b128 v[202:205], v161
	ds_read_b128 v[218:221], v161 offset:1024
	ds_read_b128 v[226:229], v161 offset:2048
	ds_read_b128 v[230:233], v161 offset:3072
	ds_read_b128 v[8:11], v156 offset:32768
	ds_read_b128 v[12:15], v156 offset:33792
	ds_read_b128 v[16:19], v155 offset:32768
	ds_read_b128 v[24:27], v155 offset:33792
	ds_read_b128 v[28:31], v154 offset:32768
	ds_read_b128 v[32:35], v154 offset:33792
	ds_read_b128 v[238:241], v153 offset:32768
	ds_read_b128 v[242:245], v153 offset:33792
	s_waitcnt vmcnt(2)
	s_barrier
	s_waitcnt lgkmcnt(0)
	v_mfma_f32_16x16x32_bf16 v[4:7], v[8:11], v[202:205], v[128:131]
	v_mfma_f32_16x16x32_bf16 v[104:107], v[12:15], v[218:221], v[4:7]
	v_mfma_f32_16x16x32_bf16 v[4:7], v[8:11], v[226:229], v[124:127]
	v_mfma_f32_16x16x32_bf16 v[116:119], v[12:15], v[230:233], v[4:7]
	v_mfma_f32_16x16x32_bf16 v[4:7], v[16:19], v[202:205], v[120:123]
	v_mfma_f32_16x16x32_bf16 v[100:103], v[24:27], v[218:221], v[4:7]
	v_mfma_f32_16x16x32_bf16 v[4:7], v[16:19], v[226:229], v[132:135]
	v_mfma_f32_16x16x32_bf16 v[108:111], v[24:27], v[230:233], v[4:7]
	v_mfma_f32_16x16x32_bf16 v[4:7], v[28:31], v[202:205], v[112:115]
	v_mfma_f32_16x16x32_bf16 v[92:95], v[32:35], v[218:221], v[4:7]
	v_mfma_f32_16x16x32_bf16 v[4:7], v[28:31], v[226:229], v[170:173]
	v_mfma_f32_16x16x32_bf16 v[96:99], v[32:35], v[230:233], v[4:7]
	v_mfma_f32_16x16x32_bf16 v[4:7], v[238:241], v[202:205], v[210:213]
	v_mfma_f32_16x16x32_bf16 v[84:87], v[242:245], v[218:221], v[4:7]
	v_mfma_f32_16x16x32_bf16 v[4:7], v[238:241], v[226:229], v[214:217]
	v_mfma_f32_16x16x32_bf16 v[88:91], v[242:245], v[230:233], v[4:7]
	s_barrier
; #define LDA8(dst, b, h) _Pragma("unroll") for (int m = 0; m < 4; ++m) _Pragma("unroll") for (int k = 0; k < 2; ++k) \
;     dst[m][k] = *(const bf16x8*)((const char*)SA8(b, h) + lds_byte8(wr * 64 + m * 16 + fr, k * 32 + fq * 8))
; #define LDB8(dst, b, h) _Pragma("unroll") for (int n = 0; n < 2; ++n) _Pragma("unroll") for (int k = 0; k < 2; ++k) \
;     dst[n][k] = *(const bf16x8*)((const char*)SB8(b, h) + lds_byte8(wc * 32 + n * 16 + fr, k * 32 + fq * 8))
; #define WAIT_V8(n) asm volatile("s_waitcnt vmcnt(" #n ")" ::: "memory")
; #define WAIT_L8(n) asm volatile("s_waitcnt lgkmcnt(" #n ")" ::: "memory")
; #define BAR8 __builtin_amdgcn_s_barrier()
;     ...
;     LDB8(B1, 1, 1); WAIT_V8(0); BAR8; WAIT_L8(0); MMA8(0, 1, At, B1); BAR8;
;     LDA8(At, 1, 1); BAR8; WAIT_L8(0); MMA8(1, 0, At, B0); MMA8(1, 1, At, B1); BAR8; }
;   if (wr == 0) BAR8;
;     ...
;   if (t < 256) {
	ds_read_b128 v[132:135], v158
	ds_read_b128 v[170:173], v158 offset:1024
	ds_read_b128 v[210:213], v158 offset:2048
	ds_read_b128 v[158:161], v158 offset:3072
	s_waitcnt vmcnt(0)
	s_barrier
	s_waitcnt lgkmcnt(0)
	v_mfma_f32_16x16x32_bf16 v[4:7], v[8:11], v[132:135], v[166:169]
	v_mfma_f32_16x16x32_bf16 v[8:11], v[8:11], v[210:213], v[178:181]
	v_mfma_f32_16x16x32_bf16 v[4:7], v[12:15], v[170:173], v[4:7]
	v_mfma_f32_16x16x32_bf16 v[20:23], v[12:15], v[158:161], v[8:11]
	v_mfma_f32_16x16x32_bf16 v[8:11], v[16:19], v[132:135], v[182:185]
	v_mfma_f32_16x16x32_bf16 v[12:15], v[16:19], v[210:213], v[186:189]
	v_mfma_f32_16x16x32_bf16 v[8:11], v[24:27], v[170:173], v[8:11]
	v_mfma_f32_16x16x32_bf16 v[24:27], v[24:27], v[158:161], v[12:15]
	v_mfma_f32_16x16x32_bf16 v[12:15], v[28:31], v[132:135], v[80:83]
	v_mfma_f32_16x16x32_bf16 v[16:19], v[28:31], v[210:213], v[76:79]
	v_mfma_f32_16x16x32_bf16 v[12:15], v[32:35], v[170:173], v[12:15]
	v_mfma_f32_16x16x32_bf16 v[28:31], v[32:35], v[158:161], v[16:19]
	v_mfma_f32_16x16x32_bf16 v[16:19], v[238:241], v[132:135], v[72:75]
	v_mfma_f32_16x16x32_bf16 v[32:35], v[238:241], v[210:213], v[68:71]
	v_mfma_f32_16x16x32_bf16 v[16:19], v[242:245], v[170:173], v[16:19]
	v_mfma_f32_16x16x32_bf16 v[32:35], v[242:245], v[158:161], v[32:35]
	s_barrier
	ds_read_b128 v[166:169], v156 offset:49152
	ds_read_b128 v[178:181], v156 offset:50176
	ds_read_b128 v[182:185], v155 offset:49152
	ds_read_b128 v[186:189], v155 offset:50176
	ds_read_b128 v[214:217], v154 offset:49152
	ds_read_b128 v[154:157], v154 offset:50176
	ds_read_b128 v[238:241], v153 offset:49152
	ds_read_b128 v[150:153], v153 offset:50176
	s_barrier
	s_waitcnt lgkmcnt(0)
	v_mfma_f32_16x16x32_bf16 v[64:67], v[166:169], v[202:205], v[64:67]
	v_mfma_f32_16x16x32_bf16 v[60:63], v[166:169], v[226:229], v[60:63]
	v_mfma_f32_16x16x32_bf16 v[56:59], v[182:185], v[202:205], v[56:59]
	v_mfma_f32_16x16x32_bf16 v[52:55], v[182:185], v[226:229], v[52:55]
	v_mfma_f32_16x16x32_bf16 v[48:51], v[214:217], v[202:205], v[48:51]
	v_mfma_f32_16x16x32_bf16 v[44:47], v[214:217], v[226:229], v[44:47]
	v_mfma_f32_16x16x32_bf16 v[40:43], v[238:241], v[202:205], v[40:43]
	v_mfma_f32_16x16x32_bf16 v[36:39], v[238:241], v[226:229], v[36:39]
	v_mfma_f32_16x16x32_bf16 v[128:131], v[178:181], v[218:221], v[64:67]
	v_mfma_f32_16x16x32_bf16 v[124:127], v[178:181], v[230:233], v[60:63]
	v_mfma_f32_16x16x32_bf16 v[120:123], v[186:189], v[218:221], v[56:59]
	v_mfma_f32_16x16x32_bf16 v[112:115], v[186:189], v[230:233], v[52:55]
	v_mfma_f32_16x16x32_bf16 v[80:83], v[154:157], v[218:221], v[48:51]
	v_mfma_f32_16x16x32_bf16 v[76:79], v[154:157], v[230:233], v[44:47]
	v_mfma_f32_16x16x32_bf16 v[72:75], v[150:153], v[218:221], v[40:43]
	v_mfma_f32_16x16x32_bf16 v[68:71], v[150:153], v[230:233], v[36:39]
	v_mfma_f32_16x16x32_bf16 v[36:39], v[166:169], v[132:135], v[136:139]
	v_mfma_f32_16x16x32_bf16 v[64:67], v[178:181], v[170:173], v[36:39]
	v_mfma_f32_16x16x32_bf16 v[36:39], v[166:169], v[210:213], v[140:143]
	v_mfma_f32_16x16x32_bf16 v[60:63], v[178:181], v[158:161], v[36:39]
	v_mfma_f32_16x16x32_bf16 v[36:39], v[182:185], v[132:135], v[162:165]
	v_mfma_f32_16x16x32_bf16 v[56:59], v[186:189], v[170:173], v[36:39]
	v_mfma_f32_16x16x32_bf16 v[36:39], v[182:185], v[210:213], v[174:177]
	v_mfma_f32_16x16x32_bf16 v[52:55], v[186:189], v[158:161], v[36:39]
	v_mfma_f32_16x16x32_bf16 v[36:39], v[214:217], v[132:135], v[206:209]
	v_mfma_f32_16x16x32_bf16 v[48:51], v[154:157], v[170:173], v[36:39]
	v_mfma_f32_16x16x32_bf16 v[36:39], v[214:217], v[210:213], v[190:193]
	v_mfma_f32_16x16x32_bf16 v[44:47], v[154:157], v[158:161], v[36:39]
	v_mfma_f32_16x16x32_bf16 v[36:39], v[238:241], v[132:135], v[194:197]
	v_mfma_f32_16x16x32_bf16 v[40:43], v[150:153], v[170:173], v[36:39]
	v_mfma_f32_16x16x32_bf16 v[36:39], v[238:241], v[210:213], v[198:201]
	v_mfma_f32_16x16x32_bf16 v[36:39], v[150:153], v[158:161], v[36:39]
	s_movk_i32 s1, 0x100
	v_cmp_gt_u32_e32 vcc, s1, v3
	s_barrier
	s_and_saveexec_b64 s[8:9], vcc
	s_cbranch_execz .LBB0_1008
	s_barrier

; #define BAR8 __builtin_amdgcn_s_barrier()
; #define G_SS ((float*)(wsp() + OFF_SS))
;     ...
;     STAGE8(SB8(0, 0), Bt, K, bcol, 0); STAGE8(SA8(0, 0), A, lda, brow, 0);
;     STAGE8(SB8(0, 1), Bt, K, bcol + 128, 0); STAGE8(SA8(0, 1), A, lda, brow + 128, 0);
;   }
;   if (wr == 1) BAR8;
; __global__ void __launch_bounds__(512, 2) mega(Params p) {
;     ...
;     for (int item = bid; item < 2 * 64 + 4 * 8; item += nb) {
;       if (item < 128) {
;         const int nt = item >> 6, mt = item & 63;
;         e.ss = G_SS; e.nss = 16; e.inv_n = 1.f / 1024.f; e.out = G_XQ; e.ldo = 512;
;         gemm_tile<EPI_PLAIN, 256, true>(G_XB, DM, wb + W_XQ, DM, mt * 256, nt * 256, e);
.LBB0_1011:
	s_and_b64 vcc, exec, s[0:1]
	s_cbranch_vccz .LBB0_1000
	s_mov_b32 s0, 25
	s_ashr_i32 s1, s0, 31
	s_lshl_b64 s[0:1], s[0:1], 3
	s_add_u32 s0, s70, s0
	s_addc_u32 s1, s71, s1
	v_readlane_b32 s6, v255, 60
	v_readlane_b32 s7, v255, 61
	s_nop 4
	s_mov_b32 s0, 25
	s_ashr_i32 s1, s0, 31
	s_lshl_b64 s[0:1], s[0:1], 3
	s_add_u32 s0, s70, s0
	s_addc_u32 s1, s71, s1
	v_readlane_b32 s2, v255, 60
	v_readlane_b32 s3, v255, 61
	s_nop 4
	s_mov_b32 s0, 25
	s_ashr_i32 s1, s0, 31
	s_lshl_b64 s[0:1], s[0:1], 3
	s_add_u32 s0, s70, s0
	s_addc_u32 s1, s71, s1
	v_mov_b32_e32 v3, v224
	v_readlane_b32 s12, v255, 60
	v_readlane_b32 s13, v255, 61
	s_nop 4
	s_lshl_b32 s0, s38, 8
	v_bfe_i32 v1, v3, 27, 1
	s_waitcnt vmcnt(10)
	v_lshlrev_b32_e32 v150, 4, v3
	s_nop 0
	v_readfirstlane_b32 s100, v150
	v_lshrrev_b32_e32 v1, 22, v1
	v_add_u32_e32 v1, v150, v1
	v_and_b32_e32 v1, 0xfffffc00, v1
	v_ashrrev_i32_e32 v0, 31, v3
	v_sub_u32_e32 v1, v150, v1
	v_lshrrev_b32_e32 v0, 26, v0
	v_lshrrev_b32_e32 v5, 4, v1
	v_add_u32_e32 v0, v3, v0
	v_bitop3_b32 v5, v5, v1, 32 bitop3:0x6c
	v_ashrrev_i32_e32 v1, 31, v1
	v_ashrrev_i32_e32 v0, 6, v0
	v_lshrrev_b32_e32 v1, 26, v1
	v_lshlrev_b32_e32 v6, 3, v0
	v_add_u32_e32 v1, v5, v1
	s_and_b32 s20, s0, 0x3f00
	s_lshl_b32 s0, s38, 2
	v_and_b32_e32 v6, -16, v6
	v_ashrrev_i32_e32 v1, 6, v1
	s_and_b32 s0, s0, 0xffffff00
	v_add_u32_e32 v6, v1, v6
	v_mul_i32_i24_e32 v1, 64, v1
	s_ashr_i32 s1, s0, 31
	v_lshlrev_b32_e32 v0, 5, v0
	v_sub_u32_e32 v1, v5, v1
	v_mov_b32_e32 v14, 1
	s_waitcnt vmcnt(9)
	v_add_u32_e32 v152, 0x2000, v150
	s_lshl_b64 s[8:9], s[0:1], 11
	v_and_b32_e32 v0, 32, v0
	v_ashrrev_i16_sdwa v1, v14, sext(v1) dst_sel:DWORD dst_unused:UNUSED_PAD src0_sel:DWORD src1_sel:BYTE_0
	v_ashrrev_i32_e32 v5, 31, v152
	s_add_u32 s8, s30, s8
	v_add_u32_sdwa v0, v0, sext(v1) dst_sel:DWORD dst_unused:UNUSED_PAD src0_sel:DWORD src1_sel:WORD_0
	v_ashrrev_i32_e32 v7, 31, v6
	v_lshrrev_b32_e32 v5, 22, v5
	s_addc_u32 s9, s31, s9
	v_lshlrev_b64 v[132:133], 11, v[6:7]
	v_ashrrev_i32_e32 v1, 31, v0
	v_add_u32_e32 v5, v152, v5
	v_lshl_add_u64 v[8:9], s[8:9], 0, v[132:133]
	v_lshlrev_b64 v[6:7], 1, v[0:1]
	v_ashrrev_i32_e32 v5, 10, v5
	v_lshl_add_u64 v[10:11], v[8:9], 0, v[6:7]
	v_mul_i32_i24_e32 v8, 0x400, v5
	v_sub_u32_e32 v8, v152, v8
	v_lshrrev_b32_e32 v9, 4, v8
	v_bitop3_b32 v9, v9, v8, 32 bitop3:0x6c
	v_ashrrev_i32_e32 v12, 31, v9
	v_lshrrev_b32_e32 v12, 26, v12
	v_add_u32_e32 v12, v9, v12
	v_lshlrev_b32_e32 v8, 3, v5
	v_ashrrev_i32_e32 v13, 6, v12
	v_and_b32_e32 v12, 0xc0, v12
	v_and_b32_e32 v8, -16, v8
	v_lshlrev_b32_e32 v5, 5, v5
	v_sub_u32_e32 v9, v9, v12
	v_add_u32_e32 v8, v13, v8
	v_and_b32_e32 v5, 32, v5
	v_ashrrev_i16_sdwa v9, v14, sext(v9) dst_sel:DWORD dst_unused:UNUSED_PAD src0_sel:DWORD src1_sel:BYTE_0
	v_add_u32_sdwa v134, v5, sext(v9) dst_sel:DWORD dst_unused:UNUSED_PAD src0_sel:DWORD src1_sel:WORD_0
	v_ashrrev_i32_e32 v9, 31, v8
	v_lshlrev_b64 v[136:137], 11, v[8:9]
	s_waitcnt vmcnt(8)
	v_mov_b32_e32 v4, v2
	s_or_b32 m0, s100, 0x10000
	v_lshl_add_u64 v[12:13], s[8:9], 0, v[136:137]
	global_load_lds_dwordx4 v[10:11], off
	s_or_b32 m0, s100, 0x12000
	s_lshl_b32 s8, s20, 11
	v_ashrrev_i32_e32 v135, 31, v134
	s_waitcnt lgkmcnt(0)
	s_add_u32 s8, s12, s8
	v_lshlrev_b64 v[8:9], 1, v[134:135]
	s_addc_u32 s9, s13, 0
	v_lshl_add_u64 v[12:13], v[12:13], 0, v[8:9]
	v_lshl_add_u64 v[14:15], s[8:9], 0, v[132:133]
	global_load_lds_dwordx4 v[12:13], off
	s_mov_b32 m0, s100
	v_lshl_add_u64 v[14:15], v[14:15], 0, v[6:7]
	global_load_lds_dwordx4 v[14:15], off
	s_or_b32 m0, s100, 0x2000
	s_or_b32 s14, s0, 0x80
	s_ashr_i32 s15, s14, 31
	s_lshl_b64 s[14:15], s[14:15], 11
	s_add_u32 s14, s30, s14
	v_lshl_add_u64 v[16:17], s[8:9], 0, v[136:137]
	s_addc_u32 s15, s31, s15
	v_lshl_add_u64 v[16:17], v[16:17], 0, v[8:9]
	v_lshl_add_u64 v[18:19], s[14:15], 0, v[132:133]
	global_load_lds_dwordx4 v[16:17], off
	v_lshl_add_u64 v[18:19], v[18:19], 0, v[6:7]
	s_or_b32 m0, s100, 0x14000
	v_lshl_add_u64 v[20:21], s[14:15], 0, v[136:137]
	global_load_lds_dwordx4 v[18:19], off
	s_or_b32 m0, s100, 0x16000
	s_add_u32 s14, s8, 0x40000
	s_addc_u32 s15, s9, 0
	v_lshl_add_u64 v[20:21], v[20:21], 0, v[8:9]
	v_lshl_add_u64 v[22:23], s[14:15], 0, v[132:133]
	global_load_lds_dwordx4 v[20:21], off
	v_lshl_add_u64 v[22:23], v[22:23], 0, v[6:7]
	s_or_b32 m0, s100, 0x4000
	global_load_lds_dwordx4 v[22:23], off
	v_lshl_add_u64 v[22:23], s[14:15], 0, v[136:137]
	v_lshl_add_u64 v[22:23], v[22:23], 0, v[8:9]
	s_or_b32 m0, s100, 0x6000
	v_ashrrev_i32_e32 v5, 8, v3
	global_load_lds_dwordx4 v[22:23], off
	v_cmp_eq_u32_e32 vcc, 1, v5
	s_and_saveexec_b64 s[14:15], vcc
	s_cbranch_execz .LBB0_1014
	s_barrier
; #define LDA8(dst, b, h) _Pragma("unroll") for (int m = 0; m < 4; ++m) _Pragma("unroll") for (int k = 0; k < 2; ++k) \
;     dst[m][k] = *(const bf16x8*)((const char*)SA8(b, h) + lds_byte8(wr * 64 + m * 16 + fr, k * 32 + fq * 8))
; #define LDB8(dst, b, h) _Pragma("unroll") for (int n = 0; n < 2; ++n) _Pragma("unroll") for (int k = 0; k < 2; ++k) \
;     dst[n][k] = *(const bf16x8*)((const char*)SB8(b, h) + lds_byte8(wc * 32 + n * 16 + fr, k * 32 + fq * 8))
; #define WAIT_V8(n) asm volatile("s_waitcnt vmcnt(" #n ")" ::: "memory")
; #define WAIT_L8(n) asm volatile("s_waitcnt lgkmcnt(" #n ")" ::: "memory")
; #define BAR8 __builtin_amdgcn_s_barrier()
; #define SCHED8 __builtin_amdgcn_sched_barrier(0)
;     ...
;   if (wr == 1) BAR8;
;   WAIT_V8(4); BAR8;
;   STAGE8(SB8(1, 0), Bt, K, bcol, 1); STAGE8(SA8(1, 0), A, lda, brow, 1); STAGE8(SB8(1, 1), Bt, K, bcol + 128, 1);
;   WAIT_V8(6); BAR8;
;   for (int tt = 0; tt < nt - 2; tt += 2) {
;     LDB8(B0, 0, 0); SCHED8; LDA8(At, 0, 0); STAGE8(SA8(1, 1), A, lda, brow + 128, tt + 1);
;     WAIT_L8(8); BAR8; WAIT_L8(0); MMA8(0, 0, At, B0); BAR8; SCHED8;
;     LDB8(B1, 0, 1); STAGE8(SB8(0, 0), Bt, K, bcol, tt + 2);
;     BAR8; WAIT_L8(0); MMA8(0, 1, At, B1); BAR8;
.LBB0_1014:
	s_or_b64 exec, exec, s[14:15]
	v_readlane_b32 s40, v254, 35
	v_readlane_b32 s42, v254, 37
	v_readlane_b32 s43, v254, 38
	s_waitcnt vmcnt(0)
	s_mov_b64 s[42:43], 0x80
	v_lshl_add_u64 v[10:11], v[10:11], 0, s[42:43]
	s_or_b32 m0, s100, 0x18000
	s_waitcnt vmcnt(4)
	s_barrier
	global_load_lds_dwordx4 v[10:11], off
	v_lshl_add_u64 v[10:11], v[12:13], 0, s[42:43]
	s_or_b32 m0, s100, 0x1a000
	global_load_lds_dwordx4 v[10:11], off
	v_lshl_add_u64 v[10:11], v[14:15], 0, s[42:43]
	s_or_b32 m0, s100, 0x8000
	global_load_lds_dwordx4 v[10:11], off
	v_lshl_add_u64 v[10:11], v[16:17], 0, s[42:43]
	s_or_b32 m0, s100, 0xa000
	global_load_lds_dwordx4 v[10:11], off
	s_or_b32 m0, s100, 0x1c000
	v_lshl_add_u64 v[10:11], v[18:19], 0, s[42:43]
	global_load_lds_dwordx4 v[10:11], off
	v_lshl_add_u64 v[10:11], v[20:21], 0, s[42:43]
	s_or_b32 m0, s100, 0x1e000
	v_and_b32_e32 v147, 15, v3
	global_load_lds_dwordx4 v[10:11], off
	v_bfe_u32 v148, v3, 4, 2
	v_lshlrev_b32_e32 v10, 4, v148
	v_lshlrev_b32_e32 v11, 6, v147
	v_lshlrev_b32_e32 v14, 2, v3
	v_or_b32_e32 v13, v10, v11
	v_and_b32_e32 v14, 32, v14
	s_mov_b32 s21, 0x10000
	v_bitop3_b32 v16, v13, s21, v14 bitop3:0xde
	s_mov_b32 s21, 0x14000
	s_and_b32 s14, s27, 63
	v_bitop3_b32 v15, v10, v14, v11 bitop3:0x36
	v_bitop3_b32 v17, v13, s21, v14 bitop3:0xde
	s_mov_b32 s21, 0x18000
	v_lshlrev_b32_e32 v11, 6, v3
	s_lshl_b32 s14, s14, 19
	s_mov_b32 s15, s40
	v_bitop3_b32 v18, v13, s21, v14 bitop3:0xde
	s_mov_b32 s21, 0x1c000
	v_and_b32_e32 v11, 0x3c0, v11
	v_bitop3_b32 v13, v13, s21, v14 bitop3:0xde
	v_bitop3_b32 v14, v11, v14, v10 bitop3:0x36
	v_lshl_add_u64 v[10:11], s[14:15], 0, v[136:137]
	v_readlane_b32 s41, v254, 36
	s_and_b32 s40, s33, 0xffffff00
	v_lshl_add_u64 v[10:11], v[10:11], 0, v[8:9]
	s_ashr_i32 s41, s40, 31
	v_lshl_add_u64 v[138:139], s[12:13], 0, v[10:11]
	v_lshl_add_u64 v[10:11], s[14:15], 0, v[132:133]
	s_lshl_b64 s[40:41], s[40:41], 11
	v_lshl_add_u64 v[10:11], v[10:11], 0, v[6:7]
	v_lshl_add_u64 v[140:141], s[12:13], 0, v[10:11]
	v_lshl_add_u64 v[10:11], s[40:41], 0, v[132:133]
	v_lshl_add_u64 v[6:7], v[10:11], 0, v[6:7]
	v_bfe_u32 v146, v3, 6, 2
	s_waitcnt vmcnt(6)
	v_lshlrev_b32_e32 v149, 6, v5
	v_lshlrev_b32_e32 v5, 13, v5
	v_lshl_add_u64 v[142:143], s[4:5], 0, v[6:7]
	v_lshl_add_u64 v[6:7], s[40:41], 0, v[136:137]
	v_lshlrev_b32_e32 v12, 12, v146
	v_or_b32_e32 v19, 0x800, v5
	v_or_b32_e32 v20, 0x1000, v5
	v_or_b32_e32 v21, 0x1800, v5
	v_lshl_add_u64 v[6:7], v[6:7], 0, v[8:9]
	v_lshl_add_u64 v[144:145], s[4:5], 0, v[6:7]
	s_mov_b32 s14, -2
	s_mov_b64 s[12:13], 0
	v_add_u32_e32 v171, v16, v12
	v_add_u32_e32 v156, v15, v5
	v_add_u32_e32 v155, v14, v19
	v_add_u32_e32 v154, v14, v20
	v_add_u32_e32 v153, v14, v21
	v_add_u32_e32 v168, v17, v12
	v_add_u32_e32 v161, v18, v12
	v_add_u32_e32 v158, v13, v12
	s_mov_b64 s[40:41], 0xc6a0100
	s_mov_b64 s[42:43], 0xc6e0100
	s_mov_b64 s[44:45], 0xc6a0180
	s_mov_b64 s[46:47], 0xc6e0180
	s_barrier
	ds_read_b128 v[174:177], v171
	ds_read_b128 v[178:181], v171 offset:1024
	ds_read_b128 v[182:185], v171 offset:2048
	ds_read_b128 v[186:189], v171 offset:3072
	v_lshl_add_u64 v[222:223], v[140:141], 0, s[12:13]
	v_lshl_add_u64 v[226:227], v[222:223], 0, s[34:35]
	s_or_b32 m0, s100, 0xc000
	v_lshl_add_u64 v[236:237], v[138:139], 0, s[12:13]
	ds_read_b128 v[190:193], v156
	ds_read_b128 v[194:197], v156 offset:1024
	ds_read_b128 v[198:201], v155
	ds_read_b128 v[202:205], v155 offset:1024
	ds_read_b128 v[206:209], v154
	ds_read_b128 v[210:213], v154 offset:1024
	ds_read_b128 v[214:217], v153
	ds_read_b128 v[218:221], v153 offset:1024
	global_load_lds_dwordx4 v[226:227], off
	s_or_b32 m0, s100, 0xe000
	v_lshl_add_u64 v[226:227], v[236:237], 0, s[34:35]
	global_load_lds_dwordx4 v[226:227], off
	s_waitcnt lgkmcnt(8)
	s_barrier
	s_waitcnt lgkmcnt(0)
	v_mfma_f32_16x16x32_f16 v[128:131], v[190:193], v[174:177], 0
	v_mfma_f32_16x16x32_f16 v[124:127], v[190:193], v[182:185], 0
	v_mfma_f32_16x16x32_f16 v[120:123], v[198:201], v[174:177], 0
	v_mfma_f32_16x16x32_f16 v[116:119], v[198:201], v[182:185], 0
	v_mfma_f32_16x16x32_f16 v[112:115], v[206:209], v[174:177], 0
	v_mfma_f32_16x16x32_f16 v[108:111], v[206:209], v[182:185], 0
	v_mfma_f32_16x16x32_f16 v[104:107], v[214:217], v[174:177], 0
	v_mfma_f32_16x16x32_f16 v[100:103], v[214:217], v[182:185], 0
	v_mfma_f32_16x16x32_f16 v[128:131], v[194:197], v[178:181], v[128:131]
	v_mfma_f32_16x16x32_f16 v[124:127], v[194:197], v[186:189], v[124:127]
	v_mfma_f32_16x16x32_f16 v[120:123], v[202:205], v[178:181], v[120:123]
	v_mfma_f32_16x16x32_f16 v[116:119], v[202:205], v[186:189], v[116:119]
	v_mfma_f32_16x16x32_f16 v[112:115], v[210:213], v[178:181], v[112:115]
	v_mfma_f32_16x16x32_f16 v[108:111], v[210:213], v[186:189], v[108:111]
	v_mfma_f32_16x16x32_f16 v[104:107], v[218:221], v[178:181], v[104:107]
	v_mfma_f32_16x16x32_f16 v[100:103], v[218:221], v[186:189], v[100:103]
	s_barrier
	v_lshl_add_u64 v[246:247], v[142:143], 0, s[12:13]
	v_lshl_add_u64 v[248:249], v[246:247], 0, s[40:41]
	s_or_b32 m0, s100, 0x10000
	ds_read_b128 v[226:229], v168
	ds_read_b128 v[230:233], v168 offset:1024
	ds_read_b128 v[238:241], v168 offset:2048
	ds_read_b128 v[242:245], v168 offset:3072
	global_load_lds_dwordx4 v[248:249], off
	v_lshl_add_u64 v[248:249], v[144:145], 0, s[12:13]
	s_or_b32 m0, s100, 0x12000
	v_lshl_add_u64 v[250:251], v[248:249], 0, s[40:41]
	global_load_lds_dwordx4 v[250:251], off
	s_barrier
; #define LDA8(dst, b, h) _Pragma("unroll") for (int m = 0; m < 4; ++m) _Pragma("unroll") for (int k = 0; k < 2; ++k) \
;     dst[m][k] = *(const bf16x8*)((const char*)SA8(b, h) + lds_byte8(wr * 64 + m * 16 + fr, k * 32 + fq * 8))
; #define LDB8(dst, b, h) _Pragma("unroll") for (int n = 0; n < 2; ++n) _Pragma("unroll") for (int k = 0; k < 2; ++k) \
;     dst[n][k] = *(const bf16x8*)((const char*)SB8(b, h) + lds_byte8(wc * 32 + n * 16 + fr, k * 32 + fq * 8))
; #define WAIT_V8(n) asm volatile("s_waitcnt vmcnt(" #n ")" ::: "memory")
; #define WAIT_L8(n) asm volatile("s_waitcnt lgkmcnt(" #n ")" ::: "memory")
; #define BAR8 __builtin_amdgcn_s_barrier()
; #define SCHED8 __builtin_amdgcn_sched_barrier(0)
;     ...
;     BAR8; WAIT_L8(0); MMA8(0, 1, At, B1); BAR8;
;     LDA8(At, 0, 1); STAGE8(SA8(0, 0), A, lda, brow, tt + 2);
;     BAR8; WAIT_L8(0); MMA8(1, 0, At, B0); BAR8; SCHED8;
;     STAGE8(SB8(0, 1), Bt, K, bcol + 128, tt + 2);
;     WAIT_V8(6); BAR8; MMA8(1, 1, At, B1); BAR8;
;     LDB8(B0, 1, 0); SCHED8; LDA8(At, 1, 0); STAGE8(SA8(0, 1), A, lda, brow + 128, tt + 2);
;     WAIT_L8(8); BAR8; WAIT_L8(0); MMA8(0, 0, At, B0); BAR8; SCHED8;
	s_waitcnt lgkmcnt(0)
	v_mfma_f32_16x16x32_f16 v[96:99], v[190:193], v[226:229], 0
	v_mfma_f32_16x16x32_f16 v[92:95], v[190:193], v[238:241], 0
	v_mfma_f32_16x16x32_f16 v[88:91], v[198:201], v[226:229], 0
	v_mfma_f32_16x16x32_f16 v[84:87], v[198:201], v[238:241], 0
	v_mfma_f32_16x16x32_f16 v[80:83], v[206:209], v[226:229], 0
	v_mfma_f32_16x16x32_f16 v[76:79], v[206:209], v[238:241], 0
	v_mfma_f32_16x16x32_f16 v[72:75], v[214:217], v[226:229], 0
	v_mfma_f32_16x16x32_f16 v[68:71], v[214:217], v[238:241], 0
	v_mfma_f32_16x16x32_f16 v[96:99], v[194:197], v[230:233], v[96:99]
	v_mfma_f32_16x16x32_f16 v[92:95], v[194:197], v[242:245], v[92:95]
	v_mfma_f32_16x16x32_f16 v[88:91], v[202:205], v[230:233], v[88:91]
	v_mfma_f32_16x16x32_f16 v[84:87], v[202:205], v[242:245], v[84:87]
	v_mfma_f32_16x16x32_f16 v[80:83], v[210:213], v[230:233], v[80:83]
	v_mfma_f32_16x16x32_f16 v[76:79], v[210:213], v[242:245], v[76:79]
	v_mfma_f32_16x16x32_f16 v[72:75], v[218:221], v[230:233], v[72:75]
	v_mfma_f32_16x16x32_f16 v[68:71], v[218:221], v[242:245], v[68:71]
	v_lshl_add_u64 v[250:251], v[222:223], 0, s[10:11]
	s_mov_b32 m0, s100
	s_barrier
	ds_read_b128 v[190:193], v156 offset:16384
	ds_read_b128 v[194:197], v156 offset:17408
	ds_read_b128 v[198:201], v155 offset:16384
	ds_read_b128 v[202:205], v155 offset:17408
	ds_read_b128 v[206:209], v154 offset:16384
	ds_read_b128 v[210:213], v154 offset:17408
	ds_read_b128 v[214:217], v153 offset:16384
	ds_read_b128 v[218:221], v153 offset:17408
	global_load_lds_dwordx4 v[250:251], off
	s_or_b32 m0, s100, 0x2000
	v_lshl_add_u64 v[250:251], v[236:237], 0, s[10:11]
	global_load_lds_dwordx4 v[250:251], off
	s_barrier
	s_waitcnt lgkmcnt(0)
	v_mfma_f32_16x16x32_f16 v[64:67], v[190:193], v[174:177], 0
	v_mfma_f32_16x16x32_f16 v[60:63], v[190:193], v[182:185], 0
	v_mfma_f32_16x16x32_f16 v[56:59], v[198:201], v[174:177], 0
	v_mfma_f32_16x16x32_f16 v[52:55], v[198:201], v[182:185], 0
	v_mfma_f32_16x16x32_f16 v[48:51], v[206:209], v[174:177], 0
	v_mfma_f32_16x16x32_f16 v[44:47], v[206:209], v[182:185], 0
	v_mfma_f32_16x16x32_f16 v[40:43], v[214:217], v[174:177], 0
	v_mfma_f32_16x16x32_f16 v[36:39], v[214:217], v[182:185], 0
	v_mfma_f32_16x16x32_f16 v[64:67], v[194:197], v[178:181], v[64:67]
	v_mfma_f32_16x16x32_f16 v[60:63], v[194:197], v[186:189], v[60:63]
	v_mfma_f32_16x16x32_f16 v[56:59], v[202:205], v[178:181], v[56:59]
	v_mfma_f32_16x16x32_f16 v[52:55], v[202:205], v[186:189], v[52:55]
	v_mfma_f32_16x16x32_f16 v[48:51], v[210:213], v[178:181], v[48:51]
	v_mfma_f32_16x16x32_f16 v[44:47], v[210:213], v[186:189], v[44:47]
	v_mfma_f32_16x16x32_f16 v[40:43], v[218:221], v[178:181], v[40:43]
	v_mfma_f32_16x16x32_f16 v[36:39], v[218:221], v[186:189], v[36:39]
	s_barrier
	s_or_b32 m0, s100, 0x14000
	v_lshl_add_u64 v[174:175], v[246:247], 0, s[42:43]
	global_load_lds_dwordx4 v[174:175], off
	s_or_b32 m0, s100, 0x16000
	v_lshl_add_u64 v[174:175], v[248:249], 0, s[42:43]
	global_load_lds_dwordx4 v[174:175], off
	s_waitcnt vmcnt(6)
	s_barrier
	v_mfma_f32_16x16x32_f16 v[32:35], v[190:193], v[226:229], 0
	v_mfma_f32_16x16x32_f16 v[28:31], v[190:193], v[238:241], 0
	v_mfma_f32_16x16x32_f16 v[24:27], v[198:201], v[226:229], 0
	v_mfma_f32_16x16x32_f16 v[20:23], v[198:201], v[238:241], 0
	v_mfma_f32_16x16x32_f16 v[16:19], v[206:209], v[226:229], 0
	v_mfma_f32_16x16x32_f16 v[12:15], v[206:209], v[238:241], 0
	v_mfma_f32_16x16x32_f16 v[8:11], v[214:217], v[226:229], 0
	v_mfma_f32_16x16x32_f16 v[4:7], v[214:217], v[238:241], 0
	v_mfma_f32_16x16x32_f16 v[32:35], v[194:197], v[230:233], v[32:35]
	v_mfma_f32_16x16x32_f16 v[28:31], v[194:197], v[242:245], v[28:31]
	v_mfma_f32_16x16x32_f16 v[24:27], v[202:205], v[230:233], v[24:27]
	v_mfma_f32_16x16x32_f16 v[20:23], v[202:205], v[242:245], v[20:23]
	v_mfma_f32_16x16x32_f16 v[16:19], v[210:213], v[230:233], v[16:19]
	v_mfma_f32_16x16x32_f16 v[12:15], v[210:213], v[242:245], v[12:15]
	v_mfma_f32_16x16x32_f16 v[8:11], v[218:221], v[230:233], v[8:11]
	v_mfma_f32_16x16x32_f16 v[4:7], v[218:221], v[242:245], v[4:7]
	s_barrier
	ds_read_b128 v[174:177], v161
	ds_read_b128 v[178:181], v161 offset:1024
	ds_read_b128 v[182:185], v161 offset:2048
	ds_read_b128 v[186:189], v161 offset:3072
	v_lshl_add_u64 v[226:227], v[222:223], 0, s[18:19]
	s_or_b32 m0, s100, 0x4000
	ds_read_b128 v[190:193], v156 offset:32768
	ds_read_b128 v[194:197], v156 offset:33792
	ds_read_b128 v[198:201], v155 offset:32768
	ds_read_b128 v[202:205], v155 offset:33792
	ds_read_b128 v[206:209], v154 offset:32768
	ds_read_b128 v[210:213], v154 offset:33792
	ds_read_b128 v[214:217], v153 offset:32768
	ds_read_b128 v[218:221], v153 offset:33792
	global_load_lds_dwordx4 v[226:227], off
	s_or_b32 m0, s100, 0x6000
	v_lshl_add_u64 v[226:227], v[236:237], 0, s[18:19]
	global_load_lds_dwordx4 v[226:227], off
	s_waitcnt lgkmcnt(8)
	s_barrier
	s_waitcnt lgkmcnt(0)
	v_mfma_f32_16x16x32_f16 v[128:131], v[190:193], v[174:177], v[128:131]
	v_mfma_f32_16x16x32_f16 v[124:127], v[190:193], v[182:185], v[124:127]
	v_mfma_f32_16x16x32_f16 v[120:123], v[198:201], v[174:177], v[120:123]
	v_mfma_f32_16x16x32_f16 v[116:119], v[198:201], v[182:185], v[116:119]
	v_mfma_f32_16x16x32_f16 v[112:115], v[206:209], v[174:177], v[112:115]
	v_mfma_f32_16x16x32_f16 v[108:111], v[206:209], v[182:185], v[108:111]
	v_mfma_f32_16x16x32_f16 v[104:107], v[214:217], v[174:177], v[104:107]
	v_mfma_f32_16x16x32_f16 v[100:103], v[214:217], v[182:185], v[100:103]
	v_mfma_f32_16x16x32_f16 v[128:131], v[194:197], v[178:181], v[128:131]
	v_mfma_f32_16x16x32_f16 v[124:127], v[194:197], v[186:189], v[124:127]
	v_mfma_f32_16x16x32_f16 v[120:123], v[202:205], v[178:181], v[120:123]
	v_mfma_f32_16x16x32_f16 v[116:119], v[202:205], v[186:189], v[116:119]
	v_mfma_f32_16x16x32_f16 v[112:115], v[210:213], v[178:181], v[112:115]
	v_mfma_f32_16x16x32_f16 v[108:111], v[210:213], v[186:189], v[108:111]
	v_mfma_f32_16x16x32_f16 v[104:107], v[218:221], v[178:181], v[104:107]
	v_mfma_f32_16x16x32_f16 v[100:103], v[218:221], v[186:189], v[100:103]
	s_barrier
; #define LDA8(dst, b, h) _Pragma("unroll") for (int m = 0; m < 4; ++m) _Pragma("unroll") for (int k = 0; k < 2; ++k) \
;     dst[m][k] = *(const bf16x8*)((const char*)SA8(b, h) + lds_byte8(wr * 64 + m * 16 + fr, k * 32 + fq * 8))
; #define LDB8(dst, b, h) _Pragma("unroll") for (int n = 0; n < 2; ++n) _Pragma("unroll") for (int k = 0; k < 2; ++k) \
;     dst[n][k] = *(const bf16x8*)((const char*)SB8(b, h) + lds_byte8(wc * 32 + n * 16 + fr, k * 32 + fq * 8))
; #define WAIT_V8(n) asm volatile("s_waitcnt vmcnt(" #n ")" ::: "memory")
; #define WAIT_L8(n) asm volatile("s_waitcnt lgkmcnt(" #n ")" ::: "memory")
; #define BAR8 __builtin_amdgcn_s_barrier()
; #define SCHED8 __builtin_amdgcn_sched_barrier(0)
;     ...
;     LDB8(B1, 1, 1); STAGE8(SB8(1, 0), Bt, K, bcol, tt + 3);
;     BAR8; WAIT_L8(0); MMA8(0, 1, At, B1); BAR8;
;     LDA8(At, 1, 1); STAGE8(SA8(1, 0), A, lda, brow, tt + 3);
;     BAR8; WAIT_L8(0); MMA8(1, 0, At, B0); BAR8; SCHED8;
;     STAGE8(SB8(1, 1), Bt, K, bcol + 128, tt + 3);
;     WAIT_V8(6); BAR8; MMA8(1, 1, At, B1); BAR8;
	v_lshl_add_u64 v[250:251], v[246:247], 0, s[44:45]
	s_or_b32 m0, s100, 0x18000
	ds_read_b128 v[226:229], v158
	ds_read_b128 v[230:233], v158 offset:1024
	ds_read_b128 v[238:241], v158 offset:2048
	ds_read_b128 v[242:245], v158 offset:3072
	global_load_lds_dwordx4 v[250:251], off
	s_or_b32 m0, s100, 0x1a000
	v_lshl_add_u64 v[250:251], v[248:249], 0, s[44:45]
	global_load_lds_dwordx4 v[250:251], off
	s_barrier
	s_waitcnt lgkmcnt(0)
	v_mfma_f32_16x16x32_f16 v[96:99], v[190:193], v[226:229], v[96:99]
	v_mfma_f32_16x16x32_f16 v[92:95], v[190:193], v[238:241], v[92:95]
	v_mfma_f32_16x16x32_f16 v[88:91], v[198:201], v[226:229], v[88:91]
	v_mfma_f32_16x16x32_f16 v[84:87], v[198:201], v[238:241], v[84:87]
	v_mfma_f32_16x16x32_f16 v[80:83], v[206:209], v[226:229], v[80:83]
	v_mfma_f32_16x16x32_f16 v[76:79], v[206:209], v[238:241], v[76:79]
	v_mfma_f32_16x16x32_f16 v[72:75], v[214:217], v[226:229], v[72:75]
	v_mfma_f32_16x16x32_f16 v[68:71], v[214:217], v[238:241], v[68:71]
	v_mfma_f32_16x16x32_f16 v[96:99], v[194:197], v[230:233], v[96:99]
	v_mfma_f32_16x16x32_f16 v[92:95], v[194:197], v[242:245], v[92:95]
	v_mfma_f32_16x16x32_f16 v[88:91], v[202:205], v[230:233], v[88:91]
	v_mfma_f32_16x16x32_f16 v[84:87], v[202:205], v[242:245], v[84:87]
	v_mfma_f32_16x16x32_f16 v[80:83], v[210:213], v[230:233], v[80:83]
	v_mfma_f32_16x16x32_f16 v[76:79], v[210:213], v[242:245], v[76:79]
	v_mfma_f32_16x16x32_f16 v[72:75], v[218:221], v[230:233], v[72:75]
	v_mfma_f32_16x16x32_f16 v[68:71], v[218:221], v[242:245], v[68:71]
	v_lshl_add_u64 v[222:223], v[222:223], 0, s[22:23]
	s_or_b32 m0, s100, 0x8000
	s_barrier
	ds_read_b128 v[190:193], v156 offset:49152
	ds_read_b128 v[194:197], v156 offset:50176
	ds_read_b128 v[198:201], v155 offset:49152
	ds_read_b128 v[202:205], v155 offset:50176
	ds_read_b128 v[206:209], v154 offset:49152
	ds_read_b128 v[210:213], v154 offset:50176
	ds_read_b128 v[214:217], v153 offset:49152
	ds_read_b128 v[218:221], v153 offset:50176
	global_load_lds_dwordx4 v[222:223], off
	s_or_b32 m0, s100, 0xa000
	v_lshl_add_u64 v[222:223], v[236:237], 0, s[22:23]
	global_load_lds_dwordx4 v[222:223], off
	s_barrier
	s_waitcnt lgkmcnt(0)
	v_mfma_f32_16x16x32_f16 v[64:67], v[190:193], v[174:177], v[64:67]
	v_mfma_f32_16x16x32_f16 v[60:63], v[190:193], v[182:185], v[60:63]
	v_mfma_f32_16x16x32_f16 v[56:59], v[198:201], v[174:177], v[56:59]
	v_mfma_f32_16x16x32_f16 v[52:55], v[198:201], v[182:185], v[52:55]
	v_mfma_f32_16x16x32_f16 v[48:51], v[206:209], v[174:177], v[48:51]
	v_mfma_f32_16x16x32_f16 v[44:47], v[206:209], v[182:185], v[44:47]
	v_mfma_f32_16x16x32_f16 v[40:43], v[214:217], v[174:177], v[40:43]
	v_mfma_f32_16x16x32_f16 v[36:39], v[214:217], v[182:185], v[36:39]
	v_mfma_f32_16x16x32_f16 v[64:67], v[194:197], v[178:181], v[64:67]
	v_mfma_f32_16x16x32_f16 v[60:63], v[194:197], v[186:189], v[60:63]
	v_mfma_f32_16x16x32_f16 v[56:59], v[202:205], v[178:181], v[56:59]
	v_mfma_f32_16x16x32_f16 v[52:55], v[202:205], v[186:189], v[52:55]
	v_mfma_f32_16x16x32_f16 v[48:51], v[210:213], v[178:181], v[48:51]
	v_mfma_f32_16x16x32_f16 v[44:47], v[210:213], v[186:189], v[44:47]
	v_mfma_f32_16x16x32_f16 v[40:43], v[218:221], v[178:181], v[40:43]
	v_mfma_f32_16x16x32_f16 v[36:39], v[218:221], v[186:189], v[36:39]
	s_barrier
	s_or_b32 m0, s100, 0x1c000
	v_lshl_add_u64 v[174:175], v[246:247], 0, s[46:47]
	global_load_lds_dwordx4 v[174:175], off
	s_or_b32 m0, s100, 0x1e000
	v_lshl_add_u64 v[174:175], v[248:249], 0, s[46:47]
	global_load_lds_dwordx4 v[174:175], off
	s_waitcnt vmcnt(6)
	s_barrier
	v_mfma_f32_16x16x32_f16 v[32:35], v[190:193], v[226:229], v[32:35]
	v_mfma_f32_16x16x32_f16 v[28:31], v[190:193], v[238:241], v[28:31]
	v_mfma_f32_16x16x32_f16 v[24:27], v[198:201], v[226:229], v[24:27]
	v_mfma_f32_16x16x32_f16 v[20:23], v[198:201], v[238:241], v[20:23]
	v_mfma_f32_16x16x32_f16 v[16:19], v[206:209], v[226:229], v[16:19]
	v_mfma_f32_16x16x32_f16 v[12:15], v[206:209], v[238:241], v[12:15]
	v_mfma_f32_16x16x32_f16 v[8:11], v[214:217], v[226:229], v[8:11]
	v_mfma_f32_16x16x32_f16 v[4:7], v[214:217], v[238:241], v[4:7]
	v_mfma_f32_16x16x32_f16 v[32:35], v[194:197], v[230:233], v[32:35]
	v_mfma_f32_16x16x32_f16 v[28:31], v[194:197], v[242:245], v[28:31]
	v_mfma_f32_16x16x32_f16 v[24:27], v[202:205], v[230:233], v[24:27]
	v_mfma_f32_16x16x32_f16 v[20:23], v[202:205], v[242:245], v[20:23]
	v_mfma_f32_16x16x32_f16 v[16:19], v[210:213], v[230:233], v[16:19]
	v_mfma_f32_16x16x32_f16 v[12:15], v[210:213], v[242:245], v[12:15]
	v_mfma_f32_16x16x32_f16 v[8:11], v[218:221], v[230:233], v[8:11]
	v_mfma_f32_16x16x32_f16 v[4:7], v[218:221], v[242:245], v[4:7]
	s_add_i32 s14, s14, 2
	s_add_u32 s12, s12, 0x100
	s_addc_u32 s13, s13, 0
	s_cmp_lt_u32 s14, 12
	s_barrier
	s_cbranch_scc0 .Lpk_exit_4
; #define LDA8(dst, b, h) _Pragma("unroll") for (int m = 0; m < 4; ++m) _Pragma("unroll") for (int k = 0; k < 2; ++k) \
;     dst[m][k] = *(const bf16x8*)((const char*)SA8(b, h) + lds_byte8(wr * 64 + m * 16 + fr, k * 32 + fq * 8))
; #define LDB8(dst, b, h) _Pragma("unroll") for (int n = 0; n < 2; ++n) _Pragma("unroll") for (int k = 0; k < 2; ++k) \
;     dst[n][k] = *(const bf16x8*)((const char*)SB8(b, h) + lds_byte8(wc * 32 + n * 16 + fr, k * 32 + fq * 8))
; #define WAIT_V8(n) asm volatile("s_waitcnt vmcnt(" #n ")" ::: "memory")
; #define WAIT_L8(n) asm volatile("s_waitcnt lgkmcnt(" #n ")" ::: "memory")
; #define BAR8 __builtin_amdgcn_s_barrier()
; #define SCHED8 __builtin_amdgcn_sched_barrier(0)
;     ...
;   for (int tt = 0; tt < nt - 2; tt += 2) {
;     LDB8(B0, 0, 0); SCHED8; LDA8(At, 0, 0); STAGE8(SA8(1, 1), A, lda, brow + 128, tt + 1);
;     WAIT_L8(8); BAR8; WAIT_L8(0); MMA8(0, 0, At, B0); BAR8; SCHED8;
;     LDB8(B1, 0, 1); STAGE8(SB8(0, 0), Bt, K, bcol, tt + 2);
;     BAR8; WAIT_L8(0); MMA8(0, 1, At, B1); BAR8;
;     LDA8(At, 0, 1); STAGE8(SA8(0, 0), A, lda, brow, tt + 2);
;     BAR8; WAIT_L8(0); MMA8(1, 0, At, B0); BAR8; SCHED8;
;     STAGE8(SB8(0, 1), Bt, K, bcol + 128, tt + 2);
;     WAIT_V8(6); BAR8; MMA8(1, 1, At, B1); BAR8;
.LBB0_1015:
	ds_read_b128 v[174:177], v171
	ds_read_b128 v[178:181], v171 offset:1024
	ds_read_b128 v[182:185], v171 offset:2048
	ds_read_b128 v[186:189], v171 offset:3072
	v_lshl_add_u64 v[222:223], v[140:141], 0, s[12:13]
	v_lshl_add_u64 v[226:227], v[222:223], 0, s[34:35]
	s_or_b32 m0, s100, 0xc000
	v_lshl_add_u64 v[236:237], v[138:139], 0, s[12:13]
	ds_read_b128 v[190:193], v156
	ds_read_b128 v[194:197], v156 offset:1024
	ds_read_b128 v[198:201], v155
	ds_read_b128 v[202:205], v155 offset:1024
	ds_read_b128 v[206:209], v154
	ds_read_b128 v[210:213], v154 offset:1024
	ds_read_b128 v[214:217], v153
	ds_read_b128 v[218:221], v153 offset:1024
	global_load_lds_dwordx4 v[226:227], off
	s_or_b32 m0, s100, 0xe000
	v_lshl_add_u64 v[226:227], v[236:237], 0, s[34:35]
	global_load_lds_dwordx4 v[226:227], off
	s_waitcnt lgkmcnt(8)
	s_barrier
	s_waitcnt lgkmcnt(0)
	v_mfma_f32_16x16x32_f16 v[128:131], v[190:193], v[174:177], v[128:131]
	v_mfma_f32_16x16x32_f16 v[124:127], v[190:193], v[182:185], v[124:127]
	v_mfma_f32_16x16x32_f16 v[120:123], v[198:201], v[174:177], v[120:123]
	v_mfma_f32_16x16x32_f16 v[116:119], v[198:201], v[182:185], v[116:119]
	v_mfma_f32_16x16x32_f16 v[112:115], v[206:209], v[174:177], v[112:115]
	v_mfma_f32_16x16x32_f16 v[108:111], v[206:209], v[182:185], v[108:111]
	v_mfma_f32_16x16x32_f16 v[104:107], v[214:217], v[174:177], v[104:107]
	v_mfma_f32_16x16x32_f16 v[100:103], v[214:217], v[182:185], v[100:103]
	v_mfma_f32_16x16x32_f16 v[128:131], v[194:197], v[178:181], v[128:131]
	v_mfma_f32_16x16x32_f16 v[124:127], v[194:197], v[186:189], v[124:127]
	v_mfma_f32_16x16x32_f16 v[120:123], v[202:205], v[178:181], v[120:123]
	v_mfma_f32_16x16x32_f16 v[116:119], v[202:205], v[186:189], v[116:119]
	v_mfma_f32_16x16x32_f16 v[112:115], v[210:213], v[178:181], v[112:115]
	v_mfma_f32_16x16x32_f16 v[108:111], v[210:213], v[186:189], v[108:111]
	v_mfma_f32_16x16x32_f16 v[104:107], v[218:221], v[178:181], v[104:107]
	v_mfma_f32_16x16x32_f16 v[100:103], v[218:221], v[186:189], v[100:103]
	s_barrier
	v_lshl_add_u64 v[246:247], v[142:143], 0, s[12:13]
	v_lshl_add_u64 v[248:249], v[246:247], 0, s[40:41]
	s_or_b32 m0, s100, 0x10000
	ds_read_b128 v[226:229], v168
	ds_read_b128 v[230:233], v168 offset:1024
	ds_read_b128 v[238:241], v168 offset:2048
	ds_read_b128 v[242:245], v168 offset:3072
	global_load_lds_dwordx4 v[248:249], off
	v_lshl_add_u64 v[248:249], v[144:145], 0, s[12:13]
	s_or_b32 m0, s100, 0x12000
	v_lshl_add_u64 v[250:251], v[248:249], 0, s[40:41]
	global_load_lds_dwordx4 v[250:251], off
	s_barrier
	s_waitcnt lgkmcnt(0)
	v_mfma_f32_16x16x32_f16 v[96:99], v[190:193], v[226:229], v[96:99]
	v_mfma_f32_16x16x32_f16 v[92:95], v[190:193], v[238:241], v[92:95]
	v_mfma_f32_16x16x32_f16 v[88:91], v[198:201], v[226:229], v[88:91]
	v_mfma_f32_16x16x32_f16 v[84:87], v[198:201], v[238:241], v[84:87]
	v_mfma_f32_16x16x32_f16 v[80:83], v[206:209], v[226:229], v[80:83]
	v_mfma_f32_16x16x32_f16 v[76:79], v[206:209], v[238:241], v[76:79]
	v_mfma_f32_16x16x32_f16 v[72:75], v[214:217], v[226:229], v[72:75]
	v_mfma_f32_16x16x32_f16 v[68:71], v[214:217], v[238:241], v[68:71]
	v_mfma_f32_16x16x32_f16 v[96:99], v[194:197], v[230:233], v[96:99]
	v_mfma_f32_16x16x32_f16 v[92:95], v[194:197], v[242:245], v[92:95]
	v_mfma_f32_16x16x32_f16 v[88:91], v[202:205], v[230:233], v[88:91]
	v_mfma_f32_16x16x32_f16 v[84:87], v[202:205], v[242:245], v[84:87]
	v_mfma_f32_16x16x32_f16 v[80:83], v[210:213], v[230:233], v[80:83]
	v_mfma_f32_16x16x32_f16 v[76:79], v[210:213], v[242:245], v[76:79]
	v_mfma_f32_16x16x32_f16 v[72:75], v[218:221], v[230:233], v[72:75]
	v_mfma_f32_16x16x32_f16 v[68:71], v[218:221], v[242:245], v[68:71]
	v_lshl_add_u64 v[250:251], v[222:223], 0, s[10:11]
	s_mov_b32 m0, s100
	s_barrier
	ds_read_b128 v[190:193], v156 offset:16384
	ds_read_b128 v[194:197], v156 offset:17408
	ds_read_b128 v[198:201], v155 offset:16384
	ds_read_b128 v[202:205], v155 offset:17408
	ds_read_b128 v[206:209], v154 offset:16384
	ds_read_b128 v[210:213], v154 offset:17408
	ds_read_b128 v[214:217], v153 offset:16384
	ds_read_b128 v[218:221], v153 offset:17408
	global_load_lds_dwordx4 v[250:251], off
	s_or_b32 m0, s100, 0x2000
	v_lshl_add_u64 v[250:251], v[236:237], 0, s[10:11]
	global_load_lds_dwordx4 v[250:251], off
	s_barrier
	s_waitcnt lgkmcnt(0)
	v_mfma_f32_16x16x32_f16 v[64:67], v[190:193], v[174:177], v[64:67]
	v_mfma_f32_16x16x32_f16 v[60:63], v[190:193], v[182:185], v[60:63]
	v_mfma_f32_16x16x32_f16 v[56:59], v[198:201], v[174:177], v[56:59]
	v_mfma_f32_16x16x32_f16 v[52:55], v[198:201], v[182:185], v[52:55]
	v_mfma_f32_16x16x32_f16 v[48:51], v[206:209], v[174:177], v[48:51]
	v_mfma_f32_16x16x32_f16 v[44:47], v[206:209], v[182:185], v[44:47]
	v_mfma_f32_16x16x32_f16 v[40:43], v[214:217], v[174:177], v[40:43]
	v_mfma_f32_16x16x32_f16 v[36:39], v[214:217], v[182:185], v[36:39]
	v_mfma_f32_16x16x32_f16 v[64:67], v[194:197], v[178:181], v[64:67]
	v_mfma_f32_16x16x32_f16 v[60:63], v[194:197], v[186:189], v[60:63]
	v_mfma_f32_16x16x32_f16 v[56:59], v[202:205], v[178:181], v[56:59]
	v_mfma_f32_16x16x32_f16 v[52:55], v[202:205], v[186:189], v[52:55]
	v_mfma_f32_16x16x32_f16 v[48:51], v[210:213], v[178:181], v[48:51]
	v_mfma_f32_16x16x32_f16 v[44:47], v[210:213], v[186:189], v[44:47]
	v_mfma_f32_16x16x32_f16 v[40:43], v[218:221], v[178:181], v[40:43]
	v_mfma_f32_16x16x32_f16 v[36:39], v[218:221], v[186:189], v[36:39]
	s_barrier
	s_or_b32 m0, s100, 0x14000
	v_lshl_add_u64 v[174:175], v[246:247], 0, s[42:43]
	global_load_lds_dwordx4 v[174:175], off
	s_or_b32 m0, s100, 0x16000
	v_lshl_add_u64 v[174:175], v[248:249], 0, s[42:43]
	global_load_lds_dwordx4 v[174:175], off
	s_waitcnt vmcnt(6)
	s_barrier
; #define LDA8(dst, b, h) _Pragma("unroll") for (int m = 0; m < 4; ++m) _Pragma("unroll") for (int k = 0; k < 2; ++k) \
;     dst[m][k] = *(const bf16x8*)((const char*)SA8(b, h) + lds_byte8(wr * 64 + m * 16 + fr, k * 32 + fq * 8))
; #define LDB8(dst, b, h) _Pragma("unroll") for (int n = 0; n < 2; ++n) _Pragma("unroll") for (int k = 0; k < 2; ++k) \
;     dst[n][k] = *(const bf16x8*)((const char*)SB8(b, h) + lds_byte8(wc * 32 + n * 16 + fr, k * 32 + fq * 8))
; #define WAIT_V8(n) asm volatile("s_waitcnt vmcnt(" #n ")" ::: "memory")
; #define WAIT_L8(n) asm volatile("s_waitcnt lgkmcnt(" #n ")" ::: "memory")
; #define BAR8 __builtin_amdgcn_s_barrier()
; #define SCHED8 __builtin_amdgcn_sched_barrier(0)
;     ...
;     LDB8(B0, 1, 0); SCHED8; LDA8(At, 1, 0); STAGE8(SA8(0, 1), A, lda, brow + 128, tt + 2);
;     WAIT_L8(8); BAR8; WAIT_L8(0); MMA8(0, 0, At, B0); BAR8; SCHED8;
;     LDB8(B1, 1, 1); STAGE8(SB8(1, 0), Bt, K, bcol, tt + 3);
;     BAR8; WAIT_L8(0); MMA8(0, 1, At, B1); BAR8;
;     LDA8(At, 1, 1); STAGE8(SA8(1, 0), A, lda, brow, tt + 3);
;     BAR8; WAIT_L8(0); MMA8(1, 0, At, B0); BAR8; SCHED8;
;     STAGE8(SB8(1, 1), Bt, K, bcol + 128, tt + 3);
;     WAIT_V8(6); BAR8; MMA8(1, 1, At, B1); BAR8;
	v_mfma_f32_16x16x32_f16 v[32:35], v[190:193], v[226:229], v[32:35]
	v_mfma_f32_16x16x32_f16 v[28:31], v[190:193], v[238:241], v[28:31]
	v_mfma_f32_16x16x32_f16 v[24:27], v[198:201], v[226:229], v[24:27]
	v_mfma_f32_16x16x32_f16 v[20:23], v[198:201], v[238:241], v[20:23]
	v_mfma_f32_16x16x32_f16 v[16:19], v[206:209], v[226:229], v[16:19]
	v_mfma_f32_16x16x32_f16 v[12:15], v[206:209], v[238:241], v[12:15]
	v_mfma_f32_16x16x32_f16 v[8:11], v[214:217], v[226:229], v[8:11]
	v_mfma_f32_16x16x32_f16 v[4:7], v[214:217], v[238:241], v[4:7]
	v_mfma_f32_16x16x32_f16 v[32:35], v[194:197], v[230:233], v[32:35]
	v_mfma_f32_16x16x32_f16 v[28:31], v[194:197], v[242:245], v[28:31]
	v_mfma_f32_16x16x32_f16 v[24:27], v[202:205], v[230:233], v[24:27]
	v_mfma_f32_16x16x32_f16 v[20:23], v[202:205], v[242:245], v[20:23]
	v_mfma_f32_16x16x32_f16 v[16:19], v[210:213], v[230:233], v[16:19]
	v_mfma_f32_16x16x32_f16 v[12:15], v[210:213], v[242:245], v[12:15]
	v_mfma_f32_16x16x32_f16 v[8:11], v[218:221], v[230:233], v[8:11]
	v_mfma_f32_16x16x32_f16 v[4:7], v[218:221], v[242:245], v[4:7]
	s_barrier
	ds_read_b128 v[174:177], v161
	ds_read_b128 v[178:181], v161 offset:1024
	ds_read_b128 v[182:185], v161 offset:2048
	ds_read_b128 v[186:189], v161 offset:3072
	v_lshl_add_u64 v[226:227], v[222:223], 0, s[18:19]
	s_or_b32 m0, s100, 0x4000
	ds_read_b128 v[190:193], v156 offset:32768
	ds_read_b128 v[194:197], v156 offset:33792
	ds_read_b128 v[198:201], v155 offset:32768
	ds_read_b128 v[202:205], v155 offset:33792
	ds_read_b128 v[206:209], v154 offset:32768
	ds_read_b128 v[210:213], v154 offset:33792
	ds_read_b128 v[214:217], v153 offset:32768
	ds_read_b128 v[218:221], v153 offset:33792
	global_load_lds_dwordx4 v[226:227], off
	s_or_b32 m0, s100, 0x6000
	v_lshl_add_u64 v[226:227], v[236:237], 0, s[18:19]
	global_load_lds_dwordx4 v[226:227], off
	s_waitcnt lgkmcnt(8)
	s_barrier
	s_waitcnt lgkmcnt(0)
	v_mfma_f32_16x16x32_f16 v[128:131], v[190:193], v[174:177], v[128:131]
	v_mfma_f32_16x16x32_f16 v[124:127], v[190:193], v[182:185], v[124:127]
	v_mfma_f32_16x16x32_f16 v[120:123], v[198:201], v[174:177], v[120:123]
	v_mfma_f32_16x16x32_f16 v[116:119], v[198:201], v[182:185], v[116:119]
	v_mfma_f32_16x16x32_f16 v[112:115], v[206:209], v[174:177], v[112:115]
	v_mfma_f32_16x16x32_f16 v[108:111], v[206:209], v[182:185], v[108:111]
	v_mfma_f32_16x16x32_f16 v[104:107], v[214:217], v[174:177], v[104:107]
	v_mfma_f32_16x16x32_f16 v[100:103], v[214:217], v[182:185], v[100:103]
	v_mfma_f32_16x16x32_f16 v[128:131], v[194:197], v[178:181], v[128:131]
	v_mfma_f32_16x16x32_f16 v[124:127], v[194:197], v[186:189], v[124:127]
	v_mfma_f32_16x16x32_f16 v[120:123], v[202:205], v[178:181], v[120:123]
	v_mfma_f32_16x16x32_f16 v[116:119], v[202:205], v[186:189], v[116:119]
	v_mfma_f32_16x16x32_f16 v[112:115], v[210:213], v[178:181], v[112:115]
	v_mfma_f32_16x16x32_f16 v[108:111], v[210:213], v[186:189], v[108:111]
	v_mfma_f32_16x16x32_f16 v[104:107], v[218:221], v[178:181], v[104:107]
	v_mfma_f32_16x16x32_f16 v[100:103], v[218:221], v[186:189], v[100:103]
	s_barrier
	v_lshl_add_u64 v[250:251], v[246:247], 0, s[44:45]
	s_or_b32 m0, s100, 0x18000
	ds_read_b128 v[226:229], v158
	ds_read_b128 v[230:233], v158 offset:1024
	ds_read_b128 v[238:241], v158 offset:2048
	ds_read_b128 v[242:245], v158 offset:3072
	global_load_lds_dwordx4 v[250:251], off
	s_or_b32 m0, s100, 0x1a000
	v_lshl_add_u64 v[250:251], v[248:249], 0, s[44:45]
	global_load_lds_dwordx4 v[250:251], off
	s_barrier
	s_waitcnt lgkmcnt(0)
	v_mfma_f32_16x16x32_f16 v[96:99], v[190:193], v[226:229], v[96:99]
	v_mfma_f32_16x16x32_f16 v[92:95], v[190:193], v[238:241], v[92:95]
	v_mfma_f32_16x16x32_f16 v[88:91], v[198:201], v[226:229], v[88:91]
	v_mfma_f32_16x16x32_f16 v[84:87], v[198:201], v[238:241], v[84:87]
	v_mfma_f32_16x16x32_f16 v[80:83], v[206:209], v[226:229], v[80:83]
	v_mfma_f32_16x16x32_f16 v[76:79], v[206:209], v[238:241], v[76:79]
	v_mfma_f32_16x16x32_f16 v[72:75], v[214:217], v[226:229], v[72:75]
	v_mfma_f32_16x16x32_f16 v[68:71], v[214:217], v[238:241], v[68:71]
	v_mfma_f32_16x16x32_f16 v[96:99], v[194:197], v[230:233], v[96:99]
	v_mfma_f32_16x16x32_f16 v[92:95], v[194:197], v[242:245], v[92:95]
	v_mfma_f32_16x16x32_f16 v[88:91], v[202:205], v[230:233], v[88:91]
	v_mfma_f32_16x16x32_f16 v[84:87], v[202:205], v[242:245], v[84:87]
	v_mfma_f32_16x16x32_f16 v[80:83], v[210:213], v[230:233], v[80:83]
	v_mfma_f32_16x16x32_f16 v[76:79], v[210:213], v[242:245], v[76:79]
	v_mfma_f32_16x16x32_f16 v[72:75], v[218:221], v[230:233], v[72:75]
	v_mfma_f32_16x16x32_f16 v[68:71], v[218:221], v[242:245], v[68:71]
	v_lshl_add_u64 v[222:223], v[222:223], 0, s[22:23]
	s_or_b32 m0, s100, 0x8000
	s_barrier
	ds_read_b128 v[190:193], v156 offset:49152
	ds_read_b128 v[194:197], v156 offset:50176
	ds_read_b128 v[198:201], v155 offset:49152
	ds_read_b128 v[202:205], v155 offset:50176
	ds_read_b128 v[206:209], v154 offset:49152
	ds_read_b128 v[210:213], v154 offset:50176
	ds_read_b128 v[214:217], v153 offset:49152
	ds_read_b128 v[218:221], v153 offset:50176
	global_load_lds_dwordx4 v[222:223], off
	s_or_b32 m0, s100, 0xa000
	v_lshl_add_u64 v[222:223], v[236:237], 0, s[22:23]
	global_load_lds_dwordx4 v[222:223], off
	s_barrier
; #define LDA8(dst, b, h) _Pragma("unroll") for (int m = 0; m < 4; ++m) _Pragma("unroll") for (int k = 0; k < 2; ++k) \
;     dst[m][k] = *(const bf16x8*)((const char*)SA8(b, h) + lds_byte8(wr * 64 + m * 16 + fr, k * 32 + fq * 8))
; #define LDB8(dst, b, h) _Pragma("unroll") for (int n = 0; n < 2; ++n) _Pragma("unroll") for (int k = 0; k < 2; ++k) \
;     dst[n][k] = *(const bf16x8*)((const char*)SB8(b, h) + lds_byte8(wc * 32 + n * 16 + fr, k * 32 + fq * 8))
; #define WAIT_V8(n) asm volatile("s_waitcnt vmcnt(" #n ")" ::: "memory")
; #define WAIT_L8(n) asm volatile("s_waitcnt lgkmcnt(" #n ")" ::: "memory")
; #define BAR8 __builtin_amdgcn_s_barrier()
;     ...
;     WAIT_V8(6); BAR8; MMA8(1, 1, At, B1); BAR8;
;   }
;   { LDB8(B0, 0, 0); LDA8(At, 0, 0); STAGE8(SA8(1, 1), A, lda, brow + 128, nt - 1);
;     BAR8; WAIT_L8(0); MMA8(0, 0, At, B0); BAR8;
;     LDB8(B1, 0, 1); BAR8; WAIT_L8(0); MMA8(0, 1, At, B1); BAR8;
;     LDA8(At, 0, 1); WAIT_V8(4); BAR8; WAIT_L8(0); MMA8(1, 0, At, B0); MMA8(1, 1, At, B1); BAR8; }
;   { LDB8(B0, 1, 0); LDA8(At, 1, 0); WAIT_V8(2); BAR8; WAIT_L8(0); MMA8(0, 0, At, B0); BAR8;
	s_waitcnt lgkmcnt(0)
	v_mfma_f32_16x16x32_f16 v[64:67], v[190:193], v[174:177], v[64:67]
	v_mfma_f32_16x16x32_f16 v[60:63], v[190:193], v[182:185], v[60:63]
	v_mfma_f32_16x16x32_f16 v[56:59], v[198:201], v[174:177], v[56:59]
	v_mfma_f32_16x16x32_f16 v[52:55], v[198:201], v[182:185], v[52:55]
	v_mfma_f32_16x16x32_f16 v[48:51], v[206:209], v[174:177], v[48:51]
	v_mfma_f32_16x16x32_f16 v[44:47], v[206:209], v[182:185], v[44:47]
	v_mfma_f32_16x16x32_f16 v[40:43], v[214:217], v[174:177], v[40:43]
	v_mfma_f32_16x16x32_f16 v[36:39], v[214:217], v[182:185], v[36:39]
	v_mfma_f32_16x16x32_f16 v[64:67], v[194:197], v[178:181], v[64:67]
	v_mfma_f32_16x16x32_f16 v[60:63], v[194:197], v[186:189], v[60:63]
	v_mfma_f32_16x16x32_f16 v[56:59], v[202:205], v[178:181], v[56:59]
	v_mfma_f32_16x16x32_f16 v[52:55], v[202:205], v[186:189], v[52:55]
	v_mfma_f32_16x16x32_f16 v[48:51], v[210:213], v[178:181], v[48:51]
	v_mfma_f32_16x16x32_f16 v[44:47], v[210:213], v[186:189], v[44:47]
	v_mfma_f32_16x16x32_f16 v[40:43], v[218:221], v[178:181], v[40:43]
	v_mfma_f32_16x16x32_f16 v[36:39], v[218:221], v[186:189], v[36:39]
	s_barrier
	s_or_b32 m0, s100, 0x1c000
	v_lshl_add_u64 v[174:175], v[246:247], 0, s[46:47]
	global_load_lds_dwordx4 v[174:175], off
	s_or_b32 m0, s100, 0x1e000
	v_lshl_add_u64 v[174:175], v[248:249], 0, s[46:47]
	global_load_lds_dwordx4 v[174:175], off
	s_waitcnt vmcnt(6)
	s_barrier
	v_mfma_f32_16x16x32_f16 v[32:35], v[190:193], v[226:229], v[32:35]
	v_mfma_f32_16x16x32_f16 v[28:31], v[190:193], v[238:241], v[28:31]
	v_mfma_f32_16x16x32_f16 v[24:27], v[198:201], v[226:229], v[24:27]
	v_mfma_f32_16x16x32_f16 v[20:23], v[198:201], v[238:241], v[20:23]
	v_mfma_f32_16x16x32_f16 v[16:19], v[206:209], v[226:229], v[16:19]
	v_mfma_f32_16x16x32_f16 v[12:15], v[206:209], v[238:241], v[12:15]
	v_mfma_f32_16x16x32_f16 v[8:11], v[214:217], v[226:229], v[8:11]
	v_mfma_f32_16x16x32_f16 v[4:7], v[214:217], v[238:241], v[4:7]
	v_mfma_f32_16x16x32_f16 v[32:35], v[194:197], v[230:233], v[32:35]
	v_mfma_f32_16x16x32_f16 v[28:31], v[194:197], v[242:245], v[28:31]
	v_mfma_f32_16x16x32_f16 v[24:27], v[202:205], v[230:233], v[24:27]
	v_mfma_f32_16x16x32_f16 v[20:23], v[202:205], v[242:245], v[20:23]
	v_mfma_f32_16x16x32_f16 v[16:19], v[210:213], v[230:233], v[16:19]
	v_mfma_f32_16x16x32_f16 v[12:15], v[210:213], v[242:245], v[12:15]
	v_mfma_f32_16x16x32_f16 v[8:11], v[218:221], v[230:233], v[8:11]
	v_mfma_f32_16x16x32_f16 v[4:7], v[218:221], v[242:245], v[4:7]
	s_add_i32 s14, s14, 2
	s_add_u32 s12, s12, 0x100
	s_addc_u32 s13, s13, 0
	s_cmp_lt_u32 s14, 12
	s_barrier
	s_cbranch_scc1 .LBB0_1015
.Lpk_exit_4:
	s_add_u32 s8, s8, 0x40780
	s_addc_u32 s9, s9, 0
	v_lshl_add_u64 v[132:133], s[8:9], 0, v[132:133]
	v_lshl_add_u64 v[0:1], v[0:1], 1, v[132:133]
	s_or_b32 m0, s100, 0xc000
	ds_read_b128 v[138:141], v171
	ds_read_b128 v[142:145], v171 offset:1024
	ds_read_b128 v[162:165], v171 offset:2048
	ds_read_b128 v[174:177], v171 offset:3072
	ds_read_b128 v[178:181], v156
	ds_read_b128 v[182:185], v156 offset:1024
	ds_read_b128 v[186:189], v155
	ds_read_b128 v[190:193], v155 offset:1024
	ds_read_b128 v[194:197], v154
	ds_read_b128 v[198:201], v154 offset:1024
	ds_read_b128 v[202:205], v153
	ds_read_b128 v[206:209], v153 offset:1024
	global_load_lds_dwordx4 v[0:1], off
	v_lshl_add_u64 v[0:1], s[8:9], 0, v[136:137]
	s_or_b32 m0, s100, 0xe000
	v_lshl_add_u64 v[0:1], v[134:135], 1, v[0:1]
	global_load_lds_dwordx4 v[0:1], off
	s_barrier
	s_waitcnt lgkmcnt(0)
	v_mfma_f32_16x16x32_f16 v[128:131], v[178:181], v[138:141], v[128:131]
	v_mfma_f32_16x16x32_f16 v[124:127], v[178:181], v[162:165], v[124:127]
	v_mfma_f32_16x16x32_f16 v[120:123], v[186:189], v[138:141], v[120:123]
	v_mfma_f32_16x16x32_f16 v[112:115], v[194:197], v[138:141], v[112:115]
	v_mfma_f32_16x16x32_f16 v[128:131], v[182:185], v[142:145], v[128:131]
	v_mfma_f32_16x16x32_f16 v[124:127], v[182:185], v[174:177], v[124:127]
	v_mfma_f32_16x16x32_f16 v[120:123], v[190:193], v[142:145], v[120:123]
	v_mfma_f32_16x16x32_f16 v[116:119], v[186:189], v[162:165], v[116:119]
	v_mfma_f32_16x16x32_f16 v[112:115], v[198:201], v[142:145], v[112:115]
	v_mfma_f32_16x16x32_f16 v[108:111], v[194:197], v[162:165], v[108:111]
	v_mfma_f32_16x16x32_f16 v[104:107], v[202:205], v[138:141], v[104:107]
	v_mfma_f32_16x16x32_f16 v[100:103], v[202:205], v[162:165], v[100:103]
	v_mfma_f32_16x16x32_f16 v[132:135], v[190:193], v[174:177], v[116:119]
	v_mfma_f32_16x16x32_f16 v[170:173], v[198:201], v[174:177], v[108:111]
	v_mfma_f32_16x16x32_f16 v[210:213], v[206:209], v[142:145], v[104:107]
	v_mfma_f32_16x16x32_f16 v[214:217], v[206:209], v[174:177], v[100:103]
	s_barrier
	s_nop 1
	ds_read_b128 v[100:103], v168
	ds_read_b128 v[104:107], v168 offset:1024
	ds_read_b128 v[108:111], v168 offset:2048
	ds_read_b128 v[116:119], v168 offset:3072
	s_barrier
	s_waitcnt lgkmcnt(0)
	v_mfma_f32_16x16x32_f16 v[80:83], v[194:197], v[100:103], v[80:83]
	v_mfma_f32_16x16x32_f16 v[76:79], v[194:197], v[108:111], v[76:79]
	v_mfma_f32_16x16x32_f16 v[72:75], v[202:205], v[100:103], v[72:75]
	v_mfma_f32_16x16x32_f16 v[68:71], v[202:205], v[108:111], v[68:71]
	v_mfma_f32_16x16x32_f16 v[96:99], v[178:181], v[100:103], v[96:99]
	v_mfma_f32_16x16x32_f16 v[92:95], v[178:181], v[108:111], v[92:95]
	v_mfma_f32_16x16x32_f16 v[88:91], v[186:189], v[100:103], v[88:91]
	v_mfma_f32_16x16x32_f16 v[84:87], v[186:189], v[108:111], v[84:87]
	v_mfma_f32_16x16x32_f16 v[80:83], v[198:201], v[104:107], v[80:83]
	v_mfma_f32_16x16x32_f16 v[76:79], v[198:201], v[116:119], v[76:79]
	v_mfma_f32_16x16x32_f16 v[72:75], v[206:209], v[104:107], v[72:75]
	v_mfma_f32_16x16x32_f16 v[68:71], v[206:209], v[116:119], v[68:71]
	v_mfma_f32_16x16x32_f16 v[166:169], v[182:185], v[104:107], v[96:99]
	v_mfma_f32_16x16x32_f16 v[178:181], v[182:185], v[116:119], v[92:95]
	v_mfma_f32_16x16x32_f16 v[182:185], v[190:193], v[104:107], v[88:91]
	v_mfma_f32_16x16x32_f16 v[186:189], v[190:193], v[116:119], v[84:87]
	s_barrier
; #define LDA8(dst, b, h) _Pragma("unroll") for (int m = 0; m < 4; ++m) _Pragma("unroll") for (int k = 0; k < 2; ++k) \
;     dst[m][k] = *(const bf16x8*)((const char*)SA8(b, h) + lds_byte8(wr * 64 + m * 16 + fr, k * 32 + fq * 8))
; #define LDB8(dst, b, h) _Pragma("unroll") for (int n = 0; n < 2; ++n) _Pragma("unroll") for (int k = 0; k < 2; ++k) \
;     dst[n][k] = *(const bf16x8*)((const char*)SB8(b, h) + lds_byte8(wc * 32 + n * 16 + fr, k * 32 + fq * 8))
; #define WAIT_V8(n) asm volatile("s_waitcnt vmcnt(" #n ")" ::: "memory")
; #define WAIT_L8(n) asm volatile("s_waitcnt lgkmcnt(" #n ")" ::: "memory")
; #define BAR8 __builtin_amdgcn_s_barrier()
;     ...
;     LDA8(At, 0, 1); WAIT_V8(4); BAR8; WAIT_L8(0); MMA8(1, 0, At, B0); MMA8(1, 1, At, B1); BAR8; }
;   { LDB8(B0, 1, 0); LDA8(At, 1, 0); WAIT_V8(2); BAR8; WAIT_L8(0); MMA8(0, 0, At, B0); BAR8;
;     LDB8(B1, 1, 1); WAIT_V8(0); BAR8; WAIT_L8(0); MMA8(0, 1, At, B1); BAR8;
;     LDA8(At, 1, 1); BAR8; WAIT_L8(0); MMA8(1, 0, At, B0); MMA8(1, 1, At, B1); BAR8; }
	s_nop 0
	ds_read_b128 v[84:87], v156 offset:16384
	ds_read_b128 v[88:91], v156 offset:17408
	ds_read_b128 v[92:95], v155 offset:16384
	ds_read_b128 v[96:99], v155 offset:17408
	ds_read_b128 v[190:193], v154 offset:16384
	ds_read_b128 v[194:197], v154 offset:17408
	ds_read_b128 v[198:201], v153 offset:16384
	ds_read_b128 v[202:205], v153 offset:17408
	s_waitcnt vmcnt(4)
	s_barrier
	s_waitcnt lgkmcnt(0)
	v_mfma_f32_16x16x32_f16 v[64:67], v[84:87], v[138:141], v[64:67]
	v_mfma_f32_16x16x32_f16 v[60:63], v[84:87], v[162:165], v[60:63]
	v_mfma_f32_16x16x32_f16 v[56:59], v[92:95], v[138:141], v[56:59]
	v_mfma_f32_16x16x32_f16 v[52:55], v[92:95], v[162:165], v[52:55]
	v_mfma_f32_16x16x32_f16 v[48:51], v[190:193], v[138:141], v[48:51]
	v_mfma_f32_16x16x32_f16 v[44:47], v[190:193], v[162:165], v[44:47]
	v_mfma_f32_16x16x32_f16 v[40:43], v[198:201], v[138:141], v[40:43]
	v_mfma_f32_16x16x32_f16 v[36:39], v[198:201], v[162:165], v[36:39]
	v_mfma_f32_16x16x32_f16 v[64:67], v[88:91], v[142:145], v[64:67]
	v_mfma_f32_16x16x32_f16 v[60:63], v[88:91], v[174:177], v[60:63]
	v_mfma_f32_16x16x32_f16 v[56:59], v[96:99], v[142:145], v[56:59]
	v_mfma_f32_16x16x32_f16 v[52:55], v[96:99], v[174:177], v[52:55]
	v_mfma_f32_16x16x32_f16 v[48:51], v[194:197], v[142:145], v[48:51]
	v_mfma_f32_16x16x32_f16 v[44:47], v[194:197], v[174:177], v[44:47]
	v_mfma_f32_16x16x32_f16 v[40:43], v[202:205], v[142:145], v[40:43]
	v_mfma_f32_16x16x32_f16 v[36:39], v[202:205], v[174:177], v[36:39]
	v_mfma_f32_16x16x32_f16 v[32:35], v[84:87], v[100:103], v[32:35]
	v_mfma_f32_16x16x32_f16 v[28:31], v[84:87], v[108:111], v[28:31]
	v_mfma_f32_16x16x32_f16 v[24:27], v[92:95], v[100:103], v[24:27]
	v_mfma_f32_16x16x32_f16 v[20:23], v[92:95], v[108:111], v[20:23]
	v_mfma_f32_16x16x32_f16 v[16:19], v[190:193], v[100:103], v[16:19]
	v_mfma_f32_16x16x32_f16 v[12:15], v[190:193], v[108:111], v[12:15]
	v_mfma_f32_16x16x32_f16 v[8:11], v[198:201], v[100:103], v[8:11]
	v_mfma_f32_16x16x32_f16 v[4:7], v[198:201], v[108:111], v[4:7]
	v_mfma_f32_16x16x32_f16 v[136:139], v[88:91], v[104:107], v[32:35]
	v_mfma_f32_16x16x32_f16 v[140:143], v[88:91], v[116:119], v[28:31]
	v_mfma_f32_16x16x32_f16 v[162:165], v[96:99], v[104:107], v[24:27]
	v_mfma_f32_16x16x32_f16 v[174:177], v[96:99], v[116:119], v[20:23]
	v_mfma_f32_16x16x32_f16 v[206:209], v[194:197], v[104:107], v[16:19]
	v_mfma_f32_16x16x32_f16 v[190:193], v[194:197], v[116:119], v[12:15]
	v_mfma_f32_16x16x32_f16 v[194:197], v[202:205], v[104:107], v[8:11]
	v_mfma_f32_16x16x32_f16 v[198:201], v[202:205], v[116:119], v[4:7]
	s_barrier
	ds_read_b128 v[202:205], v161
	ds_read_b128 v[218:221], v161 offset:1024
	ds_read_b128 v[226:229], v161 offset:2048
	ds_read_b128 v[230:233], v161 offset:3072
	ds_read_b128 v[8:11], v156 offset:32768
	ds_read_b128 v[12:15], v156 offset:33792
	ds_read_b128 v[16:19], v155 offset:32768
	ds_read_b128 v[24:27], v155 offset:33792
	ds_read_b128 v[28:31], v154 offset:32768
	ds_read_b128 v[32:35], v154 offset:33792
	ds_read_b128 v[238:241], v153 offset:32768
	ds_read_b128 v[242:245], v153 offset:33792
	s_waitcnt vmcnt(2)
	s_barrier
	s_waitcnt lgkmcnt(0)
	v_mfma_f32_16x16x32_f16 v[4:7], v[8:11], v[202:205], v[128:131]
	v_mfma_f32_16x16x32_f16 v[104:107], v[12:15], v[218:221], v[4:7]
	v_mfma_f32_16x16x32_f16 v[4:7], v[8:11], v[226:229], v[124:127]
	v_mfma_f32_16x16x32_f16 v[116:119], v[12:15], v[230:233], v[4:7]
	v_mfma_f32_16x16x32_f16 v[4:7], v[16:19], v[202:205], v[120:123]
	v_mfma_f32_16x16x32_f16 v[100:103], v[24:27], v[218:221], v[4:7]
	v_mfma_f32_16x16x32_f16 v[4:7], v[16:19], v[226:229], v[132:135]
	v_mfma_f32_16x16x32_f16 v[108:111], v[24:27], v[230:233], v[4:7]
	v_mfma_f32_16x16x32_f16 v[4:7], v[28:31], v[202:205], v[112:115]
	v_mfma_f32_16x16x32_f16 v[92:95], v[32:35], v[218:221], v[4:7]
	v_mfma_f32_16x16x32_f16 v[4:7], v[28:31], v[226:229], v[170:173]
	v_mfma_f32_16x16x32_f16 v[96:99], v[32:35], v[230:233], v[4:7]
	v_mfma_f32_16x16x32_f16 v[4:7], v[238:241], v[202:205], v[210:213]
	v_mfma_f32_16x16x32_f16 v[84:87], v[242:245], v[218:221], v[4:7]
	v_mfma_f32_16x16x32_f16 v[4:7], v[238:241], v[226:229], v[214:217]
	v_mfma_f32_16x16x32_f16 v[88:91], v[242:245], v[230:233], v[4:7]
	s_barrier
; #define LDA8(dst, b, h) _Pragma("unroll") for (int m = 0; m < 4; ++m) _Pragma("unroll") for (int k = 0; k < 2; ++k) \
;     dst[m][k] = *(const bf16x8*)((const char*)SA8(b, h) + lds_byte8(wr * 64 + m * 16 + fr, k * 32 + fq * 8))
; #define LDB8(dst, b, h) _Pragma("unroll") for (int n = 0; n < 2; ++n) _Pragma("unroll") for (int k = 0; k < 2; ++k) \
;     dst[n][k] = *(const bf16x8*)((const char*)SB8(b, h) + lds_byte8(wc * 32 + n * 16 + fr, k * 32 + fq * 8))
; #define WAIT_V8(n) asm volatile("s_waitcnt vmcnt(" #n ")" ::: "memory")
; #define WAIT_L8(n) asm volatile("s_waitcnt lgkmcnt(" #n ")" ::: "memory")
; #define BAR8 __builtin_amdgcn_s_barrier()
;     ...
;     LDB8(B1, 1, 1); WAIT_V8(0); BAR8; WAIT_L8(0); MMA8(0, 1, At, B1); BAR8;
;     LDA8(At, 1, 1); BAR8; WAIT_L8(0); MMA8(1, 0, At, B0); MMA8(1, 1, At, B1); BAR8; }
;   if (wr == 0) BAR8;
;   __syncthreads();
;     ...
;   if (t < 256) {
	ds_read_b128 v[132:135], v158
	ds_read_b128 v[170:173], v158 offset:1024
	ds_read_b128 v[210:213], v158 offset:2048
	ds_read_b128 v[158:161], v158 offset:3072
	s_waitcnt vmcnt(0)
	s_barrier
	s_waitcnt lgkmcnt(0)
	v_mfma_f32_16x16x32_f16 v[4:7], v[8:11], v[132:135], v[166:169]
	v_mfma_f32_16x16x32_f16 v[8:11], v[8:11], v[210:213], v[178:181]
	v_mfma_f32_16x16x32_f16 v[4:7], v[12:15], v[170:173], v[4:7]
	v_mfma_f32_16x16x32_f16 v[20:23], v[12:15], v[158:161], v[8:11]
	v_mfma_f32_16x16x32_f16 v[8:11], v[16:19], v[132:135], v[182:185]
	v_mfma_f32_16x16x32_f16 v[12:15], v[16:19], v[210:213], v[186:189]
	v_mfma_f32_16x16x32_f16 v[8:11], v[24:27], v[170:173], v[8:11]
	v_mfma_f32_16x16x32_f16 v[24:27], v[24:27], v[158:161], v[12:15]
	v_mfma_f32_16x16x32_f16 v[12:15], v[28:31], v[132:135], v[80:83]
	v_mfma_f32_16x16x32_f16 v[16:19], v[28:31], v[210:213], v[76:79]
	v_mfma_f32_16x16x32_f16 v[12:15], v[32:35], v[170:173], v[12:15]
	v_mfma_f32_16x16x32_f16 v[28:31], v[32:35], v[158:161], v[16:19]
	v_mfma_f32_16x16x32_f16 v[16:19], v[238:241], v[132:135], v[72:75]
	v_mfma_f32_16x16x32_f16 v[32:35], v[238:241], v[210:213], v[68:71]
	v_mfma_f32_16x16x32_f16 v[16:19], v[242:245], v[170:173], v[16:19]
	v_mfma_f32_16x16x32_f16 v[32:35], v[242:245], v[158:161], v[32:35]
	s_barrier
	ds_read_b128 v[166:169], v156 offset:49152
	ds_read_b128 v[178:181], v156 offset:50176
	ds_read_b128 v[182:185], v155 offset:49152
	ds_read_b128 v[186:189], v155 offset:50176
	ds_read_b128 v[214:217], v154 offset:49152
	ds_read_b128 v[154:157], v154 offset:50176
	ds_read_b128 v[238:241], v153 offset:49152
	ds_read_b128 v[150:153], v153 offset:50176
	s_barrier
	s_waitcnt lgkmcnt(0)
	v_mfma_f32_16x16x32_f16 v[64:67], v[166:169], v[202:205], v[64:67]
	v_mfma_f32_16x16x32_f16 v[60:63], v[166:169], v[226:229], v[60:63]
	v_mfma_f32_16x16x32_f16 v[56:59], v[182:185], v[202:205], v[56:59]
	v_mfma_f32_16x16x32_f16 v[52:55], v[182:185], v[226:229], v[52:55]
	v_mfma_f32_16x16x32_f16 v[48:51], v[214:217], v[202:205], v[48:51]
	v_mfma_f32_16x16x32_f16 v[44:47], v[214:217], v[226:229], v[44:47]
	v_mfma_f32_16x16x32_f16 v[40:43], v[238:241], v[202:205], v[40:43]
	v_mfma_f32_16x16x32_f16 v[36:39], v[238:241], v[226:229], v[36:39]
	v_mfma_f32_16x16x32_f16 v[128:131], v[178:181], v[218:221], v[64:67]
	v_mfma_f32_16x16x32_f16 v[124:127], v[178:181], v[230:233], v[60:63]
	v_mfma_f32_16x16x32_f16 v[120:123], v[186:189], v[218:221], v[56:59]
	v_mfma_f32_16x16x32_f16 v[112:115], v[186:189], v[230:233], v[52:55]
	v_mfma_f32_16x16x32_f16 v[80:83], v[154:157], v[218:221], v[48:51]
	v_mfma_f32_16x16x32_f16 v[76:79], v[154:157], v[230:233], v[44:47]
	v_mfma_f32_16x16x32_f16 v[72:75], v[150:153], v[218:221], v[40:43]
	v_mfma_f32_16x16x32_f16 v[68:71], v[150:153], v[230:233], v[36:39]
	v_mfma_f32_16x16x32_f16 v[36:39], v[166:169], v[132:135], v[136:139]
	v_mfma_f32_16x16x32_f16 v[64:67], v[178:181], v[170:173], v[36:39]
	v_mfma_f32_16x16x32_f16 v[36:39], v[166:169], v[210:213], v[140:143]
	v_mfma_f32_16x16x32_f16 v[60:63], v[178:181], v[158:161], v[36:39]
	v_mfma_f32_16x16x32_f16 v[36:39], v[182:185], v[132:135], v[162:165]
	v_mfma_f32_16x16x32_f16 v[56:59], v[186:189], v[170:173], v[36:39]
	v_mfma_f32_16x16x32_f16 v[36:39], v[182:185], v[210:213], v[174:177]
	v_mfma_f32_16x16x32_f16 v[52:55], v[186:189], v[158:161], v[36:39]
	v_mfma_f32_16x16x32_f16 v[36:39], v[214:217], v[132:135], v[206:209]
	v_mfma_f32_16x16x32_f16 v[48:51], v[154:157], v[170:173], v[36:39]
	v_mfma_f32_16x16x32_f16 v[36:39], v[214:217], v[210:213], v[190:193]
	v_mfma_f32_16x16x32_f16 v[44:47], v[154:157], v[158:161], v[36:39]
	v_mfma_f32_16x16x32_f16 v[36:39], v[238:241], v[132:135], v[194:197]
	v_mfma_f32_16x16x32_f16 v[40:43], v[150:153], v[170:173], v[36:39]
	v_mfma_f32_16x16x32_f16 v[36:39], v[238:241], v[210:213], v[198:201]
	v_mfma_f32_16x16x32_f16 v[36:39], v[150:153], v[158:161], v[36:39]
	s_movk_i32 s8, 0x100
	v_cmp_gt_u32_e32 vcc, s8, v3
	s_barrier
	s_and_saveexec_b64 s[8:9], vcc
	s_cbranch_execz .LBB0_1018
	s_barrier

; #define LDA8(dst, b, h) _Pragma("unroll") for (int m = 0; m < 4; ++m) _Pragma("unroll") for (int k = 0; k < 2; ++k) \
;     dst[m][k] = *(const bf16x8*)((const char*)SA8(b, h) + lds_byte8(wr * 64 + m * 16 + fr, k * 32 + fq * 8))
; #define LDB8(dst, b, h) _Pragma("unroll") for (int n = 0; n < 2; ++n) _Pragma("unroll") for (int k = 0; k < 2; ++k) \
;     dst[n][k] = *(const bf16x8*)((const char*)SB8(b, h) + lds_byte8(wc * 32 + n * 16 + fr, k * 32 + fq * 8))
; #define WAIT_V8(n) asm volatile("s_waitcnt vmcnt(" #n ")" ::: "memory")
; #define WAIT_L8(n) asm volatile("s_waitcnt lgkmcnt(" #n ")" ::: "memory")
; #define BAR8 __builtin_amdgcn_s_barrier()
; #define SCHED8 __builtin_amdgcn_sched_barrier(0)
;     ...
;   if (wr == 1) BAR8;
;   WAIT_V8(4); BAR8;
;   STAGE8(SB8(1, 0), Bt, K, bcol, 1); STAGE8(SA8(1, 0), A, lda, brow, 1); STAGE8(SB8(1, 1), Bt, K, bcol + 128, 1);
;   WAIT_V8(6); BAR8;
;   for (int tt = 0; tt < nt - 2; tt += 2) {
;     LDB8(B0, 0, 0); SCHED8; LDA8(At, 0, 0); STAGE8(SA8(1, 1), A, lda, brow + 128, tt + 1);
;     WAIT_L8(8); BAR8; WAIT_L8(0); MMA8(0, 0, At, B0); BAR8; SCHED8;
;     LDB8(B1, 0, 1); STAGE8(SB8(0, 0), Bt, K, bcol, tt + 2);
;     BAR8; WAIT_L8(0); MMA8(0, 1, At, B1); BAR8;
;     LDA8(At, 0, 1); STAGE8(SA8(0, 0), A, lda, brow, tt + 2);
;     BAR8; WAIT_L8(0); MMA8(1, 0, At, B0); BAR8; SCHED8;
;     STAGE8(SB8(0, 1), Bt, K, bcol + 128, tt + 2);
;     WAIT_V8(6); BAR8; MMA8(1, 1, At, B1); BAR8;
.LBB0_1151:
	s_or_b64 exec, exec, s[12:13]
	s_lshl_b32 s29, s20, 10
	s_and_b32 s36, s29, 0xfc0000
	s_mov_b64 s[38:39], 0x80
	v_lshl_add_u64 v[14:15], v[14:15], 0, s[38:39]
	s_or_b32 m0, s100, 0x18000
	s_waitcnt vmcnt(4)
	s_barrier
	global_load_lds_dwordx4 v[14:15], off
	v_lshl_add_u64 v[14:15], v[18:19], 0, s[38:39]
	s_or_b32 m0, s100, 0x1a000
	global_load_lds_dwordx4 v[14:15], off
	v_lshl_add_u64 v[14:15], v[20:21], 0, s[38:39]
	s_or_b32 m0, s100, 0x8000
	global_load_lds_dwordx4 v[14:15], off
	v_lshl_add_u64 v[14:15], v[22:23], 0, s[38:39]
	s_or_b32 m0, s100, 0xa000
	global_load_lds_dwordx4 v[14:15], off
	s_or_b32 m0, s100, 0x1c000
	v_lshl_add_u64 v[14:15], v[26:27], 0, s[38:39]
	global_load_lds_dwordx4 v[14:15], off
	v_lshl_add_u64 v[14:15], v[28:29], 0, s[38:39]
	s_or_b32 m0, s100, 0x1e000
	v_and_b32_e32 v147, 15, v3
	global_load_lds_dwordx4 v[14:15], off
	v_bfe_u32 v148, v3, 4, 2
	v_lshlrev_b32_e32 v14, 4, v148
	v_lshlrev_b32_e32 v15, 6, v147
	v_lshlrev_b32_e32 v18, 2, v3
	v_lshlrev_b64 v[136:137], 9, v[16:17]
	v_or_b32_e32 v17, v14, v15
	v_and_b32_e32 v18, 32, v18
	s_mov_b32 s29, 0x10000
	s_and_b32 s12, s21, 0xffffff00
	v_bitop3_b32 v20, v17, s29, v18 bitop3:0xde
	s_mov_b32 s29, 0x14000
	s_ashr_i32 s13, s12, 31
	v_readlane_b32 s40, v254, 35
	v_bitop3_b32 v19, v14, v18, v15 bitop3:0x36
	v_bitop3_b32 v21, v17, s29, v18 bitop3:0xde
	s_mov_b32 s29, 0x18000
	v_lshlrev_b32_e32 v15, 6, v3
	s_lshl_b64 s[12:13], s[12:13], 10
	s_mov_b32 s37, s40
	v_bitop3_b32 v22, v17, s29, v18 bitop3:0xde
	s_mov_b32 s29, 0x1c000
	v_and_b32_e32 v15, 0x3c0, v15
	v_bitop3_b32 v17, v17, s29, v18 bitop3:0xde
	v_bitop3_b32 v18, v15, v18, v14 bitop3:0x36
	v_lshl_add_u64 v[14:15], s[12:13], 0, v[6:7]
	v_lshl_add_u64 v[6:7], s[36:37], 0, v[6:7]
	v_lshl_add_u64 v[14:15], v[14:15], 0, v[8:9]
	v_lshl_add_u64 v[6:7], v[6:7], 0, v[8:9]
	v_bfe_u32 v146, v3, 6, 2
	s_waitcnt vmcnt(6)
	v_lshlrev_b32_e32 v149, 6, v5
	v_lshlrev_b32_e32 v5, 13, v5
	v_lshl_add_u64 v[138:139], s[4:5], 0, v[14:15]
	v_lshl_add_u64 v[14:15], s[12:13], 0, v[10:11]
	v_lshl_add_u64 v[142:143], s[2:3], 0, v[6:7]
	v_lshl_add_u64 v[6:7], s[36:37], 0, v[10:11]
	v_lshlrev_b64 v[134:135], 9, v[24:25]
	v_readlane_b32 s41, v254, 36
	v_readlane_b32 s42, v254, 37
	v_readlane_b32 s43, v254, 38
	v_lshlrev_b32_e32 v16, 12, v146
	v_or_b32_e32 v23, 0x800, v5
	v_or_b32_e32 v24, 0x1000, v5
	v_or_b32_e32 v25, 0x1800, v5
	v_lshl_add_u64 v[14:15], v[14:15], 0, v[12:13]
	v_lshl_add_u64 v[6:7], v[6:7], 0, v[12:13]
	v_lshl_add_u64 v[140:141], s[4:5], 0, v[14:15]
	v_lshl_add_u64 v[144:145], s[2:3], 0, v[6:7]
	s_mov_b32 s29, -2
	s_mov_b64 s[12:13], 0
	v_add_u32_e32 v171, v20, v16
	v_add_u32_e32 v156, v19, v5
	v_add_u32_e32 v155, v18, v23
	v_add_u32_e32 v154, v18, v24
	v_add_u32_e32 v153, v18, v25
	v_add_u32_e32 v167, v21, v16
	v_add_u32_e32 v160, v22, v16
	v_add_u32_e32 v158, v17, v16
	s_mov_b64 s[36:37], 0x3020080
	s_mov_b64 s[38:39], 0xc9a0100
	s_mov_b64 s[40:41], 0x3000100
	s_mov_b64 s[42:43], 0xc9c0100
	s_mov_b64 s[44:45], 0x3020100
	s_mov_b64 s[46:47], 0xc9a0180
	s_mov_b64 s[48:49], 0x3000180
	s_mov_b64 s[50:51], 0xc9c0180
	s_barrier
	ds_read_b128 v[174:177], v171
	ds_read_b128 v[178:181], v171 offset:1024
	ds_read_b128 v[182:185], v171 offset:2048
	ds_read_b128 v[186:189], v171 offset:3072
	v_lshl_add_u64 v[222:223], v[142:143], 0, s[12:13]
	v_lshl_add_u64 v[226:227], v[222:223], 0, s[36:37]
	s_or_b32 m0, s100, 0xc000
	v_lshl_add_u64 v[236:237], v[144:145], 0, s[12:13]
	ds_read_b128 v[190:193], v156
	ds_read_b128 v[194:197], v156 offset:1024
	ds_read_b128 v[198:201], v155
	ds_read_b128 v[202:205], v155 offset:1024
	ds_read_b128 v[206:209], v154
	ds_read_b128 v[210:213], v154 offset:1024
	ds_read_b128 v[214:217], v153
	ds_read_b128 v[218:221], v153 offset:1024
	global_load_lds_dwordx4 v[226:227], off
	s_or_b32 m0, s100, 0xe000
	v_lshl_add_u64 v[226:227], v[236:237], 0, s[36:37]
	global_load_lds_dwordx4 v[226:227], off
	s_waitcnt lgkmcnt(8)
	s_barrier
	s_waitcnt lgkmcnt(0)
	v_mfma_f32_16x16x32_bf16 v[128:131], v[190:193], v[174:177], 0
	v_mfma_f32_16x16x32_bf16 v[124:127], v[190:193], v[182:185], 0
	v_mfma_f32_16x16x32_bf16 v[120:123], v[198:201], v[174:177], 0
	v_mfma_f32_16x16x32_bf16 v[116:119], v[198:201], v[182:185], 0
	v_mfma_f32_16x16x32_bf16 v[112:115], v[206:209], v[174:177], 0
	v_mfma_f32_16x16x32_bf16 v[108:111], v[206:209], v[182:185], 0
	v_mfma_f32_16x16x32_bf16 v[104:107], v[214:217], v[174:177], 0
	v_mfma_f32_16x16x32_bf16 v[100:103], v[214:217], v[182:185], 0
	v_mfma_f32_16x16x32_bf16 v[128:131], v[194:197], v[178:181], v[128:131]
	v_mfma_f32_16x16x32_bf16 v[124:127], v[194:197], v[186:189], v[124:127]
	v_mfma_f32_16x16x32_bf16 v[120:123], v[202:205], v[178:181], v[120:123]
	v_mfma_f32_16x16x32_bf16 v[116:119], v[202:205], v[186:189], v[116:119]
	v_mfma_f32_16x16x32_bf16 v[112:115], v[210:213], v[178:181], v[112:115]
	v_mfma_f32_16x16x32_bf16 v[108:111], v[210:213], v[186:189], v[108:111]
	v_mfma_f32_16x16x32_bf16 v[104:107], v[218:221], v[178:181], v[104:107]
	v_mfma_f32_16x16x32_bf16 v[100:103], v[218:221], v[186:189], v[100:103]
	s_barrier
	v_lshl_add_u64 v[246:247], v[138:139], 0, s[12:13]
	v_lshl_add_u64 v[248:249], v[246:247], 0, s[38:39]
	s_or_b32 m0, s100, 0x10000
	ds_read_b128 v[226:229], v167
	ds_read_b128 v[230:233], v167 offset:1024
	ds_read_b128 v[238:241], v167 offset:2048
	ds_read_b128 v[242:245], v167 offset:3072
	global_load_lds_dwordx4 v[248:249], off
	v_lshl_add_u64 v[248:249], v[140:141], 0, s[12:13]
	s_or_b32 m0, s100, 0x12000
	v_lshl_add_u64 v[250:251], v[248:249], 0, s[38:39]
	global_load_lds_dwordx4 v[250:251], off
	s_barrier
; #define LDA8(dst, b, h) _Pragma("unroll") for (int m = 0; m < 4; ++m) _Pragma("unroll") for (int k = 0; k < 2; ++k) \
;     dst[m][k] = *(const bf16x8*)((const char*)SA8(b, h) + lds_byte8(wr * 64 + m * 16 + fr, k * 32 + fq * 8))
; #define LDB8(dst, b, h) _Pragma("unroll") for (int n = 0; n < 2; ++n) _Pragma("unroll") for (int k = 0; k < 2; ++k) \
;     dst[n][k] = *(const bf16x8*)((const char*)SB8(b, h) + lds_byte8(wc * 32 + n * 16 + fr, k * 32 + fq * 8))
; #define WAIT_V8(n) asm volatile("s_waitcnt vmcnt(" #n ")" ::: "memory")
; #define WAIT_L8(n) asm volatile("s_waitcnt lgkmcnt(" #n ")" ::: "memory")
; #define BAR8 __builtin_amdgcn_s_barrier()
; #define SCHED8 __builtin_amdgcn_sched_barrier(0)
;     ...
;     BAR8; WAIT_L8(0); MMA8(0, 1, At, B1); BAR8;
;     LDA8(At, 0, 1); STAGE8(SA8(0, 0), A, lda, brow, tt + 2);
;     BAR8; WAIT_L8(0); MMA8(1, 0, At, B0); BAR8; SCHED8;
;     STAGE8(SB8(0, 1), Bt, K, bcol + 128, tt + 2);
;     WAIT_V8(6); BAR8; MMA8(1, 1, At, B1); BAR8;
;     LDB8(B0, 1, 0); SCHED8; LDA8(At, 1, 0); STAGE8(SA8(0, 1), A, lda, brow + 128, tt + 2);
;     WAIT_L8(8); BAR8; WAIT_L8(0); MMA8(0, 0, At, B0); BAR8; SCHED8;
;     LDB8(B1, 1, 1); STAGE8(SB8(1, 0), Bt, K, bcol, tt + 3);
	s_waitcnt lgkmcnt(0)
	v_mfma_f32_16x16x32_bf16 v[96:99], v[190:193], v[226:229], 0
	v_mfma_f32_16x16x32_bf16 v[92:95], v[190:193], v[238:241], 0
	v_mfma_f32_16x16x32_bf16 v[88:91], v[198:201], v[226:229], 0
	v_mfma_f32_16x16x32_bf16 v[84:87], v[198:201], v[238:241], 0
	v_mfma_f32_16x16x32_bf16 v[80:83], v[206:209], v[226:229], 0
	v_mfma_f32_16x16x32_bf16 v[76:79], v[206:209], v[238:241], 0
	v_mfma_f32_16x16x32_bf16 v[72:75], v[214:217], v[226:229], 0
	v_mfma_f32_16x16x32_bf16 v[68:71], v[214:217], v[238:241], 0
	v_mfma_f32_16x16x32_bf16 v[96:99], v[194:197], v[230:233], v[96:99]
	v_mfma_f32_16x16x32_bf16 v[92:95], v[194:197], v[242:245], v[92:95]
	v_mfma_f32_16x16x32_bf16 v[88:91], v[202:205], v[230:233], v[88:91]
	v_mfma_f32_16x16x32_bf16 v[84:87], v[202:205], v[242:245], v[84:87]
	v_mfma_f32_16x16x32_bf16 v[80:83], v[210:213], v[230:233], v[80:83]
	v_mfma_f32_16x16x32_bf16 v[76:79], v[210:213], v[242:245], v[76:79]
	v_mfma_f32_16x16x32_bf16 v[72:75], v[218:221], v[230:233], v[72:75]
	v_mfma_f32_16x16x32_bf16 v[68:71], v[218:221], v[242:245], v[68:71]
	v_lshl_add_u64 v[250:251], v[222:223], 0, s[40:41]
	s_mov_b32 m0, s100
	s_barrier
	ds_read_b128 v[190:193], v156 offset:16384
	ds_read_b128 v[194:197], v156 offset:17408
	ds_read_b128 v[198:201], v155 offset:16384
	ds_read_b128 v[202:205], v155 offset:17408
	ds_read_b128 v[206:209], v154 offset:16384
	ds_read_b128 v[210:213], v154 offset:17408
	ds_read_b128 v[214:217], v153 offset:16384
	ds_read_b128 v[218:221], v153 offset:17408
	global_load_lds_dwordx4 v[250:251], off
	s_or_b32 m0, s100, 0x2000
	v_lshl_add_u64 v[250:251], v[236:237], 0, s[40:41]
	global_load_lds_dwordx4 v[250:251], off
	s_barrier
	s_waitcnt lgkmcnt(0)
	v_mfma_f32_16x16x32_bf16 v[64:67], v[190:193], v[174:177], 0
	v_mfma_f32_16x16x32_bf16 v[60:63], v[190:193], v[182:185], 0
	v_mfma_f32_16x16x32_bf16 v[56:59], v[198:201], v[174:177], 0
	v_mfma_f32_16x16x32_bf16 v[52:55], v[198:201], v[182:185], 0
	v_mfma_f32_16x16x32_bf16 v[48:51], v[206:209], v[174:177], 0
	v_mfma_f32_16x16x32_bf16 v[44:47], v[206:209], v[182:185], 0
	v_mfma_f32_16x16x32_bf16 v[40:43], v[214:217], v[174:177], 0
	v_mfma_f32_16x16x32_bf16 v[36:39], v[214:217], v[182:185], 0
	v_mfma_f32_16x16x32_bf16 v[64:67], v[194:197], v[178:181], v[64:67]
	v_mfma_f32_16x16x32_bf16 v[60:63], v[194:197], v[186:189], v[60:63]
	v_mfma_f32_16x16x32_bf16 v[56:59], v[202:205], v[178:181], v[56:59]
	v_mfma_f32_16x16x32_bf16 v[52:55], v[202:205], v[186:189], v[52:55]
	v_mfma_f32_16x16x32_bf16 v[48:51], v[210:213], v[178:181], v[48:51]
	v_mfma_f32_16x16x32_bf16 v[44:47], v[210:213], v[186:189], v[44:47]
	v_mfma_f32_16x16x32_bf16 v[40:43], v[218:221], v[178:181], v[40:43]
	v_mfma_f32_16x16x32_bf16 v[36:39], v[218:221], v[186:189], v[36:39]
	s_barrier
	s_or_b32 m0, s100, 0x14000
	v_lshl_add_u64 v[174:175], v[246:247], 0, s[42:43]
	global_load_lds_dwordx4 v[174:175], off
	s_or_b32 m0, s100, 0x16000
	v_lshl_add_u64 v[174:175], v[248:249], 0, s[42:43]
	global_load_lds_dwordx4 v[174:175], off
	s_waitcnt vmcnt(6)
	s_barrier
	v_mfma_f32_16x16x32_bf16 v[32:35], v[190:193], v[226:229], 0
	v_mfma_f32_16x16x32_bf16 v[28:31], v[190:193], v[238:241], 0
	v_mfma_f32_16x16x32_bf16 v[24:27], v[198:201], v[226:229], 0
	v_mfma_f32_16x16x32_bf16 v[20:23], v[198:201], v[238:241], 0
	v_mfma_f32_16x16x32_bf16 v[16:19], v[206:209], v[226:229], 0
	v_mfma_f32_16x16x32_bf16 v[12:15], v[206:209], v[238:241], 0
	v_mfma_f32_16x16x32_bf16 v[8:11], v[214:217], v[226:229], 0
	v_mfma_f32_16x16x32_bf16 v[4:7], v[214:217], v[238:241], 0
	v_mfma_f32_16x16x32_bf16 v[32:35], v[194:197], v[230:233], v[32:35]
	v_mfma_f32_16x16x32_bf16 v[28:31], v[194:197], v[242:245], v[28:31]
	v_mfma_f32_16x16x32_bf16 v[24:27], v[202:205], v[230:233], v[24:27]
	v_mfma_f32_16x16x32_bf16 v[20:23], v[202:205], v[242:245], v[20:23]
	v_mfma_f32_16x16x32_bf16 v[16:19], v[210:213], v[230:233], v[16:19]
	v_mfma_f32_16x16x32_bf16 v[12:15], v[210:213], v[242:245], v[12:15]
	v_mfma_f32_16x16x32_bf16 v[8:11], v[218:221], v[230:233], v[8:11]
	v_mfma_f32_16x16x32_bf16 v[4:7], v[218:221], v[242:245], v[4:7]
	s_barrier
	ds_read_b128 v[174:177], v160
	ds_read_b128 v[178:181], v160 offset:1024
	ds_read_b128 v[182:185], v160 offset:2048
	ds_read_b128 v[186:189], v160 offset:3072
	v_lshl_add_u64 v[226:227], v[222:223], 0, s[44:45]
	s_or_b32 m0, s100, 0x4000
	ds_read_b128 v[190:193], v156 offset:32768
	ds_read_b128 v[194:197], v156 offset:33792
	ds_read_b128 v[198:201], v155 offset:32768
	ds_read_b128 v[202:205], v155 offset:33792
	ds_read_b128 v[206:209], v154 offset:32768
	ds_read_b128 v[210:213], v154 offset:33792
	ds_read_b128 v[214:217], v153 offset:32768
	ds_read_b128 v[218:221], v153 offset:33792
	global_load_lds_dwordx4 v[226:227], off
	s_or_b32 m0, s100, 0x6000
	v_lshl_add_u64 v[226:227], v[236:237], 0, s[44:45]
	global_load_lds_dwordx4 v[226:227], off
	s_waitcnt lgkmcnt(8)
	s_barrier
	s_waitcnt lgkmcnt(0)
	v_mfma_f32_16x16x32_bf16 v[128:131], v[190:193], v[174:177], v[128:131]
	v_mfma_f32_16x16x32_bf16 v[124:127], v[190:193], v[182:185], v[124:127]
	v_mfma_f32_16x16x32_bf16 v[120:123], v[198:201], v[174:177], v[120:123]
	v_mfma_f32_16x16x32_bf16 v[116:119], v[198:201], v[182:185], v[116:119]
	v_mfma_f32_16x16x32_bf16 v[112:115], v[206:209], v[174:177], v[112:115]
	v_mfma_f32_16x16x32_bf16 v[108:111], v[206:209], v[182:185], v[108:111]
	v_mfma_f32_16x16x32_bf16 v[104:107], v[214:217], v[174:177], v[104:107]
	v_mfma_f32_16x16x32_bf16 v[100:103], v[214:217], v[182:185], v[100:103]
	v_mfma_f32_16x16x32_bf16 v[128:131], v[194:197], v[178:181], v[128:131]
	v_mfma_f32_16x16x32_bf16 v[124:127], v[194:197], v[186:189], v[124:127]
	v_mfma_f32_16x16x32_bf16 v[120:123], v[202:205], v[178:181], v[120:123]
	v_mfma_f32_16x16x32_bf16 v[116:119], v[202:205], v[186:189], v[116:119]
	v_mfma_f32_16x16x32_bf16 v[112:115], v[210:213], v[178:181], v[112:115]
	v_mfma_f32_16x16x32_bf16 v[108:111], v[210:213], v[186:189], v[108:111]
	v_mfma_f32_16x16x32_bf16 v[104:107], v[218:221], v[178:181], v[104:107]
	v_mfma_f32_16x16x32_bf16 v[100:103], v[218:221], v[186:189], v[100:103]
	s_barrier
; #define LDA8(dst, b, h) _Pragma("unroll") for (int m = 0; m < 4; ++m) _Pragma("unroll") for (int k = 0; k < 2; ++k) \
;     dst[m][k] = *(const bf16x8*)((const char*)SA8(b, h) + lds_byte8(wr * 64 + m * 16 + fr, k * 32 + fq * 8))
; #define LDB8(dst, b, h) _Pragma("unroll") for (int n = 0; n < 2; ++n) _Pragma("unroll") for (int k = 0; k < 2; ++k) \
;     dst[n][k] = *(const bf16x8*)((const char*)SB8(b, h) + lds_byte8(wc * 32 + n * 16 + fr, k * 32 + fq * 8))
; #define WAIT_V8(n) asm volatile("s_waitcnt vmcnt(" #n ")" ::: "memory")
; #define WAIT_L8(n) asm volatile("s_waitcnt lgkmcnt(" #n ")" ::: "memory")
; #define BAR8 __builtin_amdgcn_s_barrier()
; #define SCHED8 __builtin_amdgcn_sched_barrier(0)
;     ...
;     LDB8(B1, 1, 1); STAGE8(SB8(1, 0), Bt, K, bcol, tt + 3);
;     BAR8; WAIT_L8(0); MMA8(0, 1, At, B1); BAR8;
;     LDA8(At, 1, 1); STAGE8(SA8(1, 0), A, lda, brow, tt + 3);
;     BAR8; WAIT_L8(0); MMA8(1, 0, At, B0); BAR8; SCHED8;
;     STAGE8(SB8(1, 1), Bt, K, bcol + 128, tt + 3);
;     WAIT_V8(6); BAR8; MMA8(1, 1, At, B1); BAR8;
;   }
	v_lshl_add_u64 v[250:251], v[246:247], 0, s[46:47]
	s_or_b32 m0, s100, 0x18000
	ds_read_b128 v[226:229], v158
	ds_read_b128 v[230:233], v158 offset:1024
	ds_read_b128 v[238:241], v158 offset:2048
	ds_read_b128 v[242:245], v158 offset:3072
	global_load_lds_dwordx4 v[250:251], off
	s_or_b32 m0, s100, 0x1a000
	v_lshl_add_u64 v[250:251], v[248:249], 0, s[46:47]
	global_load_lds_dwordx4 v[250:251], off
	s_barrier
	s_waitcnt lgkmcnt(0)
	v_mfma_f32_16x16x32_bf16 v[96:99], v[190:193], v[226:229], v[96:99]
	v_mfma_f32_16x16x32_bf16 v[92:95], v[190:193], v[238:241], v[92:95]
	v_mfma_f32_16x16x32_bf16 v[88:91], v[198:201], v[226:229], v[88:91]
	v_mfma_f32_16x16x32_bf16 v[84:87], v[198:201], v[238:241], v[84:87]
	v_mfma_f32_16x16x32_bf16 v[80:83], v[206:209], v[226:229], v[80:83]
	v_mfma_f32_16x16x32_bf16 v[76:79], v[206:209], v[238:241], v[76:79]
	v_mfma_f32_16x16x32_bf16 v[72:75], v[214:217], v[226:229], v[72:75]
	v_mfma_f32_16x16x32_bf16 v[68:71], v[214:217], v[238:241], v[68:71]
	v_mfma_f32_16x16x32_bf16 v[96:99], v[194:197], v[230:233], v[96:99]
	v_mfma_f32_16x16x32_bf16 v[92:95], v[194:197], v[242:245], v[92:95]
	v_mfma_f32_16x16x32_bf16 v[88:91], v[202:205], v[230:233], v[88:91]
	v_mfma_f32_16x16x32_bf16 v[84:87], v[202:205], v[242:245], v[84:87]
	v_mfma_f32_16x16x32_bf16 v[80:83], v[210:213], v[230:233], v[80:83]
	v_mfma_f32_16x16x32_bf16 v[76:79], v[210:213], v[242:245], v[76:79]
	v_mfma_f32_16x16x32_bf16 v[72:75], v[218:221], v[230:233], v[72:75]
	v_mfma_f32_16x16x32_bf16 v[68:71], v[218:221], v[242:245], v[68:71]
	v_lshl_add_u64 v[222:223], v[222:223], 0, s[48:49]
	s_or_b32 m0, s100, 0x8000
	s_barrier
	ds_read_b128 v[190:193], v156 offset:49152
	ds_read_b128 v[194:197], v156 offset:50176
	ds_read_b128 v[198:201], v155 offset:49152
	ds_read_b128 v[202:205], v155 offset:50176
	ds_read_b128 v[206:209], v154 offset:49152
	ds_read_b128 v[210:213], v154 offset:50176
	ds_read_b128 v[214:217], v153 offset:49152
	ds_read_b128 v[218:221], v153 offset:50176
	global_load_lds_dwordx4 v[222:223], off
	s_or_b32 m0, s100, 0xa000
	v_lshl_add_u64 v[222:223], v[236:237], 0, s[48:49]
	global_load_lds_dwordx4 v[222:223], off
	s_barrier
	s_waitcnt lgkmcnt(0)
	v_mfma_f32_16x16x32_bf16 v[64:67], v[190:193], v[174:177], v[64:67]
	v_mfma_f32_16x16x32_bf16 v[60:63], v[190:193], v[182:185], v[60:63]
	v_mfma_f32_16x16x32_bf16 v[56:59], v[198:201], v[174:177], v[56:59]
	v_mfma_f32_16x16x32_bf16 v[52:55], v[198:201], v[182:185], v[52:55]
	v_mfma_f32_16x16x32_bf16 v[48:51], v[206:209], v[174:177], v[48:51]
	v_mfma_f32_16x16x32_bf16 v[44:47], v[206:209], v[182:185], v[44:47]
	v_mfma_f32_16x16x32_bf16 v[40:43], v[214:217], v[174:177], v[40:43]
	v_mfma_f32_16x16x32_bf16 v[36:39], v[214:217], v[182:185], v[36:39]
	v_mfma_f32_16x16x32_bf16 v[64:67], v[194:197], v[178:181], v[64:67]
	v_mfma_f32_16x16x32_bf16 v[60:63], v[194:197], v[186:189], v[60:63]
	v_mfma_f32_16x16x32_bf16 v[56:59], v[202:205], v[178:181], v[56:59]
	v_mfma_f32_16x16x32_bf16 v[52:55], v[202:205], v[186:189], v[52:55]
	v_mfma_f32_16x16x32_bf16 v[48:51], v[210:213], v[178:181], v[48:51]
	v_mfma_f32_16x16x32_bf16 v[44:47], v[210:213], v[186:189], v[44:47]
	v_mfma_f32_16x16x32_bf16 v[40:43], v[218:221], v[178:181], v[40:43]
	v_mfma_f32_16x16x32_bf16 v[36:39], v[218:221], v[186:189], v[36:39]
	s_barrier
	s_or_b32 m0, s100, 0x1c000
	v_lshl_add_u64 v[174:175], v[246:247], 0, s[50:51]
	global_load_lds_dwordx4 v[174:175], off
	s_or_b32 m0, s100, 0x1e000
	v_lshl_add_u64 v[174:175], v[248:249], 0, s[50:51]
	global_load_lds_dwordx4 v[174:175], off
	s_waitcnt vmcnt(6)
	s_barrier
	v_mfma_f32_16x16x32_bf16 v[32:35], v[190:193], v[226:229], v[32:35]
	v_mfma_f32_16x16x32_bf16 v[28:31], v[190:193], v[238:241], v[28:31]
	v_mfma_f32_16x16x32_bf16 v[24:27], v[198:201], v[226:229], v[24:27]
	v_mfma_f32_16x16x32_bf16 v[20:23], v[198:201], v[238:241], v[20:23]
	v_mfma_f32_16x16x32_bf16 v[16:19], v[206:209], v[226:229], v[16:19]
	v_mfma_f32_16x16x32_bf16 v[12:15], v[206:209], v[238:241], v[12:15]
	v_mfma_f32_16x16x32_bf16 v[8:11], v[214:217], v[226:229], v[8:11]
	v_mfma_f32_16x16x32_bf16 v[4:7], v[214:217], v[238:241], v[4:7]
	v_mfma_f32_16x16x32_bf16 v[32:35], v[194:197], v[230:233], v[32:35]
	v_mfma_f32_16x16x32_bf16 v[28:31], v[194:197], v[242:245], v[28:31]
	v_mfma_f32_16x16x32_bf16 v[24:27], v[202:205], v[230:233], v[24:27]
	v_mfma_f32_16x16x32_bf16 v[20:23], v[202:205], v[242:245], v[20:23]
	v_mfma_f32_16x16x32_bf16 v[16:19], v[210:213], v[230:233], v[16:19]
	v_mfma_f32_16x16x32_bf16 v[12:15], v[210:213], v[242:245], v[12:15]
	v_mfma_f32_16x16x32_bf16 v[8:11], v[218:221], v[230:233], v[8:11]
	v_mfma_f32_16x16x32_bf16 v[4:7], v[218:221], v[242:245], v[4:7]
	s_add_i32 s29, s29, 2
	s_add_u32 s12, s12, 0x100
	s_addc_u32 s13, s13, 0
	s_cmp_lt_u32 s29, 4
	s_barrier
	s_cbranch_scc0 .Lpk_exit_5
; #define LDA8(dst, b, h) _Pragma("unroll") for (int m = 0; m < 4; ++m) _Pragma("unroll") for (int k = 0; k < 2; ++k) \
;     dst[m][k] = *(const bf16x8*)((const char*)SA8(b, h) + lds_byte8(wr * 64 + m * 16 + fr, k * 32 + fq * 8))
; #define LDB8(dst, b, h) _Pragma("unroll") for (int n = 0; n < 2; ++n) _Pragma("unroll") for (int k = 0; k < 2; ++k) \
;     dst[n][k] = *(const bf16x8*)((const char*)SB8(b, h) + lds_byte8(wc * 32 + n * 16 + fr, k * 32 + fq * 8))
; #define WAIT_V8(n) asm volatile("s_waitcnt vmcnt(" #n ")" ::: "memory")
; #define WAIT_L8(n) asm volatile("s_waitcnt lgkmcnt(" #n ")" ::: "memory")
; #define BAR8 __builtin_amdgcn_s_barrier()
; #define SCHED8 __builtin_amdgcn_sched_barrier(0)
;     ...
;   for (int tt = 0; tt < nt - 2; tt += 2) {
;     LDB8(B0, 0, 0); SCHED8; LDA8(At, 0, 0); STAGE8(SA8(1, 1), A, lda, brow + 128, tt + 1);
;     WAIT_L8(8); BAR8; WAIT_L8(0); MMA8(0, 0, At, B0); BAR8; SCHED8;
;     LDB8(B1, 0, 1); STAGE8(SB8(0, 0), Bt, K, bcol, tt + 2);
;     BAR8; WAIT_L8(0); MMA8(0, 1, At, B1); BAR8;
;     LDA8(At, 0, 1); STAGE8(SA8(0, 0), A, lda, brow, tt + 2);
;     BAR8; WAIT_L8(0); MMA8(1, 0, At, B0); BAR8; SCHED8;
;     STAGE8(SB8(0, 1), Bt, K, bcol + 128, tt + 2);
;     WAIT_V8(6); BAR8; MMA8(1, 1, At, B1); BAR8;
.LBB0_1152:
	ds_read_b128 v[174:177], v171
	ds_read_b128 v[178:181], v171 offset:1024
	ds_read_b128 v[182:185], v171 offset:2048
	ds_read_b128 v[186:189], v171 offset:3072
	v_lshl_add_u64 v[222:223], v[142:143], 0, s[12:13]
	v_lshl_add_u64 v[226:227], v[222:223], 0, s[36:37]
	s_or_b32 m0, s100, 0xc000
	v_lshl_add_u64 v[236:237], v[144:145], 0, s[12:13]
	ds_read_b128 v[190:193], v156
	ds_read_b128 v[194:197], v156 offset:1024
	ds_read_b128 v[198:201], v155
	ds_read_b128 v[202:205], v155 offset:1024
	ds_read_b128 v[206:209], v154
	ds_read_b128 v[210:213], v154 offset:1024
	ds_read_b128 v[214:217], v153
	ds_read_b128 v[218:221], v153 offset:1024
	global_load_lds_dwordx4 v[226:227], off
	s_or_b32 m0, s100, 0xe000
	v_lshl_add_u64 v[226:227], v[236:237], 0, s[36:37]
	global_load_lds_dwordx4 v[226:227], off
	s_waitcnt lgkmcnt(8)
	s_barrier
	s_waitcnt lgkmcnt(0)
	v_mfma_f32_16x16x32_bf16 v[128:131], v[190:193], v[174:177], v[128:131]
	v_mfma_f32_16x16x32_bf16 v[124:127], v[190:193], v[182:185], v[124:127]
	v_mfma_f32_16x16x32_bf16 v[120:123], v[198:201], v[174:177], v[120:123]
	v_mfma_f32_16x16x32_bf16 v[116:119], v[198:201], v[182:185], v[116:119]
	v_mfma_f32_16x16x32_bf16 v[112:115], v[206:209], v[174:177], v[112:115]
	v_mfma_f32_16x16x32_bf16 v[108:111], v[206:209], v[182:185], v[108:111]
	v_mfma_f32_16x16x32_bf16 v[104:107], v[214:217], v[174:177], v[104:107]
	v_mfma_f32_16x16x32_bf16 v[100:103], v[214:217], v[182:185], v[100:103]
	v_mfma_f32_16x16x32_bf16 v[128:131], v[194:197], v[178:181], v[128:131]
	v_mfma_f32_16x16x32_bf16 v[124:127], v[194:197], v[186:189], v[124:127]
	v_mfma_f32_16x16x32_bf16 v[120:123], v[202:205], v[178:181], v[120:123]
	v_mfma_f32_16x16x32_bf16 v[116:119], v[202:205], v[186:189], v[116:119]
	v_mfma_f32_16x16x32_bf16 v[112:115], v[210:213], v[178:181], v[112:115]
	v_mfma_f32_16x16x32_bf16 v[108:111], v[210:213], v[186:189], v[108:111]
	v_mfma_f32_16x16x32_bf16 v[104:107], v[218:221], v[178:181], v[104:107]
	v_mfma_f32_16x16x32_bf16 v[100:103], v[218:221], v[186:189], v[100:103]
	s_barrier
	v_lshl_add_u64 v[246:247], v[138:139], 0, s[12:13]
	v_lshl_add_u64 v[248:249], v[246:247], 0, s[38:39]
	s_or_b32 m0, s100, 0x10000
	ds_read_b128 v[226:229], v167
	ds_read_b128 v[230:233], v167 offset:1024
	ds_read_b128 v[238:241], v167 offset:2048
	ds_read_b128 v[242:245], v167 offset:3072
	global_load_lds_dwordx4 v[248:249], off
	v_lshl_add_u64 v[248:249], v[140:141], 0, s[12:13]
	s_or_b32 m0, s100, 0x12000
	v_lshl_add_u64 v[250:251], v[248:249], 0, s[38:39]
	global_load_lds_dwordx4 v[250:251], off
	s_barrier
	s_waitcnt lgkmcnt(0)
	v_mfma_f32_16x16x32_bf16 v[96:99], v[190:193], v[226:229], v[96:99]
	v_mfma_f32_16x16x32_bf16 v[92:95], v[190:193], v[238:241], v[92:95]
	v_mfma_f32_16x16x32_bf16 v[88:91], v[198:201], v[226:229], v[88:91]
	v_mfma_f32_16x16x32_bf16 v[84:87], v[198:201], v[238:241], v[84:87]
	v_mfma_f32_16x16x32_bf16 v[80:83], v[206:209], v[226:229], v[80:83]
	v_mfma_f32_16x16x32_bf16 v[76:79], v[206:209], v[238:241], v[76:79]
	v_mfma_f32_16x16x32_bf16 v[72:75], v[214:217], v[226:229], v[72:75]
	v_mfma_f32_16x16x32_bf16 v[68:71], v[214:217], v[238:241], v[68:71]
	v_mfma_f32_16x16x32_bf16 v[96:99], v[194:197], v[230:233], v[96:99]
	v_mfma_f32_16x16x32_bf16 v[92:95], v[194:197], v[242:245], v[92:95]
	v_mfma_f32_16x16x32_bf16 v[88:91], v[202:205], v[230:233], v[88:91]
	v_mfma_f32_16x16x32_bf16 v[84:87], v[202:205], v[242:245], v[84:87]
	v_mfma_f32_16x16x32_bf16 v[80:83], v[210:213], v[230:233], v[80:83]
	v_mfma_f32_16x16x32_bf16 v[76:79], v[210:213], v[242:245], v[76:79]
	v_mfma_f32_16x16x32_bf16 v[72:75], v[218:221], v[230:233], v[72:75]
	v_mfma_f32_16x16x32_bf16 v[68:71], v[218:221], v[242:245], v[68:71]
	v_lshl_add_u64 v[250:251], v[222:223], 0, s[40:41]
	s_mov_b32 m0, s100
	s_barrier
	ds_read_b128 v[190:193], v156 offset:16384
	ds_read_b128 v[194:197], v156 offset:17408
	ds_read_b128 v[198:201], v155 offset:16384
	ds_read_b128 v[202:205], v155 offset:17408
	ds_read_b128 v[206:209], v154 offset:16384
	ds_read_b128 v[210:213], v154 offset:17408
	ds_read_b128 v[214:217], v153 offset:16384
	ds_read_b128 v[218:221], v153 offset:17408
	global_load_lds_dwordx4 v[250:251], off
	s_or_b32 m0, s100, 0x2000
	v_lshl_add_u64 v[250:251], v[236:237], 0, s[40:41]
	global_load_lds_dwordx4 v[250:251], off
	s_barrier
	s_waitcnt lgkmcnt(0)
	v_mfma_f32_16x16x32_bf16 v[64:67], v[190:193], v[174:177], v[64:67]
	v_mfma_f32_16x16x32_bf16 v[60:63], v[190:193], v[182:185], v[60:63]
	v_mfma_f32_16x16x32_bf16 v[56:59], v[198:201], v[174:177], v[56:59]
	v_mfma_f32_16x16x32_bf16 v[52:55], v[198:201], v[182:185], v[52:55]
	v_mfma_f32_16x16x32_bf16 v[48:51], v[206:209], v[174:177], v[48:51]
	v_mfma_f32_16x16x32_bf16 v[44:47], v[206:209], v[182:185], v[44:47]
	v_mfma_f32_16x16x32_bf16 v[40:43], v[214:217], v[174:177], v[40:43]
	v_mfma_f32_16x16x32_bf16 v[36:39], v[214:217], v[182:185], v[36:39]
	v_mfma_f32_16x16x32_bf16 v[64:67], v[194:197], v[178:181], v[64:67]
	v_mfma_f32_16x16x32_bf16 v[60:63], v[194:197], v[186:189], v[60:63]
	v_mfma_f32_16x16x32_bf16 v[56:59], v[202:205], v[178:181], v[56:59]
	v_mfma_f32_16x16x32_bf16 v[52:55], v[202:205], v[186:189], v[52:55]
	v_mfma_f32_16x16x32_bf16 v[48:51], v[210:213], v[178:181], v[48:51]
	v_mfma_f32_16x16x32_bf16 v[44:47], v[210:213], v[186:189], v[44:47]
	v_mfma_f32_16x16x32_bf16 v[40:43], v[218:221], v[178:181], v[40:43]
	v_mfma_f32_16x16x32_bf16 v[36:39], v[218:221], v[186:189], v[36:39]
	s_barrier
	s_or_b32 m0, s100, 0x14000
	v_lshl_add_u64 v[174:175], v[246:247], 0, s[42:43]
	global_load_lds_dwordx4 v[174:175], off
	s_or_b32 m0, s100, 0x16000
	v_lshl_add_u64 v[174:175], v[248:249], 0, s[42:43]
	global_load_lds_dwordx4 v[174:175], off
	s_waitcnt vmcnt(6)
	s_barrier
; #define LDA8(dst, b, h) _Pragma("unroll") for (int m = 0; m < 4; ++m) _Pragma("unroll") for (int k = 0; k < 2; ++k) \
;     dst[m][k] = *(const bf16x8*)((const char*)SA8(b, h) + lds_byte8(wr * 64 + m * 16 + fr, k * 32 + fq * 8))
; #define LDB8(dst, b, h) _Pragma("unroll") for (int n = 0; n < 2; ++n) _Pragma("unroll") for (int k = 0; k < 2; ++k) \
;     dst[n][k] = *(const bf16x8*)((const char*)SB8(b, h) + lds_byte8(wc * 32 + n * 16 + fr, k * 32 + fq * 8))
; #define WAIT_L8(n) asm volatile("s_waitcnt lgkmcnt(" #n ")" ::: "memory")
; #define BAR8 __builtin_amdgcn_s_barrier()
; #define SCHED8 __builtin_amdgcn_sched_barrier(0)
;     ...
;     LDB8(B0, 1, 0); SCHED8; LDA8(At, 1, 0); STAGE8(SA8(0, 1), A, lda, brow + 128, tt + 2);
;     WAIT_L8(8); BAR8; WAIT_L8(0); MMA8(0, 0, At, B0); BAR8; SCHED8;
;     LDB8(B1, 1, 1); STAGE8(SB8(1, 0), Bt, K, bcol, tt + 3);
;     BAR8; WAIT_L8(0); MMA8(0, 1, At, B1); BAR8;
;     LDA8(At, 1, 1); STAGE8(SA8(1, 0), A, lda, brow, tt + 3);
;     BAR8; WAIT_L8(0); MMA8(1, 0, At, B0); BAR8; SCHED8;
	v_mfma_f32_16x16x32_bf16 v[32:35], v[190:193], v[226:229], v[32:35]
	v_mfma_f32_16x16x32_bf16 v[28:31], v[190:193], v[238:241], v[28:31]
	v_mfma_f32_16x16x32_bf16 v[24:27], v[198:201], v[226:229], v[24:27]
	v_mfma_f32_16x16x32_bf16 v[20:23], v[198:201], v[238:241], v[20:23]
	v_mfma_f32_16x16x32_bf16 v[16:19], v[206:209], v[226:229], v[16:19]
	v_mfma_f32_16x16x32_bf16 v[12:15], v[206:209], v[238:241], v[12:15]
	v_mfma_f32_16x16x32_bf16 v[8:11], v[214:217], v[226:229], v[8:11]
	v_mfma_f32_16x16x32_bf16 v[4:7], v[214:217], v[238:241], v[4:7]
	v_mfma_f32_16x16x32_bf16 v[32:35], v[194:197], v[230:233], v[32:35]
	v_mfma_f32_16x16x32_bf16 v[28:31], v[194:197], v[242:245], v[28:31]
	v_mfma_f32_16x16x32_bf16 v[24:27], v[202:205], v[230:233], v[24:27]
	v_mfma_f32_16x16x32_bf16 v[20:23], v[202:205], v[242:245], v[20:23]
	v_mfma_f32_16x16x32_bf16 v[16:19], v[210:213], v[230:233], v[16:19]
	v_mfma_f32_16x16x32_bf16 v[12:15], v[210:213], v[242:245], v[12:15]
	v_mfma_f32_16x16x32_bf16 v[8:11], v[218:221], v[230:233], v[8:11]
	v_mfma_f32_16x16x32_bf16 v[4:7], v[218:221], v[242:245], v[4:7]
	s_barrier
	ds_read_b128 v[174:177], v160
	ds_read_b128 v[178:181], v160 offset:1024
	ds_read_b128 v[182:185], v160 offset:2048
	ds_read_b128 v[186:189], v160 offset:3072
	v_lshl_add_u64 v[226:227], v[222:223], 0, s[44:45]
	s_or_b32 m0, s100, 0x4000
	ds_read_b128 v[190:193], v156 offset:32768
	ds_read_b128 v[194:197], v156 offset:33792
	ds_read_b128 v[198:201], v155 offset:32768
	ds_read_b128 v[202:205], v155 offset:33792
	ds_read_b128 v[206:209], v154 offset:32768
	ds_read_b128 v[210:213], v154 offset:33792
	ds_read_b128 v[214:217], v153 offset:32768
	ds_read_b128 v[218:221], v153 offset:33792
	global_load_lds_dwordx4 v[226:227], off
	s_or_b32 m0, s100, 0x6000
	v_lshl_add_u64 v[226:227], v[236:237], 0, s[44:45]
	global_load_lds_dwordx4 v[226:227], off
	s_waitcnt lgkmcnt(8)
	s_barrier
	s_waitcnt lgkmcnt(0)
	v_mfma_f32_16x16x32_bf16 v[128:131], v[190:193], v[174:177], v[128:131]
	v_mfma_f32_16x16x32_bf16 v[124:127], v[190:193], v[182:185], v[124:127]
	v_mfma_f32_16x16x32_bf16 v[120:123], v[198:201], v[174:177], v[120:123]
	v_mfma_f32_16x16x32_bf16 v[116:119], v[198:201], v[182:185], v[116:119]
	v_mfma_f32_16x16x32_bf16 v[112:115], v[206:209], v[174:177], v[112:115]
	v_mfma_f32_16x16x32_bf16 v[108:111], v[206:209], v[182:185], v[108:111]
	v_mfma_f32_16x16x32_bf16 v[104:107], v[214:217], v[174:177], v[104:107]
	v_mfma_f32_16x16x32_bf16 v[100:103], v[214:217], v[182:185], v[100:103]
	v_mfma_f32_16x16x32_bf16 v[128:131], v[194:197], v[178:181], v[128:131]
	v_mfma_f32_16x16x32_bf16 v[124:127], v[194:197], v[186:189], v[124:127]
	v_mfma_f32_16x16x32_bf16 v[120:123], v[202:205], v[178:181], v[120:123]
	v_mfma_f32_16x16x32_bf16 v[116:119], v[202:205], v[186:189], v[116:119]
	v_mfma_f32_16x16x32_bf16 v[112:115], v[210:213], v[178:181], v[112:115]
	v_mfma_f32_16x16x32_bf16 v[108:111], v[210:213], v[186:189], v[108:111]
	v_mfma_f32_16x16x32_bf16 v[104:107], v[218:221], v[178:181], v[104:107]
	v_mfma_f32_16x16x32_bf16 v[100:103], v[218:221], v[186:189], v[100:103]
	s_barrier
	v_lshl_add_u64 v[250:251], v[246:247], 0, s[46:47]
	s_or_b32 m0, s100, 0x18000
	ds_read_b128 v[226:229], v158
	ds_read_b128 v[230:233], v158 offset:1024
	ds_read_b128 v[238:241], v158 offset:2048
	ds_read_b128 v[242:245], v158 offset:3072
	global_load_lds_dwordx4 v[250:251], off
	s_or_b32 m0, s100, 0x1a000
	v_lshl_add_u64 v[250:251], v[248:249], 0, s[46:47]
	global_load_lds_dwordx4 v[250:251], off
	s_barrier
	s_waitcnt lgkmcnt(0)
	v_mfma_f32_16x16x32_bf16 v[96:99], v[190:193], v[226:229], v[96:99]
	v_mfma_f32_16x16x32_bf16 v[92:95], v[190:193], v[238:241], v[92:95]
	v_mfma_f32_16x16x32_bf16 v[88:91], v[198:201], v[226:229], v[88:91]
	v_mfma_f32_16x16x32_bf16 v[84:87], v[198:201], v[238:241], v[84:87]
	v_mfma_f32_16x16x32_bf16 v[80:83], v[206:209], v[226:229], v[80:83]
	v_mfma_f32_16x16x32_bf16 v[76:79], v[206:209], v[238:241], v[76:79]
	v_mfma_f32_16x16x32_bf16 v[72:75], v[214:217], v[226:229], v[72:75]
	v_mfma_f32_16x16x32_bf16 v[68:71], v[214:217], v[238:241], v[68:71]
	v_mfma_f32_16x16x32_bf16 v[96:99], v[194:197], v[230:233], v[96:99]
	v_mfma_f32_16x16x32_bf16 v[92:95], v[194:197], v[242:245], v[92:95]
	v_mfma_f32_16x16x32_bf16 v[88:91], v[202:205], v[230:233], v[88:91]
	v_mfma_f32_16x16x32_bf16 v[84:87], v[202:205], v[242:245], v[84:87]
	v_mfma_f32_16x16x32_bf16 v[80:83], v[210:213], v[230:233], v[80:83]
	v_mfma_f32_16x16x32_bf16 v[76:79], v[210:213], v[242:245], v[76:79]
	v_mfma_f32_16x16x32_bf16 v[72:75], v[218:221], v[230:233], v[72:75]
	v_mfma_f32_16x16x32_bf16 v[68:71], v[218:221], v[242:245], v[68:71]
	v_lshl_add_u64 v[222:223], v[222:223], 0, s[48:49]
	s_or_b32 m0, s100, 0x8000
	s_barrier
	ds_read_b128 v[190:193], v156 offset:49152
	ds_read_b128 v[194:197], v156 offset:50176
	ds_read_b128 v[198:201], v155 offset:49152
	ds_read_b128 v[202:205], v155 offset:50176
	ds_read_b128 v[206:209], v154 offset:49152
	ds_read_b128 v[210:213], v154 offset:50176
	ds_read_b128 v[214:217], v153 offset:49152
	ds_read_b128 v[218:221], v153 offset:50176
	global_load_lds_dwordx4 v[222:223], off
	s_or_b32 m0, s100, 0xa000
	v_lshl_add_u64 v[222:223], v[236:237], 0, s[48:49]
	global_load_lds_dwordx4 v[222:223], off
	s_barrier
; #define LDA8(dst, b, h) _Pragma("unroll") for (int m = 0; m < 4; ++m) _Pragma("unroll") for (int k = 0; k < 2; ++k) \
;     dst[m][k] = *(const bf16x8*)((const char*)SA8(b, h) + lds_byte8(wr * 64 + m * 16 + fr, k * 32 + fq * 8))
; #define LDB8(dst, b, h) _Pragma("unroll") for (int n = 0; n < 2; ++n) _Pragma("unroll") for (int k = 0; k < 2; ++k) \
;     dst[n][k] = *(const bf16x8*)((const char*)SB8(b, h) + lds_byte8(wc * 32 + n * 16 + fr, k * 32 + fq * 8))
; #define WAIT_V8(n) asm volatile("s_waitcnt vmcnt(" #n ")" ::: "memory")
; #define WAIT_L8(n) asm volatile("s_waitcnt lgkmcnt(" #n ")" ::: "memory")
; #define BAR8 __builtin_amdgcn_s_barrier()
;     ...
;     STAGE8(SB8(1, 1), Bt, K, bcol + 128, tt + 3);
;     WAIT_V8(6); BAR8; MMA8(1, 1, At, B1); BAR8;
;   }
;   { LDB8(B0, 0, 0); LDA8(At, 0, 0); STAGE8(SA8(1, 1), A, lda, brow + 128, nt - 1);
;     BAR8; WAIT_L8(0); MMA8(0, 0, At, B0); BAR8;
;     LDB8(B1, 0, 1); BAR8; WAIT_L8(0); MMA8(0, 1, At, B1); BAR8;
;     LDA8(At, 0, 1); WAIT_V8(4); BAR8; WAIT_L8(0); MMA8(1, 0, At, B0); MMA8(1, 1, At, B1); BAR8; }
;   { LDB8(B0, 1, 0); LDA8(At, 1, 0); WAIT_V8(2); BAR8; WAIT_L8(0); MMA8(0, 0, At, B0); BAR8;
	s_waitcnt lgkmcnt(0)
	v_mfma_f32_16x16x32_bf16 v[64:67], v[190:193], v[174:177], v[64:67]
	v_mfma_f32_16x16x32_bf16 v[60:63], v[190:193], v[182:185], v[60:63]
	v_mfma_f32_16x16x32_bf16 v[56:59], v[198:201], v[174:177], v[56:59]
	v_mfma_f32_16x16x32_bf16 v[52:55], v[198:201], v[182:185], v[52:55]
	v_mfma_f32_16x16x32_bf16 v[48:51], v[206:209], v[174:177], v[48:51]
	v_mfma_f32_16x16x32_bf16 v[44:47], v[206:209], v[182:185], v[44:47]
	v_mfma_f32_16x16x32_bf16 v[40:43], v[214:217], v[174:177], v[40:43]
	v_mfma_f32_16x16x32_bf16 v[36:39], v[214:217], v[182:185], v[36:39]
	v_mfma_f32_16x16x32_bf16 v[64:67], v[194:197], v[178:181], v[64:67]
	v_mfma_f32_16x16x32_bf16 v[60:63], v[194:197], v[186:189], v[60:63]
	v_mfma_f32_16x16x32_bf16 v[56:59], v[202:205], v[178:181], v[56:59]
	v_mfma_f32_16x16x32_bf16 v[52:55], v[202:205], v[186:189], v[52:55]
	v_mfma_f32_16x16x32_bf16 v[48:51], v[210:213], v[178:181], v[48:51]
	v_mfma_f32_16x16x32_bf16 v[44:47], v[210:213], v[186:189], v[44:47]
	v_mfma_f32_16x16x32_bf16 v[40:43], v[218:221], v[178:181], v[40:43]
	v_mfma_f32_16x16x32_bf16 v[36:39], v[218:221], v[186:189], v[36:39]
	s_barrier
	s_or_b32 m0, s100, 0x1c000
	v_lshl_add_u64 v[174:175], v[246:247], 0, s[50:51]
	global_load_lds_dwordx4 v[174:175], off
	s_or_b32 m0, s100, 0x1e000
	v_lshl_add_u64 v[174:175], v[248:249], 0, s[50:51]
	global_load_lds_dwordx4 v[174:175], off
	s_waitcnt vmcnt(6)
	s_barrier
	v_mfma_f32_16x16x32_bf16 v[32:35], v[190:193], v[226:229], v[32:35]
	v_mfma_f32_16x16x32_bf16 v[28:31], v[190:193], v[238:241], v[28:31]
	v_mfma_f32_16x16x32_bf16 v[24:27], v[198:201], v[226:229], v[24:27]
	v_mfma_f32_16x16x32_bf16 v[20:23], v[198:201], v[238:241], v[20:23]
	v_mfma_f32_16x16x32_bf16 v[16:19], v[206:209], v[226:229], v[16:19]
	v_mfma_f32_16x16x32_bf16 v[12:15], v[206:209], v[238:241], v[12:15]
	v_mfma_f32_16x16x32_bf16 v[8:11], v[214:217], v[226:229], v[8:11]
	v_mfma_f32_16x16x32_bf16 v[4:7], v[214:217], v[238:241], v[4:7]
	v_mfma_f32_16x16x32_bf16 v[32:35], v[194:197], v[230:233], v[32:35]
	v_mfma_f32_16x16x32_bf16 v[28:31], v[194:197], v[242:245], v[28:31]
	v_mfma_f32_16x16x32_bf16 v[24:27], v[202:205], v[230:233], v[24:27]
	v_mfma_f32_16x16x32_bf16 v[20:23], v[202:205], v[242:245], v[20:23]
	v_mfma_f32_16x16x32_bf16 v[16:19], v[210:213], v[230:233], v[16:19]
	v_mfma_f32_16x16x32_bf16 v[12:15], v[210:213], v[242:245], v[12:15]
	v_mfma_f32_16x16x32_bf16 v[8:11], v[218:221], v[230:233], v[8:11]
	v_mfma_f32_16x16x32_bf16 v[4:7], v[218:221], v[242:245], v[4:7]
	s_add_i32 s29, s29, 2
	s_add_u32 s12, s12, 0x100
	s_addc_u32 s13, s13, 0
	s_cmp_lt_u32 s29, 4
	s_barrier
	s_cbranch_scc1 .LBB0_1152
.Lpk_exit_5:
	s_add_u32 s2, s2, s27
	s_addc_u32 s3, s3, 0
	s_add_u32 s2, s2, 0x3000380
	s_addc_u32 s3, s3, 0
	v_lshl_add_u64 v[136:137], v[136:137], 1, s[2:3]
	v_lshl_add_u64 v[0:1], v[0:1], 1, v[136:137]
	s_or_b32 m0, s100, 0xc000
	ds_read_b128 v[138:141], v171
	ds_read_b128 v[142:145], v171 offset:1024
	ds_read_b128 v[162:165], v171 offset:2048
	ds_read_b128 v[168:171], v171 offset:3072
	ds_read_b128 v[174:177], v156
	ds_read_b128 v[178:181], v156 offset:1024
	ds_read_b128 v[182:185], v155
	ds_read_b128 v[186:189], v155 offset:1024
	ds_read_b128 v[190:193], v154
	ds_read_b128 v[194:197], v154 offset:1024
	ds_read_b128 v[198:201], v153
	ds_read_b128 v[202:205], v153 offset:1024
	global_load_lds_dwordx4 v[0:1], off
	v_lshl_add_u64 v[0:1], v[134:135], 1, s[2:3]
	s_or_b32 m0, s100, 0xe000
	v_lshl_add_u64 v[0:1], v[132:133], 1, v[0:1]
	global_load_lds_dwordx4 v[0:1], off
	s_barrier
	s_waitcnt lgkmcnt(0)
	v_mfma_f32_16x16x32_bf16 v[128:131], v[174:177], v[138:141], v[128:131]
	v_mfma_f32_16x16x32_bf16 v[124:127], v[174:177], v[162:165], v[124:127]
	v_mfma_f32_16x16x32_bf16 v[120:123], v[182:185], v[138:141], v[120:123]
	v_mfma_f32_16x16x32_bf16 v[112:115], v[190:193], v[138:141], v[112:115]
	v_mfma_f32_16x16x32_bf16 v[128:131], v[178:181], v[142:145], v[128:131]
	v_mfma_f32_16x16x32_bf16 v[124:127], v[178:181], v[168:171], v[124:127]
	v_mfma_f32_16x16x32_bf16 v[120:123], v[186:189], v[142:145], v[120:123]
	v_mfma_f32_16x16x32_bf16 v[116:119], v[182:185], v[162:165], v[116:119]
	v_mfma_f32_16x16x32_bf16 v[112:115], v[194:197], v[142:145], v[112:115]
	v_mfma_f32_16x16x32_bf16 v[108:111], v[190:193], v[162:165], v[108:111]
	v_mfma_f32_16x16x32_bf16 v[104:107], v[198:201], v[138:141], v[104:107]
	v_mfma_f32_16x16x32_bf16 v[100:103], v[198:201], v[162:165], v[100:103]
	v_mfma_f32_16x16x32_bf16 v[132:135], v[186:189], v[168:171], v[116:119]
	v_mfma_f32_16x16x32_bf16 v[206:209], v[194:197], v[168:171], v[108:111]
	v_mfma_f32_16x16x32_bf16 v[210:213], v[202:205], v[142:145], v[104:107]
	v_mfma_f32_16x16x32_bf16 v[214:217], v[202:205], v[168:171], v[100:103]
	s_barrier
	s_nop 1
	ds_read_b128 v[100:103], v167
	ds_read_b128 v[104:107], v167 offset:1024
	ds_read_b128 v[108:111], v167 offset:2048
	ds_read_b128 v[116:119], v167 offset:3072
	s_barrier
	s_waitcnt lgkmcnt(0)
	v_mfma_f32_16x16x32_bf16 v[80:83], v[190:193], v[100:103], v[80:83]
	v_mfma_f32_16x16x32_bf16 v[76:79], v[190:193], v[108:111], v[76:79]
	v_mfma_f32_16x16x32_bf16 v[72:75], v[198:201], v[100:103], v[72:75]
	v_mfma_f32_16x16x32_bf16 v[68:71], v[198:201], v[108:111], v[68:71]
	v_mfma_f32_16x16x32_bf16 v[96:99], v[174:177], v[100:103], v[96:99]
	v_mfma_f32_16x16x32_bf16 v[92:95], v[174:177], v[108:111], v[92:95]
	v_mfma_f32_16x16x32_bf16 v[88:91], v[182:185], v[100:103], v[88:91]
	v_mfma_f32_16x16x32_bf16 v[84:87], v[182:185], v[108:111], v[84:87]
	v_mfma_f32_16x16x32_bf16 v[80:83], v[194:197], v[104:107], v[80:83]
	v_mfma_f32_16x16x32_bf16 v[76:79], v[194:197], v[116:119], v[76:79]
	v_mfma_f32_16x16x32_bf16 v[72:75], v[202:205], v[104:107], v[72:75]
	v_mfma_f32_16x16x32_bf16 v[68:71], v[202:205], v[116:119], v[68:71]
	v_mfma_f32_16x16x32_bf16 v[218:221], v[178:181], v[104:107], v[96:99]
	v_mfma_f32_16x16x32_bf16 v[172:175], v[178:181], v[116:119], v[92:95]
	v_mfma_f32_16x16x32_bf16 v[176:179], v[186:189], v[104:107], v[88:91]
	v_mfma_f32_16x16x32_bf16 v[180:183], v[186:189], v[116:119], v[84:87]
	s_barrier
; #define LDA8(dst, b, h) _Pragma("unroll") for (int m = 0; m < 4; ++m) _Pragma("unroll") for (int k = 0; k < 2; ++k) \
;     dst[m][k] = *(const bf16x8*)((const char*)SA8(b, h) + lds_byte8(wr * 64 + m * 16 + fr, k * 32 + fq * 8))
; #define LDB8(dst, b, h) _Pragma("unroll") for (int n = 0; n < 2; ++n) _Pragma("unroll") for (int k = 0; k < 2; ++k) \
;     dst[n][k] = *(const bf16x8*)((const char*)SB8(b, h) + lds_byte8(wc * 32 + n * 16 + fr, k * 32 + fq * 8))
; #define WAIT_V8(n) asm volatile("s_waitcnt vmcnt(" #n ")" ::: "memory")
; #define WAIT_L8(n) asm volatile("s_waitcnt lgkmcnt(" #n ")" ::: "memory")
; #define BAR8 __builtin_amdgcn_s_barrier()
;     ...
;     LDA8(At, 0, 1); WAIT_V8(4); BAR8; WAIT_L8(0); MMA8(1, 0, At, B0); MMA8(1, 1, At, B1); BAR8; }
;   { LDB8(B0, 1, 0); LDA8(At, 1, 0); WAIT_V8(2); BAR8; WAIT_L8(0); MMA8(0, 0, At, B0); BAR8;
;     LDB8(B1, 1, 1); WAIT_V8(0); BAR8; WAIT_L8(0); MMA8(0, 1, At, B1); BAR8;
;     LDA8(At, 1, 1); BAR8; WAIT_L8(0); MMA8(1, 0, At, B0); MMA8(1, 1, At, B1); BAR8; }
	s_nop 0
	ds_read_b128 v[84:87], v156 offset:16384
	ds_read_b128 v[88:91], v156 offset:17408
	ds_read_b128 v[92:95], v155 offset:16384
	ds_read_b128 v[96:99], v155 offset:17408
	ds_read_b128 v[184:187], v154 offset:16384
	ds_read_b128 v[188:191], v154 offset:17408
	ds_read_b128 v[192:195], v153 offset:16384
	ds_read_b128 v[196:199], v153 offset:17408
	s_waitcnt vmcnt(4)
	s_barrier
	s_waitcnt lgkmcnt(0)
	v_mfma_f32_16x16x32_bf16 v[64:67], v[84:87], v[138:141], v[64:67]
	v_mfma_f32_16x16x32_bf16 v[60:63], v[84:87], v[162:165], v[60:63]
	v_mfma_f32_16x16x32_bf16 v[56:59], v[92:95], v[138:141], v[56:59]
	v_mfma_f32_16x16x32_bf16 v[52:55], v[92:95], v[162:165], v[52:55]
	v_mfma_f32_16x16x32_bf16 v[48:51], v[184:187], v[138:141], v[48:51]
	v_mfma_f32_16x16x32_bf16 v[44:47], v[184:187], v[162:165], v[44:47]
	v_mfma_f32_16x16x32_bf16 v[40:43], v[192:195], v[138:141], v[40:43]
	v_mfma_f32_16x16x32_bf16 v[36:39], v[192:195], v[162:165], v[36:39]
	v_mfma_f32_16x16x32_bf16 v[64:67], v[88:91], v[142:145], v[64:67]
	v_mfma_f32_16x16x32_bf16 v[60:63], v[88:91], v[168:171], v[60:63]
	v_mfma_f32_16x16x32_bf16 v[56:59], v[96:99], v[142:145], v[56:59]
	v_mfma_f32_16x16x32_bf16 v[52:55], v[96:99], v[168:171], v[52:55]
	v_mfma_f32_16x16x32_bf16 v[48:51], v[188:191], v[142:145], v[48:51]
	v_mfma_f32_16x16x32_bf16 v[44:47], v[188:191], v[168:171], v[44:47]
	v_mfma_f32_16x16x32_bf16 v[40:43], v[196:199], v[142:145], v[40:43]
	v_mfma_f32_16x16x32_bf16 v[36:39], v[196:199], v[168:171], v[36:39]
	v_mfma_f32_16x16x32_bf16 v[32:35], v[84:87], v[100:103], v[32:35]
	v_mfma_f32_16x16x32_bf16 v[28:31], v[84:87], v[108:111], v[28:31]
	v_mfma_f32_16x16x32_bf16 v[24:27], v[92:95], v[100:103], v[24:27]
	v_mfma_f32_16x16x32_bf16 v[20:23], v[92:95], v[108:111], v[20:23]
	v_mfma_f32_16x16x32_bf16 v[16:19], v[184:187], v[100:103], v[16:19]
	v_mfma_f32_16x16x32_bf16 v[12:15], v[184:187], v[108:111], v[12:15]
	v_mfma_f32_16x16x32_bf16 v[8:11], v[192:195], v[100:103], v[8:11]
	v_mfma_f32_16x16x32_bf16 v[4:7], v[192:195], v[108:111], v[4:7]
	v_mfma_f32_16x16x32_bf16 v[136:139], v[88:91], v[104:107], v[32:35]
	v_mfma_f32_16x16x32_bf16 v[140:143], v[88:91], v[116:119], v[28:31]
	v_mfma_f32_16x16x32_bf16 v[162:165], v[96:99], v[104:107], v[24:27]
	v_mfma_f32_16x16x32_bf16 v[166:169], v[96:99], v[116:119], v[20:23]
	v_mfma_f32_16x16x32_bf16 v[200:203], v[188:191], v[104:107], v[16:19]
	v_mfma_f32_16x16x32_bf16 v[184:187], v[188:191], v[116:119], v[12:15]
	v_mfma_f32_16x16x32_bf16 v[188:191], v[196:199], v[104:107], v[8:11]
	v_mfma_f32_16x16x32_bf16 v[192:195], v[196:199], v[116:119], v[4:7]
	s_barrier
	ds_read_b128 v[196:199], v160
	ds_read_b128 v[226:229], v160 offset:1024
	ds_read_b128 v[230:233], v160 offset:2048
	ds_read_b128 v[238:241], v160 offset:3072
	ds_read_b128 v[8:11], v156 offset:32768
	ds_read_b128 v[12:15], v156 offset:33792
	ds_read_b128 v[16:19], v155 offset:32768
	ds_read_b128 v[24:27], v155 offset:33792
	ds_read_b128 v[28:31], v154 offset:32768
	ds_read_b128 v[32:35], v154 offset:33792
	ds_read_b128 v[242:245], v153 offset:32768
	ds_read_b128 v[246:249], v153 offset:33792
	s_waitcnt vmcnt(2)
	s_barrier
	s_waitcnt lgkmcnt(0)
	v_mfma_f32_16x16x32_bf16 v[4:7], v[8:11], v[196:199], v[128:131]
	v_mfma_f32_16x16x32_bf16 v[104:107], v[12:15], v[226:229], v[4:7]
	v_mfma_f32_16x16x32_bf16 v[4:7], v[8:11], v[230:233], v[124:127]
	v_mfma_f32_16x16x32_bf16 v[116:119], v[12:15], v[238:241], v[4:7]
	v_mfma_f32_16x16x32_bf16 v[4:7], v[16:19], v[196:199], v[120:123]
	v_mfma_f32_16x16x32_bf16 v[100:103], v[24:27], v[226:229], v[4:7]
	v_mfma_f32_16x16x32_bf16 v[4:7], v[16:19], v[230:233], v[132:135]
	v_mfma_f32_16x16x32_bf16 v[108:111], v[24:27], v[238:241], v[4:7]
	v_mfma_f32_16x16x32_bf16 v[4:7], v[28:31], v[196:199], v[112:115]
	v_mfma_f32_16x16x32_bf16 v[92:95], v[32:35], v[226:229], v[4:7]
	v_mfma_f32_16x16x32_bf16 v[4:7], v[28:31], v[230:233], v[206:209]
	v_mfma_f32_16x16x32_bf16 v[96:99], v[32:35], v[238:241], v[4:7]
	v_mfma_f32_16x16x32_bf16 v[4:7], v[242:245], v[196:199], v[210:213]
	v_mfma_f32_16x16x32_bf16 v[84:87], v[246:249], v[226:229], v[4:7]
	v_mfma_f32_16x16x32_bf16 v[4:7], v[242:245], v[230:233], v[214:217]
	v_mfma_f32_16x16x32_bf16 v[88:91], v[246:249], v[238:241], v[4:7]
	s_barrier
; #define LDA8(dst, b, h) _Pragma("unroll") for (int m = 0; m < 4; ++m) _Pragma("unroll") for (int k = 0; k < 2; ++k) \
;     dst[m][k] = *(const bf16x8*)((const char*)SA8(b, h) + lds_byte8(wr * 64 + m * 16 + fr, k * 32 + fq * 8))
; #define LDB8(dst, b, h) _Pragma("unroll") for (int n = 0; n < 2; ++n) _Pragma("unroll") for (int k = 0; k < 2; ++k) \
;     dst[n][k] = *(const bf16x8*)((const char*)SB8(b, h) + lds_byte8(wc * 32 + n * 16 + fr, k * 32 + fq * 8))
; #define WAIT_V8(n) asm volatile("s_waitcnt vmcnt(" #n ")" ::: "memory")
; #define WAIT_L8(n) asm volatile("s_waitcnt lgkmcnt(" #n ")" ::: "memory")
; #define BAR8 __builtin_amdgcn_s_barrier()
;     ...
;     LDB8(B1, 1, 1); WAIT_V8(0); BAR8; WAIT_L8(0); MMA8(0, 1, At, B1); BAR8;
;     LDA8(At, 1, 1); BAR8; WAIT_L8(0); MMA8(1, 0, At, B0); MMA8(1, 1, At, B1); BAR8; }
;   if (wr == 0) BAR8;
;   __syncthreads();
;     ...
;   if (t < 256) {
	ds_read_b128 v[132:135], v158
	ds_read_b128 v[204:207], v158 offset:1024
	ds_read_b128 v[208:211], v158 offset:2048
	ds_read_b128 v[158:161], v158 offset:3072
	s_waitcnt vmcnt(0)
	s_barrier
	s_waitcnt lgkmcnt(0)
	v_mfma_f32_16x16x32_bf16 v[4:7], v[8:11], v[132:135], v[218:221]
	v_mfma_f32_16x16x32_bf16 v[8:11], v[8:11], v[208:211], v[172:175]
	v_mfma_f32_16x16x32_bf16 v[4:7], v[12:15], v[204:207], v[4:7]
	v_mfma_f32_16x16x32_bf16 v[20:23], v[12:15], v[158:161], v[8:11]
	v_mfma_f32_16x16x32_bf16 v[8:11], v[16:19], v[132:135], v[176:179]
	v_mfma_f32_16x16x32_bf16 v[12:15], v[16:19], v[208:211], v[180:183]
	v_mfma_f32_16x16x32_bf16 v[8:11], v[24:27], v[204:207], v[8:11]
	v_mfma_f32_16x16x32_bf16 v[24:27], v[24:27], v[158:161], v[12:15]
	v_mfma_f32_16x16x32_bf16 v[12:15], v[28:31], v[132:135], v[80:83]
	v_mfma_f32_16x16x32_bf16 v[16:19], v[28:31], v[208:211], v[76:79]
	v_mfma_f32_16x16x32_bf16 v[12:15], v[32:35], v[204:207], v[12:15]
	v_mfma_f32_16x16x32_bf16 v[28:31], v[32:35], v[158:161], v[16:19]
	v_mfma_f32_16x16x32_bf16 v[16:19], v[242:245], v[132:135], v[72:75]
	v_mfma_f32_16x16x32_bf16 v[32:35], v[242:245], v[208:211], v[68:71]
	v_mfma_f32_16x16x32_bf16 v[16:19], v[246:249], v[204:207], v[16:19]
	v_mfma_f32_16x16x32_bf16 v[32:35], v[246:249], v[158:161], v[32:35]
	s_barrier
	ds_read_b128 v[170:173], v156 offset:49152
	ds_read_b128 v[174:177], v156 offset:50176
	ds_read_b128 v[178:181], v155 offset:49152
	ds_read_b128 v[212:215], v155 offset:50176
	ds_read_b128 v[216:219], v154 offset:49152
	ds_read_b128 v[154:157], v154 offset:50176
	ds_read_b128 v[220:223], v153 offset:49152
	ds_read_b128 v[150:153], v153 offset:50176
	s_barrier
	s_waitcnt lgkmcnt(0)
	v_mfma_f32_16x16x32_bf16 v[64:67], v[170:173], v[196:199], v[64:67]
	v_mfma_f32_16x16x32_bf16 v[60:63], v[170:173], v[230:233], v[60:63]
	v_mfma_f32_16x16x32_bf16 v[56:59], v[178:181], v[196:199], v[56:59]
	v_mfma_f32_16x16x32_bf16 v[52:55], v[178:181], v[230:233], v[52:55]
	v_mfma_f32_16x16x32_bf16 v[48:51], v[216:219], v[196:199], v[48:51]
	v_mfma_f32_16x16x32_bf16 v[44:47], v[216:219], v[230:233], v[44:47]
	v_mfma_f32_16x16x32_bf16 v[40:43], v[220:223], v[196:199], v[40:43]
	v_mfma_f32_16x16x32_bf16 v[36:39], v[220:223], v[230:233], v[36:39]
	v_mfma_f32_16x16x32_bf16 v[128:131], v[174:177], v[226:229], v[64:67]
	v_mfma_f32_16x16x32_bf16 v[124:127], v[174:177], v[238:241], v[60:63]
	v_mfma_f32_16x16x32_bf16 v[120:123], v[212:215], v[226:229], v[56:59]
	v_mfma_f32_16x16x32_bf16 v[112:115], v[212:215], v[238:241], v[52:55]
	v_mfma_f32_16x16x32_bf16 v[80:83], v[154:157], v[226:229], v[48:51]
	v_mfma_f32_16x16x32_bf16 v[76:79], v[154:157], v[238:241], v[44:47]
	v_mfma_f32_16x16x32_bf16 v[72:75], v[150:153], v[226:229], v[40:43]
	v_mfma_f32_16x16x32_bf16 v[68:71], v[150:153], v[238:241], v[36:39]
	v_mfma_f32_16x16x32_bf16 v[40:43], v[170:173], v[208:211], v[140:143]
	v_mfma_f32_16x16x32_bf16 v[44:47], v[178:181], v[208:211], v[166:169]
	v_mfma_f32_16x16x32_bf16 v[48:51], v[216:219], v[208:211], v[184:187]
	v_mfma_f32_16x16x32_bf16 v[36:39], v[170:173], v[132:135], v[136:139]
	v_mfma_f32_16x16x32_bf16 v[52:55], v[174:177], v[158:161], v[40:43]
	v_mfma_f32_16x16x32_bf16 v[40:43], v[178:181], v[132:135], v[162:165]
	v_mfma_f32_16x16x32_bf16 v[56:59], v[212:215], v[158:161], v[44:47]
	v_mfma_f32_16x16x32_bf16 v[44:47], v[216:219], v[132:135], v[200:203]
	v_mfma_f32_16x16x32_bf16 v[60:63], v[154:157], v[158:161], v[48:51]
	v_mfma_f32_16x16x32_bf16 v[48:51], v[220:223], v[132:135], v[188:191]
	v_mfma_f32_16x16x32_bf16 v[64:67], v[220:223], v[208:211], v[192:195]
	v_mfma_f32_16x16x32_bf16 v[36:39], v[174:177], v[204:207], v[36:39]
	v_mfma_f32_16x16x32_bf16 v[40:43], v[212:215], v[204:207], v[40:43]
	v_mfma_f32_16x16x32_bf16 v[44:47], v[154:157], v[204:207], v[44:47]
	v_mfma_f32_16x16x32_bf16 v[48:51], v[150:153], v[204:207], v[48:51]
	v_mfma_f32_16x16x32_bf16 v[64:67], v[150:153], v[158:161], v[64:67]
	s_movk_i32 s2, 0x100
	v_cmp_gt_u32_e32 vcc, s2, v3
	s_barrier
	s_and_saveexec_b64 s[2:3], vcc
	s_cbranch_execz .LBB0_1155
	s_barrier

;     ...
;   if (!pre) {
;     STAGE8(SB8(0, 0), Bt, K, bcol, 0); STAGE8(SA8(0, 0), A, lda, brow, 0);
;     STAGE8(SB8(0, 1), Bt, K, bcol + 128, 0); STAGE8(SA8(0, 1), A, lda, brow + 128, 0);
.LBB0_1253:
	s_and_b64 vcc, exec, s[0:1]
	s_cbranch_vccz .LBB0_1266
	s_mov_b32 s0, 25
	s_ashr_i32 s1, s0, 31
	s_xor_b64 s[8:9], s[8:9], -1
	s_lshl_b64 s[0:1], s[0:1], 3
	s_add_u32 s0, s70, s0
	s_addc_u32 s1, s71, s1
	v_readlane_b32 s2, v255, 60
	v_readlane_b32 s3, v255, 61
	s_nop 4
	s_lshl_b32 s0, s25, 8
	v_mov_b32_e32 v3, v224
	s_and_b32 s27, s0, 0x3f00
	s_lshl_b32 s0, s25, 2
	s_and_b32 s0, s0, 0xffffff00
	s_waitcnt vmcnt(10)
	v_lshlrev_b32_e32 v150, 4, v3
	s_nop 0
	v_readfirstlane_b32 s100, v150
	v_ashrrev_i32_e32 v0, 31, v3
	v_bfe_i32 v5, v3, 27, 1
	v_mov_b32_e32 v4, v2
	s_andn2_b64 vcc, exec, s[8:9]
	v_lshrrev_b32_e32 v1, 26, v0
	v_lshrrev_b32_e32 v0, 22, v5
	s_waitcnt vmcnt(9)
	v_add_u32_e32 v152, 0x2000, v150
	s_waitcnt vmcnt(8)
	s_cbranch_vccnz .LBB0_1256
	v_add_u32_e32 v6, v150, v0
	v_and_b32_e32 v6, 0xfffffc00, v6
	v_sub_u32_e32 v6, v150, v6
	v_lshrrev_b32_e32 v7, 4, v6
	v_add_u32_e32 v5, v3, v1
	v_bitop3_b32 v7, v7, v6, 32 bitop3:0x6c
	v_ashrrev_i32_e32 v6, 31, v6
	v_ashrrev_i32_e32 v5, 6, v5
	v_lshrrev_b32_e32 v6, 26, v6
	v_lshlrev_b32_e32 v8, 3, v5
	v_add_u32_e32 v6, v7, v6
	v_and_b32_e32 v8, -16, v8
	v_ashrrev_i32_e32 v9, 6, v6
	v_add_u32_e32 v6, v9, v8
	v_mul_i32_i24_e32 v8, 64, v9
	s_ashr_i32 s1, s0, 31
	v_lshlrev_b32_e32 v5, 5, v5
	v_sub_u32_e32 v7, v7, v8
	v_mov_b32_e32 v14, 1
	s_lshl_b64 s[8:9], s[0:1], 11
	v_and_b32_e32 v5, 32, v5
	v_ashrrev_i16_sdwa v7, v14, sext(v7) dst_sel:DWORD dst_unused:UNUSED_PAD src0_sel:DWORD src1_sel:BYTE_0
	s_add_u32 s8, s4, s8
	v_add_u32_sdwa v8, v5, sext(v7) dst_sel:DWORD dst_unused:UNUSED_PAD src0_sel:DWORD src1_sel:WORD_0
	v_ashrrev_i32_e32 v7, 31, v6
	v_ashrrev_i32_e32 v5, 31, v152
	s_addc_u32 s9, s5, s9
	v_lshlrev_b64 v[6:7], 11, v[6:7]
	v_ashrrev_i32_e32 v9, 31, v8
	v_lshrrev_b32_e32 v5, 22, v5
	v_lshl_add_u64 v[10:11], s[8:9], 0, v[6:7]
	v_lshlrev_b64 v[8:9], 1, v[8:9]
	v_add_u32_e32 v5, v152, v5
	v_lshl_add_u64 v[10:11], v[10:11], 0, v[8:9]
	s_or_b32 m0, s100, 0x10000
	v_ashrrev_i32_e32 v5, 10, v5
	global_load_lds_dwordx4 v[10:11], off
	v_mul_i32_i24_e32 v10, 0x400, v5
	v_sub_u32_e32 v10, v152, v10
	v_lshrrev_b32_e32 v11, 4, v10
	v_bitop3_b32 v11, v11, v10, 32 bitop3:0x6c
	v_ashrrev_i32_e32 v12, 31, v11
	v_lshrrev_b32_e32 v12, 26, v12
	v_add_u32_e32 v12, v11, v12
	v_lshlrev_b32_e32 v10, 3, v5
	v_ashrrev_i32_e32 v13, 6, v12
	v_and_b32_e32 v12, 0xc0, v12
	v_and_b32_e32 v10, -16, v10
	v_lshlrev_b32_e32 v5, 5, v5
	v_sub_u32_e32 v11, v11, v12
	v_add_u32_e32 v10, v13, v10
	v_and_b32_e32 v5, 32, v5
	v_ashrrev_i16_sdwa v11, v14, sext(v11) dst_sel:DWORD dst_unused:UNUSED_PAD src0_sel:DWORD src1_sel:BYTE_0
	v_add_u32_sdwa v12, v5, sext(v11) dst_sel:DWORD dst_unused:UNUSED_PAD src0_sel:DWORD src1_sel:WORD_0
	v_ashrrev_i32_e32 v11, 31, v10
	v_lshlrev_b64 v[10:11], 11, v[10:11]
	v_ashrrev_i32_e32 v13, 31, v12
	s_or_b32 m0, s100, 0x12000
	s_lshl_b32 s1, s27, 11
	v_lshl_add_u64 v[14:15], s[8:9], 0, v[10:11]
	v_lshlrev_b64 v[12:13], 1, v[12:13]
	s_waitcnt lgkmcnt(0)
	s_add_u32 s8, s2, s1
	v_lshl_add_u64 v[14:15], v[14:15], 0, v[12:13]
	s_addc_u32 s9, s3, 0
	s_or_b32 s14, s0, 0x80
	global_load_lds_dwordx4 v[14:15], off
	v_lshl_add_u64 v[14:15], s[8:9], 0, v[6:7]
	s_ashr_i32 s15, s14, 31
	v_lshl_add_u64 v[14:15], v[14:15], 0, v[8:9]
	s_mov_b32 m0, s100
	s_lshl_b64 s[14:15], s[14:15], 11
	global_load_lds_dwordx4 v[14:15], off
	v_lshl_add_u64 v[14:15], s[8:9], 0, v[10:11]
	s_add_u32 s14, s4, s14
	v_lshl_add_u64 v[14:15], v[14:15], 0, v[12:13]
	s_addc_u32 s15, s5, s15
	s_or_b32 m0, s100, 0x2000
	global_load_lds_dwordx4 v[14:15], off
	v_lshl_add_u64 v[14:15], s[14:15], 0, v[6:7]
	v_lshl_add_u64 v[14:15], v[14:15], 0, v[8:9]
	s_or_b32 m0, s100, 0x14000
	s_add_u32 s8, s8, 0x40000
	global_load_lds_dwordx4 v[14:15], off
	v_lshl_add_u64 v[14:15], s[14:15], 0, v[10:11]
	s_addc_u32 s9, s9, 0
	v_lshl_add_u64 v[14:15], v[14:15], 0, v[12:13]
	s_or_b32 m0, s100, 0x16000
	v_lshl_add_u64 v[6:7], s[8:9], 0, v[6:7]
	global_load_lds_dwordx4 v[14:15], off
	s_or_b32 m0, s100, 0x4000
	v_lshl_add_u64 v[6:7], v[6:7], 0, v[8:9]
	global_load_lds_dwordx4 v[6:7], off
	v_lshl_add_u64 v[6:7], s[8:9], 0, v[10:11]
	s_or_b32 m0, s100, 0x6000
	v_lshl_add_u64 v[6:7], v[6:7], 0, v[12:13]
	global_load_lds_dwordx4 v[6:7], off

; #define WAIT_V8(n) asm volatile("s_waitcnt vmcnt(" #n ")" ::: "memory")
; #define BAR8 __builtin_amdgcn_s_barrier()
;     ...
;   if (wr == 1) BAR8;
;   WAIT_V8(4); BAR8;
;   STAGE8(SB8(1, 0), Bt, K, bcol, 1); STAGE8(SA8(1, 0), A, lda, brow, 1); STAGE8(SB8(1, 1), Bt, K, bcol + 128, 1);
;   WAIT_V8(6); BAR8;
.LBB0_1258:
	s_or_b64 exec, exec, s[8:9]
	v_add_u32_e32 v0, v150, v0
	v_and_b32_e32 v0, 0xfffffc00, v0
	v_sub_u32_e32 v0, v150, v0
	v_lshrrev_b32_e32 v6, 4, v0
	v_add_u32_e32 v1, v3, v1
	v_bitop3_b32 v7, v6, v0, 32 bitop3:0x6c
	v_ashrrev_i32_e32 v0, 31, v0
	v_ashrrev_i32_e32 v1, 6, v1
	v_lshrrev_b32_e32 v0, 26, v0
	v_lshlrev_b32_e32 v6, 3, v1
	v_add_u32_e32 v0, v7, v0
	v_and_b32_e32 v6, -16, v6
	v_ashrrev_i32_e32 v0, 6, v0
	s_and_b32 s1, s12, 63
	s_and_b32 s8, s20, 0xffffff00
	v_add_u32_e32 v6, v0, v6
	v_mul_i32_i24_e32 v0, 64, v0
	s_lshl_b32 s12, s1, 19
	s_ashr_i32 s9, s8, 31
	s_ashr_i32 s1, s0, 31
	v_lshlrev_b32_e32 v1, 5, v1
	v_sub_u32_e32 v0, v7, v0
	v_mov_b32_e32 v13, 1
	s_lshl_b64 s[14:15], s[8:9], 11
	s_lshl_b64 s[8:9], s[0:1], 11
	v_and_b32_e32 v1, 32, v1
	v_ashrrev_i16_sdwa v0, v13, sext(v0) dst_sel:DWORD dst_unused:UNUSED_PAD src0_sel:DWORD src1_sel:BYTE_0
	s_add_u32 s8, s4, s8
	v_add_u32_sdwa v0, v1, sext(v0) dst_sel:DWORD dst_unused:UNUSED_PAD src0_sel:DWORD src1_sel:WORD_0
	v_ashrrev_i32_e32 v7, 31, v6
	v_readlane_b32 s40, v254, 35
	s_addc_u32 s9, s5, s9
	v_lshlrev_b64 v[132:133], 11, v[6:7]
	v_ashrrev_i32_e32 v1, 31, v0
	v_readlane_b32 s41, v254, 36
	v_lshl_add_u64 v[6:7], s[8:9], 0, v[132:133]
	v_lshlrev_b64 v[8:9], 1, v[0:1]
	s_mov_b32 s13, s40
	v_lshl_add_u64 v[6:7], v[6:7], 0, v[8:9]
	s_mov_b64 s[40:41], 0x80
	v_lshl_add_u64 v[6:7], v[6:7], 0, s[40:41]
	s_or_b32 m0, s100, 0x18000
	s_waitcnt vmcnt(4)
	s_barrier
	global_load_lds_dwordx4 v[6:7], off
	v_ashrrev_i32_e32 v6, 31, v152
	v_lshrrev_b32_e32 v6, 22, v6
	v_add_u32_e32 v6, v152, v6
	v_ashrrev_i32_e32 v7, 10, v6
	v_mul_i32_i24_e32 v6, 0x400, v7
	v_sub_u32_e32 v6, v152, v6
	v_lshrrev_b32_e32 v10, 4, v6
	v_bitop3_b32 v10, v10, v6, 32 bitop3:0x6c
	v_ashrrev_i32_e32 v11, 31, v10
	v_lshrrev_b32_e32 v11, 26, v11
	v_add_u32_e32 v11, v10, v11
	v_lshlrev_b32_e32 v6, 3, v7
	v_ashrrev_i32_e32 v12, 6, v11
	v_and_b32_e32 v11, 0xc0, v11
	v_and_b32_e32 v6, -16, v6
	v_lshlrev_b32_e32 v7, 5, v7
	v_sub_u32_e32 v10, v10, v11
	v_add_u32_e32 v6, v12, v6
	v_and_b32_e32 v7, 32, v7
	v_ashrrev_i16_sdwa v10, v13, sext(v10) dst_sel:DWORD dst_unused:UNUSED_PAD src0_sel:DWORD src1_sel:BYTE_0
	v_add_u32_sdwa v134, v7, sext(v10) dst_sel:DWORD dst_unused:UNUSED_PAD src0_sel:DWORD src1_sel:WORD_0
	v_ashrrev_i32_e32 v7, 31, v6
	v_lshlrev_b64 v[136:137], 11, v[6:7]
	v_ashrrev_i32_e32 v135, 31, v134
	v_lshl_add_u64 v[6:7], s[8:9], 0, v[136:137]
	v_lshlrev_b64 v[10:11], 1, v[134:135]
	s_or_b32 m0, s100, 0x1a000
	s_lshl_b32 s1, s27, 11
	v_lshl_add_u64 v[6:7], v[6:7], 0, v[10:11]
	s_waitcnt lgkmcnt(0)
	s_add_u32 s8, s2, s1
	v_lshl_add_u64 v[6:7], v[6:7], 0, s[40:41]
	s_addc_u32 s9, s3, 0
	global_load_lds_dwordx4 v[6:7], off
	v_lshl_add_u64 v[6:7], s[8:9], 0, v[132:133]
	v_lshl_add_u64 v[6:7], v[6:7], 0, v[8:9]
	s_or_b32 s36, s0, 0x80
	v_lshl_add_u64 v[6:7], v[6:7], 0, s[40:41]
	s_or_b32 m0, s100, 0x8000
	s_ashr_i32 s37, s36, 31
	global_load_lds_dwordx4 v[6:7], off
	v_lshl_add_u64 v[6:7], s[8:9], 0, v[136:137]
	s_lshl_b64 s[36:37], s[36:37], 11
	v_lshl_add_u64 v[6:7], v[6:7], 0, v[10:11]
	s_add_u32 s36, s4, s36
	v_lshl_add_u64 v[6:7], v[6:7], 0, s[40:41]
	s_addc_u32 s37, s5, s37
	s_or_b32 m0, s100, 0xa000
	global_load_lds_dwordx4 v[6:7], off
	v_lshl_add_u64 v[6:7], s[36:37], 0, v[132:133]
	v_lshl_add_u64 v[6:7], v[6:7], 0, v[8:9]
	v_lshl_add_u64 v[6:7], v[6:7], 0, s[40:41]
	s_or_b32 m0, s100, 0x1c000
	global_load_lds_dwordx4 v[6:7], off
	v_lshl_add_u64 v[6:7], s[36:37], 0, v[136:137]
	v_lshl_add_u64 v[6:7], v[6:7], 0, v[10:11]
	v_lshl_add_u64 v[6:7], v[6:7], 0, s[40:41]
	s_or_b32 m0, s100, 0x1e000
	v_and_b32_e32 v147, 15, v3
	global_load_lds_dwordx4 v[6:7], off
	v_bfe_u32 v148, v3, 4, 2
	v_lshlrev_b32_e32 v6, 4, v148
	v_lshlrev_b32_e32 v7, 6, v147
	v_lshlrev_b32_e32 v14, 2, v3
	v_or_b32_e32 v13, v6, v7
	v_and_b32_e32 v14, 32, v14
	s_mov_b32 s1, 0x10000
	v_bitop3_b32 v16, v13, s1, v14 bitop3:0xde
	s_mov_b32 s1, 0x14000
	v_bitop3_b32 v15, v6, v14, v7 bitop3:0x36
	v_bitop3_b32 v17, v13, s1, v14 bitop3:0xde
	s_mov_b32 s1, 0x18000
	v_lshlrev_b32_e32 v7, 6, v3
	v_bitop3_b32 v18, v13, s1, v14 bitop3:0xde
	s_mov_b32 s1, 0x1c000
	v_and_b32_e32 v7, 0x3c0, v7
	v_bitop3_b32 v13, v13, s1, v14 bitop3:0xde
	v_bitop3_b32 v14, v7, v14, v6 bitop3:0x36
	v_lshl_add_u64 v[6:7], s[12:13], 0, v[132:133]
	v_lshl_add_u64 v[6:7], v[6:7], 0, v[8:9]
	v_lshl_add_u64 v[138:139], s[2:3], 0, v[6:7]
	v_lshl_add_u64 v[6:7], s[12:13], 0, v[136:137]
	v_lshl_add_u64 v[6:7], v[6:7], 0, v[10:11]
	v_lshl_add_u64 v[140:141], s[2:3], 0, v[6:7]
	v_lshl_add_u64 v[6:7], s[14:15], 0, v[132:133]
	v_lshl_add_u64 v[6:7], v[6:7], 0, v[8:9]
	v_bfe_u32 v146, v3, 6, 2
	s_waitcnt vmcnt(6)
	v_lshlrev_b32_e32 v149, 6, v5
	v_lshlrev_b32_e32 v5, 13, v5
	v_lshl_add_u64 v[142:143], s[6:7], 0, v[6:7]
	v_lshl_add_u64 v[6:7], s[14:15], 0, v[136:137]
	v_readlane_b32 s42, v254, 37
	v_readlane_b32 s43, v254, 38
	v_lshlrev_b32_e32 v12, 12, v146
	v_or_b32_e32 v19, 0x800, v5
	v_or_b32_e32 v20, 0x1000, v5
	v_or_b32_e32 v21, 0x1800, v5
	v_lshl_add_u64 v[6:7], v[6:7], 0, v[10:11]
	v_lshl_add_u64 v[144:145], s[6:7], 0, v[6:7]
	s_mov_b32 s1, -2
	s_mov_b64 s[12:13], 0
	v_add_u32_e32 v171, v16, v12
	v_add_u32_e32 v161, v15, v5
	v_add_u32_e32 v160, v14, v19
	v_add_u32_e32 v159, v14, v20
	v_add_u32_e32 v158, v14, v21
	v_add_u32_e32 v169, v17, v12
	v_add_u32_e32 v163, v18, v12
	v_add_u32_e32 v162, v13, v12
	s_mov_b64 s[36:37], 0xcaa0100
	s_mov_b64 s[40:41], 0xcae0100
	s_mov_b64 s[42:43], 0xcaa0180
	s_mov_b64 s[44:45], 0xcae0180
	s_barrier
; #define LDA8(dst, b, h) _Pragma("unroll") for (int m = 0; m < 4; ++m) _Pragma("unroll") for (int k = 0; k < 2; ++k) \
;     dst[m][k] = *(const bf16x8*)((const char*)SA8(b, h) + lds_byte8(wr * 64 + m * 16 + fr, k * 32 + fq * 8))
; #define LDB8(dst, b, h) _Pragma("unroll") for (int n = 0; n < 2; ++n) _Pragma("unroll") for (int k = 0; k < 2; ++k) \
;     dst[n][k] = *(const bf16x8*)((const char*)SB8(b, h) + lds_byte8(wc * 32 + n * 16 + fr, k * 32 + fq * 8))
; #define WAIT_V8(n) asm volatile("s_waitcnt vmcnt(" #n ")" ::: "memory")
; #define WAIT_L8(n) asm volatile("s_waitcnt lgkmcnt(" #n ")" ::: "memory")
; #define BAR8 __builtin_amdgcn_s_barrier()
; #define SCHED8 __builtin_amdgcn_sched_barrier(0)
;     ...
;   for (int tt = 0; tt < nt - 2; tt += 2) {
;     LDB8(B0, 0, 0); SCHED8; LDA8(At, 0, 0); STAGE8(SA8(1, 1), A, lda, brow + 128, tt + 1);
;     WAIT_L8(8); BAR8; WAIT_L8(0); MMA8(0, 0, At, B0); BAR8; SCHED8;
;     LDB8(B1, 0, 1); STAGE8(SB8(0, 0), Bt, K, bcol, tt + 2);
;     BAR8; WAIT_L8(0); MMA8(0, 1, At, B1); BAR8;
;     LDA8(At, 0, 1); STAGE8(SA8(0, 0), A, lda, brow, tt + 2);
;     BAR8; WAIT_L8(0); MMA8(1, 0, At, B0); BAR8; SCHED8;
;     STAGE8(SB8(0, 1), Bt, K, bcol + 128, tt + 2);
;     WAIT_V8(6); BAR8; MMA8(1, 1, At, B1); BAR8;
	ds_read_b128 v[174:177], v171
	ds_read_b128 v[178:181], v171 offset:1024
	ds_read_b128 v[182:185], v171 offset:2048
	ds_read_b128 v[186:189], v171 offset:3072
	v_lshl_add_u64 v[222:223], v[138:139], 0, s[12:13]
	v_lshl_add_u64 v[226:227], v[222:223], 0, s[34:35]
	s_or_b32 m0, s100, 0xc000
	v_lshl_add_u64 v[236:237], v[140:141], 0, s[12:13]
	ds_read_b128 v[190:193], v161
	ds_read_b128 v[194:197], v161 offset:1024
	ds_read_b128 v[198:201], v160
	ds_read_b128 v[202:205], v160 offset:1024
	ds_read_b128 v[206:209], v159
	ds_read_b128 v[210:213], v159 offset:1024
	ds_read_b128 v[214:217], v158
	ds_read_b128 v[218:221], v158 offset:1024
	global_load_lds_dwordx4 v[226:227], off
	s_or_b32 m0, s100, 0xe000
	v_lshl_add_u64 v[226:227], v[236:237], 0, s[34:35]
	global_load_lds_dwordx4 v[226:227], off
	s_waitcnt lgkmcnt(8)
	s_barrier
	s_waitcnt lgkmcnt(0)
	v_mfma_f32_16x16x32_f16 v[128:131], v[190:193], v[174:177], 0
	v_mfma_f32_16x16x32_f16 v[124:127], v[190:193], v[182:185], 0
	v_mfma_f32_16x16x32_f16 v[120:123], v[198:201], v[174:177], 0
	v_mfma_f32_16x16x32_f16 v[116:119], v[198:201], v[182:185], 0
	v_mfma_f32_16x16x32_f16 v[112:115], v[206:209], v[174:177], 0
	v_mfma_f32_16x16x32_f16 v[108:111], v[206:209], v[182:185], 0
	v_mfma_f32_16x16x32_f16 v[104:107], v[214:217], v[174:177], 0
	v_mfma_f32_16x16x32_f16 v[100:103], v[214:217], v[182:185], 0
	v_mfma_f32_16x16x32_f16 v[128:131], v[194:197], v[178:181], v[128:131]
	v_mfma_f32_16x16x32_f16 v[124:127], v[194:197], v[186:189], v[124:127]
	v_mfma_f32_16x16x32_f16 v[120:123], v[202:205], v[178:181], v[120:123]
	v_mfma_f32_16x16x32_f16 v[116:119], v[202:205], v[186:189], v[116:119]
	v_mfma_f32_16x16x32_f16 v[112:115], v[210:213], v[178:181], v[112:115]
	v_mfma_f32_16x16x32_f16 v[108:111], v[210:213], v[186:189], v[108:111]
	v_mfma_f32_16x16x32_f16 v[104:107], v[218:221], v[178:181], v[104:107]
	v_mfma_f32_16x16x32_f16 v[100:103], v[218:221], v[186:189], v[100:103]
	s_barrier
	v_lshl_add_u64 v[246:247], v[142:143], 0, s[12:13]
	v_lshl_add_u64 v[248:249], v[246:247], 0, s[36:37]
	s_or_b32 m0, s100, 0x10000
	ds_read_b128 v[226:229], v169
	ds_read_b128 v[230:233], v169 offset:1024
	ds_read_b128 v[238:241], v169 offset:2048
	ds_read_b128 v[242:245], v169 offset:3072
	global_load_lds_dwordx4 v[248:249], off
	v_lshl_add_u64 v[248:249], v[144:145], 0, s[12:13]
	s_or_b32 m0, s100, 0x12000
	v_lshl_add_u64 v[250:251], v[248:249], 0, s[36:37]
	global_load_lds_dwordx4 v[250:251], off
	s_barrier
	s_waitcnt lgkmcnt(0)
	v_mfma_f32_16x16x32_f16 v[96:99], v[190:193], v[226:229], 0
	v_mfma_f32_16x16x32_f16 v[92:95], v[190:193], v[238:241], 0
	v_mfma_f32_16x16x32_f16 v[88:91], v[198:201], v[226:229], 0
	v_mfma_f32_16x16x32_f16 v[84:87], v[198:201], v[238:241], 0
	v_mfma_f32_16x16x32_f16 v[80:83], v[206:209], v[226:229], 0
	v_mfma_f32_16x16x32_f16 v[76:79], v[206:209], v[238:241], 0
	v_mfma_f32_16x16x32_f16 v[72:75], v[214:217], v[226:229], 0
	v_mfma_f32_16x16x32_f16 v[68:71], v[214:217], v[238:241], 0
	v_mfma_f32_16x16x32_f16 v[96:99], v[194:197], v[230:233], v[96:99]
	v_mfma_f32_16x16x32_f16 v[92:95], v[194:197], v[242:245], v[92:95]
	v_mfma_f32_16x16x32_f16 v[88:91], v[202:205], v[230:233], v[88:91]
	v_mfma_f32_16x16x32_f16 v[84:87], v[202:205], v[242:245], v[84:87]
	v_mfma_f32_16x16x32_f16 v[80:83], v[210:213], v[230:233], v[80:83]
	v_mfma_f32_16x16x32_f16 v[76:79], v[210:213], v[242:245], v[76:79]
	v_mfma_f32_16x16x32_f16 v[72:75], v[218:221], v[230:233], v[72:75]
	v_mfma_f32_16x16x32_f16 v[68:71], v[218:221], v[242:245], v[68:71]
	v_lshl_add_u64 v[250:251], v[222:223], 0, s[10:11]
	s_mov_b32 m0, s100
	s_barrier
	ds_read_b128 v[190:193], v161 offset:16384
	ds_read_b128 v[194:197], v161 offset:17408
	ds_read_b128 v[198:201], v160 offset:16384
	ds_read_b128 v[202:205], v160 offset:17408
	ds_read_b128 v[206:209], v159 offset:16384
	ds_read_b128 v[210:213], v159 offset:17408
	ds_read_b128 v[214:217], v158 offset:16384
	ds_read_b128 v[218:221], v158 offset:17408
	global_load_lds_dwordx4 v[250:251], off
	s_or_b32 m0, s100, 0x2000
	v_lshl_add_u64 v[250:251], v[236:237], 0, s[10:11]
	global_load_lds_dwordx4 v[250:251], off
	s_barrier
	s_waitcnt lgkmcnt(0)
	v_mfma_f32_16x16x32_f16 v[64:67], v[190:193], v[174:177], 0
	v_mfma_f32_16x16x32_f16 v[60:63], v[190:193], v[182:185], 0
	v_mfma_f32_16x16x32_f16 v[56:59], v[198:201], v[174:177], 0
	v_mfma_f32_16x16x32_f16 v[52:55], v[198:201], v[182:185], 0
	v_mfma_f32_16x16x32_f16 v[48:51], v[206:209], v[174:177], 0
	v_mfma_f32_16x16x32_f16 v[44:47], v[206:209], v[182:185], 0
	v_mfma_f32_16x16x32_f16 v[40:43], v[214:217], v[174:177], 0
	v_mfma_f32_16x16x32_f16 v[36:39], v[214:217], v[182:185], 0
	v_mfma_f32_16x16x32_f16 v[64:67], v[194:197], v[178:181], v[64:67]
	v_mfma_f32_16x16x32_f16 v[60:63], v[194:197], v[186:189], v[60:63]
	v_mfma_f32_16x16x32_f16 v[56:59], v[202:205], v[178:181], v[56:59]
	v_mfma_f32_16x16x32_f16 v[52:55], v[202:205], v[186:189], v[52:55]
	v_mfma_f32_16x16x32_f16 v[48:51], v[210:213], v[178:181], v[48:51]
	v_mfma_f32_16x16x32_f16 v[44:47], v[210:213], v[186:189], v[44:47]
	v_mfma_f32_16x16x32_f16 v[40:43], v[218:221], v[178:181], v[40:43]
	v_mfma_f32_16x16x32_f16 v[36:39], v[218:221], v[186:189], v[36:39]
	s_barrier
	s_or_b32 m0, s100, 0x14000
	v_lshl_add_u64 v[174:175], v[246:247], 0, s[40:41]
	global_load_lds_dwordx4 v[174:175], off
	s_or_b32 m0, s100, 0x16000
	v_lshl_add_u64 v[174:175], v[248:249], 0, s[40:41]
	global_load_lds_dwordx4 v[174:175], off
	s_waitcnt vmcnt(6)
	s_barrier
; #define LDA8(dst, b, h) _Pragma("unroll") for (int m = 0; m < 4; ++m) _Pragma("unroll") for (int k = 0; k < 2; ++k) \
;     dst[m][k] = *(const bf16x8*)((const char*)SA8(b, h) + lds_byte8(wr * 64 + m * 16 + fr, k * 32 + fq * 8))
; #define LDB8(dst, b, h) _Pragma("unroll") for (int n = 0; n < 2; ++n) _Pragma("unroll") for (int k = 0; k < 2; ++k) \
;     dst[n][k] = *(const bf16x8*)((const char*)SB8(b, h) + lds_byte8(wc * 32 + n * 16 + fr, k * 32 + fq * 8))
; #define WAIT_L8(n) asm volatile("s_waitcnt lgkmcnt(" #n ")" ::: "memory")
; #define BAR8 __builtin_amdgcn_s_barrier()
; #define SCHED8 __builtin_amdgcn_sched_barrier(0)
;     ...
;     LDB8(B0, 1, 0); SCHED8; LDA8(At, 1, 0); STAGE8(SA8(0, 1), A, lda, brow + 128, tt + 2);
;     WAIT_L8(8); BAR8; WAIT_L8(0); MMA8(0, 0, At, B0); BAR8; SCHED8;
;     LDB8(B1, 1, 1); STAGE8(SB8(1, 0), Bt, K, bcol, tt + 3);
;     BAR8; WAIT_L8(0); MMA8(0, 1, At, B1); BAR8;
;     LDA8(At, 1, 1); STAGE8(SA8(1, 0), A, lda, brow, tt + 3);
;     BAR8; WAIT_L8(0); MMA8(1, 0, At, B0); BAR8; SCHED8;
	v_mfma_f32_16x16x32_f16 v[32:35], v[190:193], v[226:229], 0
	v_mfma_f32_16x16x32_f16 v[28:31], v[190:193], v[238:241], 0
	v_mfma_f32_16x16x32_f16 v[24:27], v[198:201], v[226:229], 0
	v_mfma_f32_16x16x32_f16 v[20:23], v[198:201], v[238:241], 0
	v_mfma_f32_16x16x32_f16 v[16:19], v[206:209], v[226:229], 0
	v_mfma_f32_16x16x32_f16 v[12:15], v[206:209], v[238:241], 0
	v_mfma_f32_16x16x32_f16 v[8:11], v[214:217], v[226:229], 0
	v_mfma_f32_16x16x32_f16 v[4:7], v[214:217], v[238:241], 0
	v_mfma_f32_16x16x32_f16 v[32:35], v[194:197], v[230:233], v[32:35]
	v_mfma_f32_16x16x32_f16 v[28:31], v[194:197], v[242:245], v[28:31]
	v_mfma_f32_16x16x32_f16 v[24:27], v[202:205], v[230:233], v[24:27]
	v_mfma_f32_16x16x32_f16 v[20:23], v[202:205], v[242:245], v[20:23]
	v_mfma_f32_16x16x32_f16 v[16:19], v[210:213], v[230:233], v[16:19]
	v_mfma_f32_16x16x32_f16 v[12:15], v[210:213], v[242:245], v[12:15]
	v_mfma_f32_16x16x32_f16 v[8:11], v[218:221], v[230:233], v[8:11]
	v_mfma_f32_16x16x32_f16 v[4:7], v[218:221], v[242:245], v[4:7]
	s_barrier
	ds_read_b128 v[174:177], v163
	ds_read_b128 v[178:181], v163 offset:1024
	ds_read_b128 v[182:185], v163 offset:2048
	ds_read_b128 v[186:189], v163 offset:3072
	v_lshl_add_u64 v[226:227], v[222:223], 0, s[18:19]
	s_or_b32 m0, s100, 0x4000
	ds_read_b128 v[190:193], v161 offset:32768
	ds_read_b128 v[194:197], v161 offset:33792
	ds_read_b128 v[198:201], v160 offset:32768
	ds_read_b128 v[202:205], v160 offset:33792
	ds_read_b128 v[206:209], v159 offset:32768
	ds_read_b128 v[210:213], v159 offset:33792
	ds_read_b128 v[214:217], v158 offset:32768
	ds_read_b128 v[218:221], v158 offset:33792
	global_load_lds_dwordx4 v[226:227], off
	s_or_b32 m0, s100, 0x6000
	v_lshl_add_u64 v[226:227], v[236:237], 0, s[18:19]
	global_load_lds_dwordx4 v[226:227], off
	s_waitcnt lgkmcnt(8)
	s_barrier
	s_waitcnt lgkmcnt(0)
	v_mfma_f32_16x16x32_f16 v[128:131], v[190:193], v[174:177], v[128:131]
	v_mfma_f32_16x16x32_f16 v[124:127], v[190:193], v[182:185], v[124:127]
	v_mfma_f32_16x16x32_f16 v[120:123], v[198:201], v[174:177], v[120:123]
	v_mfma_f32_16x16x32_f16 v[116:119], v[198:201], v[182:185], v[116:119]
	v_mfma_f32_16x16x32_f16 v[112:115], v[206:209], v[174:177], v[112:115]
	v_mfma_f32_16x16x32_f16 v[108:111], v[206:209], v[182:185], v[108:111]
	v_mfma_f32_16x16x32_f16 v[104:107], v[214:217], v[174:177], v[104:107]
	v_mfma_f32_16x16x32_f16 v[100:103], v[214:217], v[182:185], v[100:103]
	v_mfma_f32_16x16x32_f16 v[128:131], v[194:197], v[178:181], v[128:131]
	v_mfma_f32_16x16x32_f16 v[124:127], v[194:197], v[186:189], v[124:127]
	v_mfma_f32_16x16x32_f16 v[120:123], v[202:205], v[178:181], v[120:123]
	v_mfma_f32_16x16x32_f16 v[116:119], v[202:205], v[186:189], v[116:119]
	v_mfma_f32_16x16x32_f16 v[112:115], v[210:213], v[178:181], v[112:115]
	v_mfma_f32_16x16x32_f16 v[108:111], v[210:213], v[186:189], v[108:111]
	v_mfma_f32_16x16x32_f16 v[104:107], v[218:221], v[178:181], v[104:107]
	v_mfma_f32_16x16x32_f16 v[100:103], v[218:221], v[186:189], v[100:103]
	s_barrier
	v_lshl_add_u64 v[250:251], v[246:247], 0, s[42:43]
	s_or_b32 m0, s100, 0x18000
	ds_read_b128 v[226:229], v162
	ds_read_b128 v[230:233], v162 offset:1024
	ds_read_b128 v[238:241], v162 offset:2048
	ds_read_b128 v[242:245], v162 offset:3072
	global_load_lds_dwordx4 v[250:251], off
	s_or_b32 m0, s100, 0x1a000
	v_lshl_add_u64 v[250:251], v[248:249], 0, s[42:43]
	global_load_lds_dwordx4 v[250:251], off
	s_barrier
	s_waitcnt lgkmcnt(0)
	v_mfma_f32_16x16x32_f16 v[96:99], v[190:193], v[226:229], v[96:99]
	v_mfma_f32_16x16x32_f16 v[92:95], v[190:193], v[238:241], v[92:95]
	v_mfma_f32_16x16x32_f16 v[88:91], v[198:201], v[226:229], v[88:91]
	v_mfma_f32_16x16x32_f16 v[84:87], v[198:201], v[238:241], v[84:87]
	v_mfma_f32_16x16x32_f16 v[80:83], v[206:209], v[226:229], v[80:83]
	v_mfma_f32_16x16x32_f16 v[76:79], v[206:209], v[238:241], v[76:79]
	v_mfma_f32_16x16x32_f16 v[72:75], v[214:217], v[226:229], v[72:75]
	v_mfma_f32_16x16x32_f16 v[68:71], v[214:217], v[238:241], v[68:71]
	v_mfma_f32_16x16x32_f16 v[96:99], v[194:197], v[230:233], v[96:99]
	v_mfma_f32_16x16x32_f16 v[92:95], v[194:197], v[242:245], v[92:95]
	v_mfma_f32_16x16x32_f16 v[88:91], v[202:205], v[230:233], v[88:91]
	v_mfma_f32_16x16x32_f16 v[84:87], v[202:205], v[242:245], v[84:87]
	v_mfma_f32_16x16x32_f16 v[80:83], v[210:213], v[230:233], v[80:83]
	v_mfma_f32_16x16x32_f16 v[76:79], v[210:213], v[242:245], v[76:79]
	v_mfma_f32_16x16x32_f16 v[72:75], v[218:221], v[230:233], v[72:75]
	v_mfma_f32_16x16x32_f16 v[68:71], v[218:221], v[242:245], v[68:71]
	v_lshl_add_u64 v[222:223], v[222:223], 0, s[22:23]
	s_or_b32 m0, s100, 0x8000
	s_barrier
	ds_read_b128 v[190:193], v161 offset:49152
	ds_read_b128 v[194:197], v161 offset:50176
	ds_read_b128 v[198:201], v160 offset:49152
	ds_read_b128 v[202:205], v160 offset:50176
	ds_read_b128 v[206:209], v159 offset:49152
	ds_read_b128 v[210:213], v159 offset:50176
	ds_read_b128 v[214:217], v158 offset:49152
	ds_read_b128 v[218:221], v158 offset:50176
	global_load_lds_dwordx4 v[222:223], off
	s_or_b32 m0, s100, 0xa000
	v_lshl_add_u64 v[222:223], v[236:237], 0, s[22:23]
	global_load_lds_dwordx4 v[222:223], off
	s_barrier
; #define LDA8(dst, b, h) _Pragma("unroll") for (int m = 0; m < 4; ++m) _Pragma("unroll") for (int k = 0; k < 2; ++k) \
;     dst[m][k] = *(const bf16x8*)((const char*)SA8(b, h) + lds_byte8(wr * 64 + m * 16 + fr, k * 32 + fq * 8))
; #define LDB8(dst, b, h) _Pragma("unroll") for (int n = 0; n < 2; ++n) _Pragma("unroll") for (int k = 0; k < 2; ++k) \
;     dst[n][k] = *(const bf16x8*)((const char*)SB8(b, h) + lds_byte8(wc * 32 + n * 16 + fr, k * 32 + fq * 8))
; #define WAIT_V8(n) asm volatile("s_waitcnt vmcnt(" #n ")" ::: "memory")
; #define WAIT_L8(n) asm volatile("s_waitcnt lgkmcnt(" #n ")" ::: "memory")
; #define BAR8 __builtin_amdgcn_s_barrier()
; #define SCHED8 __builtin_amdgcn_sched_barrier(0)
;     ...
;   for (int tt = 0; tt < nt - 2; tt += 2) {
;     LDB8(B0, 0, 0); SCHED8; LDA8(At, 0, 0); STAGE8(SA8(1, 1), A, lda, brow + 128, tt + 1);
;     WAIT_L8(8); BAR8; WAIT_L8(0); MMA8(0, 0, At, B0); BAR8; SCHED8;
;     LDB8(B1, 0, 1); STAGE8(SB8(0, 0), Bt, K, bcol, tt + 2);
;     BAR8; WAIT_L8(0); MMA8(0, 1, At, B1); BAR8;
;     LDA8(At, 0, 1); STAGE8(SA8(0, 0), A, lda, brow, tt + 2);
;     BAR8; WAIT_L8(0); MMA8(1, 0, At, B0); BAR8; SCHED8;
;     STAGE8(SB8(0, 1), Bt, K, bcol + 128, tt + 2);
;     WAIT_V8(6); BAR8; MMA8(1, 1, At, B1); BAR8;
;     ...
;     STAGE8(SB8(1, 1), Bt, K, bcol + 128, tt + 3);
;     WAIT_V8(6); BAR8; MMA8(1, 1, At, B1); BAR8;
;   }
	s_waitcnt lgkmcnt(0)
	v_mfma_f32_16x16x32_f16 v[64:67], v[190:193], v[174:177], v[64:67]
	v_mfma_f32_16x16x32_f16 v[60:63], v[190:193], v[182:185], v[60:63]
	v_mfma_f32_16x16x32_f16 v[56:59], v[198:201], v[174:177], v[56:59]
	v_mfma_f32_16x16x32_f16 v[52:55], v[198:201], v[182:185], v[52:55]
	v_mfma_f32_16x16x32_f16 v[48:51], v[206:209], v[174:177], v[48:51]
	v_mfma_f32_16x16x32_f16 v[44:47], v[206:209], v[182:185], v[44:47]
	v_mfma_f32_16x16x32_f16 v[40:43], v[214:217], v[174:177], v[40:43]
	v_mfma_f32_16x16x32_f16 v[36:39], v[214:217], v[182:185], v[36:39]
	v_mfma_f32_16x16x32_f16 v[64:67], v[194:197], v[178:181], v[64:67]
	v_mfma_f32_16x16x32_f16 v[60:63], v[194:197], v[186:189], v[60:63]
	v_mfma_f32_16x16x32_f16 v[56:59], v[202:205], v[178:181], v[56:59]
	v_mfma_f32_16x16x32_f16 v[52:55], v[202:205], v[186:189], v[52:55]
	v_mfma_f32_16x16x32_f16 v[48:51], v[210:213], v[178:181], v[48:51]
	v_mfma_f32_16x16x32_f16 v[44:47], v[210:213], v[186:189], v[44:47]
	v_mfma_f32_16x16x32_f16 v[40:43], v[218:221], v[178:181], v[40:43]
	v_mfma_f32_16x16x32_f16 v[36:39], v[218:221], v[186:189], v[36:39]
	s_barrier
	s_or_b32 m0, s100, 0x1c000
	v_lshl_add_u64 v[174:175], v[246:247], 0, s[44:45]
	global_load_lds_dwordx4 v[174:175], off
	s_or_b32 m0, s100, 0x1e000
	v_lshl_add_u64 v[174:175], v[248:249], 0, s[44:45]
	global_load_lds_dwordx4 v[174:175], off
	s_waitcnt vmcnt(6)
	s_barrier
	v_mfma_f32_16x16x32_f16 v[32:35], v[190:193], v[226:229], v[32:35]
	v_mfma_f32_16x16x32_f16 v[28:31], v[190:193], v[238:241], v[28:31]
	v_mfma_f32_16x16x32_f16 v[24:27], v[198:201], v[226:229], v[24:27]
	v_mfma_f32_16x16x32_f16 v[20:23], v[198:201], v[238:241], v[20:23]
	v_mfma_f32_16x16x32_f16 v[16:19], v[206:209], v[226:229], v[16:19]
	v_mfma_f32_16x16x32_f16 v[12:15], v[206:209], v[238:241], v[12:15]
	v_mfma_f32_16x16x32_f16 v[8:11], v[214:217], v[226:229], v[8:11]
	v_mfma_f32_16x16x32_f16 v[4:7], v[214:217], v[238:241], v[4:7]
	v_mfma_f32_16x16x32_f16 v[32:35], v[194:197], v[230:233], v[32:35]
	v_mfma_f32_16x16x32_f16 v[28:31], v[194:197], v[242:245], v[28:31]
	v_mfma_f32_16x16x32_f16 v[24:27], v[202:205], v[230:233], v[24:27]
	v_mfma_f32_16x16x32_f16 v[20:23], v[202:205], v[242:245], v[20:23]
	v_mfma_f32_16x16x32_f16 v[16:19], v[210:213], v[230:233], v[16:19]
	v_mfma_f32_16x16x32_f16 v[12:15], v[210:213], v[242:245], v[12:15]
	v_mfma_f32_16x16x32_f16 v[8:11], v[218:221], v[230:233], v[8:11]
	v_mfma_f32_16x16x32_f16 v[4:7], v[218:221], v[242:245], v[4:7]
	s_add_i32 s1, s1, 2
	s_add_u32 s12, s12, 0x100
	s_addc_u32 s13, s13, 0
	s_cmp_lt_u32 s1, 12
	s_barrier
	s_cbranch_scc0 .Lpk_exit_6
.LBB0_1259:
	ds_read_b128 v[174:177], v171
	ds_read_b128 v[178:181], v171 offset:1024
	ds_read_b128 v[182:185], v171 offset:2048
	ds_read_b128 v[186:189], v171 offset:3072
	v_lshl_add_u64 v[222:223], v[138:139], 0, s[12:13]
	v_lshl_add_u64 v[226:227], v[222:223], 0, s[34:35]
	s_or_b32 m0, s100, 0xc000
	v_lshl_add_u64 v[236:237], v[140:141], 0, s[12:13]
	ds_read_b128 v[190:193], v161
	ds_read_b128 v[194:197], v161 offset:1024
	ds_read_b128 v[198:201], v160
	ds_read_b128 v[202:205], v160 offset:1024
	ds_read_b128 v[206:209], v159
	ds_read_b128 v[210:213], v159 offset:1024
	ds_read_b128 v[214:217], v158
	ds_read_b128 v[218:221], v158 offset:1024
	global_load_lds_dwordx4 v[226:227], off
	s_or_b32 m0, s100, 0xe000
	v_lshl_add_u64 v[226:227], v[236:237], 0, s[34:35]
	global_load_lds_dwordx4 v[226:227], off
	s_waitcnt lgkmcnt(8)
	s_barrier
	s_waitcnt lgkmcnt(0)
	v_mfma_f32_16x16x32_f16 v[128:131], v[190:193], v[174:177], v[128:131]
	v_mfma_f32_16x16x32_f16 v[124:127], v[190:193], v[182:185], v[124:127]
	v_mfma_f32_16x16x32_f16 v[120:123], v[198:201], v[174:177], v[120:123]
	v_mfma_f32_16x16x32_f16 v[116:119], v[198:201], v[182:185], v[116:119]
	v_mfma_f32_16x16x32_f16 v[112:115], v[206:209], v[174:177], v[112:115]
	v_mfma_f32_16x16x32_f16 v[108:111], v[206:209], v[182:185], v[108:111]
	v_mfma_f32_16x16x32_f16 v[104:107], v[214:217], v[174:177], v[104:107]
	v_mfma_f32_16x16x32_f16 v[100:103], v[214:217], v[182:185], v[100:103]
	v_mfma_f32_16x16x32_f16 v[128:131], v[194:197], v[178:181], v[128:131]
	v_mfma_f32_16x16x32_f16 v[124:127], v[194:197], v[186:189], v[124:127]
	v_mfma_f32_16x16x32_f16 v[120:123], v[202:205], v[178:181], v[120:123]
	v_mfma_f32_16x16x32_f16 v[116:119], v[202:205], v[186:189], v[116:119]
	v_mfma_f32_16x16x32_f16 v[112:115], v[210:213], v[178:181], v[112:115]
	v_mfma_f32_16x16x32_f16 v[108:111], v[210:213], v[186:189], v[108:111]
	v_mfma_f32_16x16x32_f16 v[104:107], v[218:221], v[178:181], v[104:107]
	v_mfma_f32_16x16x32_f16 v[100:103], v[218:221], v[186:189], v[100:103]
	s_barrier
	v_lshl_add_u64 v[246:247], v[142:143], 0, s[12:13]
	v_lshl_add_u64 v[248:249], v[246:247], 0, s[36:37]
	s_or_b32 m0, s100, 0x10000
	ds_read_b128 v[226:229], v169
	ds_read_b128 v[230:233], v169 offset:1024
	ds_read_b128 v[238:241], v169 offset:2048
	ds_read_b128 v[242:245], v169 offset:3072
	global_load_lds_dwordx4 v[248:249], off
	v_lshl_add_u64 v[248:249], v[144:145], 0, s[12:13]
	s_or_b32 m0, s100, 0x12000
	v_lshl_add_u64 v[250:251], v[248:249], 0, s[36:37]
	global_load_lds_dwordx4 v[250:251], off
	s_barrier
; #define LDA8(dst, b, h) _Pragma("unroll") for (int m = 0; m < 4; ++m) _Pragma("unroll") for (int k = 0; k < 2; ++k) \
;     dst[m][k] = *(const bf16x8*)((const char*)SA8(b, h) + lds_byte8(wr * 64 + m * 16 + fr, k * 32 + fq * 8))
; #define LDB8(dst, b, h) _Pragma("unroll") for (int n = 0; n < 2; ++n) _Pragma("unroll") for (int k = 0; k < 2; ++k) \
;     dst[n][k] = *(const bf16x8*)((const char*)SB8(b, h) + lds_byte8(wc * 32 + n * 16 + fr, k * 32 + fq * 8))
; #define WAIT_V8(n) asm volatile("s_waitcnt vmcnt(" #n ")" ::: "memory")
; #define WAIT_L8(n) asm volatile("s_waitcnt lgkmcnt(" #n ")" ::: "memory")
; #define BAR8 __builtin_amdgcn_s_barrier()
; #define SCHED8 __builtin_amdgcn_sched_barrier(0)
;     ...
;     BAR8; WAIT_L8(0); MMA8(1, 0, At, B0); BAR8; SCHED8;
;     STAGE8(SB8(0, 1), Bt, K, bcol + 128, tt + 2);
;     WAIT_V8(6); BAR8; MMA8(1, 1, At, B1); BAR8;
;     LDB8(B0, 1, 0); SCHED8; LDA8(At, 1, 0); STAGE8(SA8(0, 1), A, lda, brow + 128, tt + 2);
;     WAIT_L8(8); BAR8; WAIT_L8(0); MMA8(0, 0, At, B0); BAR8; SCHED8;
;     LDB8(B1, 1, 1); STAGE8(SB8(1, 0), Bt, K, bcol, tt + 3);
;     BAR8; WAIT_L8(0); MMA8(0, 1, At, B1); BAR8;
;     LDA8(At, 1, 1); STAGE8(SA8(1, 0), A, lda, brow, tt + 3);
	s_waitcnt lgkmcnt(0)
	v_mfma_f32_16x16x32_f16 v[96:99], v[190:193], v[226:229], v[96:99]
	v_mfma_f32_16x16x32_f16 v[92:95], v[190:193], v[238:241], v[92:95]
	v_mfma_f32_16x16x32_f16 v[88:91], v[198:201], v[226:229], v[88:91]
	v_mfma_f32_16x16x32_f16 v[84:87], v[198:201], v[238:241], v[84:87]
	v_mfma_f32_16x16x32_f16 v[80:83], v[206:209], v[226:229], v[80:83]
	v_mfma_f32_16x16x32_f16 v[76:79], v[206:209], v[238:241], v[76:79]
	v_mfma_f32_16x16x32_f16 v[72:75], v[214:217], v[226:229], v[72:75]
	v_mfma_f32_16x16x32_f16 v[68:71], v[214:217], v[238:241], v[68:71]
	v_mfma_f32_16x16x32_f16 v[96:99], v[194:197], v[230:233], v[96:99]
	v_mfma_f32_16x16x32_f16 v[92:95], v[194:197], v[242:245], v[92:95]
	v_mfma_f32_16x16x32_f16 v[88:91], v[202:205], v[230:233], v[88:91]
	v_mfma_f32_16x16x32_f16 v[84:87], v[202:205], v[242:245], v[84:87]
	v_mfma_f32_16x16x32_f16 v[80:83], v[210:213], v[230:233], v[80:83]
	v_mfma_f32_16x16x32_f16 v[76:79], v[210:213], v[242:245], v[76:79]
	v_mfma_f32_16x16x32_f16 v[72:75], v[218:221], v[230:233], v[72:75]
	v_mfma_f32_16x16x32_f16 v[68:71], v[218:221], v[242:245], v[68:71]
	v_lshl_add_u64 v[250:251], v[222:223], 0, s[10:11]
	s_mov_b32 m0, s100
	s_barrier
	ds_read_b128 v[190:193], v161 offset:16384
	ds_read_b128 v[194:197], v161 offset:17408
	ds_read_b128 v[198:201], v160 offset:16384
	ds_read_b128 v[202:205], v160 offset:17408
	ds_read_b128 v[206:209], v159 offset:16384
	ds_read_b128 v[210:213], v159 offset:17408
	ds_read_b128 v[214:217], v158 offset:16384
	ds_read_b128 v[218:221], v158 offset:17408
	global_load_lds_dwordx4 v[250:251], off
	s_or_b32 m0, s100, 0x2000
	v_lshl_add_u64 v[250:251], v[236:237], 0, s[10:11]
	global_load_lds_dwordx4 v[250:251], off
	s_barrier
	s_waitcnt lgkmcnt(0)
	v_mfma_f32_16x16x32_f16 v[64:67], v[190:193], v[174:177], v[64:67]
	v_mfma_f32_16x16x32_f16 v[60:63], v[190:193], v[182:185], v[60:63]
	v_mfma_f32_16x16x32_f16 v[56:59], v[198:201], v[174:177], v[56:59]
	v_mfma_f32_16x16x32_f16 v[52:55], v[198:201], v[182:185], v[52:55]
	v_mfma_f32_16x16x32_f16 v[48:51], v[206:209], v[174:177], v[48:51]
	v_mfma_f32_16x16x32_f16 v[44:47], v[206:209], v[182:185], v[44:47]
	v_mfma_f32_16x16x32_f16 v[40:43], v[214:217], v[174:177], v[40:43]
	v_mfma_f32_16x16x32_f16 v[36:39], v[214:217], v[182:185], v[36:39]
	v_mfma_f32_16x16x32_f16 v[64:67], v[194:197], v[178:181], v[64:67]
	v_mfma_f32_16x16x32_f16 v[60:63], v[194:197], v[186:189], v[60:63]
	v_mfma_f32_16x16x32_f16 v[56:59], v[202:205], v[178:181], v[56:59]
	v_mfma_f32_16x16x32_f16 v[52:55], v[202:205], v[186:189], v[52:55]
	v_mfma_f32_16x16x32_f16 v[48:51], v[210:213], v[178:181], v[48:51]
	v_mfma_f32_16x16x32_f16 v[44:47], v[210:213], v[186:189], v[44:47]
	v_mfma_f32_16x16x32_f16 v[40:43], v[218:221], v[178:181], v[40:43]
	v_mfma_f32_16x16x32_f16 v[36:39], v[218:221], v[186:189], v[36:39]
	s_barrier
	s_or_b32 m0, s100, 0x14000
	v_lshl_add_u64 v[174:175], v[246:247], 0, s[40:41]
	global_load_lds_dwordx4 v[174:175], off
	s_or_b32 m0, s100, 0x16000
	v_lshl_add_u64 v[174:175], v[248:249], 0, s[40:41]
	global_load_lds_dwordx4 v[174:175], off
	s_waitcnt vmcnt(6)
	s_barrier
	v_mfma_f32_16x16x32_f16 v[32:35], v[190:193], v[226:229], v[32:35]
	v_mfma_f32_16x16x32_f16 v[28:31], v[190:193], v[238:241], v[28:31]
	v_mfma_f32_16x16x32_f16 v[24:27], v[198:201], v[226:229], v[24:27]
	v_mfma_f32_16x16x32_f16 v[20:23], v[198:201], v[238:241], v[20:23]
	v_mfma_f32_16x16x32_f16 v[16:19], v[206:209], v[226:229], v[16:19]
	v_mfma_f32_16x16x32_f16 v[12:15], v[206:209], v[238:241], v[12:15]
	v_mfma_f32_16x16x32_f16 v[8:11], v[214:217], v[226:229], v[8:11]
	v_mfma_f32_16x16x32_f16 v[4:7], v[214:217], v[238:241], v[4:7]
	v_mfma_f32_16x16x32_f16 v[32:35], v[194:197], v[230:233], v[32:35]
	v_mfma_f32_16x16x32_f16 v[28:31], v[194:197], v[242:245], v[28:31]
	v_mfma_f32_16x16x32_f16 v[24:27], v[202:205], v[230:233], v[24:27]
	v_mfma_f32_16x16x32_f16 v[20:23], v[202:205], v[242:245], v[20:23]
	v_mfma_f32_16x16x32_f16 v[16:19], v[210:213], v[230:233], v[16:19]
	v_mfma_f32_16x16x32_f16 v[12:15], v[210:213], v[242:245], v[12:15]
	v_mfma_f32_16x16x32_f16 v[8:11], v[218:221], v[230:233], v[8:11]
	v_mfma_f32_16x16x32_f16 v[4:7], v[218:221], v[242:245], v[4:7]
	s_barrier
	ds_read_b128 v[174:177], v163
	ds_read_b128 v[178:181], v163 offset:1024
	ds_read_b128 v[182:185], v163 offset:2048
	ds_read_b128 v[186:189], v163 offset:3072
	v_lshl_add_u64 v[226:227], v[222:223], 0, s[18:19]
	s_or_b32 m0, s100, 0x4000
	ds_read_b128 v[190:193], v161 offset:32768
	ds_read_b128 v[194:197], v161 offset:33792
	ds_read_b128 v[198:201], v160 offset:32768
	ds_read_b128 v[202:205], v160 offset:33792
	ds_read_b128 v[206:209], v159 offset:32768
	ds_read_b128 v[210:213], v159 offset:33792
	ds_read_b128 v[214:217], v158 offset:32768
	ds_read_b128 v[218:221], v158 offset:33792
	global_load_lds_dwordx4 v[226:227], off
	s_or_b32 m0, s100, 0x6000
	v_lshl_add_u64 v[226:227], v[236:237], 0, s[18:19]
	global_load_lds_dwordx4 v[226:227], off
	s_waitcnt lgkmcnt(8)
	s_barrier
	s_waitcnt lgkmcnt(0)
	v_mfma_f32_16x16x32_f16 v[128:131], v[190:193], v[174:177], v[128:131]
	v_mfma_f32_16x16x32_f16 v[124:127], v[190:193], v[182:185], v[124:127]
	v_mfma_f32_16x16x32_f16 v[120:123], v[198:201], v[174:177], v[120:123]
	v_mfma_f32_16x16x32_f16 v[116:119], v[198:201], v[182:185], v[116:119]
	v_mfma_f32_16x16x32_f16 v[112:115], v[206:209], v[174:177], v[112:115]
	v_mfma_f32_16x16x32_f16 v[108:111], v[206:209], v[182:185], v[108:111]
	v_mfma_f32_16x16x32_f16 v[104:107], v[214:217], v[174:177], v[104:107]
	v_mfma_f32_16x16x32_f16 v[100:103], v[214:217], v[182:185], v[100:103]
	v_mfma_f32_16x16x32_f16 v[128:131], v[194:197], v[178:181], v[128:131]
	v_mfma_f32_16x16x32_f16 v[124:127], v[194:197], v[186:189], v[124:127]
	v_mfma_f32_16x16x32_f16 v[120:123], v[202:205], v[178:181], v[120:123]
	v_mfma_f32_16x16x32_f16 v[116:119], v[202:205], v[186:189], v[116:119]
	v_mfma_f32_16x16x32_f16 v[112:115], v[210:213], v[178:181], v[112:115]
	v_mfma_f32_16x16x32_f16 v[108:111], v[210:213], v[186:189], v[108:111]
	v_mfma_f32_16x16x32_f16 v[104:107], v[218:221], v[178:181], v[104:107]
	v_mfma_f32_16x16x32_f16 v[100:103], v[218:221], v[186:189], v[100:103]
	s_barrier
; #define LDA8(dst, b, h) _Pragma("unroll") for (int m = 0; m < 4; ++m) _Pragma("unroll") for (int k = 0; k < 2; ++k) \
;     dst[m][k] = *(const bf16x8*)((const char*)SA8(b, h) + lds_byte8(wr * 64 + m * 16 + fr, k * 32 + fq * 8))
; #define WAIT_V8(n) asm volatile("s_waitcnt vmcnt(" #n ")" ::: "memory")
; #define WAIT_L8(n) asm volatile("s_waitcnt lgkmcnt(" #n ")" ::: "memory")
; #define BAR8 __builtin_amdgcn_s_barrier()
; #define SCHED8 __builtin_amdgcn_sched_barrier(0)
;     ...
;     LDA8(At, 1, 1); STAGE8(SA8(1, 0), A, lda, brow, tt + 3);
;     BAR8; WAIT_L8(0); MMA8(1, 0, At, B0); BAR8; SCHED8;
;     STAGE8(SB8(1, 1), Bt, K, bcol + 128, tt + 3);
;     WAIT_V8(6); BAR8; MMA8(1, 1, At, B1); BAR8;
;   }
	v_lshl_add_u64 v[250:251], v[246:247], 0, s[42:43]
	s_or_b32 m0, s100, 0x18000
	ds_read_b128 v[226:229], v162
	ds_read_b128 v[230:233], v162 offset:1024
	ds_read_b128 v[238:241], v162 offset:2048
	ds_read_b128 v[242:245], v162 offset:3072
	global_load_lds_dwordx4 v[250:251], off
	s_or_b32 m0, s100, 0x1a000
	v_lshl_add_u64 v[250:251], v[248:249], 0, s[42:43]
	global_load_lds_dwordx4 v[250:251], off
	s_barrier
	s_waitcnt lgkmcnt(0)
	v_mfma_f32_16x16x32_f16 v[96:99], v[190:193], v[226:229], v[96:99]
	v_mfma_f32_16x16x32_f16 v[92:95], v[190:193], v[238:241], v[92:95]
	v_mfma_f32_16x16x32_f16 v[88:91], v[198:201], v[226:229], v[88:91]
	v_mfma_f32_16x16x32_f16 v[84:87], v[198:201], v[238:241], v[84:87]
	v_mfma_f32_16x16x32_f16 v[80:83], v[206:209], v[226:229], v[80:83]
	v_mfma_f32_16x16x32_f16 v[76:79], v[206:209], v[238:241], v[76:79]
	v_mfma_f32_16x16x32_f16 v[72:75], v[214:217], v[226:229], v[72:75]
	v_mfma_f32_16x16x32_f16 v[68:71], v[214:217], v[238:241], v[68:71]
	v_mfma_f32_16x16x32_f16 v[96:99], v[194:197], v[230:233], v[96:99]
	v_mfma_f32_16x16x32_f16 v[92:95], v[194:197], v[242:245], v[92:95]
	v_mfma_f32_16x16x32_f16 v[88:91], v[202:205], v[230:233], v[88:91]
	v_mfma_f32_16x16x32_f16 v[84:87], v[202:205], v[242:245], v[84:87]
	v_mfma_f32_16x16x32_f16 v[80:83], v[210:213], v[230:233], v[80:83]
	v_mfma_f32_16x16x32_f16 v[76:79], v[210:213], v[242:245], v[76:79]
	v_mfma_f32_16x16x32_f16 v[72:75], v[218:221], v[230:233], v[72:75]
	v_mfma_f32_16x16x32_f16 v[68:71], v[218:221], v[242:245], v[68:71]
	v_lshl_add_u64 v[222:223], v[222:223], 0, s[22:23]
	s_or_b32 m0, s100, 0x8000
	s_barrier
	ds_read_b128 v[190:193], v161 offset:49152
	ds_read_b128 v[194:197], v161 offset:50176
	ds_read_b128 v[198:201], v160 offset:49152
	ds_read_b128 v[202:205], v160 offset:50176
	ds_read_b128 v[206:209], v159 offset:49152
	ds_read_b128 v[210:213], v159 offset:50176
	ds_read_b128 v[214:217], v158 offset:49152
	ds_read_b128 v[218:221], v158 offset:50176
	global_load_lds_dwordx4 v[222:223], off
	s_or_b32 m0, s100, 0xa000
	v_lshl_add_u64 v[222:223], v[236:237], 0, s[22:23]
	global_load_lds_dwordx4 v[222:223], off
	s_barrier
	s_waitcnt lgkmcnt(0)
	v_mfma_f32_16x16x32_f16 v[64:67], v[190:193], v[174:177], v[64:67]
	v_mfma_f32_16x16x32_f16 v[60:63], v[190:193], v[182:185], v[60:63]
	v_mfma_f32_16x16x32_f16 v[56:59], v[198:201], v[174:177], v[56:59]
	v_mfma_f32_16x16x32_f16 v[52:55], v[198:201], v[182:185], v[52:55]
	v_mfma_f32_16x16x32_f16 v[48:51], v[206:209], v[174:177], v[48:51]
	v_mfma_f32_16x16x32_f16 v[44:47], v[206:209], v[182:185], v[44:47]
	v_mfma_f32_16x16x32_f16 v[40:43], v[214:217], v[174:177], v[40:43]
	v_mfma_f32_16x16x32_f16 v[36:39], v[214:217], v[182:185], v[36:39]
	v_mfma_f32_16x16x32_f16 v[64:67], v[194:197], v[178:181], v[64:67]
	v_mfma_f32_16x16x32_f16 v[60:63], v[194:197], v[186:189], v[60:63]
	v_mfma_f32_16x16x32_f16 v[56:59], v[202:205], v[178:181], v[56:59]
	v_mfma_f32_16x16x32_f16 v[52:55], v[202:205], v[186:189], v[52:55]
	v_mfma_f32_16x16x32_f16 v[48:51], v[210:213], v[178:181], v[48:51]
	v_mfma_f32_16x16x32_f16 v[44:47], v[210:213], v[186:189], v[44:47]
	v_mfma_f32_16x16x32_f16 v[40:43], v[218:221], v[178:181], v[40:43]
	v_mfma_f32_16x16x32_f16 v[36:39], v[218:221], v[186:189], v[36:39]
	s_barrier
	s_or_b32 m0, s100, 0x1c000
	v_lshl_add_u64 v[174:175], v[246:247], 0, s[44:45]
	global_load_lds_dwordx4 v[174:175], off
	s_or_b32 m0, s100, 0x1e000
	v_lshl_add_u64 v[174:175], v[248:249], 0, s[44:45]
	global_load_lds_dwordx4 v[174:175], off
	s_waitcnt vmcnt(6)
	s_barrier
	v_mfma_f32_16x16x32_f16 v[32:35], v[190:193], v[226:229], v[32:35]
	v_mfma_f32_16x16x32_f16 v[28:31], v[190:193], v[238:241], v[28:31]
	v_mfma_f32_16x16x32_f16 v[24:27], v[198:201], v[226:229], v[24:27]
	v_mfma_f32_16x16x32_f16 v[20:23], v[198:201], v[238:241], v[20:23]
	v_mfma_f32_16x16x32_f16 v[16:19], v[206:209], v[226:229], v[16:19]
	v_mfma_f32_16x16x32_f16 v[12:15], v[206:209], v[238:241], v[12:15]
	v_mfma_f32_16x16x32_f16 v[8:11], v[214:217], v[226:229], v[8:11]
	v_mfma_f32_16x16x32_f16 v[4:7], v[214:217], v[238:241], v[4:7]
	v_mfma_f32_16x16x32_f16 v[32:35], v[194:197], v[230:233], v[32:35]
	v_mfma_f32_16x16x32_f16 v[28:31], v[194:197], v[242:245], v[28:31]
	v_mfma_f32_16x16x32_f16 v[24:27], v[202:205], v[230:233], v[24:27]
	v_mfma_f32_16x16x32_f16 v[20:23], v[202:205], v[242:245], v[20:23]
	v_mfma_f32_16x16x32_f16 v[16:19], v[210:213], v[230:233], v[16:19]
	v_mfma_f32_16x16x32_f16 v[12:15], v[210:213], v[242:245], v[12:15]
	v_mfma_f32_16x16x32_f16 v[8:11], v[218:221], v[230:233], v[8:11]
	v_mfma_f32_16x16x32_f16 v[4:7], v[218:221], v[242:245], v[4:7]
	s_add_i32 s1, s1, 2
	s_add_u32 s12, s12, 0x100
	s_addc_u32 s13, s13, 0
	s_cmp_lt_u32 s1, 12
	s_barrier
	s_cbranch_scc1 .LBB0_1259
; #define LDA8(dst, b, h) _Pragma("unroll") for (int m = 0; m < 4; ++m) _Pragma("unroll") for (int k = 0; k < 2; ++k) \
;     dst[m][k] = *(const bf16x8*)((const char*)SA8(b, h) + lds_byte8(wr * 64 + m * 16 + fr, k * 32 + fq * 8))
; #define LDB8(dst, b, h) _Pragma("unroll") for (int n = 0; n < 2; ++n) _Pragma("unroll") for (int k = 0; k < 2; ++k) \
;     dst[n][k] = *(const bf16x8*)((const char*)SB8(b, h) + lds_byte8(wc * 32 + n * 16 + fr, k * 32 + fq * 8))
; #define WAIT_V8(n) asm volatile("s_waitcnt vmcnt(" #n ")" ::: "memory")
; #define WAIT_L8(n) asm volatile("s_waitcnt lgkmcnt(" #n ")" ::: "memory")
; #define BAR8 __builtin_amdgcn_s_barrier()
;     ...
;   { LDB8(B0, 0, 0); LDA8(At, 0, 0); STAGE8(SA8(1, 1), A, lda, brow + 128, nt - 1);
;     BAR8; WAIT_L8(0); MMA8(0, 0, At, B0); BAR8;
;     LDB8(B1, 0, 1); BAR8; WAIT_L8(0); MMA8(0, 1, At, B1); BAR8;
;     LDA8(At, 0, 1); WAIT_V8(4); BAR8; WAIT_L8(0); MMA8(1, 0, At, B0); MMA8(1, 1, At, B1); BAR8; }
;   { LDB8(B0, 1, 0); LDA8(At, 1, 0); WAIT_V8(2); BAR8; WAIT_L8(0); MMA8(0, 0, At, B0); BAR8;
;     LDB8(B1, 1, 1); WAIT_V8(0); BAR8; WAIT_L8(0); MMA8(0, 1, At, B1); BAR8;
.Lpk_exit_6:
	s_add_u32 s8, s8, 0x40780
	s_addc_u32 s9, s9, 0
	v_lshl_add_u64 v[132:133], s[8:9], 0, v[132:133]
	v_lshl_add_u64 v[0:1], v[0:1], 1, v[132:133]
	s_or_b32 m0, s100, 0xc000
	ds_read_b128 v[138:141], v171
	ds_read_b128 v[142:145], v171 offset:1024
	ds_read_b128 v[150:153], v171 offset:2048
	ds_read_b128 v[154:157], v171 offset:3072
	ds_read_b128 v[164:167], v161
	ds_read_b128 v[174:177], v161 offset:1024
	ds_read_b128 v[178:181], v160
	ds_read_b128 v[182:185], v160 offset:1024
	ds_read_b128 v[186:189], v159
	ds_read_b128 v[190:193], v159 offset:1024
	ds_read_b128 v[194:197], v158
	ds_read_b128 v[198:201], v158 offset:1024
	global_load_lds_dwordx4 v[0:1], off
	v_lshl_add_u64 v[0:1], s[8:9], 0, v[136:137]
	s_or_b32 m0, s100, 0xe000
	v_lshl_add_u64 v[0:1], v[134:135], 1, v[0:1]
	global_load_lds_dwordx4 v[0:1], off
	s_barrier
	s_waitcnt lgkmcnt(0)
	v_mfma_f32_16x16x32_f16 v[128:131], v[164:167], v[138:141], v[128:131]
	v_mfma_f32_16x16x32_f16 v[124:127], v[164:167], v[150:153], v[124:127]
	v_mfma_f32_16x16x32_f16 v[120:123], v[178:181], v[138:141], v[120:123]
	v_mfma_f32_16x16x32_f16 v[116:119], v[178:181], v[150:153], v[116:119]
	v_mfma_f32_16x16x32_f16 v[104:107], v[194:197], v[138:141], v[104:107]
	v_mfma_f32_16x16x32_f16 v[100:103], v[194:197], v[150:153], v[100:103]
	v_mfma_f32_16x16x32_f16 v[128:131], v[174:177], v[142:145], v[128:131]
	v_mfma_f32_16x16x32_f16 v[124:127], v[174:177], v[154:157], v[124:127]
	v_mfma_f32_16x16x32_f16 v[120:123], v[182:185], v[142:145], v[120:123]
	v_mfma_f32_16x16x32_f16 v[116:119], v[182:185], v[154:157], v[116:119]
	v_mfma_f32_16x16x32_f16 v[112:115], v[186:189], v[138:141], v[112:115]
	v_mfma_f32_16x16x32_f16 v[108:111], v[186:189], v[150:153], v[108:111]
	v_mfma_f32_16x16x32_f16 v[104:107], v[198:201], v[142:145], v[104:107]
	v_mfma_f32_16x16x32_f16 v[100:103], v[198:201], v[154:157], v[100:103]
	v_mfma_f32_16x16x32_f16 v[132:135], v[190:193], v[142:145], v[112:115]
	v_mfma_f32_16x16x32_f16 v[170:173], v[190:193], v[154:157], v[108:111]
	s_barrier
	s_nop 1
	ds_read_b128 v[108:111], v169
	ds_read_b128 v[112:115], v169 offset:1024
	ds_read_b128 v[202:205], v169 offset:2048
	ds_read_b128 v[206:209], v169 offset:3072
	s_barrier
	s_waitcnt lgkmcnt(0)
	v_mfma_f32_16x16x32_f16 v[88:91], v[178:181], v[108:111], v[88:91]
	v_mfma_f32_16x16x32_f16 v[84:87], v[178:181], v[202:205], v[84:87]
	v_mfma_f32_16x16x32_f16 v[72:75], v[194:197], v[108:111], v[72:75]
	v_mfma_f32_16x16x32_f16 v[68:71], v[194:197], v[202:205], v[68:71]
	v_mfma_f32_16x16x32_f16 v[96:99], v[164:167], v[108:111], v[96:99]
	v_mfma_f32_16x16x32_f16 v[92:95], v[164:167], v[202:205], v[92:95]
	v_mfma_f32_16x16x32_f16 v[88:91], v[182:185], v[112:115], v[88:91]
	v_mfma_f32_16x16x32_f16 v[84:87], v[182:185], v[206:209], v[84:87]
	v_mfma_f32_16x16x32_f16 v[80:83], v[186:189], v[108:111], v[80:83]
	v_mfma_f32_16x16x32_f16 v[76:79], v[186:189], v[202:205], v[76:79]
	v_mfma_f32_16x16x32_f16 v[72:75], v[198:201], v[112:115], v[72:75]
	v_mfma_f32_16x16x32_f16 v[68:71], v[198:201], v[206:209], v[68:71]
	v_mfma_f32_16x16x32_f16 v[210:213], v[174:177], v[112:115], v[96:99]
	v_mfma_f32_16x16x32_f16 v[164:167], v[174:177], v[206:209], v[92:95]
	v_mfma_f32_16x16x32_f16 v[174:177], v[190:193], v[112:115], v[80:83]
	v_mfma_f32_16x16x32_f16 v[178:181], v[190:193], v[206:209], v[76:79]
	s_barrier
	s_nop 0
	ds_read_b128 v[76:79], v161 offset:16384
	ds_read_b128 v[80:83], v161 offset:17408
	ds_read_b128 v[92:95], v160 offset:16384
	ds_read_b128 v[96:99], v160 offset:17408
	ds_read_b128 v[182:185], v159 offset:16384
	ds_read_b128 v[186:189], v159 offset:17408
	ds_read_b128 v[190:193], v158 offset:16384
	ds_read_b128 v[194:197], v158 offset:17408
	s_waitcnt vmcnt(4)
	s_barrier
	s_waitcnt lgkmcnt(0)
	v_mfma_f32_16x16x32_f16 v[64:67], v[76:79], v[138:141], v[64:67]
	v_mfma_f32_16x16x32_f16 v[60:63], v[76:79], v[150:153], v[60:63]
	v_mfma_f32_16x16x32_f16 v[56:59], v[92:95], v[138:141], v[56:59]
	v_mfma_f32_16x16x32_f16 v[52:55], v[92:95], v[150:153], v[52:55]
	v_mfma_f32_16x16x32_f16 v[40:43], v[190:193], v[138:141], v[40:43]
	v_mfma_f32_16x16x32_f16 v[36:39], v[190:193], v[150:153], v[36:39]
	v_mfma_f32_16x16x32_f16 v[64:67], v[80:83], v[142:145], v[64:67]
	v_mfma_f32_16x16x32_f16 v[60:63], v[80:83], v[154:157], v[60:63]
	v_mfma_f32_16x16x32_f16 v[56:59], v[96:99], v[142:145], v[56:59]
	v_mfma_f32_16x16x32_f16 v[52:55], v[96:99], v[154:157], v[52:55]
	v_mfma_f32_16x16x32_f16 v[48:51], v[182:185], v[138:141], v[48:51]
	v_mfma_f32_16x16x32_f16 v[44:47], v[182:185], v[150:153], v[44:47]
	v_mfma_f32_16x16x32_f16 v[40:43], v[194:197], v[142:145], v[40:43]
	v_mfma_f32_16x16x32_f16 v[36:39], v[194:197], v[154:157], v[36:39]
	v_mfma_f32_16x16x32_f16 v[198:201], v[186:189], v[142:145], v[48:51]
	v_mfma_f32_16x16x32_f16 v[214:217], v[186:189], v[154:157], v[44:47]
	v_mfma_f32_16x16x32_f16 v[24:27], v[92:95], v[108:111], v[24:27]
	v_mfma_f32_16x16x32_f16 v[20:23], v[92:95], v[202:205], v[20:23]
	v_mfma_f32_16x16x32_f16 v[8:11], v[190:193], v[108:111], v[8:11]
	v_mfma_f32_16x16x32_f16 v[4:7], v[190:193], v[202:205], v[4:7]
	v_mfma_f32_16x16x32_f16 v[32:35], v[76:79], v[108:111], v[32:35]
	v_mfma_f32_16x16x32_f16 v[28:31], v[76:79], v[202:205], v[28:31]
	v_mfma_f32_16x16x32_f16 v[24:27], v[96:99], v[112:115], v[24:27]
	v_mfma_f32_16x16x32_f16 v[20:23], v[96:99], v[206:209], v[20:23]
	v_mfma_f32_16x16x32_f16 v[16:19], v[182:185], v[108:111], v[16:19]
	v_mfma_f32_16x16x32_f16 v[12:15], v[182:185], v[202:205], v[12:15]
	v_mfma_f32_16x16x32_f16 v[8:11], v[194:197], v[112:115], v[8:11]
	v_mfma_f32_16x16x32_f16 v[4:7], v[194:197], v[206:209], v[4:7]
	v_mfma_f32_16x16x32_f16 v[136:139], v[80:83], v[112:115], v[32:35]
	v_mfma_f32_16x16x32_f16 v[140:143], v[80:83], v[206:209], v[28:31]
	v_mfma_f32_16x16x32_f16 v[150:153], v[186:189], v[112:115], v[16:19]
	v_mfma_f32_16x16x32_f16 v[154:157], v[186:189], v[206:209], v[12:15]
	s_barrier
; #define LDA8(dst, b, h) _Pragma("unroll") for (int m = 0; m < 4; ++m) _Pragma("unroll") for (int k = 0; k < 2; ++k) \
;     dst[m][k] = *(const bf16x8*)((const char*)SA8(b, h) + lds_byte8(wr * 64 + m * 16 + fr, k * 32 + fq * 8))
; #define LDB8(dst, b, h) _Pragma("unroll") for (int n = 0; n < 2; ++n) _Pragma("unroll") for (int k = 0; k < 2; ++k) \
;     dst[n][k] = *(const bf16x8*)((const char*)SB8(b, h) + lds_byte8(wc * 32 + n * 16 + fr, k * 32 + fq * 8))
; #define WAIT_V8(n) asm volatile("s_waitcnt vmcnt(" #n ")" ::: "memory")
; #define WAIT_L8(n) asm volatile("s_waitcnt lgkmcnt(" #n ")" ::: "memory")
; #define BAR8 __builtin_amdgcn_s_barrier()
;     ...
;   { LDB8(B0, 1, 0); LDA8(At, 1, 0); WAIT_V8(2); BAR8; WAIT_L8(0); MMA8(0, 0, At, B0); BAR8;
;     LDB8(B1, 1, 1); WAIT_V8(0); BAR8; WAIT_L8(0); MMA8(0, 1, At, B1); BAR8;
;     LDA8(At, 1, 1); BAR8; WAIT_L8(0); MMA8(1, 0, At, B0); MMA8(1, 1, At, B1); BAR8; }
;   if (wr == 0) BAR8;
;   __syncthreads();
;     ...
;   if (t < 256) {
	s_nop 0
	ds_read_b128 v[12:15], v163
	ds_read_b128 v[16:19], v163 offset:1024
	ds_read_b128 v[182:185], v163 offset:2048
	ds_read_b128 v[186:189], v163 offset:3072
	ds_read_b128 v[28:31], v161 offset:32768
	ds_read_b128 v[32:35], v161 offset:33792
	ds_read_b128 v[44:47], v160 offset:32768
	ds_read_b128 v[48:51], v160 offset:33792
	ds_read_b128 v[190:193], v159 offset:32768
	ds_read_b128 v[194:197], v159 offset:33792
	ds_read_b128 v[202:205], v158 offset:32768
	ds_read_b128 v[206:209], v158 offset:33792
	s_waitcnt vmcnt(2)
	s_barrier
	s_waitcnt lgkmcnt(0)
	v_mfma_f32_16x16x32_f16 v[76:79], v[28:31], v[12:15], v[128:131]
	v_mfma_f32_16x16x32_f16 v[128:131], v[32:35], v[16:19], v[76:79]
	v_mfma_f32_16x16x32_f16 v[76:79], v[28:31], v[182:185], v[124:127]
	v_mfma_f32_16x16x32_f16 v[124:127], v[32:35], v[186:189], v[76:79]
	v_mfma_f32_16x16x32_f16 v[76:79], v[44:47], v[12:15], v[120:123]
	v_mfma_f32_16x16x32_f16 v[112:115], v[48:51], v[16:19], v[76:79]
	v_mfma_f32_16x16x32_f16 v[76:79], v[44:47], v[182:185], v[116:119]
	v_mfma_f32_16x16x32_f16 v[108:111], v[48:51], v[186:189], v[76:79]
	v_mfma_f32_16x16x32_f16 v[76:79], v[190:193], v[12:15], v[132:135]
	v_mfma_f32_16x16x32_f16 v[96:99], v[194:197], v[16:19], v[76:79]
	v_mfma_f32_16x16x32_f16 v[76:79], v[190:193], v[182:185], v[170:173]
	v_mfma_f32_16x16x32_f16 v[92:95], v[194:197], v[186:189], v[76:79]
	v_mfma_f32_16x16x32_f16 v[76:79], v[202:205], v[12:15], v[104:107]
	v_mfma_f32_16x16x32_f16 v[80:83], v[206:209], v[16:19], v[76:79]
	v_mfma_f32_16x16x32_f16 v[76:79], v[202:205], v[182:185], v[100:103]
	v_mfma_f32_16x16x32_f16 v[76:79], v[206:209], v[186:189], v[76:79]
	s_barrier
	ds_read_b128 v[132:135], v162
	ds_read_b128 v[168:171], v162 offset:1024
	ds_read_b128 v[218:221], v162 offset:2048
	ds_read_b128 v[226:229], v162 offset:3072
	s_waitcnt vmcnt(0)
	s_barrier
	s_waitcnt lgkmcnt(0)
	v_mfma_f32_16x16x32_f16 v[100:103], v[28:31], v[132:135], v[210:213]
	v_mfma_f32_16x16x32_f16 v[28:31], v[28:31], v[218:221], v[164:167]
	v_mfma_f32_16x16x32_f16 v[116:119], v[32:35], v[226:229], v[28:31]
	v_mfma_f32_16x16x32_f16 v[28:31], v[44:47], v[132:135], v[88:91]
	v_mfma_f32_16x16x32_f16 v[104:107], v[48:51], v[168:171], v[28:31]
	v_mfma_f32_16x16x32_f16 v[28:31], v[44:47], v[218:221], v[84:87]
	v_mfma_f32_16x16x32_f16 v[120:123], v[32:35], v[168:171], v[100:103]
	v_mfma_f32_16x16x32_f16 v[100:103], v[48:51], v[226:229], v[28:31]
	v_mfma_f32_16x16x32_f16 v[28:31], v[190:193], v[132:135], v[174:177]
	v_mfma_f32_16x16x32_f16 v[88:91], v[194:197], v[168:171], v[28:31]
	v_mfma_f32_16x16x32_f16 v[28:31], v[190:193], v[218:221], v[178:181]
	v_mfma_f32_16x16x32_f16 v[84:87], v[194:197], v[226:229], v[28:31]
	v_mfma_f32_16x16x32_f16 v[28:31], v[202:205], v[132:135], v[72:75]
	v_mfma_f32_16x16x32_f16 v[72:75], v[206:209], v[168:171], v[28:31]
	v_mfma_f32_16x16x32_f16 v[28:31], v[202:205], v[218:221], v[68:71]
	v_mfma_f32_16x16x32_f16 v[68:71], v[206:209], v[226:229], v[28:31]
	s_barrier
	ds_read_b128 v[162:165], v161 offset:49152
	ds_read_b128 v[172:175], v161 offset:50176
	ds_read_b128 v[176:179], v160 offset:49152
	ds_read_b128 v[190:193], v160 offset:50176
	ds_read_b128 v[194:197], v159 offset:49152
	ds_read_b128 v[202:205], v159 offset:50176
	ds_read_b128 v[206:209], v158 offset:49152
	ds_read_b128 v[158:161], v158 offset:50176
	s_barrier
	s_waitcnt lgkmcnt(0)
	v_mfma_f32_16x16x32_f16 v[28:31], v[162:165], v[12:15], v[64:67]
	v_mfma_f32_16x16x32_f16 v[64:67], v[172:175], v[16:19], v[28:31]
	v_mfma_f32_16x16x32_f16 v[28:31], v[162:165], v[182:185], v[60:63]
	v_mfma_f32_16x16x32_f16 v[60:63], v[172:175], v[186:189], v[28:31]
	v_mfma_f32_16x16x32_f16 v[28:31], v[176:179], v[12:15], v[56:59]
	v_mfma_f32_16x16x32_f16 v[48:51], v[190:193], v[16:19], v[28:31]
	v_mfma_f32_16x16x32_f16 v[28:31], v[176:179], v[182:185], v[52:55]
	v_mfma_f32_16x16x32_f16 v[44:47], v[190:193], v[186:189], v[28:31]
	v_mfma_f32_16x16x32_f16 v[28:31], v[194:197], v[12:15], v[198:201]
	v_mfma_f32_16x16x32_f16 v[12:15], v[206:209], v[12:15], v[40:43]
	v_mfma_f32_16x16x32_f16 v[32:35], v[202:205], v[16:19], v[28:31]
	v_mfma_f32_16x16x32_f16 v[28:31], v[194:197], v[182:185], v[214:217]
	v_mfma_f32_16x16x32_f16 v[16:19], v[158:161], v[16:19], v[12:15]
	v_mfma_f32_16x16x32_f16 v[12:15], v[206:209], v[182:185], v[36:39]
	v_mfma_f32_16x16x32_f16 v[28:31], v[202:205], v[186:189], v[28:31]
	v_mfma_f32_16x16x32_f16 v[12:15], v[158:161], v[186:189], v[12:15]
	v_mfma_f32_16x16x32_f16 v[36:39], v[162:165], v[132:135], v[136:139]
	v_mfma_f32_16x16x32_f16 v[56:59], v[172:175], v[168:171], v[36:39]
	v_mfma_f32_16x16x32_f16 v[36:39], v[162:165], v[218:221], v[140:143]
	v_mfma_f32_16x16x32_f16 v[20:23], v[176:179], v[218:221], v[20:23]
	v_mfma_f32_16x16x32_f16 v[52:55], v[172:175], v[226:229], v[36:39]
	v_mfma_f32_16x16x32_f16 v[24:27], v[176:179], v[132:135], v[24:27]
	v_mfma_f32_16x16x32_f16 v[36:39], v[190:193], v[226:229], v[20:23]
	v_mfma_f32_16x16x32_f16 v[20:23], v[194:197], v[132:135], v[150:153]
	v_mfma_f32_16x16x32_f16 v[40:43], v[190:193], v[168:171], v[24:27]
	v_mfma_f32_16x16x32_f16 v[24:27], v[202:205], v[168:171], v[20:23]
	v_mfma_f32_16x16x32_f16 v[20:23], v[194:197], v[218:221], v[154:157]
	v_mfma_f32_16x16x32_f16 v[8:11], v[206:209], v[132:135], v[8:11]
	v_mfma_f32_16x16x32_f16 v[4:7], v[206:209], v[218:221], v[4:7]
	v_mfma_f32_16x16x32_f16 v[20:23], v[202:205], v[226:229], v[20:23]
	v_mfma_f32_16x16x32_f16 v[8:11], v[158:161], v[168:171], v[8:11]
	v_mfma_f32_16x16x32_f16 v[4:7], v[158:161], v[226:229], v[4:7]
	s_movk_i32 s1, 0x100
	v_cmp_gt_u32_e32 vcc, s1, v3
	s_barrier
	s_and_saveexec_b64 s[8:9], vcc
	s_cbranch_execz .LBB0_1262
	s_barrier

; #define LDA8(dst, b, h) _Pragma("unroll") for (int m = 0; m < 4; ++m) _Pragma("unroll") for (int k = 0; k < 2; ++k) \
;     dst[m][k] = *(const bf16x8*)((const char*)SA8(b, h) + lds_byte8(wr * 64 + m * 16 + fr, k * 32 + fq * 8))
; #define LDB8(dst, b, h) _Pragma("unroll") for (int n = 0; n < 2; ++n) _Pragma("unroll") for (int k = 0; k < 2; ++k) \
;     dst[n][k] = *(const bf16x8*)((const char*)SB8(b, h) + lds_byte8(wc * 32 + n * 16 + fr, k * 32 + fq * 8))
; #define WAIT_V8(n) asm volatile("s_waitcnt vmcnt(" #n ")" ::: "memory")
; #define WAIT_L8(n) asm volatile("s_waitcnt lgkmcnt(" #n ")" ::: "memory")
; #define BAR8 __builtin_amdgcn_s_barrier()
; #define SCHED8 __builtin_amdgcn_sched_barrier(0)
;     ...
;   if (wr == 1) BAR8;
;   WAIT_V8(4); BAR8;
;   STAGE8(SB8(1, 0), Bt, K, bcol, 1); STAGE8(SA8(1, 0), A, lda, brow, 1); STAGE8(SB8(1, 1), Bt, K, bcol + 128, 1);
;   WAIT_V8(6); BAR8;
;   for (int tt = 0; tt < nt - 2; tt += 2) {
;     LDB8(B0, 0, 0); SCHED8; LDA8(At, 0, 0); STAGE8(SA8(1, 1), A, lda, brow + 128, tt + 1);
;     WAIT_L8(8); BAR8; WAIT_L8(0); MMA8(0, 0, At, B0); BAR8; SCHED8;
;     LDB8(B1, 0, 1); STAGE8(SB8(0, 0), Bt, K, bcol, tt + 2);
;     BAR8; WAIT_L8(0); MMA8(0, 1, At, B1); BAR8;
;     LDA8(At, 0, 1); STAGE8(SA8(0, 0), A, lda, brow, tt + 2);
;     BAR8; WAIT_L8(0); MMA8(1, 0, At, B0); BAR8; SCHED8;
;     STAGE8(SB8(0, 1), Bt, K, bcol + 128, tt + 2);
;     WAIT_V8(6); BAR8; MMA8(1, 1, At, B1); BAR8;
.LBB0_1324:
	s_or_b64 exec, exec, s[12:13]
	s_mov_b64 s[36:37], 0x80
	v_lshl_add_u64 v[10:11], v[10:11], 0, s[36:37]
	s_or_b32 m0, s100, 0x18000
	s_waitcnt vmcnt(4)
	s_barrier
	global_load_lds_dwordx4 v[10:11], off
	v_lshl_add_u64 v[10:11], v[12:13], 0, s[36:37]
	s_or_b32 m0, s100, 0x1a000
	global_load_lds_dwordx4 v[10:11], off
	v_lshl_add_u64 v[10:11], v[14:15], 0, s[36:37]
	s_or_b32 m0, s100, 0x8000
	global_load_lds_dwordx4 v[10:11], off
	v_lshl_add_u64 v[10:11], v[16:17], 0, s[36:37]
	s_or_b32 m0, s100, 0xa000
	global_load_lds_dwordx4 v[10:11], off
	s_or_b32 m0, s100, 0x1c000
	v_lshl_add_u64 v[10:11], v[18:19], 0, s[36:37]
	global_load_lds_dwordx4 v[10:11], off
	v_lshl_add_u64 v[10:11], v[20:21], 0, s[36:37]
	s_or_b32 m0, s100, 0x1e000
	v_and_b32_e32 v147, 15, v3
	global_load_lds_dwordx4 v[10:11], off
	v_bfe_u32 v148, v3, 4, 2
	v_lshlrev_b32_e32 v10, 4, v148
	v_lshlrev_b32_e32 v11, 6, v147
	v_lshlrev_b32_e32 v13, 2, v3
	v_or_b32_e32 v12, v10, v11
	v_and_b32_e32 v13, 32, v13
	s_mov_b32 s12, 0x10000
	v_bitop3_b32 v18, v12, s12, v13 bitop3:0xde
	s_mov_b32 s12, 0x14000
	v_bitop3_b32 v17, v10, v13, v11 bitop3:0x36
	v_bitop3_b32 v19, v12, s12, v13 bitop3:0xde
	s_mov_b32 s12, 0x18000
	v_lshlrev_b32_e32 v11, 6, v3
	v_bitop3_b32 v20, v12, s12, v13 bitop3:0xde
	s_mov_b32 s12, 0x1c000
	v_and_b32_e32 v11, 0x3c0, v11
	s_movk_i32 s31, 0x1600
	s_and_b32 s29, s21, 0xffffff00
	v_bitop3_b32 v21, v12, s12, v13 bitop3:0xde
	v_bitop3_b32 v24, v11, v13, v10 bitop3:0x36
	v_mad_i64_i32 v[10:11], s[12:13], v5, s31, 0
	v_mov_b32_e32 v5, 0x1600
	v_mad_i64_i32 v[12:13], s[12:13], s29, v5, v[10:11]
	v_lshl_add_u64 v[12:13], v[12:13], 0, v[6:7]
	v_lshl_add_u64 v[138:139], s[4:5], 0, v[12:13]
	v_mad_i64_i32 v[12:13], s[12:13], v22, s31, 0
	v_mad_i64_i32 v[14:15], s[12:13], s29, v5, v[12:13]
	s_bfe_u32 s29, s20, 0x60008
	v_mov_b32_e32 v5, 0x160000
	v_mad_u64_u32 v[10:11], s[12:13], s29, v5, v[10:11]
	v_lshl_add_u64 v[6:7], v[10:11], 0, v[6:7]
	v_bfe_u32 v146, v3, 6, 2
	s_waitcnt vmcnt(6)
	v_lshlrev_b32_e32 v149, 6, v23
	v_lshlrev_b32_e32 v23, 13, v23
	v_lshl_add_u64 v[142:143], s[2:3], 0, v[6:7]
	v_mad_u64_u32 v[6:7], s[12:13], s29, v5, v[12:13]
	v_lshlrev_b32_e32 v16, 12, v146
	v_or_b32_e32 v25, 0x800, v23
	v_or_b32_e32 v26, 0x1000, v23
	v_or_b32_e32 v27, 0x1800, v23
	v_lshl_add_u64 v[14:15], v[14:15], 0, v[8:9]
	v_lshl_add_u64 v[6:7], v[6:7], 0, v[8:9]
	s_ashr_i32 s9, s8, 31
	v_lshl_add_u64 v[140:141], s[4:5], 0, v[14:15]
	v_lshl_add_u64 v[144:145], s[2:3], 0, v[6:7]
	s_mov_b32 s29, -2
	s_mov_b64 s[12:13], 0
	v_add_u32_e32 v171, v18, v16
	v_add_u32_e32 v156, v17, v23
	v_add_u32_e32 v155, v24, v25
	v_add_u32_e32 v154, v24, v26
	v_add_u32_e32 v153, v24, v27
	v_add_u32_e32 v169, v19, v16
	v_add_u32_e32 v159, v20, v16
	v_add_u32_e32 v158, v21, v16
	s_mov_b64 s[36:37], 0x20b0080
	s_mov_b64 s[38:39], 0xd5a0100
	s_mov_b64 s[40:41], 0x2000100
	s_mov_b64 s[42:43], 0xd650100
	s_mov_b64 s[44:45], 0x20b0100
	s_mov_b64 s[46:47], 0xd5a0180
	s_mov_b64 s[48:49], 0x2000180
	s_mov_b64 s[50:51], 0xd650180
	s_barrier
	ds_read_b128 v[174:177], v171
	ds_read_b128 v[178:181], v171 offset:1024
	ds_read_b128 v[182:185], v171 offset:2048
	ds_read_b128 v[186:189], v171 offset:3072
	v_lshl_add_u64 v[222:223], v[142:143], 0, s[12:13]
	v_lshl_add_u64 v[226:227], v[222:223], 0, s[36:37]
	s_or_b32 m0, s100, 0xc000
	v_lshl_add_u64 v[236:237], v[144:145], 0, s[12:13]
	ds_read_b128 v[190:193], v156
	ds_read_b128 v[194:197], v156 offset:1024
	ds_read_b128 v[198:201], v155
	ds_read_b128 v[202:205], v155 offset:1024
	ds_read_b128 v[206:209], v154
	ds_read_b128 v[210:213], v154 offset:1024
	ds_read_b128 v[214:217], v153
	ds_read_b128 v[218:221], v153 offset:1024
	global_load_lds_dwordx4 v[226:227], off
	s_or_b32 m0, s100, 0xe000
	v_lshl_add_u64 v[226:227], v[236:237], 0, s[36:37]
	global_load_lds_dwordx4 v[226:227], off
	s_waitcnt lgkmcnt(8)
	s_barrier
	s_waitcnt lgkmcnt(0)
	v_mfma_f32_16x16x32_bf16 v[128:131], v[190:193], v[174:177], 0
	v_mfma_f32_16x16x32_bf16 v[124:127], v[190:193], v[182:185], 0
	v_mfma_f32_16x16x32_bf16 v[120:123], v[198:201], v[174:177], 0
	v_mfma_f32_16x16x32_bf16 v[116:119], v[198:201], v[182:185], 0
	v_mfma_f32_16x16x32_bf16 v[112:115], v[206:209], v[174:177], 0
	v_mfma_f32_16x16x32_bf16 v[108:111], v[206:209], v[182:185], 0
	v_mfma_f32_16x16x32_bf16 v[104:107], v[214:217], v[174:177], 0
	v_mfma_f32_16x16x32_bf16 v[100:103], v[214:217], v[182:185], 0
	v_mfma_f32_16x16x32_bf16 v[128:131], v[194:197], v[178:181], v[128:131]
	v_mfma_f32_16x16x32_bf16 v[124:127], v[194:197], v[186:189], v[124:127]
	v_mfma_f32_16x16x32_bf16 v[120:123], v[202:205], v[178:181], v[120:123]
	v_mfma_f32_16x16x32_bf16 v[116:119], v[202:205], v[186:189], v[116:119]
	v_mfma_f32_16x16x32_bf16 v[112:115], v[210:213], v[178:181], v[112:115]
	v_mfma_f32_16x16x32_bf16 v[108:111], v[210:213], v[186:189], v[108:111]
	v_mfma_f32_16x16x32_bf16 v[104:107], v[218:221], v[178:181], v[104:107]
	v_mfma_f32_16x16x32_bf16 v[100:103], v[218:221], v[186:189], v[100:103]
	s_barrier
	v_lshl_add_u64 v[246:247], v[138:139], 0, s[12:13]
	v_lshl_add_u64 v[248:249], v[246:247], 0, s[38:39]
	s_or_b32 m0, s100, 0x10000
	ds_read_b128 v[226:229], v169
	ds_read_b128 v[230:233], v169 offset:1024
	ds_read_b128 v[238:241], v169 offset:2048
	ds_read_b128 v[242:245], v169 offset:3072
	global_load_lds_dwordx4 v[248:249], off
	v_lshl_add_u64 v[248:249], v[140:141], 0, s[12:13]
	s_or_b32 m0, s100, 0x12000
	v_lshl_add_u64 v[250:251], v[248:249], 0, s[38:39]
	global_load_lds_dwordx4 v[250:251], off
	s_barrier
; #define LDA8(dst, b, h) _Pragma("unroll") for (int m = 0; m < 4; ++m) _Pragma("unroll") for (int k = 0; k < 2; ++k) \
;     dst[m][k] = *(const bf16x8*)((const char*)SA8(b, h) + lds_byte8(wr * 64 + m * 16 + fr, k * 32 + fq * 8))
; #define LDB8(dst, b, h) _Pragma("unroll") for (int n = 0; n < 2; ++n) _Pragma("unroll") for (int k = 0; k < 2; ++k) \
;     dst[n][k] = *(const bf16x8*)((const char*)SB8(b, h) + lds_byte8(wc * 32 + n * 16 + fr, k * 32 + fq * 8))
; #define WAIT_V8(n) asm volatile("s_waitcnt vmcnt(" #n ")" ::: "memory")
; #define WAIT_L8(n) asm volatile("s_waitcnt lgkmcnt(" #n ")" ::: "memory")
; #define BAR8 __builtin_amdgcn_s_barrier()
; #define SCHED8 __builtin_amdgcn_sched_barrier(0)
;     ...
;   for (int tt = 0; tt < nt - 2; tt += 2) {
;     LDB8(B0, 0, 0); SCHED8; LDA8(At, 0, 0); STAGE8(SA8(1, 1), A, lda, brow + 128, tt + 1);
;     WAIT_L8(8); BAR8; WAIT_L8(0); MMA8(0, 0, At, B0); BAR8; SCHED8;
;     LDB8(B1, 0, 1); STAGE8(SB8(0, 0), Bt, K, bcol, tt + 2);
;     BAR8; WAIT_L8(0); MMA8(0, 1, At, B1); BAR8;
;     LDA8(At, 0, 1); STAGE8(SA8(0, 0), A, lda, brow, tt + 2);
;     BAR8; WAIT_L8(0); MMA8(1, 0, At, B0); BAR8; SCHED8;
;     STAGE8(SB8(0, 1), Bt, K, bcol + 128, tt + 2);
;     WAIT_V8(6); BAR8; MMA8(1, 1, At, B1); BAR8;
;     LDB8(B0, 1, 0); SCHED8; LDA8(At, 1, 0); STAGE8(SA8(0, 1), A, lda, brow + 128, tt + 2);
;     WAIT_L8(8); BAR8; WAIT_L8(0); MMA8(0, 0, At, B0); BAR8; SCHED8;
;     LDB8(B1, 1, 1); STAGE8(SB8(1, 0), Bt, K, bcol, tt + 3);
;     BAR8; WAIT_L8(0); MMA8(0, 1, At, B1); BAR8;
;     LDA8(At, 1, 1); STAGE8(SA8(1, 0), A, lda, brow, tt + 3);
;     BAR8; WAIT_L8(0); MMA8(1, 0, At, B0); BAR8; SCHED8;
;     STAGE8(SB8(1, 1), Bt, K, bcol + 128, tt + 3);
;     WAIT_V8(6); BAR8; MMA8(1, 1, At, B1); BAR8;
;   }
	s_waitcnt lgkmcnt(0)
	v_mfma_f32_16x16x32_bf16 v[96:99], v[190:193], v[226:229], 0
	v_mfma_f32_16x16x32_bf16 v[92:95], v[190:193], v[238:241], 0
	v_mfma_f32_16x16x32_bf16 v[88:91], v[198:201], v[226:229], 0
	v_mfma_f32_16x16x32_bf16 v[84:87], v[198:201], v[238:241], 0
	v_mfma_f32_16x16x32_bf16 v[80:83], v[206:209], v[226:229], 0
	v_mfma_f32_16x16x32_bf16 v[76:79], v[206:209], v[238:241], 0
	v_mfma_f32_16x16x32_bf16 v[72:75], v[214:217], v[226:229], 0
	v_mfma_f32_16x16x32_bf16 v[68:71], v[214:217], v[238:241], 0
	v_mfma_f32_16x16x32_bf16 v[96:99], v[194:197], v[230:233], v[96:99]
	v_mfma_f32_16x16x32_bf16 v[92:95], v[194:197], v[242:245], v[92:95]
	v_mfma_f32_16x16x32_bf16 v[88:91], v[202:205], v[230:233], v[88:91]
	v_mfma_f32_16x16x32_bf16 v[84:87], v[202:205], v[242:245], v[84:87]
	v_mfma_f32_16x16x32_bf16 v[80:83], v[210:213], v[230:233], v[80:83]
	v_mfma_f32_16x16x32_bf16 v[76:79], v[210:213], v[242:245], v[76:79]
	v_mfma_f32_16x16x32_bf16 v[72:75], v[218:221], v[230:233], v[72:75]
	v_mfma_f32_16x16x32_bf16 v[68:71], v[218:221], v[242:245], v[68:71]
	v_lshl_add_u64 v[250:251], v[222:223], 0, s[40:41]
	s_mov_b32 m0, s100
	s_barrier
	ds_read_b128 v[190:193], v156 offset:16384
	ds_read_b128 v[194:197], v156 offset:17408
	ds_read_b128 v[198:201], v155 offset:16384
	ds_read_b128 v[202:205], v155 offset:17408
	ds_read_b128 v[206:209], v154 offset:16384
	ds_read_b128 v[210:213], v154 offset:17408
	ds_read_b128 v[214:217], v153 offset:16384
	ds_read_b128 v[218:221], v153 offset:17408
	global_load_lds_dwordx4 v[250:251], off
	s_or_b32 m0, s100, 0x2000
	v_lshl_add_u64 v[250:251], v[236:237], 0, s[40:41]
	global_load_lds_dwordx4 v[250:251], off
	s_barrier
	s_waitcnt lgkmcnt(0)
	v_mfma_f32_16x16x32_bf16 v[64:67], v[190:193], v[174:177], 0
	v_mfma_f32_16x16x32_bf16 v[60:63], v[190:193], v[182:185], 0
	v_mfma_f32_16x16x32_bf16 v[56:59], v[198:201], v[174:177], 0
	v_mfma_f32_16x16x32_bf16 v[52:55], v[198:201], v[182:185], 0
	v_mfma_f32_16x16x32_bf16 v[48:51], v[206:209], v[174:177], 0
	v_mfma_f32_16x16x32_bf16 v[44:47], v[206:209], v[182:185], 0
	v_mfma_f32_16x16x32_bf16 v[40:43], v[214:217], v[174:177], 0
	v_mfma_f32_16x16x32_bf16 v[36:39], v[214:217], v[182:185], 0
	v_mfma_f32_16x16x32_bf16 v[64:67], v[194:197], v[178:181], v[64:67]
	v_mfma_f32_16x16x32_bf16 v[60:63], v[194:197], v[186:189], v[60:63]
	v_mfma_f32_16x16x32_bf16 v[56:59], v[202:205], v[178:181], v[56:59]
	v_mfma_f32_16x16x32_bf16 v[52:55], v[202:205], v[186:189], v[52:55]
	v_mfma_f32_16x16x32_bf16 v[48:51], v[210:213], v[178:181], v[48:51]
	v_mfma_f32_16x16x32_bf16 v[44:47], v[210:213], v[186:189], v[44:47]
	v_mfma_f32_16x16x32_bf16 v[40:43], v[218:221], v[178:181], v[40:43]
	v_mfma_f32_16x16x32_bf16 v[36:39], v[218:221], v[186:189], v[36:39]
	s_barrier
	s_or_b32 m0, s100, 0x14000
	v_lshl_add_u64 v[174:175], v[246:247], 0, s[42:43]
	global_load_lds_dwordx4 v[174:175], off
	s_or_b32 m0, s100, 0x16000
	v_lshl_add_u64 v[174:175], v[248:249], 0, s[42:43]
	global_load_lds_dwordx4 v[174:175], off
	s_waitcnt vmcnt(6)
	s_barrier
	v_mfma_f32_16x16x32_bf16 v[32:35], v[190:193], v[226:229], 0
	v_mfma_f32_16x16x32_bf16 v[28:31], v[190:193], v[238:241], 0
	v_mfma_f32_16x16x32_bf16 v[24:27], v[198:201], v[226:229], 0
	v_mfma_f32_16x16x32_bf16 v[20:23], v[198:201], v[238:241], 0
	v_mfma_f32_16x16x32_bf16 v[16:19], v[206:209], v[226:229], 0
	v_mfma_f32_16x16x32_bf16 v[12:15], v[206:209], v[238:241], 0
	v_mfma_f32_16x16x32_bf16 v[8:11], v[214:217], v[226:229], 0
	v_mfma_f32_16x16x32_bf16 v[4:7], v[214:217], v[238:241], 0
	v_mfma_f32_16x16x32_bf16 v[32:35], v[194:197], v[230:233], v[32:35]
	v_mfma_f32_16x16x32_bf16 v[28:31], v[194:197], v[242:245], v[28:31]
	v_mfma_f32_16x16x32_bf16 v[24:27], v[202:205], v[230:233], v[24:27]
	v_mfma_f32_16x16x32_bf16 v[20:23], v[202:205], v[242:245], v[20:23]
	v_mfma_f32_16x16x32_bf16 v[16:19], v[210:213], v[230:233], v[16:19]
	v_mfma_f32_16x16x32_bf16 v[12:15], v[210:213], v[242:245], v[12:15]
	v_mfma_f32_16x16x32_bf16 v[8:11], v[218:221], v[230:233], v[8:11]
	v_mfma_f32_16x16x32_bf16 v[4:7], v[218:221], v[242:245], v[4:7]
	s_barrier
	ds_read_b128 v[174:177], v159
	ds_read_b128 v[178:181], v159 offset:1024
	ds_read_b128 v[182:185], v159 offset:2048
	ds_read_b128 v[186:189], v159 offset:3072
	v_lshl_add_u64 v[226:227], v[222:223], 0, s[44:45]
	s_or_b32 m0, s100, 0x4000
	ds_read_b128 v[190:193], v156 offset:32768
	ds_read_b128 v[194:197], v156 offset:33792
	ds_read_b128 v[198:201], v155 offset:32768
	ds_read_b128 v[202:205], v155 offset:33792
	ds_read_b128 v[206:209], v154 offset:32768
	ds_read_b128 v[210:213], v154 offset:33792
	ds_read_b128 v[214:217], v153 offset:32768
	ds_read_b128 v[218:221], v153 offset:33792
	global_load_lds_dwordx4 v[226:227], off
	s_or_b32 m0, s100, 0x6000
	v_lshl_add_u64 v[226:227], v[236:237], 0, s[44:45]
	global_load_lds_dwordx4 v[226:227], off
	s_waitcnt lgkmcnt(8)
	s_barrier
	s_waitcnt lgkmcnt(0)
	v_mfma_f32_16x16x32_bf16 v[128:131], v[190:193], v[174:177], v[128:131]
	v_mfma_f32_16x16x32_bf16 v[124:127], v[190:193], v[182:185], v[124:127]
	v_mfma_f32_16x16x32_bf16 v[120:123], v[198:201], v[174:177], v[120:123]
	v_mfma_f32_16x16x32_bf16 v[116:119], v[198:201], v[182:185], v[116:119]
	v_mfma_f32_16x16x32_bf16 v[112:115], v[206:209], v[174:177], v[112:115]
	v_mfma_f32_16x16x32_bf16 v[108:111], v[206:209], v[182:185], v[108:111]
	v_mfma_f32_16x16x32_bf16 v[104:107], v[214:217], v[174:177], v[104:107]
	v_mfma_f32_16x16x32_bf16 v[100:103], v[214:217], v[182:185], v[100:103]
	v_mfma_f32_16x16x32_bf16 v[128:131], v[194:197], v[178:181], v[128:131]
	v_mfma_f32_16x16x32_bf16 v[124:127], v[194:197], v[186:189], v[124:127]
	v_mfma_f32_16x16x32_bf16 v[120:123], v[202:205], v[178:181], v[120:123]
	v_mfma_f32_16x16x32_bf16 v[116:119], v[202:205], v[186:189], v[116:119]
	v_mfma_f32_16x16x32_bf16 v[112:115], v[210:213], v[178:181], v[112:115]
	v_mfma_f32_16x16x32_bf16 v[108:111], v[210:213], v[186:189], v[108:111]
	v_mfma_f32_16x16x32_bf16 v[104:107], v[218:221], v[178:181], v[104:107]
	v_mfma_f32_16x16x32_bf16 v[100:103], v[218:221], v[186:189], v[100:103]
	s_barrier
; #define LDA8(dst, b, h) _Pragma("unroll") for (int m = 0; m < 4; ++m) _Pragma("unroll") for (int k = 0; k < 2; ++k) \
;     dst[m][k] = *(const bf16x8*)((const char*)SA8(b, h) + lds_byte8(wr * 64 + m * 16 + fr, k * 32 + fq * 8))
; #define LDB8(dst, b, h) _Pragma("unroll") for (int n = 0; n < 2; ++n) _Pragma("unroll") for (int k = 0; k < 2; ++k) \
;     dst[n][k] = *(const bf16x8*)((const char*)SB8(b, h) + lds_byte8(wc * 32 + n * 16 + fr, k * 32 + fq * 8))
; #define WAIT_V8(n) asm volatile("s_waitcnt vmcnt(" #n ")" ::: "memory")
; #define WAIT_L8(n) asm volatile("s_waitcnt lgkmcnt(" #n ")" ::: "memory")
; #define BAR8 __builtin_amdgcn_s_barrier()
; #define SCHED8 __builtin_amdgcn_sched_barrier(0)
;     ...
;     BAR8; WAIT_L8(0); MMA8(1, 0, At, B0); BAR8; SCHED8;
;     STAGE8(SB8(0, 1), Bt, K, bcol + 128, tt + 2);
;     WAIT_V8(6); BAR8; MMA8(1, 1, At, B1); BAR8;
;     LDB8(B0, 1, 0); SCHED8; LDA8(At, 1, 0); STAGE8(SA8(0, 1), A, lda, brow + 128, tt + 2);
;     WAIT_L8(8); BAR8; WAIT_L8(0); MMA8(0, 0, At, B0); BAR8; SCHED8;
;     LDB8(B1, 1, 1); STAGE8(SB8(1, 0), Bt, K, bcol, tt + 3);
;     BAR8; WAIT_L8(0); MMA8(0, 1, At, B1); BAR8;
;     LDA8(At, 1, 1); STAGE8(SA8(1, 0), A, lda, brow, tt + 3);
;     BAR8; WAIT_L8(0); MMA8(1, 0, At, B0); BAR8; SCHED8;
;     STAGE8(SB8(1, 1), Bt, K, bcol + 128, tt + 3);
;     WAIT_V8(6); BAR8; MMA8(1, 1, At, B1); BAR8;
;   }
	v_lshl_add_u64 v[250:251], v[246:247], 0, s[46:47]
	s_or_b32 m0, s100, 0x18000
	ds_read_b128 v[226:229], v158
	ds_read_b128 v[230:233], v158 offset:1024
	ds_read_b128 v[238:241], v158 offset:2048
	ds_read_b128 v[242:245], v158 offset:3072
	global_load_lds_dwordx4 v[250:251], off
	s_or_b32 m0, s100, 0x1a000
	v_lshl_add_u64 v[250:251], v[248:249], 0, s[46:47]
	global_load_lds_dwordx4 v[250:251], off
	s_barrier
	s_waitcnt lgkmcnt(0)
	v_mfma_f32_16x16x32_bf16 v[96:99], v[190:193], v[226:229], v[96:99]
	v_mfma_f32_16x16x32_bf16 v[92:95], v[190:193], v[238:241], v[92:95]
	v_mfma_f32_16x16x32_bf16 v[88:91], v[198:201], v[226:229], v[88:91]
	v_mfma_f32_16x16x32_bf16 v[84:87], v[198:201], v[238:241], v[84:87]
	v_mfma_f32_16x16x32_bf16 v[80:83], v[206:209], v[226:229], v[80:83]
	v_mfma_f32_16x16x32_bf16 v[76:79], v[206:209], v[238:241], v[76:79]
	v_mfma_f32_16x16x32_bf16 v[72:75], v[214:217], v[226:229], v[72:75]
	v_mfma_f32_16x16x32_bf16 v[68:71], v[214:217], v[238:241], v[68:71]
	v_mfma_f32_16x16x32_bf16 v[96:99], v[194:197], v[230:233], v[96:99]
	v_mfma_f32_16x16x32_bf16 v[92:95], v[194:197], v[242:245], v[92:95]
	v_mfma_f32_16x16x32_bf16 v[88:91], v[202:205], v[230:233], v[88:91]
	v_mfma_f32_16x16x32_bf16 v[84:87], v[202:205], v[242:245], v[84:87]
	v_mfma_f32_16x16x32_bf16 v[80:83], v[210:213], v[230:233], v[80:83]
	v_mfma_f32_16x16x32_bf16 v[76:79], v[210:213], v[242:245], v[76:79]
	v_mfma_f32_16x16x32_bf16 v[72:75], v[218:221], v[230:233], v[72:75]
	v_mfma_f32_16x16x32_bf16 v[68:71], v[218:221], v[242:245], v[68:71]
	v_lshl_add_u64 v[222:223], v[222:223], 0, s[48:49]
	s_or_b32 m0, s100, 0x8000
	s_barrier
	ds_read_b128 v[190:193], v156 offset:49152
	ds_read_b128 v[194:197], v156 offset:50176
	ds_read_b128 v[198:201], v155 offset:49152
	ds_read_b128 v[202:205], v155 offset:50176
	ds_read_b128 v[206:209], v154 offset:49152
	ds_read_b128 v[210:213], v154 offset:50176
	ds_read_b128 v[214:217], v153 offset:49152
	ds_read_b128 v[218:221], v153 offset:50176
	global_load_lds_dwordx4 v[222:223], off
	s_or_b32 m0, s100, 0xa000
	v_lshl_add_u64 v[222:223], v[236:237], 0, s[48:49]
	global_load_lds_dwordx4 v[222:223], off
	s_barrier
	s_waitcnt lgkmcnt(0)
	v_mfma_f32_16x16x32_bf16 v[64:67], v[190:193], v[174:177], v[64:67]
	v_mfma_f32_16x16x32_bf16 v[60:63], v[190:193], v[182:185], v[60:63]
	v_mfma_f32_16x16x32_bf16 v[56:59], v[198:201], v[174:177], v[56:59]
	v_mfma_f32_16x16x32_bf16 v[52:55], v[198:201], v[182:185], v[52:55]
	v_mfma_f32_16x16x32_bf16 v[48:51], v[206:209], v[174:177], v[48:51]
	v_mfma_f32_16x16x32_bf16 v[44:47], v[206:209], v[182:185], v[44:47]
	v_mfma_f32_16x16x32_bf16 v[40:43], v[214:217], v[174:177], v[40:43]
	v_mfma_f32_16x16x32_bf16 v[36:39], v[214:217], v[182:185], v[36:39]
	v_mfma_f32_16x16x32_bf16 v[64:67], v[194:197], v[178:181], v[64:67]
	v_mfma_f32_16x16x32_bf16 v[60:63], v[194:197], v[186:189], v[60:63]
	v_mfma_f32_16x16x32_bf16 v[56:59], v[202:205], v[178:181], v[56:59]
	v_mfma_f32_16x16x32_bf16 v[52:55], v[202:205], v[186:189], v[52:55]
	v_mfma_f32_16x16x32_bf16 v[48:51], v[210:213], v[178:181], v[48:51]
	v_mfma_f32_16x16x32_bf16 v[44:47], v[210:213], v[186:189], v[44:47]
	v_mfma_f32_16x16x32_bf16 v[40:43], v[218:221], v[178:181], v[40:43]
	v_mfma_f32_16x16x32_bf16 v[36:39], v[218:221], v[186:189], v[36:39]
	s_barrier
	s_or_b32 m0, s100, 0x1c000
	v_lshl_add_u64 v[174:175], v[246:247], 0, s[50:51]
	global_load_lds_dwordx4 v[174:175], off
	s_or_b32 m0, s100, 0x1e000
	v_lshl_add_u64 v[174:175], v[248:249], 0, s[50:51]
	global_load_lds_dwordx4 v[174:175], off
	s_waitcnt vmcnt(6)
	s_barrier
	v_mfma_f32_16x16x32_bf16 v[32:35], v[190:193], v[226:229], v[32:35]
	v_mfma_f32_16x16x32_bf16 v[28:31], v[190:193], v[238:241], v[28:31]
	v_mfma_f32_16x16x32_bf16 v[24:27], v[198:201], v[226:229], v[24:27]
	v_mfma_f32_16x16x32_bf16 v[20:23], v[198:201], v[238:241], v[20:23]
	v_mfma_f32_16x16x32_bf16 v[16:19], v[206:209], v[226:229], v[16:19]
	v_mfma_f32_16x16x32_bf16 v[12:15], v[206:209], v[238:241], v[12:15]
	v_mfma_f32_16x16x32_bf16 v[8:11], v[214:217], v[226:229], v[8:11]
	v_mfma_f32_16x16x32_bf16 v[4:7], v[214:217], v[238:241], v[4:7]
	v_mfma_f32_16x16x32_bf16 v[32:35], v[194:197], v[230:233], v[32:35]
	v_mfma_f32_16x16x32_bf16 v[28:31], v[194:197], v[242:245], v[28:31]
	v_mfma_f32_16x16x32_bf16 v[24:27], v[202:205], v[230:233], v[24:27]
	v_mfma_f32_16x16x32_bf16 v[20:23], v[202:205], v[242:245], v[20:23]
	v_mfma_f32_16x16x32_bf16 v[16:19], v[210:213], v[230:233], v[16:19]
	v_mfma_f32_16x16x32_bf16 v[12:15], v[210:213], v[242:245], v[12:15]
	v_mfma_f32_16x16x32_bf16 v[8:11], v[218:221], v[230:233], v[8:11]
	v_mfma_f32_16x16x32_bf16 v[4:7], v[218:221], v[242:245], v[4:7]
	s_add_i32 s29, s29, 2
	s_add_u32 s12, s12, 0x100
	s_addc_u32 s13, s13, 0
	s_cmp_lt_u32 s29, 40
	s_barrier
	s_cbranch_scc0 .Lpk_exit_7
; #define LDA8(dst, b, h) _Pragma("unroll") for (int m = 0; m < 4; ++m) _Pragma("unroll") for (int k = 0; k < 2; ++k) \
;     dst[m][k] = *(const bf16x8*)((const char*)SA8(b, h) + lds_byte8(wr * 64 + m * 16 + fr, k * 32 + fq * 8))
; #define LDB8(dst, b, h) _Pragma("unroll") for (int n = 0; n < 2; ++n) _Pragma("unroll") for (int k = 0; k < 2; ++k) \
;     dst[n][k] = *(const bf16x8*)((const char*)SB8(b, h) + lds_byte8(wc * 32 + n * 16 + fr, k * 32 + fq * 8))
; #define WAIT_V8(n) asm volatile("s_waitcnt vmcnt(" #n ")" ::: "memory")
; #define WAIT_L8(n) asm volatile("s_waitcnt lgkmcnt(" #n ")" ::: "memory")
; #define BAR8 __builtin_amdgcn_s_barrier()
; #define SCHED8 __builtin_amdgcn_sched_barrier(0)
;     ...
;   for (int tt = 0; tt < nt - 2; tt += 2) {
;     LDB8(B0, 0, 0); SCHED8; LDA8(At, 0, 0); STAGE8(SA8(1, 1), A, lda, brow + 128, tt + 1);
;     WAIT_L8(8); BAR8; WAIT_L8(0); MMA8(0, 0, At, B0); BAR8; SCHED8;
;     LDB8(B1, 0, 1); STAGE8(SB8(0, 0), Bt, K, bcol, tt + 2);
;     BAR8; WAIT_L8(0); MMA8(0, 1, At, B1); BAR8;
;     LDA8(At, 0, 1); STAGE8(SA8(0, 0), A, lda, brow, tt + 2);
;     BAR8; WAIT_L8(0); MMA8(1, 0, At, B0); BAR8; SCHED8;
;     STAGE8(SB8(0, 1), Bt, K, bcol + 128, tt + 2);
;     WAIT_V8(6); BAR8; MMA8(1, 1, At, B1); BAR8;
;     LDB8(B0, 1, 0); SCHED8; LDA8(At, 1, 0); STAGE8(SA8(0, 1), A, lda, brow + 128, tt + 2);
;     WAIT_L8(8); BAR8; WAIT_L8(0); MMA8(0, 0, At, B0); BAR8; SCHED8;
.LBB0_1325:
	ds_read_b128 v[174:177], v171
	ds_read_b128 v[178:181], v171 offset:1024
	ds_read_b128 v[182:185], v171 offset:2048
	ds_read_b128 v[186:189], v171 offset:3072
	v_lshl_add_u64 v[222:223], v[142:143], 0, s[12:13]
	v_lshl_add_u64 v[226:227], v[222:223], 0, s[36:37]
	s_or_b32 m0, s100, 0xc000
	v_lshl_add_u64 v[236:237], v[144:145], 0, s[12:13]
	ds_read_b128 v[190:193], v156
	ds_read_b128 v[194:197], v156 offset:1024
	ds_read_b128 v[198:201], v155
	ds_read_b128 v[202:205], v155 offset:1024
	ds_read_b128 v[206:209], v154
	ds_read_b128 v[210:213], v154 offset:1024
	ds_read_b128 v[214:217], v153
	ds_read_b128 v[218:221], v153 offset:1024
	global_load_lds_dwordx4 v[226:227], off
	s_or_b32 m0, s100, 0xe000
	v_lshl_add_u64 v[226:227], v[236:237], 0, s[36:37]
	global_load_lds_dwordx4 v[226:227], off
	s_waitcnt lgkmcnt(8)
	s_barrier
	s_waitcnt lgkmcnt(0)
	v_mfma_f32_16x16x32_bf16 v[128:131], v[190:193], v[174:177], v[128:131]
	v_mfma_f32_16x16x32_bf16 v[124:127], v[190:193], v[182:185], v[124:127]
	v_mfma_f32_16x16x32_bf16 v[120:123], v[198:201], v[174:177], v[120:123]
	v_mfma_f32_16x16x32_bf16 v[116:119], v[198:201], v[182:185], v[116:119]
	v_mfma_f32_16x16x32_bf16 v[112:115], v[206:209], v[174:177], v[112:115]
	v_mfma_f32_16x16x32_bf16 v[108:111], v[206:209], v[182:185], v[108:111]
	v_mfma_f32_16x16x32_bf16 v[104:107], v[214:217], v[174:177], v[104:107]
	v_mfma_f32_16x16x32_bf16 v[100:103], v[214:217], v[182:185], v[100:103]
	v_mfma_f32_16x16x32_bf16 v[128:131], v[194:197], v[178:181], v[128:131]
	v_mfma_f32_16x16x32_bf16 v[124:127], v[194:197], v[186:189], v[124:127]
	v_mfma_f32_16x16x32_bf16 v[120:123], v[202:205], v[178:181], v[120:123]
	v_mfma_f32_16x16x32_bf16 v[116:119], v[202:205], v[186:189], v[116:119]
	v_mfma_f32_16x16x32_bf16 v[112:115], v[210:213], v[178:181], v[112:115]
	v_mfma_f32_16x16x32_bf16 v[108:111], v[210:213], v[186:189], v[108:111]
	v_mfma_f32_16x16x32_bf16 v[104:107], v[218:221], v[178:181], v[104:107]
	v_mfma_f32_16x16x32_bf16 v[100:103], v[218:221], v[186:189], v[100:103]
	s_barrier
	v_lshl_add_u64 v[246:247], v[138:139], 0, s[12:13]
	v_lshl_add_u64 v[248:249], v[246:247], 0, s[38:39]
	s_or_b32 m0, s100, 0x10000
	ds_read_b128 v[226:229], v169
	ds_read_b128 v[230:233], v169 offset:1024
	ds_read_b128 v[238:241], v169 offset:2048
	ds_read_b128 v[242:245], v169 offset:3072
	global_load_lds_dwordx4 v[248:249], off
	v_lshl_add_u64 v[248:249], v[140:141], 0, s[12:13]
	s_or_b32 m0, s100, 0x12000
	v_lshl_add_u64 v[250:251], v[248:249], 0, s[38:39]
	global_load_lds_dwordx4 v[250:251], off
	s_barrier
	s_waitcnt lgkmcnt(0)
	v_mfma_f32_16x16x32_bf16 v[96:99], v[190:193], v[226:229], v[96:99]
	v_mfma_f32_16x16x32_bf16 v[92:95], v[190:193], v[238:241], v[92:95]
	v_mfma_f32_16x16x32_bf16 v[88:91], v[198:201], v[226:229], v[88:91]
	v_mfma_f32_16x16x32_bf16 v[84:87], v[198:201], v[238:241], v[84:87]
	v_mfma_f32_16x16x32_bf16 v[80:83], v[206:209], v[226:229], v[80:83]
	v_mfma_f32_16x16x32_bf16 v[76:79], v[206:209], v[238:241], v[76:79]
	v_mfma_f32_16x16x32_bf16 v[72:75], v[214:217], v[226:229], v[72:75]
	v_mfma_f32_16x16x32_bf16 v[68:71], v[214:217], v[238:241], v[68:71]
	v_mfma_f32_16x16x32_bf16 v[96:99], v[194:197], v[230:233], v[96:99]
	v_mfma_f32_16x16x32_bf16 v[92:95], v[194:197], v[242:245], v[92:95]
	v_mfma_f32_16x16x32_bf16 v[88:91], v[202:205], v[230:233], v[88:91]
	v_mfma_f32_16x16x32_bf16 v[84:87], v[202:205], v[242:245], v[84:87]
	v_mfma_f32_16x16x32_bf16 v[80:83], v[210:213], v[230:233], v[80:83]
	v_mfma_f32_16x16x32_bf16 v[76:79], v[210:213], v[242:245], v[76:79]
	v_mfma_f32_16x16x32_bf16 v[72:75], v[218:221], v[230:233], v[72:75]
	v_mfma_f32_16x16x32_bf16 v[68:71], v[218:221], v[242:245], v[68:71]
	v_lshl_add_u64 v[250:251], v[222:223], 0, s[40:41]
	s_mov_b32 m0, s100
	s_barrier
	ds_read_b128 v[190:193], v156 offset:16384
	ds_read_b128 v[194:197], v156 offset:17408
	ds_read_b128 v[198:201], v155 offset:16384
	ds_read_b128 v[202:205], v155 offset:17408
	ds_read_b128 v[206:209], v154 offset:16384
	ds_read_b128 v[210:213], v154 offset:17408
	ds_read_b128 v[214:217], v153 offset:16384
	ds_read_b128 v[218:221], v153 offset:17408
	global_load_lds_dwordx4 v[250:251], off
	s_or_b32 m0, s100, 0x2000
	v_lshl_add_u64 v[250:251], v[236:237], 0, s[40:41]
	global_load_lds_dwordx4 v[250:251], off
	s_barrier
	s_waitcnt lgkmcnt(0)
	v_mfma_f32_16x16x32_bf16 v[64:67], v[190:193], v[174:177], v[64:67]
	v_mfma_f32_16x16x32_bf16 v[60:63], v[190:193], v[182:185], v[60:63]
	v_mfma_f32_16x16x32_bf16 v[56:59], v[198:201], v[174:177], v[56:59]
	v_mfma_f32_16x16x32_bf16 v[52:55], v[198:201], v[182:185], v[52:55]
	v_mfma_f32_16x16x32_bf16 v[48:51], v[206:209], v[174:177], v[48:51]
	v_mfma_f32_16x16x32_bf16 v[44:47], v[206:209], v[182:185], v[44:47]
	v_mfma_f32_16x16x32_bf16 v[40:43], v[214:217], v[174:177], v[40:43]
	v_mfma_f32_16x16x32_bf16 v[36:39], v[214:217], v[182:185], v[36:39]
	v_mfma_f32_16x16x32_bf16 v[64:67], v[194:197], v[178:181], v[64:67]
	v_mfma_f32_16x16x32_bf16 v[60:63], v[194:197], v[186:189], v[60:63]
	v_mfma_f32_16x16x32_bf16 v[56:59], v[202:205], v[178:181], v[56:59]
	v_mfma_f32_16x16x32_bf16 v[52:55], v[202:205], v[186:189], v[52:55]
	v_mfma_f32_16x16x32_bf16 v[48:51], v[210:213], v[178:181], v[48:51]
	v_mfma_f32_16x16x32_bf16 v[44:47], v[210:213], v[186:189], v[44:47]
	v_mfma_f32_16x16x32_bf16 v[40:43], v[218:221], v[178:181], v[40:43]
	v_mfma_f32_16x16x32_bf16 v[36:39], v[218:221], v[186:189], v[36:39]
	s_barrier
	s_or_b32 m0, s100, 0x14000
	v_lshl_add_u64 v[174:175], v[246:247], 0, s[42:43]
	global_load_lds_dwordx4 v[174:175], off
	s_or_b32 m0, s100, 0x16000
	v_lshl_add_u64 v[174:175], v[248:249], 0, s[42:43]
	global_load_lds_dwordx4 v[174:175], off
	s_waitcnt vmcnt(6)
	s_barrier
; #define LDA8(dst, b, h) _Pragma("unroll") for (int m = 0; m < 4; ++m) _Pragma("unroll") for (int k = 0; k < 2; ++k) \
;     dst[m][k] = *(const bf16x8*)((const char*)SA8(b, h) + lds_byte8(wr * 64 + m * 16 + fr, k * 32 + fq * 8))
; #define LDB8(dst, b, h) _Pragma("unroll") for (int n = 0; n < 2; ++n) _Pragma("unroll") for (int k = 0; k < 2; ++k) \
;     dst[n][k] = *(const bf16x8*)((const char*)SB8(b, h) + lds_byte8(wc * 32 + n * 16 + fr, k * 32 + fq * 8))
; #define WAIT_V8(n) asm volatile("s_waitcnt vmcnt(" #n ")" ::: "memory")
; #define WAIT_L8(n) asm volatile("s_waitcnt lgkmcnt(" #n ")" ::: "memory")
; #define BAR8 __builtin_amdgcn_s_barrier()
; #define SCHED8 __builtin_amdgcn_sched_barrier(0)
;     ...
;     WAIT_V8(6); BAR8; MMA8(1, 1, At, B1); BAR8;
;     LDB8(B0, 1, 0); SCHED8; LDA8(At, 1, 0); STAGE8(SA8(0, 1), A, lda, brow + 128, tt + 2);
;     WAIT_L8(8); BAR8; WAIT_L8(0); MMA8(0, 0, At, B0); BAR8; SCHED8;
;     LDB8(B1, 1, 1); STAGE8(SB8(1, 0), Bt, K, bcol, tt + 3);
;     BAR8; WAIT_L8(0); MMA8(0, 1, At, B1); BAR8;
;     LDA8(At, 1, 1); STAGE8(SA8(1, 0), A, lda, brow, tt + 3);
;     BAR8; WAIT_L8(0); MMA8(1, 0, At, B0); BAR8; SCHED8;
;     STAGE8(SB8(1, 1), Bt, K, bcol + 128, tt + 3);
	v_mfma_f32_16x16x32_bf16 v[32:35], v[190:193], v[226:229], v[32:35]
	v_mfma_f32_16x16x32_bf16 v[28:31], v[190:193], v[238:241], v[28:31]
	v_mfma_f32_16x16x32_bf16 v[24:27], v[198:201], v[226:229], v[24:27]
	v_mfma_f32_16x16x32_bf16 v[20:23], v[198:201], v[238:241], v[20:23]
	v_mfma_f32_16x16x32_bf16 v[16:19], v[206:209], v[226:229], v[16:19]
	v_mfma_f32_16x16x32_bf16 v[12:15], v[206:209], v[238:241], v[12:15]
	v_mfma_f32_16x16x32_bf16 v[8:11], v[214:217], v[226:229], v[8:11]
	v_mfma_f32_16x16x32_bf16 v[4:7], v[214:217], v[238:241], v[4:7]
	v_mfma_f32_16x16x32_bf16 v[32:35], v[194:197], v[230:233], v[32:35]
	v_mfma_f32_16x16x32_bf16 v[28:31], v[194:197], v[242:245], v[28:31]
	v_mfma_f32_16x16x32_bf16 v[24:27], v[202:205], v[230:233], v[24:27]
	v_mfma_f32_16x16x32_bf16 v[20:23], v[202:205], v[242:245], v[20:23]
	v_mfma_f32_16x16x32_bf16 v[16:19], v[210:213], v[230:233], v[16:19]
	v_mfma_f32_16x16x32_bf16 v[12:15], v[210:213], v[242:245], v[12:15]
	v_mfma_f32_16x16x32_bf16 v[8:11], v[218:221], v[230:233], v[8:11]
	v_mfma_f32_16x16x32_bf16 v[4:7], v[218:221], v[242:245], v[4:7]
	s_barrier
	ds_read_b128 v[174:177], v159
	ds_read_b128 v[178:181], v159 offset:1024
	ds_read_b128 v[182:185], v159 offset:2048
	ds_read_b128 v[186:189], v159 offset:3072
	v_lshl_add_u64 v[226:227], v[222:223], 0, s[44:45]
	s_or_b32 m0, s100, 0x4000
	ds_read_b128 v[190:193], v156 offset:32768
	ds_read_b128 v[194:197], v156 offset:33792
	ds_read_b128 v[198:201], v155 offset:32768
	ds_read_b128 v[202:205], v155 offset:33792
	ds_read_b128 v[206:209], v154 offset:32768
	ds_read_b128 v[210:213], v154 offset:33792
	ds_read_b128 v[214:217], v153 offset:32768
	ds_read_b128 v[218:221], v153 offset:33792
	global_load_lds_dwordx4 v[226:227], off
	s_or_b32 m0, s100, 0x6000
	v_lshl_add_u64 v[226:227], v[236:237], 0, s[44:45]
	global_load_lds_dwordx4 v[226:227], off
	s_waitcnt lgkmcnt(8)
	s_barrier
	s_waitcnt lgkmcnt(0)
	v_mfma_f32_16x16x32_bf16 v[128:131], v[190:193], v[174:177], v[128:131]
	v_mfma_f32_16x16x32_bf16 v[124:127], v[190:193], v[182:185], v[124:127]
	v_mfma_f32_16x16x32_bf16 v[120:123], v[198:201], v[174:177], v[120:123]
	v_mfma_f32_16x16x32_bf16 v[116:119], v[198:201], v[182:185], v[116:119]
	v_mfma_f32_16x16x32_bf16 v[112:115], v[206:209], v[174:177], v[112:115]
	v_mfma_f32_16x16x32_bf16 v[108:111], v[206:209], v[182:185], v[108:111]
	v_mfma_f32_16x16x32_bf16 v[104:107], v[214:217], v[174:177], v[104:107]
	v_mfma_f32_16x16x32_bf16 v[100:103], v[214:217], v[182:185], v[100:103]
	v_mfma_f32_16x16x32_bf16 v[128:131], v[194:197], v[178:181], v[128:131]
	v_mfma_f32_16x16x32_bf16 v[124:127], v[194:197], v[186:189], v[124:127]
	v_mfma_f32_16x16x32_bf16 v[120:123], v[202:205], v[178:181], v[120:123]
	v_mfma_f32_16x16x32_bf16 v[116:119], v[202:205], v[186:189], v[116:119]
	v_mfma_f32_16x16x32_bf16 v[112:115], v[210:213], v[178:181], v[112:115]
	v_mfma_f32_16x16x32_bf16 v[108:111], v[210:213], v[186:189], v[108:111]
	v_mfma_f32_16x16x32_bf16 v[104:107], v[218:221], v[178:181], v[104:107]
	v_mfma_f32_16x16x32_bf16 v[100:103], v[218:221], v[186:189], v[100:103]
	s_barrier
	v_lshl_add_u64 v[250:251], v[246:247], 0, s[46:47]
	s_or_b32 m0, s100, 0x18000
	ds_read_b128 v[226:229], v158
	ds_read_b128 v[230:233], v158 offset:1024
	ds_read_b128 v[238:241], v158 offset:2048
	ds_read_b128 v[242:245], v158 offset:3072
	global_load_lds_dwordx4 v[250:251], off
	s_or_b32 m0, s100, 0x1a000
	v_lshl_add_u64 v[250:251], v[248:249], 0, s[46:47]
	global_load_lds_dwordx4 v[250:251], off
	s_barrier
	s_waitcnt lgkmcnt(0)
	v_mfma_f32_16x16x32_bf16 v[96:99], v[190:193], v[226:229], v[96:99]
	v_mfma_f32_16x16x32_bf16 v[92:95], v[190:193], v[238:241], v[92:95]
	v_mfma_f32_16x16x32_bf16 v[88:91], v[198:201], v[226:229], v[88:91]
	v_mfma_f32_16x16x32_bf16 v[84:87], v[198:201], v[238:241], v[84:87]
	v_mfma_f32_16x16x32_bf16 v[80:83], v[206:209], v[226:229], v[80:83]
	v_mfma_f32_16x16x32_bf16 v[76:79], v[206:209], v[238:241], v[76:79]
	v_mfma_f32_16x16x32_bf16 v[72:75], v[214:217], v[226:229], v[72:75]
	v_mfma_f32_16x16x32_bf16 v[68:71], v[214:217], v[238:241], v[68:71]
	v_mfma_f32_16x16x32_bf16 v[96:99], v[194:197], v[230:233], v[96:99]
	v_mfma_f32_16x16x32_bf16 v[92:95], v[194:197], v[242:245], v[92:95]
	v_mfma_f32_16x16x32_bf16 v[88:91], v[202:205], v[230:233], v[88:91]
	v_mfma_f32_16x16x32_bf16 v[84:87], v[202:205], v[242:245], v[84:87]
	v_mfma_f32_16x16x32_bf16 v[80:83], v[210:213], v[230:233], v[80:83]
	v_mfma_f32_16x16x32_bf16 v[76:79], v[210:213], v[242:245], v[76:79]
	v_mfma_f32_16x16x32_bf16 v[72:75], v[218:221], v[230:233], v[72:75]
	v_mfma_f32_16x16x32_bf16 v[68:71], v[218:221], v[242:245], v[68:71]
	v_lshl_add_u64 v[222:223], v[222:223], 0, s[48:49]
	s_or_b32 m0, s100, 0x8000
	s_barrier
	ds_read_b128 v[190:193], v156 offset:49152
	ds_read_b128 v[194:197], v156 offset:50176
	ds_read_b128 v[198:201], v155 offset:49152
	ds_read_b128 v[202:205], v155 offset:50176
	ds_read_b128 v[206:209], v154 offset:49152
	ds_read_b128 v[210:213], v154 offset:50176
	ds_read_b128 v[214:217], v153 offset:49152
	ds_read_b128 v[218:221], v153 offset:50176
	global_load_lds_dwordx4 v[222:223], off
	s_or_b32 m0, s100, 0xa000
	v_lshl_add_u64 v[222:223], v[236:237], 0, s[48:49]
	global_load_lds_dwordx4 v[222:223], off
	s_barrier
; #define LDA8(dst, b, h) _Pragma("unroll") for (int m = 0; m < 4; ++m) _Pragma("unroll") for (int k = 0; k < 2; ++k) \
;     dst[m][k] = *(const bf16x8*)((const char*)SA8(b, h) + lds_byte8(wr * 64 + m * 16 + fr, k * 32 + fq * 8))
; #define LDB8(dst, b, h) _Pragma("unroll") for (int n = 0; n < 2; ++n) _Pragma("unroll") for (int k = 0; k < 2; ++k) \
;     dst[n][k] = *(const bf16x8*)((const char*)SB8(b, h) + lds_byte8(wc * 32 + n * 16 + fr, k * 32 + fq * 8))
; #define WAIT_V8(n) asm volatile("s_waitcnt vmcnt(" #n ")" ::: "memory")
; #define WAIT_L8(n) asm volatile("s_waitcnt lgkmcnt(" #n ")" ::: "memory")
; #define BAR8 __builtin_amdgcn_s_barrier()
;     ...
;     STAGE8(SB8(1, 1), Bt, K, bcol + 128, tt + 3);
;     WAIT_V8(6); BAR8; MMA8(1, 1, At, B1); BAR8;
;   }
;   { LDB8(B0, 0, 0); LDA8(At, 0, 0); STAGE8(SA8(1, 1), A, lda, brow + 128, nt - 1);
;     BAR8; WAIT_L8(0); MMA8(0, 0, At, B0); BAR8;
;     LDB8(B1, 0, 1); BAR8; WAIT_L8(0); MMA8(0, 1, At, B1); BAR8;
;     LDA8(At, 0, 1); WAIT_V8(4); BAR8; WAIT_L8(0); MMA8(1, 0, At, B0); MMA8(1, 1, At, B1); BAR8; }
	s_waitcnt lgkmcnt(0)
	v_mfma_f32_16x16x32_bf16 v[64:67], v[190:193], v[174:177], v[64:67]
	v_mfma_f32_16x16x32_bf16 v[60:63], v[190:193], v[182:185], v[60:63]
	v_mfma_f32_16x16x32_bf16 v[56:59], v[198:201], v[174:177], v[56:59]
	v_mfma_f32_16x16x32_bf16 v[52:55], v[198:201], v[182:185], v[52:55]
	v_mfma_f32_16x16x32_bf16 v[48:51], v[206:209], v[174:177], v[48:51]
	v_mfma_f32_16x16x32_bf16 v[44:47], v[206:209], v[182:185], v[44:47]
	v_mfma_f32_16x16x32_bf16 v[40:43], v[214:217], v[174:177], v[40:43]
	v_mfma_f32_16x16x32_bf16 v[36:39], v[214:217], v[182:185], v[36:39]
	v_mfma_f32_16x16x32_bf16 v[64:67], v[194:197], v[178:181], v[64:67]
	v_mfma_f32_16x16x32_bf16 v[60:63], v[194:197], v[186:189], v[60:63]
	v_mfma_f32_16x16x32_bf16 v[56:59], v[202:205], v[178:181], v[56:59]
	v_mfma_f32_16x16x32_bf16 v[52:55], v[202:205], v[186:189], v[52:55]
	v_mfma_f32_16x16x32_bf16 v[48:51], v[210:213], v[178:181], v[48:51]
	v_mfma_f32_16x16x32_bf16 v[44:47], v[210:213], v[186:189], v[44:47]
	v_mfma_f32_16x16x32_bf16 v[40:43], v[218:221], v[178:181], v[40:43]
	v_mfma_f32_16x16x32_bf16 v[36:39], v[218:221], v[186:189], v[36:39]
	s_barrier
	s_or_b32 m0, s100, 0x1c000
	v_lshl_add_u64 v[174:175], v[246:247], 0, s[50:51]
	global_load_lds_dwordx4 v[174:175], off
	s_or_b32 m0, s100, 0x1e000
	v_lshl_add_u64 v[174:175], v[248:249], 0, s[50:51]
	global_load_lds_dwordx4 v[174:175], off
	s_waitcnt vmcnt(6)
	s_barrier
	v_mfma_f32_16x16x32_bf16 v[32:35], v[190:193], v[226:229], v[32:35]
	v_mfma_f32_16x16x32_bf16 v[28:31], v[190:193], v[238:241], v[28:31]
	v_mfma_f32_16x16x32_bf16 v[24:27], v[198:201], v[226:229], v[24:27]
	v_mfma_f32_16x16x32_bf16 v[20:23], v[198:201], v[238:241], v[20:23]
	v_mfma_f32_16x16x32_bf16 v[16:19], v[206:209], v[226:229], v[16:19]
	v_mfma_f32_16x16x32_bf16 v[12:15], v[206:209], v[238:241], v[12:15]
	v_mfma_f32_16x16x32_bf16 v[8:11], v[214:217], v[226:229], v[8:11]
	v_mfma_f32_16x16x32_bf16 v[4:7], v[214:217], v[238:241], v[4:7]
	v_mfma_f32_16x16x32_bf16 v[32:35], v[194:197], v[230:233], v[32:35]
	v_mfma_f32_16x16x32_bf16 v[28:31], v[194:197], v[242:245], v[28:31]
	v_mfma_f32_16x16x32_bf16 v[24:27], v[202:205], v[230:233], v[24:27]
	v_mfma_f32_16x16x32_bf16 v[20:23], v[202:205], v[242:245], v[20:23]
	v_mfma_f32_16x16x32_bf16 v[16:19], v[210:213], v[230:233], v[16:19]
	v_mfma_f32_16x16x32_bf16 v[12:15], v[210:213], v[242:245], v[12:15]
	v_mfma_f32_16x16x32_bf16 v[8:11], v[218:221], v[230:233], v[8:11]
	v_mfma_f32_16x16x32_bf16 v[4:7], v[218:221], v[242:245], v[4:7]
	s_add_i32 s29, s29, 2
	s_add_u32 s12, s12, 0x100
	s_addc_u32 s13, s13, 0
	s_cmp_lt_u32 s29, 40
	s_barrier
	s_cbranch_scc1 .LBB0_1325
.Lpk_exit_7:
	s_add_i32 s27, s27, 0xb0000
	s_add_u32 s2, s2, s27
	s_addc_u32 s3, s3, 0
	s_add_u32 s2, s2, 0x2001580
	s_addc_u32 s3, s3, 0
	v_lshl_add_u64 v[132:133], v[132:133], 1, s[2:3]
	v_lshl_add_u64 v[0:1], v[0:1], 1, v[132:133]
	s_or_b32 m0, s100, 0xc000
	ds_read_b128 v[138:141], v171
	ds_read_b128 v[142:145], v171 offset:1024
	ds_read_b128 v[160:163], v171 offset:2048
	ds_read_b128 v[164:167], v171 offset:3072
	ds_read_b128 v[174:177], v156
	ds_read_b128 v[178:181], v156 offset:1024
	ds_read_b128 v[182:185], v155
	ds_read_b128 v[186:189], v155 offset:1024
	ds_read_b128 v[190:193], v154
	ds_read_b128 v[194:197], v154 offset:1024
	ds_read_b128 v[198:201], v153
	ds_read_b128 v[202:205], v153 offset:1024
	global_load_lds_dwordx4 v[0:1], off
	v_lshl_add_u64 v[0:1], v[136:137], 1, s[2:3]
	s_or_b32 m0, s100, 0xe000
	v_lshl_add_u64 v[0:1], v[134:135], 1, v[0:1]
	global_load_lds_dwordx4 v[0:1], off
	s_barrier
	s_waitcnt lgkmcnt(0)
	v_mfma_f32_16x16x32_bf16 v[128:131], v[174:177], v[138:141], v[128:131]
	v_mfma_f32_16x16x32_bf16 v[124:127], v[174:177], v[160:163], v[124:127]
	v_mfma_f32_16x16x32_bf16 v[120:123], v[182:185], v[138:141], v[120:123]
	v_mfma_f32_16x16x32_bf16 v[112:115], v[190:193], v[138:141], v[112:115]
	v_mfma_f32_16x16x32_bf16 v[128:131], v[178:181], v[142:145], v[128:131]
	v_mfma_f32_16x16x32_bf16 v[124:127], v[178:181], v[164:167], v[124:127]
	v_mfma_f32_16x16x32_bf16 v[120:123], v[186:189], v[142:145], v[120:123]
	v_mfma_f32_16x16x32_bf16 v[116:119], v[182:185], v[160:163], v[116:119]
	v_mfma_f32_16x16x32_bf16 v[112:115], v[194:197], v[142:145], v[112:115]
	v_mfma_f32_16x16x32_bf16 v[108:111], v[190:193], v[160:163], v[108:111]
	v_mfma_f32_16x16x32_bf16 v[104:107], v[198:201], v[138:141], v[104:107]
	v_mfma_f32_16x16x32_bf16 v[100:103], v[198:201], v[160:163], v[100:103]
	v_mfma_f32_16x16x32_bf16 v[132:135], v[186:189], v[164:167], v[116:119]
	v_mfma_f32_16x16x32_bf16 v[170:173], v[194:197], v[164:167], v[108:111]
	v_mfma_f32_16x16x32_bf16 v[206:209], v[202:205], v[142:145], v[104:107]
	v_mfma_f32_16x16x32_bf16 v[210:213], v[202:205], v[164:167], v[100:103]
	s_barrier
	s_nop 1
	ds_read_b128 v[100:103], v169
	ds_read_b128 v[104:107], v169 offset:1024
	ds_read_b128 v[108:111], v169 offset:2048
	ds_read_b128 v[116:119], v169 offset:3072
	s_barrier
	s_waitcnt lgkmcnt(0)
	v_mfma_f32_16x16x32_bf16 v[80:83], v[190:193], v[100:103], v[80:83]
	v_mfma_f32_16x16x32_bf16 v[76:79], v[190:193], v[108:111], v[76:79]
	v_mfma_f32_16x16x32_bf16 v[72:75], v[198:201], v[100:103], v[72:75]
	v_mfma_f32_16x16x32_bf16 v[68:71], v[198:201], v[108:111], v[68:71]
	v_mfma_f32_16x16x32_bf16 v[96:99], v[174:177], v[100:103], v[96:99]
	v_mfma_f32_16x16x32_bf16 v[92:95], v[174:177], v[108:111], v[92:95]
	v_mfma_f32_16x16x32_bf16 v[88:91], v[182:185], v[100:103], v[88:91]
	v_mfma_f32_16x16x32_bf16 v[84:87], v[182:185], v[108:111], v[84:87]
	v_mfma_f32_16x16x32_bf16 v[80:83], v[194:197], v[104:107], v[80:83]
	v_mfma_f32_16x16x32_bf16 v[76:79], v[194:197], v[116:119], v[76:79]
	v_mfma_f32_16x16x32_bf16 v[72:75], v[202:205], v[104:107], v[72:75]
	v_mfma_f32_16x16x32_bf16 v[68:71], v[202:205], v[116:119], v[68:71]
	v_mfma_f32_16x16x32_bf16 v[214:217], v[178:181], v[104:107], v[96:99]
	v_mfma_f32_16x16x32_bf16 v[174:177], v[178:181], v[116:119], v[92:95]
	v_mfma_f32_16x16x32_bf16 v[178:181], v[186:189], v[104:107], v[88:91]
	v_mfma_f32_16x16x32_bf16 v[182:185], v[186:189], v[116:119], v[84:87]
	s_barrier
; #define LDA8(dst, b, h) _Pragma("unroll") for (int m = 0; m < 4; ++m) _Pragma("unroll") for (int k = 0; k < 2; ++k) \
;     dst[m][k] = *(const bf16x8*)((const char*)SA8(b, h) + lds_byte8(wr * 64 + m * 16 + fr, k * 32 + fq * 8))
; #define LDB8(dst, b, h) _Pragma("unroll") for (int n = 0; n < 2; ++n) _Pragma("unroll") for (int k = 0; k < 2; ++k) \
;     dst[n][k] = *(const bf16x8*)((const char*)SB8(b, h) + lds_byte8(wc * 32 + n * 16 + fr, k * 32 + fq * 8))
; #define WAIT_V8(n) asm volatile("s_waitcnt vmcnt(" #n ")" ::: "memory")
; #define WAIT_L8(n) asm volatile("s_waitcnt lgkmcnt(" #n ")" ::: "memory")
; #define BAR8 __builtin_amdgcn_s_barrier()
;     ...
;     LDA8(At, 0, 1); WAIT_V8(4); BAR8; WAIT_L8(0); MMA8(1, 0, At, B0); MMA8(1, 1, At, B1); BAR8; }
;   { LDB8(B0, 1, 0); LDA8(At, 1, 0); WAIT_V8(2); BAR8; WAIT_L8(0); MMA8(0, 0, At, B0); BAR8;
;     LDB8(B1, 1, 1); WAIT_V8(0); BAR8; WAIT_L8(0); MMA8(0, 1, At, B1); BAR8;
	s_nop 0
	ds_read_b128 v[84:87], v156 offset:16384
	ds_read_b128 v[88:91], v156 offset:17408
	ds_read_b128 v[92:95], v155 offset:16384
	ds_read_b128 v[96:99], v155 offset:17408
	ds_read_b128 v[186:189], v154 offset:16384
	ds_read_b128 v[190:193], v154 offset:17408
	ds_read_b128 v[194:197], v153 offset:16384
	ds_read_b128 v[198:201], v153 offset:17408
	s_waitcnt vmcnt(4)
	s_barrier
	s_waitcnt lgkmcnt(0)
	v_mfma_f32_16x16x32_bf16 v[64:67], v[84:87], v[138:141], v[64:67]
	v_mfma_f32_16x16x32_bf16 v[60:63], v[84:87], v[160:163], v[60:63]
	v_mfma_f32_16x16x32_bf16 v[56:59], v[92:95], v[138:141], v[56:59]
	v_mfma_f32_16x16x32_bf16 v[52:55], v[92:95], v[160:163], v[52:55]
	v_mfma_f32_16x16x32_bf16 v[48:51], v[186:189], v[138:141], v[48:51]
	v_mfma_f32_16x16x32_bf16 v[44:47], v[186:189], v[160:163], v[44:47]
	v_mfma_f32_16x16x32_bf16 v[40:43], v[194:197], v[138:141], v[40:43]
	v_mfma_f32_16x16x32_bf16 v[36:39], v[194:197], v[160:163], v[36:39]
	v_mfma_f32_16x16x32_bf16 v[64:67], v[88:91], v[142:145], v[64:67]
	v_mfma_f32_16x16x32_bf16 v[60:63], v[88:91], v[164:167], v[60:63]
	v_mfma_f32_16x16x32_bf16 v[56:59], v[96:99], v[142:145], v[56:59]
	v_mfma_f32_16x16x32_bf16 v[52:55], v[96:99], v[164:167], v[52:55]
	v_mfma_f32_16x16x32_bf16 v[48:51], v[190:193], v[142:145], v[48:51]
	v_mfma_f32_16x16x32_bf16 v[44:47], v[190:193], v[164:167], v[44:47]
	v_mfma_f32_16x16x32_bf16 v[40:43], v[198:201], v[142:145], v[40:43]
	v_mfma_f32_16x16x32_bf16 v[36:39], v[198:201], v[164:167], v[36:39]
	v_mfma_f32_16x16x32_bf16 v[32:35], v[84:87], v[100:103], v[32:35]
	v_mfma_f32_16x16x32_bf16 v[28:31], v[84:87], v[108:111], v[28:31]
	v_mfma_f32_16x16x32_bf16 v[24:27], v[92:95], v[100:103], v[24:27]
	v_mfma_f32_16x16x32_bf16 v[20:23], v[92:95], v[108:111], v[20:23]
	v_mfma_f32_16x16x32_bf16 v[16:19], v[186:189], v[100:103], v[16:19]
	v_mfma_f32_16x16x32_bf16 v[12:15], v[186:189], v[108:111], v[12:15]
	v_mfma_f32_16x16x32_bf16 v[8:11], v[194:197], v[100:103], v[8:11]
	v_mfma_f32_16x16x32_bf16 v[4:7], v[194:197], v[108:111], v[4:7]
	v_mfma_f32_16x16x32_bf16 v[136:139], v[88:91], v[104:107], v[32:35]
	v_mfma_f32_16x16x32_bf16 v[140:143], v[88:91], v[116:119], v[28:31]
	v_mfma_f32_16x16x32_bf16 v[160:163], v[96:99], v[104:107], v[24:27]
	v_mfma_f32_16x16x32_bf16 v[164:167], v[96:99], v[116:119], v[20:23]
	v_mfma_f32_16x16x32_bf16 v[202:205], v[190:193], v[104:107], v[16:19]
	v_mfma_f32_16x16x32_bf16 v[186:189], v[190:193], v[116:119], v[12:15]
	v_mfma_f32_16x16x32_bf16 v[190:193], v[198:201], v[104:107], v[8:11]
	v_mfma_f32_16x16x32_bf16 v[194:197], v[198:201], v[116:119], v[4:7]
	s_barrier
	ds_read_b128 v[198:201], v159
	ds_read_b128 v[218:221], v159 offset:1024
	ds_read_b128 v[226:229], v159 offset:2048
	ds_read_b128 v[230:233], v159 offset:3072
	ds_read_b128 v[8:11], v156 offset:32768
	ds_read_b128 v[12:15], v156 offset:33792
	ds_read_b128 v[16:19], v155 offset:32768
	ds_read_b128 v[24:27], v155 offset:33792
	ds_read_b128 v[28:31], v154 offset:32768
	ds_read_b128 v[32:35], v154 offset:33792
	ds_read_b128 v[238:241], v153 offset:32768
	ds_read_b128 v[242:245], v153 offset:33792
	s_waitcnt vmcnt(2)
	s_barrier
	s_waitcnt lgkmcnt(0)
	v_mfma_f32_16x16x32_bf16 v[4:7], v[8:11], v[198:201], v[128:131]
	v_mfma_f32_16x16x32_bf16 v[104:107], v[12:15], v[218:221], v[4:7]
	v_mfma_f32_16x16x32_bf16 v[4:7], v[8:11], v[226:229], v[124:127]
	v_mfma_f32_16x16x32_bf16 v[116:119], v[12:15], v[230:233], v[4:7]
	v_mfma_f32_16x16x32_bf16 v[4:7], v[16:19], v[198:201], v[120:123]
	v_mfma_f32_16x16x32_bf16 v[100:103], v[24:27], v[218:221], v[4:7]
	v_mfma_f32_16x16x32_bf16 v[4:7], v[16:19], v[226:229], v[132:135]
	v_mfma_f32_16x16x32_bf16 v[108:111], v[24:27], v[230:233], v[4:7]
	v_mfma_f32_16x16x32_bf16 v[4:7], v[28:31], v[198:201], v[112:115]
	v_mfma_f32_16x16x32_bf16 v[92:95], v[32:35], v[218:221], v[4:7]
	v_mfma_f32_16x16x32_bf16 v[4:7], v[28:31], v[226:229], v[170:173]
	v_mfma_f32_16x16x32_bf16 v[96:99], v[32:35], v[230:233], v[4:7]
	v_mfma_f32_16x16x32_bf16 v[4:7], v[238:241], v[198:201], v[206:209]
	v_mfma_f32_16x16x32_bf16 v[84:87], v[242:245], v[218:221], v[4:7]
	v_mfma_f32_16x16x32_bf16 v[4:7], v[238:241], v[226:229], v[210:213]
	v_mfma_f32_16x16x32_bf16 v[88:91], v[242:245], v[230:233], v[4:7]
	s_barrier
; #define LDA8(dst, b, h) _Pragma("unroll") for (int m = 0; m < 4; ++m) _Pragma("unroll") for (int k = 0; k < 2; ++k) \
;     dst[m][k] = *(const bf16x8*)((const char*)SA8(b, h) + lds_byte8(wr * 64 + m * 16 + fr, k * 32 + fq * 8))
; #define LDB8(dst, b, h) _Pragma("unroll") for (int n = 0; n < 2; ++n) _Pragma("unroll") for (int k = 0; k < 2; ++k) \
;     dst[n][k] = *(const bf16x8*)((const char*)SB8(b, h) + lds_byte8(wc * 32 + n * 16 + fr, k * 32 + fq * 8))
; #define WAIT_V8(n) asm volatile("s_waitcnt vmcnt(" #n ")" ::: "memory")
; #define WAIT_L8(n) asm volatile("s_waitcnt lgkmcnt(" #n ")" ::: "memory")
; #define BAR8 __builtin_amdgcn_s_barrier()
;     ...
;     LDB8(B1, 1, 1); WAIT_V8(0); BAR8; WAIT_L8(0); MMA8(0, 1, At, B1); BAR8;
;     LDA8(At, 1, 1); BAR8; WAIT_L8(0); MMA8(1, 0, At, B0); MMA8(1, 1, At, B1); BAR8; }
;   if (wr == 0) BAR8;
;   __syncthreads();
	ds_read_b128 v[132:135], v158
	ds_read_b128 v[168:171], v158 offset:1024
	ds_read_b128 v[206:209], v158 offset:2048
	ds_read_b128 v[210:213], v158 offset:3072
	s_waitcnt vmcnt(0)
	s_barrier
	s_waitcnt lgkmcnt(0)
	v_mfma_f32_16x16x32_bf16 v[4:7], v[8:11], v[132:135], v[214:217]
	v_mfma_f32_16x16x32_bf16 v[8:11], v[8:11], v[206:209], v[174:177]
	v_mfma_f32_16x16x32_bf16 v[4:7], v[12:15], v[168:171], v[4:7]
	v_mfma_f32_16x16x32_bf16 v[20:23], v[12:15], v[210:213], v[8:11]
	v_mfma_f32_16x16x32_bf16 v[8:11], v[16:19], v[132:135], v[178:181]
	v_mfma_f32_16x16x32_bf16 v[12:15], v[16:19], v[206:209], v[182:185]
	v_mfma_f32_16x16x32_bf16 v[8:11], v[24:27], v[168:171], v[8:11]
	v_mfma_f32_16x16x32_bf16 v[24:27], v[24:27], v[210:213], v[12:15]
	v_mfma_f32_16x16x32_bf16 v[12:15], v[28:31], v[132:135], v[80:83]
	v_mfma_f32_16x16x32_bf16 v[16:19], v[28:31], v[206:209], v[76:79]
	v_mfma_f32_16x16x32_bf16 v[12:15], v[32:35], v[168:171], v[12:15]
	v_mfma_f32_16x16x32_bf16 v[28:31], v[32:35], v[210:213], v[16:19]
	v_mfma_f32_16x16x32_bf16 v[16:19], v[238:241], v[132:135], v[72:75]
	v_mfma_f32_16x16x32_bf16 v[32:35], v[238:241], v[206:209], v[68:71]
	v_mfma_f32_16x16x32_bf16 v[16:19], v[242:245], v[168:171], v[16:19]
	v_mfma_f32_16x16x32_bf16 v[32:35], v[242:245], v[210:213], v[32:35]
	s_barrier
	ds_read_b128 v[172:175], v156 offset:49152
	ds_read_b128 v[156:159], v156 offset:50176
	ds_read_b128 v[176:179], v155 offset:49152
	ds_read_b128 v[180:183], v155 offset:50176
	ds_read_b128 v[214:217], v154 offset:49152
	ds_read_b128 v[238:241], v154 offset:50176
	ds_read_b128 v[242:245], v153 offset:49152
	ds_read_b128 v[150:153], v153 offset:50176
	s_barrier
	s_waitcnt lgkmcnt(0)
	v_mfma_f32_16x16x32_bf16 v[64:67], v[172:175], v[198:201], v[64:67]
	v_mfma_f32_16x16x32_bf16 v[60:63], v[172:175], v[226:229], v[60:63]
	v_mfma_f32_16x16x32_bf16 v[56:59], v[176:179], v[198:201], v[56:59]
	v_mfma_f32_16x16x32_bf16 v[52:55], v[176:179], v[226:229], v[52:55]
	v_mfma_f32_16x16x32_bf16 v[48:51], v[214:217], v[198:201], v[48:51]
	v_mfma_f32_16x16x32_bf16 v[44:47], v[214:217], v[226:229], v[44:47]
	v_mfma_f32_16x16x32_bf16 v[40:43], v[242:245], v[198:201], v[40:43]
	v_mfma_f32_16x16x32_bf16 v[36:39], v[242:245], v[226:229], v[36:39]
	v_mfma_f32_16x16x32_bf16 v[128:131], v[156:159], v[218:221], v[64:67]
	v_mfma_f32_16x16x32_bf16 v[124:127], v[156:159], v[230:233], v[60:63]
	v_mfma_f32_16x16x32_bf16 v[120:123], v[180:183], v[218:221], v[56:59]
	v_mfma_f32_16x16x32_bf16 v[112:115], v[180:183], v[230:233], v[52:55]
	v_mfma_f32_16x16x32_bf16 v[80:83], v[238:241], v[218:221], v[48:51]
	v_mfma_f32_16x16x32_bf16 v[76:79], v[238:241], v[230:233], v[44:47]
	v_mfma_f32_16x16x32_bf16 v[72:75], v[150:153], v[218:221], v[40:43]
	v_mfma_f32_16x16x32_bf16 v[68:71], v[150:153], v[230:233], v[36:39]
	v_mfma_f32_16x16x32_bf16 v[40:43], v[172:175], v[206:209], v[140:143]
	v_mfma_f32_16x16x32_bf16 v[44:47], v[176:179], v[206:209], v[164:167]
	v_mfma_f32_16x16x32_bf16 v[48:51], v[214:217], v[206:209], v[186:189]
	v_mfma_f32_16x16x32_bf16 v[36:39], v[172:175], v[132:135], v[136:139]
	v_mfma_f32_16x16x32_bf16 v[52:55], v[156:159], v[210:213], v[40:43]
	v_mfma_f32_16x16x32_bf16 v[40:43], v[176:179], v[132:135], v[160:163]
	v_mfma_f32_16x16x32_bf16 v[56:59], v[180:183], v[210:213], v[44:47]
	v_mfma_f32_16x16x32_bf16 v[44:47], v[214:217], v[132:135], v[202:205]
	v_mfma_f32_16x16x32_bf16 v[60:63], v[238:241], v[210:213], v[48:51]
	v_mfma_f32_16x16x32_bf16 v[48:51], v[242:245], v[132:135], v[190:193]
	v_mfma_f32_16x16x32_bf16 v[64:67], v[242:245], v[206:209], v[194:197]
	v_mfma_f32_16x16x32_bf16 v[36:39], v[156:159], v[168:171], v[36:39]
	v_mfma_f32_16x16x32_bf16 v[40:43], v[180:183], v[168:171], v[40:43]
	v_mfma_f32_16x16x32_bf16 v[44:47], v[238:241], v[168:171], v[44:47]
	v_mfma_f32_16x16x32_bf16 v[48:51], v[150:153], v[168:171], v[48:51]
	v_mfma_f32_16x16x32_bf16 v[64:67], v[150:153], v[210:213], v[64:67]
	s_movk_i32 s2, 0x100
	v_cmp_gt_u32_e32 vcc, s2, v3
	s_barrier
	s_and_saveexec_b64 s[2:3], vcc
	s_cbranch_execz .LBB0_1328
	s_barrier
